# VALU trimming: att softmax copy without band-mask selects for provably unmasked tiles; rg_coeffs epilogue parameter loads batched
# baseline (speedup 1.0000x reference)
.LBB0_580:
	v_add_u32_e32 v68, v67, v65
	ds_read_b128 v[72:75], v67 offset:18432
	ds_read_b128 v[76:79], v68
	s_add_i32 s0, s0, 32
	s_cmp_lt_u32 s0, 48
	s_waitcnt lgkmcnt(0)
	v_mfma_f32_32x32x16_bf16 v[48:63], v[76:79], v[72:75], v[48:63]
	ds_read_b128 v[72:75], v67 offset:23040
	s_waitcnt lgkmcnt(0)
	v_mfma_f32_32x32x16_bf16 v[16:31], v[76:79], v[72:75], v[16:31]
	ds_read_b128 v[72:75], v67 offset:27648
	s_waitcnt lgkmcnt(0)
	v_mfma_f32_32x32x16_bf16 v[32:47], v[76:79], v[72:75], v[32:47]
	ds_read_b128 v[72:75], v67 offset:32256
	ds_read_b128 v[80:83], v67 offset:18464
	s_waitcnt lgkmcnt(1)
	v_mfma_f32_32x32x16_bf16 v[0:15], v[76:79], v[72:75], v[0:15]
	ds_read_b128 v[72:75], v68 offset:32
	ds_read_b128 v[76:79], v67 offset:23072
	s_waitcnt lgkmcnt(0)
	v_mfma_f32_32x32x16_bf16 v[16:31], v[72:75], v[76:79], v[16:31]
	ds_read_b128 v[76:79], v67 offset:27680
	s_waitcnt lgkmcnt(0)
	v_mfma_f32_32x32x16_bf16 v[32:47], v[72:75], v[76:79], v[32:47]
	ds_read_b128 v[76:79], v67 offset:32288
	v_add_u32_e32 v67, 64, v67
	v_mfma_f32_32x32x16_bf16 v[48:63], v[72:75], v[80:83], v[48:63]
	s_waitcnt lgkmcnt(0)
	v_mfma_f32_32x32x16_bf16 v[0:15], v[72:75], v[76:79], v[0:15]
	s_cbranch_scc1 .LBB0_580
	s_lshl_b32 s0, s39, 9
	s_or_b32 s6, s0, s3
	v_or_b32_e32 v96, s6, v71
	v_readlane_b32 s8, v251, 20
	v_lshlrev_b32_e32 v67, 11, v64
	v_lshlrev_b64 v[64:65], 2, v[96:97]
	v_readlane_b32 s10, v251, 22
	v_readlane_b32 s11, v251, 23
	s_barrier
	s_nop 0
	v_lshl_add_u64 v[68:69], s[10:11], 0, v[64:65]
	v_readlane_b32 s100, v251, 16
	v_readlane_b32 s101, v251, 17
	s_nop 1
	v_lshl_add_u64 v[220:221], s[100:101], 0, v[64:65]
	v_readlane_b32 s100, v251, 20
	v_readlane_b32 s101, v251, 21
	s_nop 1
	v_lshl_add_u64 v[222:223], s[100:101], 0, v[64:65]
	global_load_dword v224, v[220:221], off
	global_load_dword v225, v[222:223], off
	global_load_dword v226, v[68:69], off offset:128
	global_load_dword v227, v[222:223], off offset:128
	global_load_dword v228, v[220:221], off offset:128
	global_load_dword v68, v[68:69], off
	s_mov_b32 s7, 0x3f2aaaab
	s_mov_b32 s39, 0x3f317218
	v_readlane_b32 s12, v251, 24
	v_readlane_b32 s13, v251, 25
	v_readlane_b32 s14, v251, 26
	v_readlane_b32 s15, v251, 27
	v_readlane_b32 s16, v251, 28
	v_readlane_b32 s17, v251, 29
	v_readlane_b32 s18, v251, 30
	v_readlane_b32 s19, v251, 31
	v_readlane_b32 s20, v251, 32
	v_readlane_b32 s21, v251, 33
	v_readlane_b32 s22, v251, 34
	v_readlane_b32 s23, v251, 35
	v_readlane_b32 s12, v251, 4
	v_readlane_b32 s24, v251, 16
	v_readlane_b32 s25, v251, 17
	v_readlane_b32 s9, v251, 21
	s_mov_b32 s40, 0x7f800000
	s_mov_b32 s41, 0x33800000
	v_readlane_b32 s15, v251, 7
	s_mov_b32 s15, 0x43000000
	v_readlane_b32 s16, v251, 8
	s_mov_b32 s16, 0x42b17217
	v_readlane_b32 s17, v251, 9
	s_mov_b32 s17, 0xf800000
	v_readlane_b32 s18, v251, 10
	s_mov_b32 s18, 0xc1880000
	v_add_u32_e32 v96, s6, v71
	s_cmp_eq_u32 s38, 0
	s_mov_b32 s4, 0
	v_readlane_b32 s13, v251, 5
	v_readlane_b32 s14, v251, 6
	v_readlane_b32 s19, v251, 11
	v_readlane_b32 s20, v251, 12
	v_readlane_b32 s21, v251, 13
	v_readlane_b32 s22, v251, 14
	v_readlane_b32 s23, v251, 15
	v_readlane_b32 s26, v251, 18
	v_readlane_b32 s27, v251, 19
	s_waitcnt vmcnt(0)
	v_mul_f32_e32 v68, 0xbfb8aa3b, v68
	v_exp_f32_e32 v70, v68
	s_nop 0
	v_add_f32_e32 v72, 1.0, v70
	v_add_f32_e32 v68, -1.0, v72
	v_sub_f32_e32 v69, v68, v72
	v_add_f32_e32 v69, 1.0, v69
	v_sub_f32_e32 v68, v70, v68
	v_add_f32_e32 v73, v68, v69
	v_frexp_mant_f32_e32 v68, v72
	v_cmp_gt_f32_e32 vcc, s7, v68
	v_cvt_f64_f32_e32 v[68:69], v72
	v_frexp_exp_i32_f64_e32 v68, v[68:69]
	v_subbrev_co_u32_e32 v78, vcc, 0, v68, vcc
	v_sub_u32_e32 v68, 0, v78
	v_ldexp_f32 v69, v72, v68
	v_add_f32_e32 v72, -1.0, v69
	v_add_f32_e32 v74, 1.0, v69
	v_ldexp_f32 v68, v73, v68
	v_add_f32_e32 v73, 1.0, v72
	v_add_f32_e32 v75, -1.0, v74
	v_sub_f32_e32 v73, v69, v73
	v_sub_f32_e32 v69, v69, v75
	v_add_f32_e32 v73, v68, v73
	v_add_f32_e32 v68, v68, v69
	v_add_f32_e32 v79, v74, v68
	v_rcp_f32_e32 v81, v79
	v_sub_f32_e32 v69, v79, v74
	v_sub_f32_e32 v80, v68, v69
	v_add_f32_e32 v69, v72, v73
	v_mul_f32_e32 v83, v69, v81
	v_sub_f32_e32 v68, v69, v72
	v_mul_f32_e32 v72, v79, v83
	v_fma_f32 v74, v83, v79, -v72
	v_fmac_f32_e32 v74, v83, v80
	v_sub_f32_e32 v82, v73, v68
	v_add_f32_e32 v68, v72, v74
	v_sub_f32_e32 v73, v69, v68
	v_pk_add_f32 v[76:77], v[68:69], v[72:73] neg_lo:[0,1] neg_hi:[0,1]
	v_mov_b32_e32 v75, v68
	v_pk_add_f32 v[68:69], v[76:77], v[74:75] neg_lo:[0,1] neg_hi:[0,1]
	v_cmp_neq_f32_e32 vcc, s40, v70
	v_add_f32_e32 v69, v82, v69
	v_add_f32_e32 v68, v68, v69
	v_add_f32_e32 v69, v73, v68
	v_mul_f32_e32 v82, v81, v69
	v_mul_f32_e32 v72, v79, v82
	v_fma_f32 v74, v82, v79, -v72
	v_fmac_f32_e32 v74, v82, v80
	v_sub_f32_e32 v73, v73, v69
	v_add_f32_e32 v79, v68, v73
	v_add_f32_e32 v68, v72, v74
	v_sub_f32_e32 v73, v69, v68
	v_pk_add_f32 v[76:77], v[68:69], v[72:73] neg_lo:[0,1] neg_hi:[0,1]
	v_mov_b32_e32 v75, v68
	v_pk_add_f32 v[68:69], v[76:77], v[74:75] neg_lo:[0,1] neg_hi:[0,1]
	s_nop 0
	v_add_f32_e32 v69, v79, v69
	v_add_f32_e32 v68, v68, v69
	v_add_f32_e32 v69, v83, v82
	v_add_f32_e32 v68, v73, v68
	v_sub_f32_e32 v72, v69, v83
	v_mul_f32_e32 v68, v81, v68
	v_sub_f32_e32 v72, v82, v72
	v_add_f32_e32 v72, v72, v68
	v_add_f32_e32 v74, v69, v72
	v_mul_f32_e32 v75, v74, v74
	v_fmamk_f32 v68, v75, 0x3e9b6dac, v191
	v_fmaak_f32 v169, v75, v68, 0x3f2aaada
	v_cvt_f32_i32_e32 v68, v78
	v_sub_f32_e32 v69, v74, v69
	v_sub_f32_e32 v69, v72, v69
	v_ldexp_f32 v76, v69, 1
	v_mul_f32_e32 v69, v74, v75
	v_ldexp_f32 v73, v74, 1
	v_pk_mul_f32 v[74:75], v[68:69], v[168:169]
	s_nop 0
	v_fma_f32 v72, v68, s39, -v74
	v_fmac_f32_e32 v72, 0xb102e308, v68
	v_pk_add_f32 v[68:69], v[74:75], v[72:73]
	s_nop 0
	v_sub_f32_e32 v73, v69, v73
	v_sub_f32_e32 v73, v75, v73
	v_add_f32_e32 v77, v76, v73
	v_mov_b32_e32 v76, v74
	v_pk_add_f32 v[74:75], v[68:69], v[74:75] neg_lo:[0,1] neg_hi:[0,1]
	v_pk_add_f32 v[78:79], v[68:69], v[76:77]
	v_mov_b32_e32 v73, v68
	v_mov_b32_e32 v75, v79
	v_pk_add_f32 v[80:81], v[72:73], v[74:75] neg_lo:[0,1] neg_hi:[0,1]
	v_pk_add_f32 v[72:73], v[72:73], v[74:75]
	v_mov_b32_e32 v76, v77
	v_pk_add_f32 v[74:75], v[72:73], v[68:69] op_sel:[1,0] op_sel_hi:[0,1] neg_lo:[0,1] neg_hi:[0,1]
	v_pk_add_f32 v[82:83], v[78:79], v[74:75] op_sel_hi:[1,0] neg_lo:[0,1] neg_hi:[0,1]
	v_mov_b32_e32 v78, v79
	v_mov_b32_e32 v79, v73
	v_pk_mov_b32 v[74:75], v[68:69], v[74:75] op_sel:[1,0]
	v_mov_b32_e32 v77, v68
	v_pk_add_f32 v[74:75], v[78:79], v[74:75] neg_lo:[0,1] neg_hi:[0,1]
	v_mov_b32_e32 v82, v80
	v_pk_add_f32 v[68:69], v[76:77], v[74:75] neg_lo:[0,1] neg_hi:[0,1]
	v_mov_b32_e32 v81, v73
	v_pk_add_f32 v[74:75], v[82:83], v[68:69]
	s_nop 0
	v_pk_add_f32 v[76:77], v[74:75], v[74:75] op_sel:[0,1] op_sel_hi:[1,0]
	s_nop 0
	v_pk_add_f32 v[72:73], v[72:73], v[76:77] op_sel:[1,0] op_sel_hi:[0,1]
	v_mov_b32_e32 v75, v72
	v_pk_add_f32 v[78:79], v[74:75], v[80:81] neg_lo:[0,1] neg_hi:[0,1]
	v_mov_b32_e32 v69, v76
	v_sub_f32_e32 v73, v74, v78
	v_pk_add_f32 v[68:69], v[68:69], v[78:79] neg_lo:[0,1] neg_hi:[0,1]
	v_sub_f32_e32 v73, v80, v73
	v_add_f32_e32 v68, v68, v73
	v_add_f32_e32 v68, v68, v69
	v_add_f32_e32 v68, v72, v68
	v_lshl_add_u64 v[72:73], s[24:25], 0, v[64:65]
	v_mov_b32_e32 v74, v224
	v_lshl_add_u64 v[64:65], s[8:9], 0, v[64:65]
	v_mov_b32_e32 v73, v225
	v_cndmask_b32_e32 v68, v199, v68, vcc
	v_cmp_ngt_f32_e32 vcc, -1.0, v70
	s_waitcnt vmcnt(1)
	v_add_f32_e32 v48, v48, v74
	v_mul_f32_e32 v48, 0xbfb8aa3b, v48
	v_exp_f32_e32 v48, v48
	v_cndmask_b32_e32 v68, v200, v68, vcc
	v_cmp_neq_f32_e32 vcc, -1.0, v70
	s_waitcnt vmcnt(0)
	v_add_f32_e32 v32, v32, v73
	v_add_f32_e32 v48, 1.0, v48
	v_rcp_f32_e32 v48, v48
	v_cndmask_b32_e32 v68, v201, v68, vcc
	v_cmp_lt_f32_e64 vcc, |v70|, s41
	v_mul_f32_e32 v32, 0xbfb8aa3b, v32
	v_exp_f32_e32 v32, v32
	v_cndmask_b32_e32 v68, v68, v70, vcc
	v_mul_f32_e32 v72, 0xc1000000, v68
	v_mul_f32_e32 v48, v48, v72
	v_mul_f32_e32 v64, 0x3fb8aa3b, v48
	v_add_f32_e32 v48, v48, v48
	v_exp_f32_e32 v68, v64
	v_mul_f32_e32 v64, 0x3fb8aa3b, v48
	v_rndne_f32_e32 v64, v64
	v_fmamk_f32 v65, v64, 0xbf317218, v48
	v_fmac_f32_e32 v65, 0x3102e308, v64
	v_fmamk_f32 v69, v65, 0x395133b1, v192
	v_cmp_eq_f32_e32 vcc, s15, v64
	v_cvt_i32_f32_e32 v64, v64
	v_fmaak_f32 v69, v65, v69, 0x3c0887f9
	v_fmaak_f32 v69, v65, v69, 0x3d2aaa81
	v_fmaak_f32 v69, v65, v69, 0x3e2aaaab
	v_fma_f32 v69, v65, v69, 0.5
	v_ldexp_f32 v64, 1.0, v64
	v_mul_f32_e32 v69, v65, v69
	v_cndmask_b32_e32 v64, v64, v202, vcc
	v_fmac_f32_e32 v65, v65, v69
	v_add_f32_e32 v69, -1.0, v64
	v_fmac_f32_e32 v69, v64, v65
	v_add_f32_e32 v64, v69, v69
	v_cndmask_b32_e32 v64, v69, v64, vcc
	v_cmp_nlt_f32_e32 vcc, s16, v48
	v_add_f32_e32 v32, 1.0, v32
	v_rcp_f32_e32 v32, v32
	v_cndmask_b32_e64 v64, v201, -v64, vcc
	v_cmp_gt_f32_e32 vcc, s17, v64
	v_mul_f32_e32 v65, 0x4f800000, v64
	v_add_f32_e32 v33, v33, v73
	v_cndmask_b32_e32 v64, v64, v65, vcc
	v_sqrt_f32_e32 v65, v64
	v_mul_f32_e32 v33, 0xbfb8aa3b, v33
	v_exp_f32_e32 v33, v33
	v_add_f32_e32 v34, v34, v73
	v_add_u32_e32 v69, -1, v65
	v_fma_f32 v70, -v69, v65, v64
	v_cmp_ge_f32_e64 s[0:1], 0, v70
	v_add_u32_e32 v70, 1, v65
	v_add_f32_e32 v33, 1.0, v33
	v_cndmask_b32_e64 v69, v65, v69, s[0:1]
	v_fma_f32 v65, -v70, v65, v64
	v_cmp_lt_f32_e64 s[0:1], 0, v65
	v_rcp_f32_e32 v33, v33
	v_mul_f32_e32 v34, 0xbfb8aa3b, v34
	v_cndmask_b32_e64 v65, v69, v70, s[0:1]
	v_mul_f32_e32 v69, 0x37800000, v65
	v_cndmask_b32_e32 v65, v65, v69, vcc
	v_cmp_class_f32_e32 vcc, v64, v193
	v_exp_f32_e32 v34, v34
	s_nop 0
	v_cndmask_b32_e32 v64, v65, v64, vcc
	v_cmp_ngt_f32_e32 vcc, s18, v48
	v_add_f32_e32 v34, 1.0, v34
	v_rcp_f32_e32 v34, v34
	v_cndmask_b32_e32 v48, 1.0, v64, vcc
	v_mul_f32_e32 v48, v32, v48
	v_and_b32_e32 v32, 0x100, v66
	v_or3_b32 v32, v67, v71, v32
	v_lshl_add_u32 v70, v32, 2, 0
	v_add_u32_e32 v32, 0x9000, v70
	ds_read2_b32 v[64:65], v32 offset1:32
	s_waitcnt lgkmcnt(0)
	v_mul_f32_e32 v48, v64, v48
	ds_write_b32 v70, v68
	ds_write_b32 v70, v48 offset:36864
	v_add_f32_e32 v48, v49, v74
	v_mul_f32_e32 v48, 0xbfb8aa3b, v48
	v_exp_f32_e32 v48, v48
	s_nop 0
	v_add_f32_e32 v48, 1.0, v48
	v_rcp_f32_e32 v48, v48
	s_nop 0
	v_mul_f32_e32 v48, v48, v72
	v_mul_f32_e32 v49, 0x3fb8aa3b, v48
	v_add_f32_e32 v48, v48, v48
	v_exp_f32_e32 v64, v49
	v_mul_f32_e32 v49, 0x3fb8aa3b, v48
	v_rndne_f32_e32 v49, v49
	v_fmamk_f32 v66, v49, 0xbf317218, v48
	v_fmac_f32_e32 v66, 0x3102e308, v49
	v_fmamk_f32 v67, v66, 0x395133b1, v192
	v_cmp_eq_f32_e32 vcc, s15, v49
	v_cvt_i32_f32_e32 v49, v49
	v_fmaak_f32 v67, v66, v67, 0x3c0887f9
	v_fmaak_f32 v67, v66, v67, 0x3d2aaa81
	v_fmaak_f32 v67, v66, v67, 0x3e2aaaab
	v_fma_f32 v67, v66, v67, 0.5
	v_ldexp_f32 v49, 1.0, v49
	v_mul_f32_e32 v67, v66, v67
	v_cndmask_b32_e32 v49, v49, v202, vcc
	v_fmac_f32_e32 v66, v66, v67
	v_add_f32_e32 v67, -1.0, v49
	v_fmac_f32_e32 v67, v49, v66
	v_add_f32_e32 v49, v67, v67
	v_cndmask_b32_e32 v49, v67, v49, vcc
	v_cmp_nlt_f32_e32 vcc, s16, v48
	s_nop 1
	v_cndmask_b32_e64 v49, v201, -v49, vcc
	v_cmp_gt_f32_e32 vcc, s17, v49
	v_mul_f32_e32 v66, 0x4f800000, v49
	s_nop 0
	v_cndmask_b32_e32 v49, v49, v66, vcc
	v_sqrt_f32_e32 v66, v49
	s_nop 0
	v_add_u32_e32 v67, -1, v66
	v_fma_f32 v68, -v67, v66, v49
	v_cmp_ge_f32_e64 s[0:1], 0, v68
	v_add_u32_e32 v68, 1, v66
	s_nop 0
	v_cndmask_b32_e64 v67, v66, v67, s[0:1]
	v_fma_f32 v66, -v68, v66, v49
	v_cmp_lt_f32_e64 s[0:1], 0, v66
	s_nop 1
	v_cndmask_b32_e64 v66, v67, v68, s[0:1]
	v_mul_f32_e32 v67, 0x37800000, v66
	v_cndmask_b32_e32 v66, v66, v67, vcc
	v_cmp_class_f32_e32 vcc, v49, v193
	s_nop 1
	v_cndmask_b32_e32 v49, v66, v49, vcc
	v_cmp_ngt_f32_e32 vcc, s18, v48
	s_nop 1
	v_cndmask_b32_e32 v48, 1.0, v49, vcc
	v_mul_f32_e32 v33, v33, v48
	ds_read2_b32 v[48:49], v32 offset0:64 offset1:96
	s_waitcnt lgkmcnt(0)
	v_mul_f32_e32 v33, v48, v33
	ds_write_b32 v70, v64 offset:256
	ds_write_b32 v70, v33 offset:37120
	v_add_f32_e32 v33, v50, v74
	v_mul_f32_e32 v33, 0xbfb8aa3b, v33
	v_exp_f32_e32 v33, v33
	s_nop 0
	v_add_f32_e32 v33, 1.0, v33
	v_rcp_f32_e32 v33, v33
	s_nop 0
	v_mul_f32_e32 v33, v33, v72
	v_mul_f32_e32 v48, 0x3fb8aa3b, v33
	v_add_f32_e32 v33, v33, v33
	v_mul_f32_e32 v50, 0x3fb8aa3b, v33
	v_rndne_f32_e32 v50, v50
	v_fmamk_f32 v64, v50, 0xbf317218, v33
	v_fmac_f32_e32 v64, 0x3102e308, v50
	v_fmamk_f32 v66, v64, 0x395133b1, v192
	v_cmp_eq_f32_e32 vcc, s15, v50
	v_cvt_i32_f32_e32 v50, v50
	v_fmaak_f32 v66, v64, v66, 0x3c0887f9
	v_fmaak_f32 v66, v64, v66, 0x3d2aaa81
	v_fmaak_f32 v66, v64, v66, 0x3e2aaaab
	v_fma_f32 v66, v64, v66, 0.5
	v_ldexp_f32 v50, 1.0, v50
	v_mul_f32_e32 v66, v64, v66
	v_cndmask_b32_e32 v50, v50, v202, vcc
	v_fmac_f32_e32 v64, v64, v66
	v_add_f32_e32 v66, -1.0, v50
	v_fmac_f32_e32 v66, v50, v64
	v_add_f32_e32 v50, v66, v66
	v_cndmask_b32_e32 v50, v66, v50, vcc
	v_cmp_nlt_f32_e32 vcc, s16, v33
	v_exp_f32_e32 v48, v48
	s_nop 0
	v_cndmask_b32_e64 v50, v201, -v50, vcc
	v_cmp_gt_f32_e32 vcc, s17, v50
	v_mul_f32_e32 v64, 0x4f800000, v50
	s_nop 0
	v_cndmask_b32_e32 v50, v50, v64, vcc
	v_sqrt_f32_e32 v64, v50
	s_nop 0
	v_add_u32_e32 v66, -1, v64
	v_fma_f32 v67, -v66, v64, v50
	v_cmp_ge_f32_e64 s[0:1], 0, v67
	v_add_u32_e32 v67, 1, v64
	s_nop 0
	v_cndmask_b32_e64 v66, v64, v66, s[0:1]
	v_fma_f32 v64, -v67, v64, v50
	v_cmp_lt_f32_e64 s[0:1], 0, v64
	s_nop 1
	v_cndmask_b32_e64 v64, v66, v67, s[0:1]
	v_mul_f32_e32 v66, 0x37800000, v64
	v_cndmask_b32_e32 v64, v64, v66, vcc
	ds_read2_b32 v[66:67], v32 offset0:128 offset1:160
	v_cmp_class_f32_e32 vcc, v50, v193
	s_nop 1
	v_cndmask_b32_e32 v50, v64, v50, vcc
	v_cmp_ngt_f32_e32 vcc, s18, v33
	s_nop 1
	v_cndmask_b32_e32 v33, 1.0, v50, vcc
	v_mul_f32_e32 v33, v34, v33
	s_waitcnt lgkmcnt(0)
	v_mul_f32_e32 v33, v66, v33
	ds_write_b32 v70, v48 offset:512
	ds_write_b32 v70, v33 offset:37376
	v_add_f32_e32 v33, v51, v74
	v_mul_f32_e32 v33, 0xbfb8aa3b, v33
	v_exp_f32_e32 v33, v33
	v_add_f32_e32 v34, v35, v73
	v_mul_f32_e32 v34, 0xbfb8aa3b, v34
	v_exp_f32_e32 v34, v34
	v_add_f32_e32 v33, 1.0, v33
	v_rcp_f32_e32 v33, v33
	v_add_f32_e32 v34, 1.0, v34
	v_rcp_f32_e32 v34, v34
	v_mul_f32_e32 v33, v33, v72
	v_mul_f32_e32 v35, 0x3fb8aa3b, v33
	v_add_f32_e32 v33, v33, v33
	v_mul_f32_e32 v48, 0x3fb8aa3b, v33
	v_rndne_f32_e32 v48, v48
	v_fmamk_f32 v50, v48, 0xbf317218, v33
	v_fmac_f32_e32 v50, 0x3102e308, v48
	v_fmamk_f32 v51, v50, 0x395133b1, v192
	v_cmp_eq_f32_e32 vcc, s15, v48
	v_cvt_i32_f32_e32 v48, v48
	v_fmaak_f32 v51, v50, v51, 0x3c0887f9
	v_fmaak_f32 v51, v50, v51, 0x3d2aaa81
	v_fmaak_f32 v51, v50, v51, 0x3e2aaaab
	v_fma_f32 v51, v50, v51, 0.5
	v_ldexp_f32 v48, 1.0, v48
	v_mul_f32_e32 v51, v50, v51
	v_cndmask_b32_e32 v48, v48, v202, vcc
	v_fmac_f32_e32 v50, v50, v51
	v_add_f32_e32 v51, -1.0, v48
	v_fmac_f32_e32 v51, v48, v50
	v_add_f32_e32 v48, v51, v51
	v_cndmask_b32_e32 v48, v51, v48, vcc
	v_cmp_nlt_f32_e32 vcc, s16, v33
	v_exp_f32_e32 v35, v35
	s_nop 0
	v_cndmask_b32_e64 v48, v201, -v48, vcc
	v_cmp_gt_f32_e32 vcc, s17, v48
	v_mul_f32_e32 v50, 0x4f800000, v48
	s_nop 0
	v_cndmask_b32_e32 v48, v48, v50, vcc
	v_sqrt_f32_e32 v50, v48
	s_nop 0
	v_add_u32_e32 v51, -1, v50
	v_fma_f32 v64, -v51, v50, v48
	v_cmp_ge_f32_e64 s[0:1], 0, v64
	v_add_u32_e32 v64, 1, v50
	s_nop 0
	v_cndmask_b32_e64 v51, v50, v51, s[0:1]
	v_fma_f32 v50, -v64, v50, v48
	v_cmp_lt_f32_e64 s[0:1], 0, v50
	s_nop 1
	v_cndmask_b32_e64 v50, v51, v64, s[0:1]
	v_mul_f32_e32 v51, 0x37800000, v50
	v_cndmask_b32_e32 v50, v50, v51, vcc
	v_cmp_class_f32_e32 vcc, v48, v193
	s_nop 1
	v_cndmask_b32_e32 v48, v50, v48, vcc
	ds_read2_b32 v[50:51], v32 offset0:192 offset1:224
	v_cmp_ngt_f32_e32 vcc, s18, v33
	s_nop 1
	v_cndmask_b32_e32 v33, 1.0, v48, vcc
	v_mul_f32_e32 v33, v34, v33
	s_waitcnt lgkmcnt(0)
	v_mul_f32_e32 v32, v50, v33
	ds_write_b32 v70, v35 offset:768
	ds_write_b32 v70, v32 offset:37632
	v_add_f32_e32 v32, v52, v74
	v_mul_f32_e32 v32, 0xbfb8aa3b, v32
	v_exp_f32_e32 v32, v32
	v_add_f32_e32 v33, v36, v73
	v_mul_f32_e32 v33, 0xbfb8aa3b, v33
	v_exp_f32_e32 v33, v33
	v_add_f32_e32 v32, 1.0, v32
	v_rcp_f32_e32 v32, v32
	v_add_f32_e32 v33, 1.0, v33
	v_rcp_f32_e32 v33, v33
	v_mul_f32_e32 v32, v32, v72
	v_mul_f32_e32 v34, 0x3fb8aa3b, v32
	v_add_f32_e32 v32, v32, v32
	v_mul_f32_e32 v35, 0x3fb8aa3b, v32
	v_rndne_f32_e32 v35, v35
	v_fmamk_f32 v36, v35, 0xbf317218, v32
	v_fmac_f32_e32 v36, 0x3102e308, v35
	v_fmamk_f32 v48, v36, 0x395133b1, v192
	v_cmp_eq_f32_e32 vcc, s15, v35
	v_cvt_i32_f32_e32 v35, v35
	v_fmaak_f32 v48, v36, v48, 0x3c0887f9
	v_fmaak_f32 v48, v36, v48, 0x3d2aaa81
	v_fmaak_f32 v48, v36, v48, 0x3e2aaaab
	v_fma_f32 v48, v36, v48, 0.5
	v_ldexp_f32 v35, 1.0, v35
	v_mul_f32_e32 v48, v36, v48
	v_cndmask_b32_e32 v35, v35, v202, vcc
	v_fmac_f32_e32 v36, v36, v48
	v_add_f32_e32 v48, -1.0, v35
	v_fmac_f32_e32 v48, v35, v36
	v_add_f32_e32 v35, v48, v48
	v_cndmask_b32_e32 v35, v48, v35, vcc
	v_cmp_nlt_f32_e32 vcc, s16, v32
	v_exp_f32_e32 v34, v34
	s_nop 0
	v_cndmask_b32_e64 v35, v201, -v35, vcc
	v_cmp_gt_f32_e32 vcc, s17, v35
	v_mul_f32_e32 v36, 0x4f800000, v35
	s_nop 0
	v_cndmask_b32_e32 v35, v35, v36, vcc
	v_sqrt_f32_e32 v36, v35
	s_nop 0
	v_add_u32_e32 v48, -1, v36
	v_fma_f32 v50, -v48, v36, v35
	v_cmp_ge_f32_e64 s[0:1], 0, v50
	v_add_u32_e32 v50, 1, v36
	s_nop 0
	v_cndmask_b32_e64 v48, v36, v48, s[0:1]
	v_fma_f32 v36, -v50, v36, v35
	v_cmp_lt_f32_e64 s[0:1], 0, v36
	s_nop 1
	v_cndmask_b32_e64 v36, v48, v50, s[0:1]
	v_mul_f32_e32 v48, 0x37800000, v36
	v_cndmask_b32_e32 v36, v36, v48, vcc
	v_cmp_class_f32_e32 vcc, v35, v193
	s_nop 1
	v_cndmask_b32_e32 v35, v36, v35, vcc
	v_cmp_ngt_f32_e32 vcc, s18, v32
	s_nop 1
	v_cndmask_b32_e32 v32, 1.0, v35, vcc
	v_mul_f32_e32 v33, v33, v32
	v_add_u32_e32 v32, 0x9800, v70
	ds_read2_b32 v[68:69], v32 offset1:32
	s_waitcnt lgkmcnt(0)
	v_mul_f32_e32 v33, v68, v33
	ds_write_b32 v70, v34 offset:2048
	ds_write_b32 v70, v33 offset:38912
	v_add_f32_e32 v33, v53, v74
	v_mul_f32_e32 v33, 0xbfb8aa3b, v33
	v_exp_f32_e32 v33, v33
	v_add_f32_e32 v34, v37, v73
	v_mul_f32_e32 v34, 0xbfb8aa3b, v34
	v_exp_f32_e32 v34, v34
	v_add_f32_e32 v33, 1.0, v33
	v_rcp_f32_e32 v33, v33
	v_add_f32_e32 v34, 1.0, v34
	v_rcp_f32_e32 v34, v34
	v_mul_f32_e32 v33, v33, v72
	v_mul_f32_e32 v35, 0x3fb8aa3b, v33
	v_add_f32_e32 v33, v33, v33
	v_mul_f32_e32 v36, 0x3fb8aa3b, v33
	v_rndne_f32_e32 v36, v36
	v_fmamk_f32 v37, v36, 0xbf317218, v33
	v_fmac_f32_e32 v37, 0x3102e308, v36
	v_fmamk_f32 v48, v37, 0x395133b1, v192
	v_cmp_eq_f32_e32 vcc, s15, v36
	v_cvt_i32_f32_e32 v36, v36
	v_fmaak_f32 v48, v37, v48, 0x3c0887f9
	v_fmaak_f32 v48, v37, v48, 0x3d2aaa81
	v_fmaak_f32 v48, v37, v48, 0x3e2aaaab
	v_fma_f32 v48, v37, v48, 0.5
	v_ldexp_f32 v36, 1.0, v36
	v_mul_f32_e32 v48, v37, v48
	v_cndmask_b32_e32 v36, v36, v202, vcc
	v_fmac_f32_e32 v37, v37, v48
	v_add_f32_e32 v48, -1.0, v36
	v_fmac_f32_e32 v48, v36, v37
	v_add_f32_e32 v36, v48, v48
	v_cndmask_b32_e32 v36, v48, v36, vcc
	v_cmp_nlt_f32_e32 vcc, s16, v33
	v_exp_f32_e32 v35, v35
	s_nop 0
	v_cndmask_b32_e64 v36, v201, -v36, vcc
	v_cmp_gt_f32_e32 vcc, s17, v36
	v_mul_f32_e32 v37, 0x4f800000, v36
	s_nop 0
	v_cndmask_b32_e32 v36, v36, v37, vcc
	v_sqrt_f32_e32 v37, v36
	s_nop 0
	v_add_u32_e32 v48, -1, v37
	v_fma_f32 v50, -v48, v37, v36
	v_cmp_ge_f32_e64 s[0:1], 0, v50
	v_add_u32_e32 v50, 1, v37
	s_nop 0
	v_cndmask_b32_e64 v48, v37, v48, s[0:1]
	v_fma_f32 v37, -v50, v37, v36
	v_cmp_lt_f32_e64 s[0:1], 0, v37
	s_nop 1
	v_cndmask_b32_e64 v37, v48, v50, s[0:1]
	v_mul_f32_e32 v48, 0x37800000, v37
	v_cndmask_b32_e32 v37, v37, v48, vcc
	v_cmp_class_f32_e32 vcc, v36, v193
	s_nop 1
	v_cndmask_b32_e32 v36, v37, v36, vcc
	v_cmp_ngt_f32_e32 vcc, s18, v33
	s_nop 1
	v_cndmask_b32_e32 v33, 1.0, v36, vcc
	ds_read2_b32 v[36:37], v32 offset0:64 offset1:96
	v_mul_f32_e32 v33, v34, v33
	v_add_f32_e32 v34, v38, v73
	v_mul_f32_e32 v34, 0xbfb8aa3b, v34
	v_exp_f32_e32 v34, v34
	s_waitcnt lgkmcnt(0)
	v_mul_f32_e32 v33, v36, v33
	ds_write_b32 v70, v35 offset:2304
	ds_write_b32 v70, v33 offset:39168
	v_add_f32_e32 v33, v54, v74
	v_mul_f32_e32 v33, 0xbfb8aa3b, v33
	v_exp_f32_e32 v33, v33
	v_add_f32_e32 v34, 1.0, v34
	v_rcp_f32_e32 v34, v34
	ds_read2_b32 v[52:53], v32 offset0:128 offset1:160
	v_add_f32_e32 v33, 1.0, v33
	v_rcp_f32_e32 v33, v33
	s_nop 0
	v_mul_f32_e32 v33, v33, v72
	v_mul_f32_e32 v35, 0x3fb8aa3b, v33
	v_add_f32_e32 v33, v33, v33
	v_mul_f32_e32 v36, 0x3fb8aa3b, v33
	v_rndne_f32_e32 v36, v36
	v_fmamk_f32 v38, v36, 0xbf317218, v33
	v_fmac_f32_e32 v38, 0x3102e308, v36
	v_fmamk_f32 v48, v38, 0x395133b1, v192
	v_cmp_eq_f32_e32 vcc, s15, v36
	v_cvt_i32_f32_e32 v36, v36
	v_fmaak_f32 v48, v38, v48, 0x3c0887f9
	v_fmaak_f32 v48, v38, v48, 0x3d2aaa81
	v_fmaak_f32 v48, v38, v48, 0x3e2aaaab
	v_fma_f32 v48, v38, v48, 0.5
	v_ldexp_f32 v36, 1.0, v36
	v_mul_f32_e32 v48, v38, v48
	v_cndmask_b32_e32 v36, v36, v202, vcc
	v_fmac_f32_e32 v38, v38, v48
	v_add_f32_e32 v48, -1.0, v36
	v_fmac_f32_e32 v48, v36, v38
	v_add_f32_e32 v36, v48, v48
	v_cndmask_b32_e32 v36, v48, v36, vcc
	v_cmp_nlt_f32_e32 vcc, s16, v33
	v_exp_f32_e32 v35, v35
	s_nop 0
	v_cndmask_b32_e64 v36, v201, -v36, vcc
	v_cmp_gt_f32_e32 vcc, s17, v36
	v_mul_f32_e32 v38, 0x4f800000, v36
	s_nop 0
	v_cndmask_b32_e32 v36, v36, v38, vcc
	v_sqrt_f32_e32 v38, v36
	s_nop 0
	v_add_u32_e32 v48, -1, v38
	v_fma_f32 v50, -v48, v38, v36
	v_cmp_ge_f32_e64 s[0:1], 0, v50
	v_add_u32_e32 v50, 1, v38
	s_nop 0
	v_cndmask_b32_e64 v48, v38, v48, s[0:1]
	v_fma_f32 v38, -v50, v38, v36
	v_cmp_lt_f32_e64 s[0:1], 0, v38
	s_nop 1
	v_cndmask_b32_e64 v38, v48, v50, s[0:1]
	v_mul_f32_e32 v48, 0x37800000, v38
	v_cndmask_b32_e32 v38, v38, v48, vcc
	v_cmp_class_f32_e32 vcc, v36, v193
	s_nop 1
	v_cndmask_b32_e32 v36, v38, v36, vcc
	v_cmp_ngt_f32_e32 vcc, s18, v33
	s_nop 1
	v_cndmask_b32_e32 v33, 1.0, v36, vcc
	v_mul_f32_e32 v33, v34, v33
	s_waitcnt lgkmcnt(0)
	v_mul_f32_e32 v33, v52, v33
	ds_write_b32 v70, v35 offset:2560
	ds_write_b32 v70, v33 offset:39424
	v_add_f32_e32 v33, v55, v74
	v_mul_f32_e32 v33, 0xbfb8aa3b, v33
	v_exp_f32_e32 v33, v33
	v_add_f32_e32 v34, v39, v73
	v_mul_f32_e32 v34, 0xbfb8aa3b, v34
	v_exp_f32_e32 v34, v34
	v_add_f32_e32 v33, 1.0, v33
	v_rcp_f32_e32 v33, v33
	v_add_f32_e32 v34, 1.0, v34
	v_rcp_f32_e32 v34, v34
	v_mul_f32_e32 v33, v33, v72
	v_mul_f32_e32 v35, 0x3fb8aa3b, v33
	v_add_f32_e32 v33, v33, v33
	v_mul_f32_e32 v36, 0x3fb8aa3b, v33
	v_rndne_f32_e32 v36, v36
	v_fmamk_f32 v38, v36, 0xbf317218, v33
	v_fmac_f32_e32 v38, 0x3102e308, v36
	v_fmamk_f32 v39, v38, 0x395133b1, v192
	v_cmp_eq_f32_e32 vcc, s15, v36
	v_cvt_i32_f32_e32 v36, v36
	v_fmaak_f32 v39, v38, v39, 0x3c0887f9
	v_fmaak_f32 v39, v38, v39, 0x3d2aaa81
	v_fmaak_f32 v39, v38, v39, 0x3e2aaaab
	v_fma_f32 v39, v38, v39, 0.5
	v_ldexp_f32 v36, 1.0, v36
	v_mul_f32_e32 v39, v38, v39
	v_cndmask_b32_e32 v36, v36, v202, vcc
	v_fmac_f32_e32 v38, v38, v39
	v_add_f32_e32 v39, -1.0, v36
	v_fmac_f32_e32 v39, v36, v38
	v_add_f32_e32 v36, v39, v39
	v_cndmask_b32_e32 v36, v39, v36, vcc
	v_cmp_nlt_f32_e32 vcc, s16, v33
	v_exp_f32_e32 v35, v35
	s_nop 0
	v_cndmask_b32_e64 v36, v201, -v36, vcc
	v_cmp_gt_f32_e32 vcc, s17, v36
	v_mul_f32_e32 v38, 0x4f800000, v36
	s_nop 0
	v_cndmask_b32_e32 v36, v36, v38, vcc
	v_sqrt_f32_e32 v38, v36
	s_nop 0
	v_add_u32_e32 v39, -1, v38
	v_fma_f32 v48, -v39, v38, v36
	v_cmp_ge_f32_e64 s[0:1], 0, v48
	v_add_u32_e32 v48, 1, v38
	s_nop 0
	v_cndmask_b32_e64 v39, v38, v39, s[0:1]
	v_fma_f32 v38, -v48, v38, v36
	v_cmp_lt_f32_e64 s[0:1], 0, v38
	s_nop 1
	v_cndmask_b32_e64 v38, v39, v48, s[0:1]
	v_mul_f32_e32 v39, 0x37800000, v38
	v_cndmask_b32_e32 v38, v38, v39, vcc
	v_cmp_class_f32_e32 vcc, v36, v193
	s_nop 1
	v_cndmask_b32_e32 v36, v38, v36, vcc
	ds_read2_b32 v[38:39], v32 offset0:192 offset1:224
	v_cmp_ngt_f32_e32 vcc, s18, v33
	s_nop 1
	v_cndmask_b32_e32 v33, 1.0, v36, vcc
	v_mul_f32_e32 v33, v34, v33
	s_waitcnt lgkmcnt(0)
	v_mul_f32_e32 v32, v38, v33
	ds_write_b32 v70, v35 offset:2816
	ds_write_b32 v70, v32 offset:39680
	v_add_f32_e32 v32, v56, v74
	v_mul_f32_e32 v32, 0xbfb8aa3b, v32
	v_exp_f32_e32 v32, v32
	v_add_f32_e32 v33, v40, v73
	v_mul_f32_e32 v33, 0xbfb8aa3b, v33
	v_exp_f32_e32 v33, v33
	v_add_f32_e32 v32, 1.0, v32
	v_rcp_f32_e32 v32, v32
	v_add_f32_e32 v33, 1.0, v33
	v_rcp_f32_e32 v33, v33
	v_mul_f32_e32 v32, v32, v72
	v_mul_f32_e32 v34, 0x3fb8aa3b, v32
	v_add_f32_e32 v32, v32, v32
	v_mul_f32_e32 v35, 0x3fb8aa3b, v32
	v_rndne_f32_e32 v35, v35
	v_fmamk_f32 v36, v35, 0xbf317218, v32
	v_fmac_f32_e32 v36, 0x3102e308, v35
	v_fmamk_f32 v38, v36, 0x395133b1, v192
	v_cmp_eq_f32_e32 vcc, s15, v35
	v_cvt_i32_f32_e32 v35, v35
	v_fmaak_f32 v38, v36, v38, 0x3c0887f9
	v_fmaak_f32 v38, v36, v38, 0x3d2aaa81
	v_fmaak_f32 v38, v36, v38, 0x3e2aaaab
	v_fma_f32 v38, v36, v38, 0.5
	v_ldexp_f32 v35, 1.0, v35
	v_mul_f32_e32 v38, v36, v38
	v_cndmask_b32_e32 v35, v35, v202, vcc
	v_fmac_f32_e32 v36, v36, v38
	v_add_f32_e32 v38, -1.0, v35
	v_fmac_f32_e32 v38, v35, v36
	v_add_f32_e32 v35, v38, v38
	v_cndmask_b32_e32 v35, v38, v35, vcc
	v_cmp_nlt_f32_e32 vcc, s16, v32
	v_exp_f32_e32 v34, v34
	s_nop 0
	v_cndmask_b32_e64 v35, v201, -v35, vcc
	v_cmp_gt_f32_e32 vcc, s17, v35
	v_mul_f32_e32 v36, 0x4f800000, v35
	s_nop 0
	v_cndmask_b32_e32 v35, v35, v36, vcc
	v_sqrt_f32_e32 v36, v35
	s_nop 0
	v_add_u32_e32 v38, -1, v36
	v_fma_f32 v40, -v38, v36, v35
	v_cmp_ge_f32_e64 s[0:1], 0, v40
	v_add_u32_e32 v40, 1, v36
	s_nop 0
	v_cndmask_b32_e64 v38, v36, v38, s[0:1]
	v_fma_f32 v36, -v40, v36, v35
	v_cmp_lt_f32_e64 s[0:1], 0, v36
	s_nop 1
	v_cndmask_b32_e64 v36, v38, v40, s[0:1]
	v_mul_f32_e32 v38, 0x37800000, v36
	v_cndmask_b32_e32 v36, v36, v38, vcc
	v_cmp_class_f32_e32 vcc, v35, v193
	s_nop 1
	v_cndmask_b32_e32 v35, v36, v35, vcc
	v_cmp_ngt_f32_e32 vcc, s18, v32
	s_nop 1
	v_cndmask_b32_e32 v32, 1.0, v35, vcc
	v_mul_f32_e32 v33, v33, v32
	v_add_u32_e32 v32, 0xa000, v70
	ds_read2_b32 v[54:55], v32 offset1:32
	s_waitcnt lgkmcnt(0)
	v_mul_f32_e32 v33, v54, v33
	ds_write_b32 v70, v34 offset:4096
	ds_write_b32 v70, v33 offset:40960
	v_add_f32_e32 v33, v57, v74
	v_mul_f32_e32 v33, 0xbfb8aa3b, v33
	v_exp_f32_e32 v33, v33
	v_add_f32_e32 v34, v41, v73
	v_mul_f32_e32 v34, 0xbfb8aa3b, v34
	v_exp_f32_e32 v34, v34
	v_add_f32_e32 v33, 1.0, v33
	v_rcp_f32_e32 v33, v33
	v_add_f32_e32 v34, 1.0, v34
	v_rcp_f32_e32 v34, v34
	v_mul_f32_e32 v33, v33, v72
	v_mul_f32_e32 v35, 0x3fb8aa3b, v33
	v_add_f32_e32 v33, v33, v33
	v_mul_f32_e32 v36, 0x3fb8aa3b, v33
	v_rndne_f32_e32 v36, v36
	v_fmamk_f32 v38, v36, 0xbf317218, v33
	v_fmac_f32_e32 v38, 0x3102e308, v36
	v_fmamk_f32 v40, v38, 0x395133b1, v192
	v_cmp_eq_f32_e32 vcc, s15, v36
	v_cvt_i32_f32_e32 v36, v36
	v_fmaak_f32 v40, v38, v40, 0x3c0887f9
	v_fmaak_f32 v40, v38, v40, 0x3d2aaa81
	v_fmaak_f32 v40, v38, v40, 0x3e2aaaab
	v_fma_f32 v40, v38, v40, 0.5
	v_ldexp_f32 v36, 1.0, v36
	v_mul_f32_e32 v40, v38, v40
	v_cndmask_b32_e32 v36, v36, v202, vcc
	v_fmac_f32_e32 v38, v38, v40
	v_add_f32_e32 v40, -1.0, v36
	v_fmac_f32_e32 v40, v36, v38
	v_add_f32_e32 v36, v40, v40
	v_cndmask_b32_e32 v36, v40, v36, vcc
	v_cmp_nlt_f32_e32 vcc, s16, v33
	v_exp_f32_e32 v35, v35
	s_nop 0
	v_cndmask_b32_e64 v36, v201, -v36, vcc
	v_cmp_gt_f32_e32 vcc, s17, v36
	v_mul_f32_e32 v38, 0x4f800000, v36
	s_nop 0
	v_cndmask_b32_e32 v36, v36, v38, vcc
	v_sqrt_f32_e32 v38, v36
	s_nop 0
	v_add_u32_e32 v40, -1, v38
	v_fma_f32 v41, -v40, v38, v36
	v_cmp_ge_f32_e64 s[0:1], 0, v41
	v_add_u32_e32 v41, 1, v38
	s_nop 0
	v_cndmask_b32_e64 v40, v38, v40, s[0:1]
	v_fma_f32 v38, -v41, v38, v36
	v_cmp_lt_f32_e64 s[0:1], 0, v38
	s_nop 1
	v_cndmask_b32_e64 v38, v40, v41, s[0:1]
	v_mul_f32_e32 v40, 0x37800000, v38
	v_cndmask_b32_e32 v38, v38, v40, vcc
	ds_read2_b32 v[40:41], v32 offset0:64 offset1:96
	v_cmp_class_f32_e32 vcc, v36, v193
	s_nop 1
	v_cndmask_b32_e32 v36, v38, v36, vcc
	v_cmp_ngt_f32_e32 vcc, s18, v33
	s_nop 1
	v_cndmask_b32_e32 v33, 1.0, v36, vcc
	v_mul_f32_e32 v33, v34, v33
	s_waitcnt lgkmcnt(0)
	v_mul_f32_e32 v33, v40, v33
	ds_write_b32 v70, v35 offset:4352
	ds_write_b32 v70, v33 offset:41216
	v_add_f32_e32 v33, v58, v74
	v_mul_f32_e32 v33, 0xbfb8aa3b, v33
	v_exp_f32_e32 v33, v33
	v_add_f32_e32 v34, v42, v73
	v_mul_f32_e32 v34, 0xbfb8aa3b, v34
	v_exp_f32_e32 v34, v34
	v_add_f32_e32 v33, 1.0, v33
	v_rcp_f32_e32 v33, v33
	ds_read2_b32 v[56:57], v32 offset0:128 offset1:160
	v_add_f32_e32 v34, 1.0, v34
	v_rcp_f32_e32 v34, v34
	v_mul_f32_e32 v33, v33, v72
	v_mul_f32_e32 v35, 0x3fb8aa3b, v33
	v_add_f32_e32 v33, v33, v33
	v_mul_f32_e32 v36, 0x3fb8aa3b, v33
	v_rndne_f32_e32 v36, v36
	v_fmamk_f32 v38, v36, 0xbf317218, v33
	v_fmac_f32_e32 v38, 0x3102e308, v36
	v_fmamk_f32 v40, v38, 0x395133b1, v192
	v_cmp_eq_f32_e32 vcc, s15, v36
	v_cvt_i32_f32_e32 v36, v36
	v_fmaak_f32 v40, v38, v40, 0x3c0887f9
	v_fmaak_f32 v40, v38, v40, 0x3d2aaa81
	v_fmaak_f32 v40, v38, v40, 0x3e2aaaab
	v_fma_f32 v40, v38, v40, 0.5
	v_ldexp_f32 v36, 1.0, v36
	v_mul_f32_e32 v40, v38, v40
	v_cndmask_b32_e32 v36, v36, v202, vcc
	v_fmac_f32_e32 v38, v38, v40
	v_add_f32_e32 v40, -1.0, v36
	v_fmac_f32_e32 v40, v36, v38
	v_add_f32_e32 v36, v40, v40
	v_cndmask_b32_e32 v36, v40, v36, vcc
	v_cmp_nlt_f32_e32 vcc, s16, v33
	v_exp_f32_e32 v35, v35
	s_nop 0
	v_cndmask_b32_e64 v36, v201, -v36, vcc
	v_cmp_gt_f32_e32 vcc, s17, v36
	v_mul_f32_e32 v38, 0x4f800000, v36
	s_nop 0
	v_cndmask_b32_e32 v36, v36, v38, vcc
	v_sqrt_f32_e32 v38, v36
	s_nop 0
	v_add_u32_e32 v40, -1, v38
	v_fma_f32 v42, -v40, v38, v36
	v_cmp_ge_f32_e64 s[0:1], 0, v42
	v_add_u32_e32 v42, 1, v38
	s_nop 0
	v_cndmask_b32_e64 v40, v38, v40, s[0:1]
	v_fma_f32 v38, -v42, v38, v36
	v_cmp_lt_f32_e64 s[0:1], 0, v38
	s_nop 1
	v_cndmask_b32_e64 v38, v40, v42, s[0:1]
	v_mul_f32_e32 v40, 0x37800000, v38
	v_cndmask_b32_e32 v38, v38, v40, vcc
	v_cmp_class_f32_e32 vcc, v36, v193
	s_nop 1
	v_cndmask_b32_e32 v36, v38, v36, vcc
	v_cmp_ngt_f32_e32 vcc, s18, v33
	s_nop 1
	v_cndmask_b32_e32 v33, 1.0, v36, vcc
	v_mul_f32_e32 v33, v34, v33
	s_waitcnt lgkmcnt(0)
	v_mul_f32_e32 v33, v56, v33
	ds_write_b32 v70, v35 offset:4608
	ds_write_b32 v70, v33 offset:41472
	v_add_f32_e32 v33, v59, v74
	v_mul_f32_e32 v33, 0xbfb8aa3b, v33
	v_exp_f32_e32 v33, v33
	v_add_f32_e32 v34, v43, v73
	v_mul_f32_e32 v34, 0xbfb8aa3b, v34
	v_exp_f32_e32 v34, v34
	v_add_f32_e32 v33, 1.0, v33
	v_rcp_f32_e32 v33, v33
	v_add_f32_e32 v34, 1.0, v34
	v_rcp_f32_e32 v34, v34
	v_mul_f32_e32 v33, v33, v72
	v_mul_f32_e32 v35, 0x3fb8aa3b, v33
	v_add_f32_e32 v33, v33, v33
	v_mul_f32_e32 v36, 0x3fb8aa3b, v33
	v_rndne_f32_e32 v36, v36
	v_fmamk_f32 v38, v36, 0xbf317218, v33
	v_fmac_f32_e32 v38, 0x3102e308, v36
	v_fmamk_f32 v40, v38, 0x395133b1, v192
	v_cmp_eq_f32_e32 vcc, s15, v36
	v_cvt_i32_f32_e32 v36, v36
	v_fmaak_f32 v40, v38, v40, 0x3c0887f9
	v_fmaak_f32 v40, v38, v40, 0x3d2aaa81
	v_fmaak_f32 v40, v38, v40, 0x3e2aaaab
	v_fma_f32 v40, v38, v40, 0.5
	v_ldexp_f32 v36, 1.0, v36
	v_mul_f32_e32 v40, v38, v40
	v_cndmask_b32_e32 v36, v36, v202, vcc
	v_fmac_f32_e32 v38, v38, v40
	v_add_f32_e32 v40, -1.0, v36
	v_fmac_f32_e32 v40, v36, v38
	v_add_f32_e32 v36, v40, v40
	v_cndmask_b32_e32 v36, v40, v36, vcc
	v_cmp_nlt_f32_e32 vcc, s16, v33
	v_exp_f32_e32 v35, v35
	s_nop 0
	v_cndmask_b32_e64 v36, v201, -v36, vcc
	v_cmp_gt_f32_e32 vcc, s17, v36
	v_mul_f32_e32 v38, 0x4f800000, v36
	s_nop 0
	v_cndmask_b32_e32 v36, v36, v38, vcc
	v_sqrt_f32_e32 v38, v36
	s_nop 0
	v_add_u32_e32 v40, -1, v38
	v_fma_f32 v42, -v40, v38, v36
	v_cmp_ge_f32_e64 s[0:1], 0, v42
	v_add_u32_e32 v42, 1, v38
	s_nop 0
	v_cndmask_b32_e64 v40, v38, v40, s[0:1]
	v_fma_f32 v38, -v42, v38, v36
	v_cmp_lt_f32_e64 s[0:1], 0, v38
	s_nop 1
	v_cndmask_b32_e64 v38, v40, v42, s[0:1]
	v_mul_f32_e32 v40, 0x37800000, v38
	ds_read2_b32 v[42:43], v32 offset0:192 offset1:224
	v_cndmask_b32_e32 v38, v38, v40, vcc
	v_cmp_class_f32_e32 vcc, v36, v193
	s_nop 1
	v_cndmask_b32_e32 v36, v38, v36, vcc
	v_cmp_ngt_f32_e32 vcc, s18, v33
	s_nop 1
	v_cndmask_b32_e32 v33, 1.0, v36, vcc
	v_mul_f32_e32 v33, v34, v33
	s_waitcnt lgkmcnt(0)
	v_mul_f32_e32 v32, v42, v33
	ds_write_b32 v70, v35 offset:4864
	ds_write_b32 v70, v32 offset:41728
	v_add_f32_e32 v32, v60, v74
	v_mul_f32_e32 v32, 0xbfb8aa3b, v32
	v_exp_f32_e32 v32, v32
	v_add_f32_e32 v33, v44, v73
	v_mul_f32_e32 v33, 0xbfb8aa3b, v33
	v_exp_f32_e32 v33, v33
	v_add_f32_e32 v32, 1.0, v32
	v_rcp_f32_e32 v32, v32
	v_add_f32_e32 v33, 1.0, v33
	v_rcp_f32_e32 v33, v33
	v_mul_f32_e32 v32, v32, v72
	v_mul_f32_e32 v34, 0x3fb8aa3b, v32
	v_add_f32_e32 v32, v32, v32
	v_mul_f32_e32 v35, 0x3fb8aa3b, v32
	v_rndne_f32_e32 v35, v35
	v_fmamk_f32 v36, v35, 0xbf317218, v32
	v_fmac_f32_e32 v36, 0x3102e308, v35
	v_fmamk_f32 v38, v36, 0x395133b1, v192
	v_cmp_eq_f32_e32 vcc, s15, v35
	v_cvt_i32_f32_e32 v35, v35
	v_fmaak_f32 v38, v36, v38, 0x3c0887f9
	v_fmaak_f32 v38, v36, v38, 0x3d2aaa81
	v_fmaak_f32 v38, v36, v38, 0x3e2aaaab
	v_fma_f32 v38, v36, v38, 0.5
	v_ldexp_f32 v35, 1.0, v35
	v_mul_f32_e32 v38, v36, v38
	v_cndmask_b32_e32 v35, v35, v202, vcc
	v_fmac_f32_e32 v36, v36, v38
	v_add_f32_e32 v38, -1.0, v35
	v_fmac_f32_e32 v38, v35, v36
	v_add_f32_e32 v35, v38, v38
	v_cndmask_b32_e32 v35, v38, v35, vcc
	v_cmp_nlt_f32_e32 vcc, s16, v32
	v_exp_f32_e32 v34, v34
	s_nop 0
	v_cndmask_b32_e64 v35, v201, -v35, vcc
	v_cmp_gt_f32_e32 vcc, s17, v35
	v_mul_f32_e32 v36, 0x4f800000, v35
	s_nop 0
	v_cndmask_b32_e32 v35, v35, v36, vcc
	v_sqrt_f32_e32 v36, v35
	s_nop 0
	v_add_u32_e32 v38, -1, v36
	v_fma_f32 v40, -v38, v36, v35
	v_cmp_ge_f32_e64 s[0:1], 0, v40
	v_add_u32_e32 v40, 1, v36
	s_nop 0
	v_cndmask_b32_e64 v38, v36, v38, s[0:1]
	v_fma_f32 v36, -v40, v36, v35
	v_cmp_lt_f32_e64 s[0:1], 0, v36
	s_nop 1
	v_cndmask_b32_e64 v36, v38, v40, s[0:1]
	v_mul_f32_e32 v38, 0x37800000, v36
	v_cndmask_b32_e32 v36, v36, v38, vcc
	v_cmp_class_f32_e32 vcc, v35, v193
	s_nop 1
	v_cndmask_b32_e32 v35, v36, v35, vcc
	v_cmp_ngt_f32_e32 vcc, s18, v32
	s_nop 1
	v_cndmask_b32_e32 v32, 1.0, v35, vcc
	v_mul_f32_e32 v32, v33, v32
	v_add_u32_e32 v33, 0xa800, v70
	ds_read2_b32 v[58:59], v33 offset1:32
	s_waitcnt lgkmcnt(0)
	v_mul_f32_e32 v32, v58, v32
	ds_write_b32 v70, v34 offset:6144
	ds_write_b32 v70, v32 offset:43008
	v_add_f32_e32 v32, v61, v74
	v_mul_f32_e32 v32, 0xbfb8aa3b, v32
	v_exp_f32_e32 v32, v32
	v_add_f32_e32 v34, v45, v73
	v_mul_f32_e32 v34, 0xbfb8aa3b, v34
	v_exp_f32_e32 v34, v34
	v_add_f32_e32 v32, 1.0, v32
	v_rcp_f32_e32 v32, v32
	ds_read2_b32 v[44:45], v33 offset0:64 offset1:96
	v_add_f32_e32 v34, 1.0, v34
	v_rcp_f32_e32 v34, v34
	v_mul_f32_e32 v32, v32, v72
	v_mul_f32_e32 v35, 0x3fb8aa3b, v32
	v_add_f32_e32 v32, v32, v32
	v_mul_f32_e32 v36, 0x3fb8aa3b, v32
	v_rndne_f32_e32 v36, v36
	v_fmamk_f32 v38, v36, 0xbf317218, v32
	v_fmac_f32_e32 v38, 0x3102e308, v36
	v_fmamk_f32 v40, v38, 0x395133b1, v192
	v_cmp_eq_f32_e32 vcc, s15, v36
	v_cvt_i32_f32_e32 v36, v36
	v_fmaak_f32 v40, v38, v40, 0x3c0887f9
	v_fmaak_f32 v40, v38, v40, 0x3d2aaa81
	v_fmaak_f32 v40, v38, v40, 0x3e2aaaab
	v_fma_f32 v40, v38, v40, 0.5
	v_ldexp_f32 v36, 1.0, v36
	v_mul_f32_e32 v40, v38, v40
	v_cndmask_b32_e32 v36, v36, v202, vcc
	v_fmac_f32_e32 v38, v38, v40
	v_add_f32_e32 v40, -1.0, v36
	v_fmac_f32_e32 v40, v36, v38
	v_add_f32_e32 v36, v40, v40
	v_cndmask_b32_e32 v36, v40, v36, vcc
	v_cmp_nlt_f32_e32 vcc, s16, v32
	v_exp_f32_e32 v35, v35
	s_nop 0
	v_cndmask_b32_e64 v36, v201, -v36, vcc
	v_cmp_gt_f32_e32 vcc, s17, v36
	v_mul_f32_e32 v38, 0x4f800000, v36
	s_nop 0
	v_cndmask_b32_e32 v36, v36, v38, vcc
	v_sqrt_f32_e32 v38, v36
	s_nop 0
	v_add_u32_e32 v40, -1, v38
	v_fma_f32 v42, -v40, v38, v36
	v_cmp_ge_f32_e64 s[0:1], 0, v42
	v_add_u32_e32 v42, 1, v38
	s_nop 0
	v_cndmask_b32_e64 v40, v38, v40, s[0:1]
	v_fma_f32 v38, -v42, v38, v36
	v_cmp_lt_f32_e64 s[0:1], 0, v38
	s_nop 1
	v_cndmask_b32_e64 v38, v40, v42, s[0:1]
	v_mul_f32_e32 v40, 0x37800000, v38
	v_cndmask_b32_e32 v38, v38, v40, vcc
	v_cmp_class_f32_e32 vcc, v36, v193
	s_nop 1
	v_cndmask_b32_e32 v36, v38, v36, vcc
	v_cmp_ngt_f32_e32 vcc, s18, v32
	s_nop 1
	v_cndmask_b32_e32 v32, 1.0, v36, vcc
	v_mul_f32_e32 v32, v34, v32
	s_waitcnt lgkmcnt(0)
	v_mul_f32_e32 v32, v44, v32
	ds_write_b32 v70, v35 offset:6400
	ds_write_b32 v70, v32 offset:43264
	v_add_f32_e32 v32, v62, v74
	v_mul_f32_e32 v32, 0xbfb8aa3b, v32
	v_exp_f32_e32 v32, v32
	v_add_f32_e32 v34, v46, v73
	v_mul_f32_e32 v34, 0xbfb8aa3b, v34
	v_exp_f32_e32 v34, v34
	v_add_f32_e32 v32, 1.0, v32
	v_rcp_f32_e32 v32, v32
	v_add_f32_e32 v34, 1.0, v34
	v_rcp_f32_e32 v34, v34
	v_mul_f32_e32 v32, v32, v72
	v_mul_f32_e32 v35, 0x3fb8aa3b, v32
	v_add_f32_e32 v32, v32, v32
	v_exp_f32_e32 v36, v35
	v_mul_f32_e32 v35, 0x3fb8aa3b, v32
	v_rndne_f32_e32 v35, v35
	v_fmamk_f32 v38, v35, 0xbf317218, v32
	v_fmac_f32_e32 v38, 0x3102e308, v35
	v_fmamk_f32 v40, v38, 0x395133b1, v192
	v_cmp_eq_f32_e32 vcc, s15, v35
	v_cvt_i32_f32_e32 v35, v35
	v_fmaak_f32 v40, v38, v40, 0x3c0887f9
	v_fmaak_f32 v40, v38, v40, 0x3d2aaa81
	v_fmaak_f32 v40, v38, v40, 0x3e2aaaab
	v_fma_f32 v40, v38, v40, 0.5
	v_ldexp_f32 v35, 1.0, v35
	v_mul_f32_e32 v40, v38, v40
	v_cndmask_b32_e32 v35, v35, v202, vcc
	v_fmac_f32_e32 v38, v38, v40
	v_add_f32_e32 v40, -1.0, v35
	v_fmac_f32_e32 v40, v35, v38
	v_add_f32_e32 v35, v40, v40
	v_cndmask_b32_e32 v35, v40, v35, vcc
	v_cmp_nlt_f32_e32 vcc, s16, v32
	s_nop 1
	v_cndmask_b32_e64 v35, v201, -v35, vcc
	v_cmp_gt_f32_e32 vcc, s17, v35
	v_mul_f32_e32 v38, 0x4f800000, v35
	s_nop 0
	v_cndmask_b32_e32 v35, v35, v38, vcc
	v_sqrt_f32_e32 v38, v35
	s_nop 0
	v_add_u32_e32 v40, -1, v38
	v_fma_f32 v42, -v40, v38, v35
	v_cmp_ge_f32_e64 s[0:1], 0, v42
	v_add_u32_e32 v42, 1, v38
	s_nop 0
	v_cndmask_b32_e64 v40, v38, v40, s[0:1]
	v_fma_f32 v38, -v42, v38, v35
	v_cmp_lt_f32_e64 s[0:1], 0, v38
	s_nop 1
	v_cndmask_b32_e64 v38, v40, v42, s[0:1]
	v_mul_f32_e32 v40, 0x37800000, v38
	v_cndmask_b32_e32 v38, v38, v40, vcc
	v_cmp_class_f32_e32 vcc, v35, v193
	s_nop 1
	v_cndmask_b32_e32 v35, v38, v35, vcc
	v_cmp_ngt_f32_e32 vcc, s18, v32
	s_nop 1
	v_cndmask_b32_e32 v32, 1.0, v35, vcc
	v_mul_f32_e32 v32, v34, v32
	ds_read2_b32 v[34:35], v33 offset0:128 offset1:160
	s_waitcnt lgkmcnt(0)
	v_mul_f32_e32 v32, v34, v32
	ds_write_b32 v70, v36 offset:6656
	ds_write_b32 v70, v32 offset:43520
	v_add_f32_e32 v32, v63, v74
	v_mul_f32_e32 v32, 0xbfb8aa3b, v32
	v_exp_f32_e32 v32, v32
	v_add_f32_e32 v34, v47, v73
	v_mul_f32_e32 v34, 0xbfb8aa3b, v34
	v_exp_f32_e32 v34, v34
	v_add_f32_e32 v32, 1.0, v32
	v_rcp_f32_e32 v32, v32
	v_lshlrev_b64 v[46:47], 2, v[96:97]
	v_add_f32_e32 v34, 1.0, v34
	v_rcp_f32_e32 v36, v34
	v_mul_f32_e32 v32, v32, v72
	v_mul_f32_e32 v34, 0x3fb8aa3b, v32
	v_add_f32_e32 v32, v32, v32
	v_mul_f32_e32 v38, 0x3fb8aa3b, v32
	v_rndne_f32_e32 v38, v38
	v_fmamk_f32 v40, v38, 0xbf317218, v32
	v_fmac_f32_e32 v40, 0x3102e308, v38
	v_fmamk_f32 v42, v40, 0x395133b1, v192
	v_cmp_eq_f32_e32 vcc, s15, v38
	v_cvt_i32_f32_e32 v38, v38
	v_fmaak_f32 v42, v40, v42, 0x3c0887f9
	v_fmaak_f32 v42, v40, v42, 0x3d2aaa81
	v_fmaak_f32 v42, v40, v42, 0x3e2aaaab
	v_fma_f32 v42, v40, v42, 0.5
	v_ldexp_f32 v38, 1.0, v38
	v_mul_f32_e32 v42, v40, v42
	v_cndmask_b32_e32 v38, v38, v202, vcc
	v_fmac_f32_e32 v40, v40, v42
	v_add_f32_e32 v42, -1.0, v38
	v_fmac_f32_e32 v42, v38, v40
	v_add_f32_e32 v38, v42, v42
	v_cndmask_b32_e32 v38, v42, v38, vcc
	v_cmp_nlt_f32_e32 vcc, s16, v32
	v_lshl_add_u64 v[60:61], s[10:11], 0, v[46:47]
	v_exp_f32_e32 v34, v34
	v_cndmask_b32_e64 v38, v201, -v38, vcc
	v_cmp_gt_f32_e32 vcc, s17, v38
	v_mul_f32_e32 v40, 0x4f800000, v38
	s_nop 0
	v_cndmask_b32_e32 v38, v38, v40, vcc
	v_sqrt_f32_e32 v40, v38
	s_nop 0
	v_add_u32_e32 v42, -1, v40
	v_fma_f32 v44, -v42, v40, v38
	v_cmp_ge_f32_e64 s[0:1], 0, v44
	v_add_u32_e32 v44, 1, v40
	s_nop 0
	v_cndmask_b32_e64 v42, v40, v42, s[0:1]
	v_fma_f32 v40, -v44, v40, v38
	v_cmp_lt_f32_e64 s[0:1], 0, v40
	s_nop 1
	v_cndmask_b32_e64 v40, v42, v44, s[0:1]
	v_mul_f32_e32 v42, 0x37800000, v40
	v_cndmask_b32_e32 v40, v40, v42, vcc
	v_cmp_class_f32_e32 vcc, v38, v193
	s_nop 1
	v_cndmask_b32_e32 v38, v40, v38, vcc
	v_cmp_ngt_f32_e32 vcc, s18, v32
	s_nop 1
	v_cndmask_b32_e32 v32, 1.0, v38, vcc
	v_mul_f32_e32 v36, v36, v32
	ds_read2_b32 v[32:33], v33 offset0:192 offset1:224
	s_waitcnt lgkmcnt(0)
	v_mul_f32_e32 v32, v32, v36
	ds_write_b32 v70, v32 offset:43776
	v_mov_b32_e32 v32, v226
	s_waitcnt vmcnt(0)
	v_mul_f32_e32 v32, 0xbfb8aa3b, v32
	v_exp_f32_e32 v32, v32
	s_nop 0
	v_add_f32_e32 v36, 1.0, v32
	v_add_f32_e32 v38, -1.0, v36
	v_sub_f32_e32 v40, v38, v36
	v_add_f32_e32 v40, 1.0, v40
	v_sub_f32_e32 v38, v32, v38
	v_add_f32_e32 v38, v38, v40
	v_frexp_mant_f32_e32 v40, v36
	v_cvt_f64_f32_e32 v[60:61], v36
	v_cmp_gt_f32_e32 vcc, s7, v40
	v_frexp_exp_i32_f64_e32 v40, v[60:61]
	s_nop 0
	v_subbrev_co_u32_e32 v40, vcc, 0, v40, vcc
	v_sub_u32_e32 v42, 0, v40
	v_ldexp_f32 v36, v36, v42
	v_ldexp_f32 v38, v38, v42
	v_add_f32_e32 v42, -1.0, v36
	v_add_f32_e32 v48, 1.0, v36
	v_add_f32_e32 v44, 1.0, v42
	v_add_f32_e32 v50, -1.0, v48
	v_sub_f32_e32 v44, v36, v44
	v_sub_f32_e32 v36, v36, v50
	v_add_f32_e32 v36, v38, v36
	v_add_f32_e32 v44, v38, v44
	v_add_f32_e32 v38, v48, v36
	v_sub_f32_e32 v48, v38, v48
	v_sub_f32_e32 v36, v36, v48
	v_rcp_f32_e32 v48, v38
	v_add_f32_e32 v61, v42, v44
	v_sub_f32_e32 v42, v61, v42
	v_sub_f32_e32 v42, v44, v42
	v_mul_f32_e32 v44, v61, v48
	v_mul_f32_e32 v62, v38, v44
	v_fma_f32 v72, v44, v38, -v62
	v_fmac_f32_e32 v72, v44, v36
	v_add_f32_e32 v60, v62, v72
	v_sub_f32_e32 v63, v61, v60
	v_pk_add_f32 v[74:75], v[60:61], v[62:63] neg_lo:[0,1] neg_hi:[0,1]
	v_mov_b32_e32 v73, v60
	v_pk_add_f32 v[60:61], v[74:75], v[72:73] neg_lo:[0,1] neg_hi:[0,1]
	v_cmp_neq_f32_e32 vcc, s40, v32
	v_add_f32_e32 v42, v42, v61
	v_add_f32_e32 v42, v60, v42
	v_add_f32_e32 v61, v63, v42
	v_mul_f32_e32 v50, v48, v61
	v_mul_f32_e32 v62, v38, v50
	v_fma_f32 v72, v50, v38, -v62
	v_fmac_f32_e32 v72, v50, v36
	v_add_f32_e32 v60, v62, v72
	v_sub_f32_e32 v36, v63, v61
	v_sub_f32_e32 v63, v61, v60
	v_pk_add_f32 v[74:75], v[60:61], v[62:63] neg_lo:[0,1] neg_hi:[0,1]
	v_mov_b32_e32 v73, v60
	v_add_f32_e32 v36, v42, v36
	v_pk_add_f32 v[60:61], v[74:75], v[72:73] neg_lo:[0,1] neg_hi:[0,1]
	v_add_f32_e32 v38, v44, v50
	v_add_f32_e32 v36, v36, v61
	v_add_f32_e32 v36, v60, v36
	v_add_f32_e32 v36, v63, v36
	v_sub_f32_e32 v42, v38, v44
	v_mul_f32_e32 v36, v48, v36
	v_sub_f32_e32 v42, v50, v42
	v_add_f32_e32 v36, v42, v36
	v_add_f32_e32 v42, v38, v36
	v_cvt_f32_i32_e32 v60, v40
	v_mul_f32_e32 v44, v42, v42
	v_fmamk_f32 v48, v44, 0x3e9b6dac, v191
	v_fmaak_f32 v169, v44, v48, 0x3f2aaada
	v_mul_f32_e32 v61, v42, v44
	v_pk_mul_f32 v[72:73], v[60:61], v[168:169]
	v_ldexp_f32 v63, v42, 1
	v_fma_f32 v62, v60, s39, -v72
	v_fmac_f32_e32 v62, 0xb102e308, v60
	v_sub_f32_e32 v38, v42, v38
	v_pk_add_f32 v[60:61], v[72:73], v[62:63]
	v_sub_f32_e32 v36, v36, v38
	v_sub_f32_e32 v38, v61, v63
	v_ldexp_f32 v36, v36, 1
	v_sub_f32_e32 v38, v73, v38
	v_add_f32_e32 v75, v36, v38
	v_mov_b32_e32 v74, v72
	v_pk_add_f32 v[72:73], v[60:61], v[72:73] neg_lo:[0,1] neg_hi:[0,1]
	v_pk_add_f32 v[76:77], v[60:61], v[74:75]
	v_mov_b32_e32 v63, v60
	v_mov_b32_e32 v73, v77
	v_pk_add_f32 v[78:79], v[62:63], v[72:73] neg_lo:[0,1] neg_hi:[0,1]
	v_pk_add_f32 v[62:63], v[62:63], v[72:73]
	v_mov_b32_e32 v74, v75
	v_pk_add_f32 v[72:73], v[62:63], v[60:61] op_sel:[1,0] op_sel_hi:[0,1] neg_lo:[0,1] neg_hi:[0,1]
	v_pk_add_f32 v[80:81], v[76:77], v[72:73] op_sel_hi:[1,0] neg_lo:[0,1] neg_hi:[0,1]
	v_mov_b32_e32 v76, v77
	v_mov_b32_e32 v77, v63
	v_pk_mov_b32 v[72:73], v[60:61], v[72:73] op_sel:[1,0]
	v_mov_b32_e32 v75, v60
	v_pk_add_f32 v[72:73], v[76:77], v[72:73] neg_lo:[0,1] neg_hi:[0,1]
	v_mov_b32_e32 v80, v78
	v_pk_add_f32 v[60:61], v[74:75], v[72:73] neg_lo:[0,1] neg_hi:[0,1]
	v_mov_b32_e32 v79, v63
	v_pk_add_f32 v[72:73], v[80:81], v[60:61]
	s_nop 0
	v_pk_add_f32 v[74:75], v[72:73], v[72:73] op_sel:[0,1] op_sel_hi:[1,0]
	s_nop 0
	v_pk_add_f32 v[62:63], v[62:63], v[74:75] op_sel:[1,0] op_sel_hi:[0,1]
	v_mov_b32_e32 v73, v62
	v_pk_add_f32 v[76:77], v[72:73], v[78:79] neg_lo:[0,1] neg_hi:[0,1]
	v_mov_b32_e32 v61, v74
	v_sub_f32_e32 v36, v72, v76
	v_pk_add_f32 v[60:61], v[60:61], v[76:77] neg_lo:[0,1] neg_hi:[0,1]
	v_sub_f32_e32 v36, v78, v36
	v_add_f32_e32 v36, v60, v36
	v_add_f32_e32 v36, v36, v61
	v_add_f32_e32 v36, v62, v36
	v_cndmask_b32_e32 v36, v199, v36, vcc
	v_cmp_ngt_f32_e32 vcc, -1.0, v32
	v_lshl_add_u64 v[60:61], s[24:25], 0, v[46:47]
	v_lshl_add_u64 v[46:47], s[8:9], 0, v[46:47]
	v_cndmask_b32_e32 v36, v200, v36, vcc
	v_cmp_neq_f32_e32 vcc, -1.0, v32
	v_mov_b32_e32 v38, v227
	s_waitcnt vmcnt(0)
	v_add_f32_e32 v0, v0, v38
	v_cndmask_b32_e32 v36, v201, v36, vcc
	v_cmp_lt_f32_e64 vcc, |v32|, s41
	v_mul_f32_e32 v0, 0xbfb8aa3b, v0
	v_exp_f32_e32 v0, v0
	v_cndmask_b32_e32 v32, v36, v32, vcc
	v_mov_b32_e32 v36, v228
	v_mul_f32_e32 v32, 0xc1000000, v32
	v_add_f32_e32 v0, 1.0, v0
	v_rcp_f32_e32 v0, v0
	v_add_f32_e32 v1, v1, v38
	v_mul_f32_e32 v1, 0xbfb8aa3b, v1
	v_exp_f32_e32 v1, v1
	s_waitcnt vmcnt(0)
	v_add_f32_e32 v16, v16, v36
	v_mul_f32_e32 v16, 0xbfb8aa3b, v16
	v_exp_f32_e32 v16, v16
	v_add_f32_e32 v1, 1.0, v1
	v_rcp_f32_e32 v1, v1
	v_add_f32_e32 v16, 1.0, v16
	v_rcp_f32_e32 v16, v16
	s_nop 0
	v_mul_f32_e32 v16, v16, v32
	v_mul_f32_e32 v40, 0x3fb8aa3b, v16
	v_add_f32_e32 v16, v16, v16
	v_mul_f32_e32 v42, 0x3fb8aa3b, v16
	v_rndne_f32_e32 v42, v42
	v_fmamk_f32 v44, v42, 0xbf317218, v16
	v_fmac_f32_e32 v44, 0x3102e308, v42
	v_fmamk_f32 v46, v44, 0x395133b1, v192
	v_cmp_eq_f32_e32 vcc, s15, v42
	v_cvt_i32_f32_e32 v42, v42
	v_fmaak_f32 v46, v44, v46, 0x3c0887f9
	v_fmaak_f32 v46, v44, v46, 0x3d2aaa81
	v_fmaak_f32 v46, v44, v46, 0x3e2aaaab
	v_fma_f32 v46, v44, v46, 0.5
	v_ldexp_f32 v42, 1.0, v42
	v_mul_f32_e32 v46, v44, v46
	v_cndmask_b32_e32 v42, v42, v202, vcc
	v_fmac_f32_e32 v44, v44, v46
	v_add_f32_e32 v46, -1.0, v42
	v_fmac_f32_e32 v46, v42, v44
	v_add_f32_e32 v42, v46, v46
	v_cndmask_b32_e32 v42, v46, v42, vcc
	v_cmp_nlt_f32_e32 vcc, s16, v16
	v_exp_f32_e32 v40, v40
	s_nop 0
	v_cndmask_b32_e64 v42, v201, -v42, vcc
	v_cmp_gt_f32_e32 vcc, s17, v42
	v_mul_f32_e32 v44, 0x4f800000, v42
	s_nop 0
	v_cndmask_b32_e32 v42, v42, v44, vcc
	v_sqrt_f32_e32 v44, v42
	s_nop 0
	v_add_u32_e32 v46, -1, v44
	v_fma_f32 v47, -v46, v44, v42
	v_cmp_ge_f32_e64 s[0:1], 0, v47
	v_add_u32_e32 v47, 1, v44
	s_nop 0
	v_cndmask_b32_e64 v46, v44, v46, s[0:1]
	v_fma_f32 v44, -v47, v44, v42
	v_cmp_lt_f32_e64 s[0:1], 0, v44
	s_nop 1
	v_cndmask_b32_e64 v44, v46, v47, s[0:1]
	v_mul_f32_e32 v46, 0x37800000, v44
	v_cndmask_b32_e32 v44, v44, v46, vcc
	v_cmp_class_f32_e32 vcc, v42, v193
	s_nop 1
	v_cndmask_b32_e32 v42, v44, v42, vcc
	v_cmp_ngt_f32_e32 vcc, s18, v16
	s_nop 1
	v_cndmask_b32_e32 v16, 1.0, v42, vcc
	v_mul_f32_e32 v0, v0, v16
	v_mul_f32_e32 v0, v65, v0
	ds_write_b32 v70, v40 offset:128
	ds_write_b32 v70, v0 offset:36992
	v_add_f32_e32 v0, v17, v36
	v_mul_f32_e32 v0, 0xbfb8aa3b, v0
	v_exp_f32_e32 v0, v0
	s_nop 0
	v_add_f32_e32 v0, 1.0, v0
	v_rcp_f32_e32 v0, v0
	s_nop 0
	v_mul_f32_e32 v0, v0, v32
	v_mul_f32_e32 v16, 0x3fb8aa3b, v0
	v_add_f32_e32 v0, v0, v0
	v_mul_f32_e32 v17, 0x3fb8aa3b, v0
	v_rndne_f32_e32 v17, v17
	v_fmamk_f32 v40, v17, 0xbf317218, v0
	v_fmac_f32_e32 v40, 0x3102e308, v17
	v_fmamk_f32 v42, v40, 0x395133b1, v192
	v_cmp_eq_f32_e32 vcc, s15, v17
	v_cvt_i32_f32_e32 v17, v17
	v_fmaak_f32 v42, v40, v42, 0x3c0887f9
	v_fmaak_f32 v42, v40, v42, 0x3d2aaa81
	v_fmaak_f32 v42, v40, v42, 0x3e2aaaab
	v_fma_f32 v42, v40, v42, 0.5
	v_ldexp_f32 v17, 1.0, v17
	v_mul_f32_e32 v42, v40, v42
	v_cndmask_b32_e32 v17, v17, v202, vcc
	v_fmac_f32_e32 v40, v40, v42
	v_add_f32_e32 v42, -1.0, v17
	v_fmac_f32_e32 v42, v17, v40
	v_add_f32_e32 v17, v42, v42
	v_cndmask_b32_e32 v17, v42, v17, vcc
	v_cmp_nlt_f32_e32 vcc, s16, v0
	v_exp_f32_e32 v16, v16
	s_nop 0
	v_cndmask_b32_e64 v17, v201, -v17, vcc
	v_cmp_gt_f32_e32 vcc, s17, v17
	v_mul_f32_e32 v40, 0x4f800000, v17
	s_nop 0
	v_cndmask_b32_e32 v17, v17, v40, vcc
	v_sqrt_f32_e32 v40, v17
	s_nop 0
	v_add_u32_e32 v42, -1, v40
	v_fma_f32 v44, -v42, v40, v17
	v_cmp_ge_f32_e64 s[0:1], 0, v44
	v_add_u32_e32 v44, 1, v40
	s_nop 0
	v_cndmask_b32_e64 v42, v40, v42, s[0:1]
	v_fma_f32 v40, -v44, v40, v17
	v_cmp_lt_f32_e64 s[0:1], 0, v40
	s_nop 1
	v_cndmask_b32_e64 v40, v42, v44, s[0:1]
	v_mul_f32_e32 v42, 0x37800000, v40
	v_cndmask_b32_e32 v40, v40, v42, vcc
	v_cmp_class_f32_e32 vcc, v17, v193
	s_nop 1
	v_cndmask_b32_e32 v17, v40, v17, vcc
	v_cmp_ngt_f32_e32 vcc, s18, v0
	s_nop 1
	v_cndmask_b32_e32 v0, 1.0, v17, vcc
	v_mul_f32_e32 v0, v1, v0
	v_mul_f32_e32 v0, v49, v0
	ds_write_b32 v70, v16 offset:384
	ds_write_b32 v70, v0 offset:37248
	v_add_f32_e32 v0, v18, v36
	v_mul_f32_e32 v0, 0xbfb8aa3b, v0
	v_exp_f32_e32 v0, v0
	v_add_f32_e32 v1, v2, v38
	v_mul_f32_e32 v1, 0xbfb8aa3b, v1
	v_exp_f32_e32 v1, v1
	v_add_f32_e32 v0, 1.0, v0
	v_rcp_f32_e32 v0, v0
	v_add_f32_e32 v1, 1.0, v1
	v_rcp_f32_e32 v1, v1
	v_mul_f32_e32 v0, v0, v32
	v_mul_f32_e32 v2, 0x3fb8aa3b, v0
	v_add_f32_e32 v0, v0, v0
	v_mul_f32_e32 v16, 0x3fb8aa3b, v0
	v_rndne_f32_e32 v16, v16
	v_fmamk_f32 v17, v16, 0xbf317218, v0
	v_fmac_f32_e32 v17, 0x3102e308, v16
	v_fmamk_f32 v18, v17, 0x395133b1, v192
	v_cmp_eq_f32_e32 vcc, s15, v16
	v_cvt_i32_f32_e32 v16, v16
	v_fmaak_f32 v18, v17, v18, 0x3c0887f9
	v_fmaak_f32 v18, v17, v18, 0x3d2aaa81
	v_fmaak_f32 v18, v17, v18, 0x3e2aaaab
	v_fma_f32 v18, v17, v18, 0.5
	v_ldexp_f32 v16, 1.0, v16
	v_mul_f32_e32 v18, v17, v18
	v_cndmask_b32_e32 v16, v16, v202, vcc
	v_fmac_f32_e32 v17, v17, v18
	v_add_f32_e32 v18, -1.0, v16
	v_fmac_f32_e32 v18, v16, v17
	v_add_f32_e32 v16, v18, v18
	v_cndmask_b32_e32 v16, v18, v16, vcc
	v_cmp_nlt_f32_e32 vcc, s16, v0
	v_exp_f32_e32 v2, v2
	s_nop 0
	v_cndmask_b32_e64 v16, v201, -v16, vcc
	v_cmp_gt_f32_e32 vcc, s17, v16
	v_mul_f32_e32 v17, 0x4f800000, v16
	s_nop 0
	v_cndmask_b32_e32 v16, v16, v17, vcc
	v_sqrt_f32_e32 v17, v16
	s_nop 0
	v_add_u32_e32 v18, -1, v17
	v_fma_f32 v40, -v18, v17, v16
	v_cmp_ge_f32_e64 s[0:1], 0, v40
	v_add_u32_e32 v40, 1, v17
	s_nop 0
	v_cndmask_b32_e64 v18, v17, v18, s[0:1]
	v_fma_f32 v17, -v40, v17, v16
	v_cmp_lt_f32_e64 s[0:1], 0, v17
	s_nop 1
	v_cndmask_b32_e64 v17, v18, v40, s[0:1]
	v_mul_f32_e32 v18, 0x37800000, v17
	v_cndmask_b32_e32 v17, v17, v18, vcc
	v_cmp_class_f32_e32 vcc, v16, v193
	s_nop 1
	v_cndmask_b32_e32 v16, v17, v16, vcc
	v_cmp_ngt_f32_e32 vcc, s18, v0
	s_nop 1
	v_cndmask_b32_e32 v0, 1.0, v16, vcc
	v_mul_f32_e32 v0, v1, v0
	v_mul_f32_e32 v0, v67, v0
	ds_write_b32 v70, v2 offset:640
	ds_write_b32 v70, v0 offset:37504
	v_add_f32_e32 v0, v19, v36
	v_mul_f32_e32 v0, 0xbfb8aa3b, v0
	v_exp_f32_e32 v0, v0
	v_add_f32_e32 v1, v3, v38
	v_mul_f32_e32 v1, 0xbfb8aa3b, v1
	v_exp_f32_e32 v1, v1
	v_add_f32_e32 v0, 1.0, v0
	v_rcp_f32_e32 v0, v0
	v_add_f32_e32 v1, 1.0, v1
	v_rcp_f32_e32 v1, v1
	v_mul_f32_e32 v0, v0, v32
	v_mul_f32_e32 v2, 0x3fb8aa3b, v0
	v_add_f32_e32 v0, v0, v0
	v_mul_f32_e32 v3, 0x3fb8aa3b, v0
	v_rndne_f32_e32 v3, v3
	v_fmamk_f32 v16, v3, 0xbf317218, v0
	v_fmac_f32_e32 v16, 0x3102e308, v3
	v_fmamk_f32 v17, v16, 0x395133b1, v192
	v_cmp_eq_f32_e32 vcc, s15, v3
	v_cvt_i32_f32_e32 v3, v3
	v_fmaak_f32 v17, v16, v17, 0x3c0887f9
	v_fmaak_f32 v17, v16, v17, 0x3d2aaa81
	v_fmaak_f32 v17, v16, v17, 0x3e2aaaab
	v_fma_f32 v17, v16, v17, 0.5
	v_ldexp_f32 v3, 1.0, v3
	v_mul_f32_e32 v17, v16, v17
	v_cndmask_b32_e32 v3, v3, v202, vcc
	v_fmac_f32_e32 v16, v16, v17
	v_add_f32_e32 v17, -1.0, v3
	v_fmac_f32_e32 v17, v3, v16
	v_add_f32_e32 v3, v17, v17
	v_cndmask_b32_e32 v3, v17, v3, vcc
	v_cmp_nlt_f32_e32 vcc, s16, v0
	v_exp_f32_e32 v2, v2
	s_nop 0
	v_cndmask_b32_e64 v3, v201, -v3, vcc
	v_cmp_gt_f32_e32 vcc, s17, v3
	v_mul_f32_e32 v16, 0x4f800000, v3
	s_nop 0
	v_cndmask_b32_e32 v3, v3, v16, vcc
	v_sqrt_f32_e32 v16, v3
	s_nop 0
	v_add_u32_e32 v17, -1, v16
	v_fma_f32 v18, -v17, v16, v3
	v_cmp_ge_f32_e64 s[0:1], 0, v18
	v_add_u32_e32 v18, 1, v16
	s_nop 0
	v_cndmask_b32_e64 v17, v16, v17, s[0:1]
	v_fma_f32 v16, -v18, v16, v3
	v_cmp_lt_f32_e64 s[0:1], 0, v16
	s_nop 1
	v_cndmask_b32_e64 v16, v17, v18, s[0:1]
	v_mul_f32_e32 v17, 0x37800000, v16
	v_cndmask_b32_e32 v16, v16, v17, vcc
	v_cmp_class_f32_e32 vcc, v3, v193
	s_nop 1
	v_cndmask_b32_e32 v3, v16, v3, vcc
	v_cmp_ngt_f32_e32 vcc, s18, v0
	s_nop 1
	v_cndmask_b32_e32 v0, 1.0, v3, vcc
	v_mul_f32_e32 v0, v1, v0
	v_mul_f32_e32 v0, v51, v0
	ds_write_b32 v70, v2 offset:896
	ds_write_b32 v70, v0 offset:37760
	v_add_f32_e32 v0, v20, v36
	v_mul_f32_e32 v0, 0xbfb8aa3b, v0
	v_exp_f32_e32 v0, v0
	v_add_f32_e32 v1, v4, v38
	v_mul_f32_e32 v1, 0xbfb8aa3b, v1
	v_exp_f32_e32 v1, v1
	v_add_f32_e32 v0, 1.0, v0
	v_rcp_f32_e32 v0, v0
	v_add_f32_e32 v1, 1.0, v1
	v_rcp_f32_e32 v1, v1
	v_mul_f32_e32 v0, v0, v32
	v_mul_f32_e32 v2, 0x3fb8aa3b, v0
	v_add_f32_e32 v0, v0, v0
	v_mul_f32_e32 v3, 0x3fb8aa3b, v0
	v_rndne_f32_e32 v3, v3
	v_fmamk_f32 v4, v3, 0xbf317218, v0
	v_fmac_f32_e32 v4, 0x3102e308, v3
	v_fmamk_f32 v16, v4, 0x395133b1, v192
	v_cmp_eq_f32_e32 vcc, s15, v3
	v_cvt_i32_f32_e32 v3, v3
	v_fmaak_f32 v16, v4, v16, 0x3c0887f9
	v_fmaak_f32 v16, v4, v16, 0x3d2aaa81
	v_fmaak_f32 v16, v4, v16, 0x3e2aaaab
	v_fma_f32 v16, v4, v16, 0.5
	v_ldexp_f32 v3, 1.0, v3
	v_mul_f32_e32 v16, v4, v16
	v_cndmask_b32_e32 v3, v3, v202, vcc
	v_fmac_f32_e32 v4, v4, v16
	v_add_f32_e32 v16, -1.0, v3
	v_fmac_f32_e32 v16, v3, v4
	v_add_f32_e32 v3, v16, v16
	v_cndmask_b32_e32 v3, v16, v3, vcc
	v_cmp_nlt_f32_e32 vcc, s16, v0
	v_exp_f32_e32 v2, v2
	s_nop 0
	v_cndmask_b32_e64 v3, v201, -v3, vcc
	v_cmp_gt_f32_e32 vcc, s17, v3
	v_mul_f32_e32 v4, 0x4f800000, v3
	s_nop 0
	v_cndmask_b32_e32 v3, v3, v4, vcc
	v_sqrt_f32_e32 v4, v3
	s_nop 0
	v_add_u32_e32 v16, -1, v4
	v_fma_f32 v17, -v16, v4, v3
	v_cmp_ge_f32_e64 s[0:1], 0, v17
	v_add_u32_e32 v17, 1, v4
	s_nop 0
	v_cndmask_b32_e64 v16, v4, v16, s[0:1]
	v_fma_f32 v4, -v17, v4, v3
	v_cmp_lt_f32_e64 s[0:1], 0, v4
	s_nop 1
	v_cndmask_b32_e64 v4, v16, v17, s[0:1]
	v_mul_f32_e32 v16, 0x37800000, v4
	v_cndmask_b32_e32 v4, v4, v16, vcc
	v_cmp_class_f32_e32 vcc, v3, v193
	s_nop 1
	v_cndmask_b32_e32 v3, v4, v3, vcc
	v_cmp_ngt_f32_e32 vcc, s18, v0
	s_nop 1
	v_cndmask_b32_e32 v0, 1.0, v3, vcc
	v_mul_f32_e32 v0, v1, v0
	v_mul_f32_e32 v0, v69, v0
	ds_write_b32 v70, v2 offset:2176
	ds_write_b32 v70, v0 offset:39040
	v_add_f32_e32 v0, v21, v36
	v_mul_f32_e32 v0, 0xbfb8aa3b, v0
	v_exp_f32_e32 v0, v0
	v_add_f32_e32 v1, v5, v38
	v_mul_f32_e32 v1, 0xbfb8aa3b, v1
	v_exp_f32_e32 v1, v1
	v_add_f32_e32 v0, 1.0, v0
	v_rcp_f32_e32 v0, v0
	v_add_f32_e32 v1, 1.0, v1
	v_rcp_f32_e32 v1, v1
	v_mul_f32_e32 v0, v0, v32
	v_mul_f32_e32 v2, 0x3fb8aa3b, v0
	v_add_f32_e32 v0, v0, v0
	v_mul_f32_e32 v3, 0x3fb8aa3b, v0
	v_rndne_f32_e32 v3, v3
	v_fmamk_f32 v4, v3, 0xbf317218, v0
	v_fmac_f32_e32 v4, 0x3102e308, v3
	v_fmamk_f32 v5, v4, 0x395133b1, v192
	v_cmp_eq_f32_e32 vcc, s15, v3
	v_cvt_i32_f32_e32 v3, v3
	v_fmaak_f32 v5, v4, v5, 0x3c0887f9
	v_fmaak_f32 v5, v4, v5, 0x3d2aaa81
	v_fmaak_f32 v5, v4, v5, 0x3e2aaaab
	v_fma_f32 v5, v4, v5, 0.5
	v_ldexp_f32 v3, 1.0, v3
	v_mul_f32_e32 v5, v4, v5
	v_cndmask_b32_e32 v3, v3, v202, vcc
	v_fmac_f32_e32 v4, v4, v5
	v_add_f32_e32 v5, -1.0, v3
	v_fmac_f32_e32 v5, v3, v4
	v_add_f32_e32 v3, v5, v5
	v_cndmask_b32_e32 v3, v5, v3, vcc
	v_cmp_nlt_f32_e32 vcc, s16, v0
	v_exp_f32_e32 v2, v2
	s_nop 0
	v_cndmask_b32_e64 v3, v201, -v3, vcc
	v_cmp_gt_f32_e32 vcc, s17, v3
	v_mul_f32_e32 v4, 0x4f800000, v3
	s_nop 0
	v_cndmask_b32_e32 v3, v3, v4, vcc
	v_sqrt_f32_e32 v4, v3
	s_nop 0
	v_add_u32_e32 v5, -1, v4
	v_fma_f32 v16, -v5, v4, v3
	v_cmp_ge_f32_e64 s[0:1], 0, v16
	v_add_u32_e32 v16, 1, v4
	s_nop 0
	v_cndmask_b32_e64 v5, v4, v5, s[0:1]
	v_fma_f32 v4, -v16, v4, v3
	v_cmp_lt_f32_e64 s[0:1], 0, v4
	s_nop 1
	v_cndmask_b32_e64 v4, v5, v16, s[0:1]
	v_mul_f32_e32 v5, 0x37800000, v4
	v_cndmask_b32_e32 v4, v4, v5, vcc
	v_cmp_class_f32_e32 vcc, v3, v193
	s_nop 1
	v_cndmask_b32_e32 v3, v4, v3, vcc
	v_cmp_ngt_f32_e32 vcc, s18, v0
	s_nop 1
	v_cndmask_b32_e32 v0, 1.0, v3, vcc
	v_mul_f32_e32 v0, v1, v0
	v_mul_f32_e32 v0, v37, v0
	ds_write_b32 v70, v2 offset:2432
	ds_write_b32 v70, v0 offset:39296
	v_add_f32_e32 v0, v22, v36
	v_mul_f32_e32 v0, 0xbfb8aa3b, v0
	v_exp_f32_e32 v0, v0
	v_add_f32_e32 v1, v6, v38
	v_mul_f32_e32 v1, 0xbfb8aa3b, v1
	v_exp_f32_e32 v1, v1
	v_add_f32_e32 v0, 1.0, v0
	v_rcp_f32_e32 v0, v0
	v_add_f32_e32 v1, 1.0, v1
	v_rcp_f32_e32 v1, v1
	v_mul_f32_e32 v0, v0, v32
	v_mul_f32_e32 v2, 0x3fb8aa3b, v0
	v_add_f32_e32 v0, v0, v0
	v_mul_f32_e32 v3, 0x3fb8aa3b, v0
	v_rndne_f32_e32 v3, v3
	v_fmamk_f32 v4, v3, 0xbf317218, v0
	v_fmac_f32_e32 v4, 0x3102e308, v3
	v_fmamk_f32 v5, v4, 0x395133b1, v192
	v_cmp_eq_f32_e32 vcc, s15, v3
	v_cvt_i32_f32_e32 v3, v3
	v_fmaak_f32 v5, v4, v5, 0x3c0887f9
	v_fmaak_f32 v5, v4, v5, 0x3d2aaa81
	v_fmaak_f32 v5, v4, v5, 0x3e2aaaab
	v_fma_f32 v5, v4, v5, 0.5
	v_ldexp_f32 v3, 1.0, v3
	v_mul_f32_e32 v5, v4, v5
	v_cndmask_b32_e32 v3, v3, v202, vcc
	v_fmac_f32_e32 v4, v4, v5
	v_add_f32_e32 v5, -1.0, v3
	v_fmac_f32_e32 v5, v3, v4
	v_add_f32_e32 v3, v5, v5
	v_cndmask_b32_e32 v3, v5, v3, vcc
	v_cmp_nlt_f32_e32 vcc, s16, v0
	v_exp_f32_e32 v2, v2
	s_nop 0
	v_cndmask_b32_e64 v3, v201, -v3, vcc
	v_cmp_gt_f32_e32 vcc, s17, v3
	v_mul_f32_e32 v4, 0x4f800000, v3
	s_nop 0
	v_cndmask_b32_e32 v3, v3, v4, vcc
	v_sqrt_f32_e32 v4, v3
	s_nop 0
	v_add_u32_e32 v5, -1, v4
	v_fma_f32 v6, -v5, v4, v3
	v_cmp_ge_f32_e64 s[0:1], 0, v6
	v_add_u32_e32 v6, 1, v4
	s_nop 0
	v_cndmask_b32_e64 v5, v4, v5, s[0:1]
	v_fma_f32 v4, -v6, v4, v3
	v_cmp_lt_f32_e64 s[0:1], 0, v4
	s_nop 1
	v_cndmask_b32_e64 v4, v5, v6, s[0:1]
	v_mul_f32_e32 v5, 0x37800000, v4
	v_cndmask_b32_e32 v4, v4, v5, vcc
	v_cmp_class_f32_e32 vcc, v3, v193
	s_nop 1
	v_cndmask_b32_e32 v3, v4, v3, vcc
	v_cmp_ngt_f32_e32 vcc, s18, v0
	s_nop 1
	v_cndmask_b32_e32 v0, 1.0, v3, vcc
	v_mul_f32_e32 v0, v1, v0
	v_mul_f32_e32 v0, v53, v0
	ds_write_b32 v70, v2 offset:2688
	ds_write_b32 v70, v0 offset:39552
	v_add_f32_e32 v0, v23, v36
	v_mul_f32_e32 v0, 0xbfb8aa3b, v0
	v_exp_f32_e32 v0, v0
	v_add_f32_e32 v1, v7, v38
	v_mul_f32_e32 v1, 0xbfb8aa3b, v1
	v_exp_f32_e32 v1, v1
	v_add_f32_e32 v0, 1.0, v0
	v_rcp_f32_e32 v0, v0
	v_add_f32_e32 v1, 1.0, v1
	v_rcp_f32_e32 v1, v1
	v_mul_f32_e32 v0, v0, v32
	v_mul_f32_e32 v2, 0x3fb8aa3b, v0
	v_add_f32_e32 v0, v0, v0
	v_mul_f32_e32 v3, 0x3fb8aa3b, v0
	v_rndne_f32_e32 v3, v3
	v_fmamk_f32 v4, v3, 0xbf317218, v0
	v_fmac_f32_e32 v4, 0x3102e308, v3
	v_fmamk_f32 v5, v4, 0x395133b1, v192
	v_cmp_eq_f32_e32 vcc, s15, v3
	v_cvt_i32_f32_e32 v3, v3
	v_fmaak_f32 v5, v4, v5, 0x3c0887f9
	v_fmaak_f32 v5, v4, v5, 0x3d2aaa81
	v_fmaak_f32 v5, v4, v5, 0x3e2aaaab
	v_fma_f32 v5, v4, v5, 0.5
	v_ldexp_f32 v3, 1.0, v3
	v_mul_f32_e32 v5, v4, v5
	v_cndmask_b32_e32 v3, v3, v202, vcc
	v_fmac_f32_e32 v4, v4, v5
	v_add_f32_e32 v5, -1.0, v3
	v_fmac_f32_e32 v5, v3, v4
	v_add_f32_e32 v3, v5, v5
	v_cndmask_b32_e32 v3, v5, v3, vcc
	v_cmp_nlt_f32_e32 vcc, s16, v0
	v_exp_f32_e32 v2, v2
	s_nop 0
	v_cndmask_b32_e64 v3, v201, -v3, vcc
	v_cmp_gt_f32_e32 vcc, s17, v3
	v_mul_f32_e32 v4, 0x4f800000, v3
	s_nop 0
	v_cndmask_b32_e32 v3, v3, v4, vcc
	v_sqrt_f32_e32 v4, v3
	s_nop 0
	v_add_u32_e32 v5, -1, v4
	v_fma_f32 v6, -v5, v4, v3
	v_cmp_ge_f32_e64 s[0:1], 0, v6
	v_add_u32_e32 v6, 1, v4
	s_nop 0
	v_cndmask_b32_e64 v5, v4, v5, s[0:1]
	v_fma_f32 v4, -v6, v4, v3
	v_cmp_lt_f32_e64 s[0:1], 0, v4
	s_nop 1
	v_cndmask_b32_e64 v4, v5, v6, s[0:1]
	v_mul_f32_e32 v5, 0x37800000, v4
	v_cndmask_b32_e32 v4, v4, v5, vcc
	v_cmp_class_f32_e32 vcc, v3, v193
	s_nop 1
	v_cndmask_b32_e32 v3, v4, v3, vcc
	v_cmp_ngt_f32_e32 vcc, s18, v0
	s_nop 1
	v_cndmask_b32_e32 v0, 1.0, v3, vcc
	v_mul_f32_e32 v0, v1, v0
	v_mul_f32_e32 v0, v39, v0
	ds_write_b32 v70, v2 offset:2944
	ds_write_b32 v70, v0 offset:39808
	v_add_f32_e32 v0, v24, v36
	v_mul_f32_e32 v0, 0xbfb8aa3b, v0
	v_exp_f32_e32 v0, v0
	v_add_f32_e32 v1, v8, v38
	v_mul_f32_e32 v1, 0xbfb8aa3b, v1
	v_exp_f32_e32 v1, v1
	v_add_f32_e32 v0, 1.0, v0
	v_rcp_f32_e32 v0, v0
	v_add_f32_e32 v1, 1.0, v1
	v_rcp_f32_e32 v1, v1
	v_mul_f32_e32 v0, v0, v32
	v_mul_f32_e32 v2, 0x3fb8aa3b, v0
	v_add_f32_e32 v0, v0, v0
	v_mul_f32_e32 v3, 0x3fb8aa3b, v0
	v_rndne_f32_e32 v3, v3
	v_fmamk_f32 v4, v3, 0xbf317218, v0
	v_fmac_f32_e32 v4, 0x3102e308, v3
	v_fmamk_f32 v5, v4, 0x395133b1, v192
	v_cmp_eq_f32_e32 vcc, s15, v3
	v_cvt_i32_f32_e32 v3, v3
	v_fmaak_f32 v5, v4, v5, 0x3c0887f9
	v_fmaak_f32 v5, v4, v5, 0x3d2aaa81
	v_fmaak_f32 v5, v4, v5, 0x3e2aaaab
	v_fma_f32 v5, v4, v5, 0.5
	v_ldexp_f32 v3, 1.0, v3
	v_mul_f32_e32 v5, v4, v5
	v_cndmask_b32_e32 v3, v3, v202, vcc
	v_fmac_f32_e32 v4, v4, v5
	v_add_f32_e32 v5, -1.0, v3
	v_fmac_f32_e32 v5, v3, v4
	v_add_f32_e32 v3, v5, v5
	v_cndmask_b32_e32 v3, v5, v3, vcc
	v_cmp_nlt_f32_e32 vcc, s16, v0
	v_exp_f32_e32 v2, v2
	s_nop 0
	v_cndmask_b32_e64 v3, v201, -v3, vcc
	v_cmp_gt_f32_e32 vcc, s17, v3
	v_mul_f32_e32 v4, 0x4f800000, v3
	s_nop 0
	v_cndmask_b32_e32 v3, v3, v4, vcc
	v_sqrt_f32_e32 v4, v3
	s_nop 0
	v_add_u32_e32 v5, -1, v4
	v_fma_f32 v6, -v5, v4, v3
	v_cmp_ge_f32_e64 s[0:1], 0, v6
	v_add_u32_e32 v6, 1, v4
	s_nop 0
	v_cndmask_b32_e64 v5, v4, v5, s[0:1]
	v_fma_f32 v4, -v6, v4, v3
	v_cmp_lt_f32_e64 s[0:1], 0, v4
	s_nop 1
	v_cndmask_b32_e64 v4, v5, v6, s[0:1]
	v_mul_f32_e32 v5, 0x37800000, v4
	v_cndmask_b32_e32 v4, v4, v5, vcc
	v_cmp_class_f32_e32 vcc, v3, v193
	s_nop 1
	v_cndmask_b32_e32 v3, v4, v3, vcc
	v_cmp_ngt_f32_e32 vcc, s18, v0
	s_nop 1
	v_cndmask_b32_e32 v0, 1.0, v3, vcc
	v_mul_f32_e32 v0, v1, v0
	v_mul_f32_e32 v0, v55, v0
	ds_write_b32 v70, v2 offset:4224
	ds_write_b32 v70, v0 offset:41088
	v_add_f32_e32 v0, v25, v36
	v_mul_f32_e32 v0, 0xbfb8aa3b, v0
	v_exp_f32_e32 v0, v0
	v_add_f32_e32 v1, v9, v38
	v_mul_f32_e32 v1, 0xbfb8aa3b, v1
	v_exp_f32_e32 v1, v1
	v_add_f32_e32 v0, 1.0, v0
	v_rcp_f32_e32 v0, v0
	v_add_f32_e32 v1, 1.0, v1
	v_rcp_f32_e32 v1, v1
	v_mul_f32_e32 v0, v0, v32
	v_mul_f32_e32 v2, 0x3fb8aa3b, v0
	v_add_f32_e32 v0, v0, v0
	v_mul_f32_e32 v3, 0x3fb8aa3b, v0
	v_rndne_f32_e32 v3, v3
	v_fmamk_f32 v4, v3, 0xbf317218, v0
	v_fmac_f32_e32 v4, 0x3102e308, v3
	v_fmamk_f32 v5, v4, 0x395133b1, v192
	v_cmp_eq_f32_e32 vcc, s15, v3
	v_cvt_i32_f32_e32 v3, v3
	v_fmaak_f32 v5, v4, v5, 0x3c0887f9
	v_fmaak_f32 v5, v4, v5, 0x3d2aaa81
	v_fmaak_f32 v5, v4, v5, 0x3e2aaaab
	v_fma_f32 v5, v4, v5, 0.5
	v_ldexp_f32 v3, 1.0, v3
	v_mul_f32_e32 v5, v4, v5
	v_cndmask_b32_e32 v3, v3, v202, vcc
	v_fmac_f32_e32 v4, v4, v5
	v_add_f32_e32 v5, -1.0, v3
	v_fmac_f32_e32 v5, v3, v4
	v_add_f32_e32 v3, v5, v5
	v_cndmask_b32_e32 v3, v5, v3, vcc
	v_cmp_nlt_f32_e32 vcc, s16, v0
	v_exp_f32_e32 v2, v2
	s_nop 0
	v_cndmask_b32_e64 v3, v201, -v3, vcc
	v_cmp_gt_f32_e32 vcc, s17, v3
	v_mul_f32_e32 v4, 0x4f800000, v3
	s_nop 0
	v_cndmask_b32_e32 v3, v3, v4, vcc
	v_sqrt_f32_e32 v4, v3
	s_nop 0
	v_add_u32_e32 v5, -1, v4
	v_fma_f32 v6, -v5, v4, v3
	v_cmp_ge_f32_e64 s[0:1], 0, v6
	v_add_u32_e32 v6, 1, v4
	s_nop 0
	v_cndmask_b32_e64 v5, v4, v5, s[0:1]
	v_fma_f32 v4, -v6, v4, v3
	v_cmp_lt_f32_e64 s[0:1], 0, v4
	s_nop 1
	v_cndmask_b32_e64 v4, v5, v6, s[0:1]
	v_mul_f32_e32 v5, 0x37800000, v4
	v_cndmask_b32_e32 v4, v4, v5, vcc
	v_cmp_class_f32_e32 vcc, v3, v193
	s_nop 1
	v_cndmask_b32_e32 v3, v4, v3, vcc
	v_cmp_ngt_f32_e32 vcc, s18, v0
	s_nop 1
	v_cndmask_b32_e32 v0, 1.0, v3, vcc
	v_mul_f32_e32 v0, v1, v0
	v_mul_f32_e32 v0, v41, v0
	ds_write_b32 v70, v2 offset:4480
	ds_write_b32 v70, v0 offset:41344
	v_add_f32_e32 v0, v26, v36
	v_mul_f32_e32 v0, 0xbfb8aa3b, v0
	v_exp_f32_e32 v0, v0
	v_add_f32_e32 v1, v10, v38
	v_mul_f32_e32 v1, 0xbfb8aa3b, v1
	v_exp_f32_e32 v1, v1
	v_add_f32_e32 v0, 1.0, v0
	v_rcp_f32_e32 v0, v0
	v_add_f32_e32 v1, 1.0, v1
	v_rcp_f32_e32 v1, v1
	v_mul_f32_e32 v0, v0, v32
	v_mul_f32_e32 v2, 0x3fb8aa3b, v0
	v_add_f32_e32 v0, v0, v0
	v_mul_f32_e32 v3, 0x3fb8aa3b, v0
	v_rndne_f32_e32 v3, v3
	v_fmamk_f32 v4, v3, 0xbf317218, v0
	v_fmac_f32_e32 v4, 0x3102e308, v3
	v_fmamk_f32 v5, v4, 0x395133b1, v192
	v_cmp_eq_f32_e32 vcc, s15, v3
	v_cvt_i32_f32_e32 v3, v3
	v_fmaak_f32 v5, v4, v5, 0x3c0887f9
	v_fmaak_f32 v5, v4, v5, 0x3d2aaa81
	v_fmaak_f32 v5, v4, v5, 0x3e2aaaab
	v_fma_f32 v5, v4, v5, 0.5
	v_ldexp_f32 v3, 1.0, v3
	v_mul_f32_e32 v5, v4, v5
	v_cndmask_b32_e32 v3, v3, v202, vcc
	v_fmac_f32_e32 v4, v4, v5
	v_add_f32_e32 v5, -1.0, v3
	v_fmac_f32_e32 v5, v3, v4
	v_add_f32_e32 v3, v5, v5
	v_cndmask_b32_e32 v3, v5, v3, vcc
	v_cmp_nlt_f32_e32 vcc, s16, v0
	v_exp_f32_e32 v2, v2
	s_nop 0
	v_cndmask_b32_e64 v3, v201, -v3, vcc
	v_cmp_gt_f32_e32 vcc, s17, v3
	v_mul_f32_e32 v4, 0x4f800000, v3
	s_nop 0
	v_cndmask_b32_e32 v3, v3, v4, vcc
	v_sqrt_f32_e32 v4, v3
	s_nop 0
	v_add_u32_e32 v5, -1, v4
	v_fma_f32 v6, -v5, v4, v3
	v_cmp_ge_f32_e64 s[0:1], 0, v6
	v_add_u32_e32 v6, 1, v4
	s_nop 0
	v_cndmask_b32_e64 v5, v4, v5, s[0:1]
	v_fma_f32 v4, -v6, v4, v3
	v_cmp_lt_f32_e64 s[0:1], 0, v4
	s_nop 1
	v_cndmask_b32_e64 v4, v5, v6, s[0:1]
	v_mul_f32_e32 v5, 0x37800000, v4
	v_cndmask_b32_e32 v4, v4, v5, vcc
	v_cmp_class_f32_e32 vcc, v3, v193
	s_nop 1
	v_cndmask_b32_e32 v3, v4, v3, vcc
	v_cmp_ngt_f32_e32 vcc, s18, v0
	s_nop 1
	v_cndmask_b32_e32 v0, 1.0, v3, vcc
	v_mul_f32_e32 v0, v1, v0
	v_mul_f32_e32 v0, v57, v0
	ds_write_b32 v70, v2 offset:4736
	ds_write_b32 v70, v0 offset:41600
	v_add_f32_e32 v0, v27, v36
	v_mul_f32_e32 v0, 0xbfb8aa3b, v0
	v_exp_f32_e32 v0, v0
	v_add_f32_e32 v1, v11, v38
	v_mul_f32_e32 v1, 0xbfb8aa3b, v1
	v_exp_f32_e32 v1, v1
	v_add_f32_e32 v0, 1.0, v0
	v_rcp_f32_e32 v0, v0
	v_add_f32_e32 v1, 1.0, v1
	v_rcp_f32_e32 v1, v1
	v_mul_f32_e32 v0, v0, v32
	v_mul_f32_e32 v2, 0x3fb8aa3b, v0
	v_add_f32_e32 v0, v0, v0
	v_mul_f32_e32 v3, 0x3fb8aa3b, v0
	v_rndne_f32_e32 v3, v3
	v_fmamk_f32 v4, v3, 0xbf317218, v0
	v_fmac_f32_e32 v4, 0x3102e308, v3
	v_fmamk_f32 v5, v4, 0x395133b1, v192
	v_cmp_eq_f32_e32 vcc, s15, v3
	v_cvt_i32_f32_e32 v3, v3
	v_fmaak_f32 v5, v4, v5, 0x3c0887f9
	v_fmaak_f32 v5, v4, v5, 0x3d2aaa81
	v_fmaak_f32 v5, v4, v5, 0x3e2aaaab
	v_fma_f32 v5, v4, v5, 0.5
	v_ldexp_f32 v3, 1.0, v3
	v_mul_f32_e32 v5, v4, v5
	v_cndmask_b32_e32 v3, v3, v202, vcc
	v_fmac_f32_e32 v4, v4, v5
	v_add_f32_e32 v5, -1.0, v3
	v_fmac_f32_e32 v5, v3, v4
	v_add_f32_e32 v3, v5, v5
	v_cndmask_b32_e32 v3, v5, v3, vcc
	v_cmp_nlt_f32_e32 vcc, s16, v0
	v_exp_f32_e32 v2, v2
	s_nop 0
	v_cndmask_b32_e64 v3, v201, -v3, vcc
	v_cmp_gt_f32_e32 vcc, s17, v3
	v_mul_f32_e32 v4, 0x4f800000, v3
	s_nop 0
	v_cndmask_b32_e32 v3, v3, v4, vcc
	v_sqrt_f32_e32 v4, v3
	s_nop 0
	v_add_u32_e32 v5, -1, v4
	v_fma_f32 v6, -v5, v4, v3
	v_cmp_ge_f32_e64 s[0:1], 0, v6
	v_add_u32_e32 v6, 1, v4
	s_nop 0
	v_cndmask_b32_e64 v5, v4, v5, s[0:1]
	v_fma_f32 v4, -v6, v4, v3
	v_cmp_lt_f32_e64 s[0:1], 0, v4
	s_nop 1
	v_cndmask_b32_e64 v4, v5, v6, s[0:1]
	v_mul_f32_e32 v5, 0x37800000, v4
	v_cndmask_b32_e32 v4, v4, v5, vcc
	v_cmp_class_f32_e32 vcc, v3, v193
	s_nop 1
	v_cndmask_b32_e32 v3, v4, v3, vcc
	v_cmp_ngt_f32_e32 vcc, s18, v0
	s_nop 1
	v_cndmask_b32_e32 v0, 1.0, v3, vcc
	v_mul_f32_e32 v0, v1, v0
	v_mul_f32_e32 v0, v43, v0
	ds_write_b32 v70, v2 offset:4992
	ds_write_b32 v70, v0 offset:41856
	v_add_f32_e32 v0, v28, v36
	v_mul_f32_e32 v0, 0xbfb8aa3b, v0
	v_exp_f32_e32 v0, v0
	v_add_f32_e32 v1, v12, v38
	v_mul_f32_e32 v1, 0xbfb8aa3b, v1
	v_exp_f32_e32 v1, v1
	v_add_f32_e32 v0, 1.0, v0
	v_rcp_f32_e32 v0, v0
	v_add_f32_e32 v1, 1.0, v1
	v_rcp_f32_e32 v1, v1
	v_mul_f32_e32 v0, v0, v32
	v_mul_f32_e32 v2, 0x3fb8aa3b, v0
	v_add_f32_e32 v0, v0, v0
	v_mul_f32_e32 v3, 0x3fb8aa3b, v0
	v_rndne_f32_e32 v3, v3
	v_fmamk_f32 v4, v3, 0xbf317218, v0
	v_fmac_f32_e32 v4, 0x3102e308, v3
	v_fmamk_f32 v5, v4, 0x395133b1, v192
	v_cmp_eq_f32_e32 vcc, s15, v3
	v_cvt_i32_f32_e32 v3, v3
	v_fmaak_f32 v5, v4, v5, 0x3c0887f9
	v_fmaak_f32 v5, v4, v5, 0x3d2aaa81
	v_fmaak_f32 v5, v4, v5, 0x3e2aaaab
	v_fma_f32 v5, v4, v5, 0.5
	v_ldexp_f32 v3, 1.0, v3
	v_mul_f32_e32 v5, v4, v5
	v_cndmask_b32_e32 v3, v3, v202, vcc
	v_fmac_f32_e32 v4, v4, v5
	v_add_f32_e32 v5, -1.0, v3
	v_fmac_f32_e32 v5, v3, v4
	v_add_f32_e32 v3, v5, v5
	v_cndmask_b32_e32 v3, v5, v3, vcc
	v_cmp_nlt_f32_e32 vcc, s16, v0
	v_exp_f32_e32 v2, v2
	s_nop 0
	v_cndmask_b32_e64 v3, v201, -v3, vcc
	v_cmp_gt_f32_e32 vcc, s17, v3
	v_mul_f32_e32 v4, 0x4f800000, v3
	s_nop 0
	v_cndmask_b32_e32 v3, v3, v4, vcc
	v_sqrt_f32_e32 v4, v3
	s_nop 0
	v_add_u32_e32 v5, -1, v4
	v_fma_f32 v6, -v5, v4, v3
	v_cmp_ge_f32_e64 s[0:1], 0, v6
	v_add_u32_e32 v6, 1, v4
	s_nop 0
	v_cndmask_b32_e64 v5, v4, v5, s[0:1]
	v_fma_f32 v4, -v6, v4, v3
	v_cmp_lt_f32_e64 s[0:1], 0, v4
	s_nop 1
	v_cndmask_b32_e64 v4, v5, v6, s[0:1]
	v_mul_f32_e32 v5, 0x37800000, v4
	v_cndmask_b32_e32 v4, v4, v5, vcc
	v_cmp_class_f32_e32 vcc, v3, v193
	s_nop 1
	v_cndmask_b32_e32 v3, v4, v3, vcc
	v_cmp_ngt_f32_e32 vcc, s18, v0
	s_nop 1
	v_cndmask_b32_e32 v0, 1.0, v3, vcc
	v_mul_f32_e32 v0, v1, v0
	v_mul_f32_e32 v0, v59, v0
	ds_write_b32 v70, v2 offset:6272
	ds_write_b32 v70, v0 offset:43136
	v_add_f32_e32 v0, v29, v36
	v_mul_f32_e32 v0, 0xbfb8aa3b, v0
	v_exp_f32_e32 v0, v0
	v_add_f32_e32 v1, v13, v38
	v_mul_f32_e32 v1, 0xbfb8aa3b, v1
	v_exp_f32_e32 v1, v1
	v_add_f32_e32 v0, 1.0, v0
	v_rcp_f32_e32 v0, v0
	v_add_f32_e32 v1, 1.0, v1
	v_rcp_f32_e32 v1, v1
	v_mul_f32_e32 v0, v0, v32
	v_mul_f32_e32 v2, 0x3fb8aa3b, v0
	v_add_f32_e32 v0, v0, v0
	v_mul_f32_e32 v3, 0x3fb8aa3b, v0
	v_rndne_f32_e32 v3, v3
	v_fmamk_f32 v4, v3, 0xbf317218, v0
	v_fmac_f32_e32 v4, 0x3102e308, v3
	v_fmamk_f32 v5, v4, 0x395133b1, v192
	v_cmp_eq_f32_e32 vcc, s15, v3
	v_cvt_i32_f32_e32 v3, v3
	v_fmaak_f32 v5, v4, v5, 0x3c0887f9
	v_fmaak_f32 v5, v4, v5, 0x3d2aaa81
	v_fmaak_f32 v5, v4, v5, 0x3e2aaaab
	v_fma_f32 v5, v4, v5, 0.5
	v_ldexp_f32 v3, 1.0, v3
	v_mul_f32_e32 v5, v4, v5
	v_cndmask_b32_e32 v3, v3, v202, vcc
	v_fmac_f32_e32 v4, v4, v5
	v_add_f32_e32 v5, -1.0, v3
	v_fmac_f32_e32 v5, v3, v4
	v_add_f32_e32 v3, v5, v5
	v_cndmask_b32_e32 v3, v5, v3, vcc
	v_cmp_nlt_f32_e32 vcc, s16, v0
	v_exp_f32_e32 v2, v2
	s_nop 0
	v_cndmask_b32_e64 v3, v201, -v3, vcc
	v_cmp_gt_f32_e32 vcc, s17, v3
	v_mul_f32_e32 v4, 0x4f800000, v3
	s_nop 0
	v_cndmask_b32_e32 v3, v3, v4, vcc
	v_sqrt_f32_e32 v4, v3
	s_nop 0
	v_add_u32_e32 v5, -1, v4
	v_fma_f32 v6, -v5, v4, v3
	v_cmp_ge_f32_e64 s[0:1], 0, v6
	v_add_u32_e32 v6, 1, v4
	s_nop 0
	v_cndmask_b32_e64 v5, v4, v5, s[0:1]
	v_fma_f32 v4, -v6, v4, v3
	v_cmp_lt_f32_e64 s[0:1], 0, v4
	s_nop 1
	v_cndmask_b32_e64 v4, v5, v6, s[0:1]
	v_mul_f32_e32 v5, 0x37800000, v4
	v_cndmask_b32_e32 v4, v4, v5, vcc
	v_cmp_class_f32_e32 vcc, v3, v193
	s_nop 1
	v_cndmask_b32_e32 v3, v4, v3, vcc
	v_cmp_ngt_f32_e32 vcc, s18, v0
	s_nop 1
	v_cndmask_b32_e32 v0, 1.0, v3, vcc
	v_mul_f32_e32 v0, v1, v0
	v_mul_f32_e32 v0, v45, v0
	ds_write_b32 v70, v2 offset:6528
	ds_write_b32 v70, v0 offset:43392
	v_add_f32_e32 v0, v30, v36
	v_mul_f32_e32 v0, 0xbfb8aa3b, v0
	v_exp_f32_e32 v0, v0
	v_add_f32_e32 v1, v14, v38
	v_mul_f32_e32 v1, 0xbfb8aa3b, v1
	v_exp_f32_e32 v1, v1
	v_add_f32_e32 v0, 1.0, v0
	v_rcp_f32_e32 v0, v0
	v_add_f32_e32 v1, 1.0, v1
	v_rcp_f32_e32 v1, v1
	v_mul_f32_e32 v0, v0, v32
	v_mul_f32_e32 v2, 0x3fb8aa3b, v0
	v_add_f32_e32 v0, v0, v0
	v_mul_f32_e32 v3, 0x3fb8aa3b, v0
	v_rndne_f32_e32 v3, v3
	v_fmamk_f32 v4, v3, 0xbf317218, v0
	v_fmac_f32_e32 v4, 0x3102e308, v3
	v_fmamk_f32 v5, v4, 0x395133b1, v192
	v_cmp_eq_f32_e32 vcc, s15, v3
	v_cvt_i32_f32_e32 v3, v3
	v_fmaak_f32 v5, v4, v5, 0x3c0887f9
	v_fmaak_f32 v5, v4, v5, 0x3d2aaa81
	v_fmaak_f32 v5, v4, v5, 0x3e2aaaab
	v_fma_f32 v5, v4, v5, 0.5
	v_ldexp_f32 v3, 1.0, v3
	v_mul_f32_e32 v5, v4, v5
	v_cndmask_b32_e32 v3, v3, v202, vcc
	v_fmac_f32_e32 v4, v4, v5
	v_add_f32_e32 v5, -1.0, v3
	v_fmac_f32_e32 v5, v3, v4
	v_add_f32_e32 v3, v5, v5
	v_cndmask_b32_e32 v3, v5, v3, vcc
	v_cmp_nlt_f32_e32 vcc, s16, v0
	v_exp_f32_e32 v2, v2
	s_nop 0
	v_cndmask_b32_e64 v3, v201, -v3, vcc
	v_cmp_gt_f32_e32 vcc, s17, v3
	v_mul_f32_e32 v4, 0x4f800000, v3
	s_nop 0
	v_cndmask_b32_e32 v3, v3, v4, vcc
	v_sqrt_f32_e32 v4, v3
	s_nop 0
	v_add_u32_e32 v5, -1, v4
	v_fma_f32 v6, -v5, v4, v3
	v_cmp_ge_f32_e64 s[0:1], 0, v6
	v_add_u32_e32 v6, 1, v4
	s_nop 0
	v_cndmask_b32_e64 v5, v4, v5, s[0:1]
	v_fma_f32 v4, -v6, v4, v3
	v_cmp_lt_f32_e64 s[0:1], 0, v4
	s_nop 1
	v_cndmask_b32_e64 v4, v5, v6, s[0:1]
	v_mul_f32_e32 v5, 0x37800000, v4
	v_cndmask_b32_e32 v4, v4, v5, vcc
	v_cmp_class_f32_e32 vcc, v3, v193
	s_nop 1
	v_cndmask_b32_e32 v3, v4, v3, vcc
	v_cmp_ngt_f32_e32 vcc, s18, v0
	s_nop 1
	v_cndmask_b32_e32 v0, 1.0, v3, vcc
	v_mul_f32_e32 v0, v1, v0
	v_mul_f32_e32 v0, v35, v0
	v_add_u32_e32 v1, 0x1800, v70
	ds_write2_b32 v1, v2, v34 offset0:160 offset1:192
	ds_write_b32 v70, v0 offset:43648
	v_add_f32_e32 v0, v31, v36
	v_mul_f32_e32 v0, 0xbfb8aa3b, v0
	v_exp_f32_e32 v0, v0
	v_add_f32_e32 v1, v15, v38
	v_mul_f32_e32 v1, 0xbfb8aa3b, v1
	v_exp_f32_e32 v1, v1
	v_add_f32_e32 v0, 1.0, v0
	v_rcp_f32_e32 v0, v0
	v_add_f32_e32 v1, 1.0, v1
	v_rcp_f32_e32 v1, v1
	v_mul_f32_e32 v0, v0, v32
	v_mul_f32_e32 v2, 0x3fb8aa3b, v0
	v_add_f32_e32 v0, v0, v0
	v_mul_f32_e32 v3, 0x3fb8aa3b, v0
	v_rndne_f32_e32 v3, v3
	v_fmamk_f32 v4, v3, 0xbf317218, v0
	v_fmac_f32_e32 v4, 0x3102e308, v3
	v_fmamk_f32 v5, v4, 0x395133b1, v192
	v_cmp_eq_f32_e32 vcc, s15, v3
	v_cvt_i32_f32_e32 v3, v3
	v_fmaak_f32 v5, v4, v5, 0x3c0887f9
	v_fmaak_f32 v5, v4, v5, 0x3d2aaa81
	v_fmaak_f32 v5, v4, v5, 0x3e2aaaab
	v_fma_f32 v5, v4, v5, 0.5
	v_ldexp_f32 v3, 1.0, v3
	v_mul_f32_e32 v5, v4, v5
	v_cndmask_b32_e32 v3, v3, v202, vcc
	v_fmac_f32_e32 v4, v4, v5
	v_add_f32_e32 v5, -1.0, v3
	v_fmac_f32_e32 v5, v3, v4
	v_add_f32_e32 v3, v5, v5
	v_cndmask_b32_e32 v3, v5, v3, vcc
	v_cmp_nlt_f32_e32 vcc, s16, v0
	v_exp_f32_e32 v2, v2
	s_nop 0
	v_cndmask_b32_e64 v3, v201, -v3, vcc
	v_cmp_gt_f32_e32 vcc, s17, v3
	v_mul_f32_e32 v4, 0x4f800000, v3
	s_nop 0
	v_cndmask_b32_e32 v3, v3, v4, vcc
	v_sqrt_f32_e32 v4, v3
	s_nop 0
	v_add_u32_e32 v5, -1, v4
	v_fma_f32 v6, -v5, v4, v3
	v_cmp_ge_f32_e64 s[0:1], 0, v6
	v_add_u32_e32 v6, 1, v4
	s_nop 0
	v_cndmask_b32_e64 v5, v4, v5, s[0:1]
	v_fma_f32 v4, -v6, v4, v3
	v_cmp_lt_f32_e64 s[0:1], 0, v4
	s_nop 1
	v_cndmask_b32_e64 v4, v5, v6, s[0:1]
	v_mul_f32_e32 v5, 0x37800000, v4
	v_cndmask_b32_e32 v4, v4, v5, vcc
	v_cmp_class_f32_e32 vcc, v3, v193
	v_mov_b32_e32 v6, 1.0
	s_mov_b32 s0, 24
	v_cndmask_b32_e32 v3, v4, v3, vcc
	v_cmp_ngt_f32_e32 vcc, s18, v0
	s_nop 1
	v_cndmask_b32_e32 v0, 1.0, v3, vcc
	v_mul_f32_e32 v0, v1, v0
	v_mul_f32_e32 v0, v33, v0
	ds_write_b32 v70, v2 offset:7040
	ds_write_b32 v70, v0 offset:43904
	v_mov_b32_e32 v2, v162
	s_waitcnt lgkmcnt(0)
	s_barrier
	s_cselect_b64 vcc, -1, 0
	v_and_b32_e32 v3, 63, v2
	v_ashrrev_i32_e32 v4, 6, v2
	v_lshl_or_b32 v5, v4, 11, v3
	v_mov_b32_e32 v1, 0

.LBB0_717:
	s_or_b64 exec, exec, s[6:7]
	ds_write_b128 v70, v[52:55]
	ds_write_b128 v70, v[56:59] offset:4608
	ds_write_b128 v70, v[60:63] offset:9216
	ds_write_b128 v70, v[64:67] offset:13824
	s_waitcnt lgkmcnt(0)
	s_barrier
	ds_read_b128 v[32:35], v158
	ds_read_b128 v[36:39], v158 offset:4608
	s_waitcnt lgkmcnt(1)
	v_mfma_f32_32x32x16_bf16 v[80:95], v[98:101], v[32:35], 0
	s_waitcnt lgkmcnt(0)
	v_mfma_f32_32x32x16_bf16 v[48:63], v[98:101], v[36:39], 0
	ds_read_b128 v[32:35], v158 offset:9216
	ds_read_b128 v[36:39], v158 offset:13824
	s_waitcnt lgkmcnt(1)
	v_mfma_f32_32x32x16_bf16 v[64:79], v[98:101], v[32:35], 0
	s_waitcnt lgkmcnt(0)
	v_mfma_f32_32x32x16_bf16 v[32:47], v[98:101], v[36:39], 0
	ds_read_b128 v[148:151], v158 offset:32
	s_waitcnt lgkmcnt(0)
	v_mfma_f32_32x32x16_bf16 v[80:95], v[102:105], v[148:151], v[80:95]
	ds_read_b128 v[148:151], v158 offset:4640
	s_waitcnt lgkmcnt(0)
	v_mfma_f32_32x32x16_bf16 v[48:63], v[102:105], v[148:151], v[48:63]
	ds_read_b128 v[148:151], v158 offset:9248
	s_waitcnt lgkmcnt(0)
	v_mfma_f32_32x32x16_bf16 v[64:79], v[102:105], v[148:151], v[64:79]
	ds_read_b128 v[148:151], v158 offset:13856
	s_waitcnt lgkmcnt(0)
	v_mfma_f32_32x32x16_bf16 v[32:47], v[102:105], v[148:151], v[32:47]
	ds_read_b128 v[148:151], v158 offset:64
	s_waitcnt lgkmcnt(0)
	v_mfma_f32_32x32x16_bf16 v[80:95], v[106:109], v[148:151], v[80:95]
	ds_read_b128 v[148:151], v158 offset:4672
	s_waitcnt lgkmcnt(0)
	v_mfma_f32_32x32x16_bf16 v[48:63], v[106:109], v[148:151], v[48:63]
	ds_read_b128 v[148:151], v158 offset:9280
	s_waitcnt lgkmcnt(0)
	v_mfma_f32_32x32x16_bf16 v[64:79], v[106:109], v[148:151], v[64:79]
	ds_read_b128 v[148:151], v158 offset:13888
	s_waitcnt lgkmcnt(0)
	v_mfma_f32_32x32x16_bf16 v[32:47], v[106:109], v[148:151], v[32:47]
	ds_read_b128 v[148:151], v158 offset:96
	s_waitcnt lgkmcnt(0)
	v_mfma_f32_32x32x16_bf16 v[80:95], v[110:113], v[148:151], v[80:95]
	ds_read_b128 v[148:151], v158 offset:4704
	s_waitcnt lgkmcnt(0)
	v_mfma_f32_32x32x16_bf16 v[48:63], v[110:113], v[148:151], v[48:63]
	ds_read_b128 v[148:151], v158 offset:9312
	s_waitcnt lgkmcnt(0)
	v_mfma_f32_32x32x16_bf16 v[64:79], v[110:113], v[148:151], v[64:79]
	ds_read_b128 v[148:151], v158 offset:13920
	s_waitcnt lgkmcnt(0)
	v_mfma_f32_32x32x16_bf16 v[32:47], v[110:113], v[148:151], v[32:47]
	s_cmp_eq_u32 s53, 1
	s_cbranch_scc1 .Latt_nm
	s_cmp_gt_u32 s53, 2
	s_cbranch_scc1 .Latt_nm
	s_add_i32 s6, s53, s49
	v_mbcnt_hi_u32_b32 v148, -1, v195
	v_lshl_add_u32 v96, s6, 7, v183
	v_and_b32_e32 v147, 64, v148
	v_add_u32_e32 v149, 64, v147
	v_sub_u32_e32 v147, v96, v159
	v_cmp_gt_u32_e32 vcc, s58, v147
	s_or_b64 vcc, s[2:3], vcc
	v_add_u32_e32 v150, 32, v147
	v_cndmask_b32_e32 v80, v204, v80, vcc
	v_cmp_gt_u32_e32 vcc, s58, v150
	s_or_b64 vcc, s[2:3], vcc
	v_add_u32_e32 v151, 64, v147
	v_cndmask_b32_e32 v48, v204, v48, vcc
	v_cmp_gt_u32_e32 vcc, s58, v151
	s_or_b64 vcc, s[2:3], vcc
	v_add_u32_e32 v147, 0x60, v147
	v_cndmask_b32_e32 v64, v204, v64, vcc
	v_cmp_gt_u32_e32 vcc, s58, v147
	s_or_b64 vcc, s[2:3], vcc
	v_xor_b32_e32 v147, 16, v148
	v_cndmask_b32_e32 v32, v204, v32, vcc
	v_cmp_lt_i32_e32 vcc, v147, v149
	v_max3_f32 v150, v80, s59, v48
	v_max3_f32 v150, v150, v64, v32
	v_cndmask_b32_e32 v147, v148, v147, vcc
	v_lshlrev_b32_e32 v147, 2, v147
	v_mov_b32_e32 v151, v150
	v_mov_b32_e32 v255, v150
	s_nop 1
	v_permlane16_swap_b32_e32 v151, v255
	s_nop 1
	v_mov_b32_dpp v151, v255 quad_perm:[0,1,2,3] row_mask:0x5 bank_mask:0xf
	v_add_u32_e32 v187, 0x8800, v186
	v_add_u32_e32 v215, 0x9000, v186
	s_nop 0
	s_nop 0
	v_max_f32_e32 v150, v150, v151
	v_xor_b32_e32 v151, 8, v148
	v_cmp_lt_i32_e32 vcc, v151, v149
	s_nop 1
	v_cndmask_b32_e32 v151, v148, v151, vcc
	v_lshlrev_b32_e32 v208, 2, v151
	v_mov_b32_dpp v151, v150 row_ror:8 row_mask:0xf bank_mask:0xf
	s_nop 0
	s_nop 0
	v_max_f32_e32 v150, v150, v151
	v_xor_b32_e32 v151, 4, v148
	v_cmp_lt_i32_e32 vcc, v151, v149
	s_nop 1
	v_cndmask_b32_e32 v151, v148, v151, vcc
	v_lshlrev_b32_e32 v209, 2, v151
	v_mov_b32_dpp v151, v150 row_shl:4 row_mask:0xf bank_mask:0x5
	v_mov_b32_dpp v151, v150 row_shr:4 row_mask:0xf bank_mask:0xa
	s_nop 0
	s_nop 0
	v_max_f32_e32 v150, v150, v151
	v_xor_b32_e32 v151, 2, v148
	v_cmp_lt_i32_e32 vcc, v151, v149
	s_nop 1
	v_cndmask_b32_e32 v151, v148, v151, vcc
	v_lshlrev_b32_e32 v210, 2, v151
	v_mov_b32_dpp v151, v150 quad_perm:[2,3,0,1] row_mask:0xf bank_mask:0xf
	s_nop 0
	s_nop 0
	v_max_f32_e32 v150, v150, v151
	v_xor_b32_e32 v151, 1, v148
	v_cmp_lt_i32_e32 vcc, v151, v149
	v_sub_u32_e32 v149, v96, v161
	s_nop 0
	v_cndmask_b32_e32 v148, v148, v151, vcc
	v_cmp_gt_u32_e32 vcc, s58, v149
	s_or_b64 vcc, s[2:3], vcc
	v_lshlrev_b32_e32 v211, 2, v148
	v_cndmask_b32_e32 v151, v204, v81, vcc
	v_add_u32_e32 v81, 32, v149
	v_cmp_gt_u32_e32 vcc, s58, v81
	s_or_b64 vcc, s[2:3], vcc
	v_add_u32_e32 v81, 64, v149
	v_cndmask_b32_e32 v152, v204, v49, vcc
	v_cmp_gt_u32_e32 vcc, s58, v81
	s_or_b64 vcc, s[2:3], vcc
	v_max3_f32 v49, v151, s59, v152
	v_cndmask_b32_e32 v153, v204, v65, vcc
	v_add_u32_e32 v65, 0x60, v149
	v_cmp_gt_u32_e32 vcc, s58, v65
	s_or_b64 vcc, s[2:3], vcc
	v_mov_b32_dpp v148, v150 quad_perm:[1,0,3,2] row_mask:0xf bank_mask:0xf
	v_cndmask_b32_e32 v154, v204, v33, vcc
	v_max3_f32 v33, v49, v153, v154
	v_mov_b32_e32 v49, v33
	v_mov_b32_e32 v255, v33
	s_nop 1
	v_permlane16_swap_b32_e32 v49, v255
	s_nop 1
	v_mov_b32_dpp v49, v255 quad_perm:[0,1,2,3] row_mask:0x5 bank_mask:0xf
	s_nop 0
	v_max3_f32 v207, v130, v150, v148
	v_sub_f32_e32 v48, v48, v207
	v_mul_f32_e32 v48, 0x3fb8aa3b, v48
	s_nop 0
	v_max_f32_e32 v49, v49, v49
	v_max_f32_e32 v49, v33, v49
	s_nop 1
	v_mov_b32_dpp v65, v49 row_ror:8 row_mask:0xf bank_mask:0xf
	v_sub_f32_e32 v33, v80, v207
	v_sub_f32_e32 v32, v32, v207
	v_mul_f32_e32 v32, 0x3fb8aa3b, v32
	v_sub_f32_e32 v130, v130, v207
	s_nop 0
	v_max_f32_e32 v65, v65, v65
	v_max_f32_e32 v65, v49, v65
	s_nop 1
	v_mov_b32_dpp v80, v65 row_shl:4 row_mask:0xf bank_mask:0x5
	v_mov_b32_dpp v80, v65 row_shr:4 row_mask:0xf bank_mask:0xa
	v_exp_f32_e32 v49, v48
	v_sub_f32_e32 v48, v64, v207
	v_mul_f32_e32 v48, 0x3fb8aa3b, v48
	v_exp_f32_e32 v81, v48
	s_nop 0
	v_max_f32_e32 v64, v80, v80
	v_max_f32_e32 v64, v65, v64
	s_nop 1
	v_mov_b32_dpp v80, v64 quad_perm:[2,3,0,1] row_mask:0xf bank_mask:0xf
	v_exp_f32_e32 v65, v32
	v_mul_f32_e32 v33, 0x3fb8aa3b, v33
	v_exp_f32_e32 v33, v33
	s_nop 0
	v_max_f32_e32 v32, v80, v80
	v_max_f32_e32 v32, v64, v32
	s_nop 1
	v_mov_b32_dpp v48, v32 quad_perm:[1,0,3,2] row_mask:0xf bank_mask:0xf
	v_mul_f32_e32 v64, 0x3fb8aa3b, v130
	v_exp_f32_e32 v130, v64
	v_cvt_pk_bf16_f32 v148, v33, v49
	v_cvt_pk_bf16_f32 v149, v81, v65
	s_nop 0
	v_max3_f32 v206, v131, v32, v48
	v_sub_u32_e32 v32, v96, v169
	v_cmp_gt_u32_e32 vcc, s58, v32
	s_or_b64 vcc, s[2:3], vcc
	v_add_u32_e32 v48, 32, v32
	v_cndmask_b32_e32 v82, v204, v82, vcc
	v_cmp_gt_u32_e32 vcc, s58, v48
	s_or_b64 vcc, s[2:3], vcc
	v_add_u32_e32 v64, 64, v32
	v_cndmask_b32_e32 v50, v204, v50, vcc
	v_cmp_gt_u32_e32 vcc, s58, v64
	s_or_b64 vcc, s[2:3], vcc
	v_add_u32_e32 v32, 0x60, v32
	v_cndmask_b32_e32 v66, v204, v66, vcc
	v_cmp_gt_u32_e32 vcc, s58, v32
	s_or_b64 vcc, s[2:3], vcc
	v_max3_f32 v48, v82, s59, v50
	v_cndmask_b32_e32 v34, v204, v34, vcc
	v_max3_f32 v48, v48, v66, v34
	v_mov_b32_e32 v64, v48
	v_mov_b32_e32 v255, v48
	s_nop 1
	v_permlane16_swap_b32_e32 v64, v255
	s_nop 1
	v_mov_b32_dpp v64, v255 quad_perm:[0,1,2,3] row_mask:0x5 bank_mask:0xf
	v_sub_f32_e32 v32, v151, v206
	v_sub_f32_e32 v80, v152, v206
	v_mul_f32_e32 v32, 0x3fb8aa3b, v32
	v_exp_f32_e32 v32, v32
	s_nop 0
	v_max_f32_e32 v64, v64, v64
	v_max_f32_e32 v64, v48, v64
	s_nop 1
	v_mov_b32_dpp v150, v64 row_ror:8 row_mask:0xf bank_mask:0xf
	v_mul_f32_e32 v48, 0x3fb8aa3b, v80
	v_sub_f32_e32 v80, v153, v206
	v_mul_f32_e32 v80, 0x3fb8aa3b, v80
	v_exp_f32_e32 v48, v48
	s_nop 0
	v_max_f32_e32 v150, v150, v150
	v_max_f32_e32 v150, v64, v150
	v_sub_f32_e32 v64, v154, v206
	v_sub_u32_e32 v154, v96, v170
	v_cmp_gt_u32_e32 vcc, s58, v154
	s_or_b64 vcc, s[2:3], vcc
	v_mov_b32_dpp v151, v150 row_shl:4 row_mask:0xf bank_mask:0x5
	v_mov_b32_dpp v151, v150 row_shr:4 row_mask:0xf bank_mask:0xa
	v_cndmask_b32_e32 v155, v204, v83, vcc
	v_add_u32_e32 v83, 32, v154
	v_cmp_gt_u32_e32 vcc, s58, v83
	s_or_b64 vcc, s[2:3], vcc
	v_add_u32_e32 v83, 64, v154
	v_cndmask_b32_e32 v156, v204, v51, vcc
	v_cmp_gt_u32_e32 vcc, s58, v83
	s_or_b64 vcc, s[2:3], vcc
	v_max3_f32 v51, v155, s59, v156
	v_cndmask_b32_e32 v160, v204, v67, vcc
	v_add_u32_e32 v67, 0x60, v154
	v_cmp_gt_u32_e32 vcc, s58, v67
	s_or_b64 vcc, s[2:3], vcc
	s_nop 0
	v_max_f32_e32 v151, v151, v151
	v_cndmask_b32_e32 v154, v204, v35, vcc
	v_max3_f32 v35, v51, v160, v154
	v_max_f32_e32 v152, v150, v151
	v_mov_b32_e32 v51, v35
	v_mov_b32_e32 v255, v35
	s_nop 1
	v_permlane16_swap_b32_e32 v51, v255
	s_nop 1
	v_mov_b32_dpp v51, v255 quad_perm:[0,1,2,3] row_mask:0x5 bank_mask:0xf
	s_nop 1
	v_mov_b32_dpp v153, v152 quad_perm:[2,3,0,1] row_mask:0xf bank_mask:0xf
	v_mul_f32_e32 v64, 0x3fb8aa3b, v64
	v_exp_f32_e32 v80, v80
	v_exp_f32_e32 v64, v64
	s_nop 0
	v_max_f32_e32 v51, v51, v51
	s_nop 0
	v_max_f32_e32 v153, v153, v153
	v_max_f32_e32 v51, v35, v51
	v_max_f32_e32 v152, v152, v153
	s_nop 1
	v_mov_b32_dpp v67, v51 row_ror:8 row_mask:0xf bank_mask:0xf
	s_nop 1
	v_mov_b32_dpp v153, v152 quad_perm:[1,0,3,2] row_mask:0xf bank_mask:0xf
	v_cvt_pk_bf16_f32 v150, v32, v48
	v_cvt_pk_bf16_f32 v151, v80, v64
	ds_write2_b64 v187, v[148:149], v[150:151] offset0:128 offset1:162
	s_nop 0
	v_max_f32_e32 v67, v67, v67
	s_nop 0
	v_max3_f32 v189, v132, v152, v153
	v_max_f32_e32 v67, v51, v67
	v_sub_f32_e32 v35, v82, v189
	s_nop 1
	v_mov_b32_dpp v82, v67 row_shl:4 row_mask:0xf bank_mask:0x5
	v_mov_b32_dpp v82, v67 row_shr:4 row_mask:0xf bank_mask:0xa
	v_sub_f32_e32 v50, v50, v189
	v_mul_f32_e32 v50, 0x3fb8aa3b, v50
	v_exp_f32_e32 v51, v50
	v_sub_f32_e32 v50, v66, v189
	s_waitcnt lgkmcnt(0)
	v_max_f32_e32 v66, v82, v82
	v_max_f32_e32 v66, v67, v66
	s_nop 1
	v_mov_b32_dpp v82, v66 quad_perm:[2,3,0,1] row_mask:0xf bank_mask:0xf
	v_sub_f32_e32 v34, v34, v189
	v_mul_f32_e32 v34, 0x3fb8aa3b, v34
	v_exp_f32_e32 v67, v34
	v_mul_f32_e32 v50, 0x3fb8aa3b, v50
	s_nop 0
	v_max_f32_e32 v34, v82, v82
	v_max_f32_e32 v34, v66, v34
	v_exp_f32_e32 v83, v50
	s_nop 1
	v_mov_b32_dpp v50, v34 quad_perm:[1,0,3,2] row_mask:0xf bank_mask:0xf
	v_sub_f32_e32 v132, v132, v189
	v_mul_f32_e32 v66, 0x3fb8aa3b, v132
	v_exp_f32_e32 v132, v66
	v_mul_f32_e32 v35, 0x3fb8aa3b, v35
	s_nop 0
	v_max3_f32 v188, v133, v34, v50
	v_sub_u32_e32 v34, v96, v171
	v_cmp_gt_u32_e32 vcc, s58, v34
	s_or_b64 vcc, s[2:3], vcc
	v_add_u32_e32 v50, 32, v34
	v_cndmask_b32_e32 v84, v204, v84, vcc
	v_cmp_gt_u32_e32 vcc, s58, v50
	s_or_b64 vcc, s[2:3], vcc
	v_add_u32_e32 v66, 64, v34
	v_cndmask_b32_e32 v52, v204, v52, vcc
	v_cmp_gt_u32_e32 vcc, s58, v66
	s_or_b64 vcc, s[2:3], vcc
	v_add_u32_e32 v34, 0x60, v34
	v_cndmask_b32_e32 v68, v204, v68, vcc
	v_cmp_gt_u32_e32 vcc, s58, v34
	s_or_b64 vcc, s[2:3], vcc
	v_max3_f32 v50, v84, s59, v52
	v_cndmask_b32_e32 v150, v204, v36, vcc
	v_max3_f32 v34, v50, v68, v150
	v_mov_b32_e32 v36, v34
	v_mov_b32_e32 v255, v34
	s_nop 1
	v_permlane16_swap_b32_e32 v36, v255
	s_nop 1
	v_mov_b32_dpp v36, v255 quad_perm:[0,1,2,3] row_mask:0x5 bank_mask:0xf
	v_sub_f32_e32 v151, v154, v188
	v_sub_f32_e32 v50, v133, v188
	v_mul_f32_e32 v133, 0x3fb8aa3b, v50
	v_sub_f32_e32 v50, v155, v188
	s_nop 0
	v_max_f32_e32 v36, v36, v36
	v_max_f32_e32 v36, v34, v36
	s_nop 1
	v_mov_b32_dpp v66, v36 row_ror:8 row_mask:0xf bank_mask:0xf
	v_mul_f32_e32 v50, 0x3fb8aa3b, v50
	v_exp_f32_e32 v34, v50
	v_sub_f32_e32 v50, v156, v188
	v_sub_f32_e32 v82, v160, v188
	s_nop 0
	v_max_f32_e32 v66, v66, v66
	v_max_f32_e32 v36, v36, v66
	s_nop 1
	v_mov_b32_dpp v66, v36 row_shl:4 row_mask:0xf bank_mask:0x5
	v_mov_b32_dpp v66, v36 row_shr:4 row_mask:0xf bank_mask:0xa
	v_mul_f32_e32 v50, 0x3fb8aa3b, v50
	v_mul_f32_e32 v82, 0x3fb8aa3b, v82
	v_exp_f32_e32 v35, v35
	v_exp_f32_e32 v50, v50
	s_nop 0
	v_max_f32_e32 v66, v66, v66
	v_max_f32_e32 v152, v36, v66
	s_nop 1
	v_mov_b32_dpp v153, v152 quad_perm:[2,3,0,1] row_mask:0xf bank_mask:0xf
	v_mul_f32_e32 v36, 0x3fb8aa3b, v151
	v_exp_f32_e32 v82, v82
	v_exp_f32_e32 v66, v36
	v_cvt_pk_bf16_f32 v148, v35, v51
	s_nop 0
	v_max_f32_e32 v151, v153, v153
	v_sub_u32_e32 v153, v96, v172
	v_cmp_gt_u32_e32 vcc, s58, v153
	s_or_b64 vcc, s[2:3], vcc
	v_cvt_pk_bf16_f32 v149, v83, v67
	v_cndmask_b32_e32 v154, v204, v85, vcc
	v_add_u32_e32 v85, 32, v153
	v_cmp_gt_u32_e32 vcc, s58, v85
	s_or_b64 vcc, s[2:3], vcc
	v_add_u32_e32 v85, 64, v153
	v_cndmask_b32_e32 v155, v204, v53, vcc
	v_cmp_gt_u32_e32 vcc, s58, v85
	s_or_b64 vcc, s[2:3], vcc
	v_max3_f32 v53, v154, s59, v155
	v_cndmask_b32_e32 v156, v204, v69, vcc
	v_add_u32_e32 v69, 0x60, v153
	v_cmp_gt_u32_e32 vcc, s58, v69
	s_or_b64 vcc, s[2:3], vcc
	v_cvt_pk_bf16_f32 v36, v34, v50
	v_cndmask_b32_e32 v153, v204, v37, vcc
	v_max3_f32 v53, v53, v156, v153
	v_mov_b32_e32 v69, v53
	v_mov_b32_e32 v255, v53
	s_nop 1
	v_permlane16_swap_b32_e32 v69, v255
	s_nop 1
	v_mov_b32_dpp v69, v255 quad_perm:[0,1,2,3] row_mask:0x5 bank_mask:0xf
	v_cvt_pk_bf16_f32 v37, v82, v66
	ds_write2_b64 v187, v[148:149], v[36:37] offset0:196 offset1:230
	v_max_f32_e32 v151, v152, v151
	s_nop 1
	v_mov_b32_dpp v152, v151 quad_perm:[1,0,3,2] row_mask:0xf bank_mask:0xf
	s_nop 0
	v_max_f32_e32 v37, v69, v69
	v_max_f32_e32 v53, v53, v37
	s_nop 1
	v_mov_b32_dpp v69, v53 row_ror:8 row_mask:0xf bank_mask:0xf
	v_sub_f32_e32 v131, v131, v206
	s_waitcnt lgkmcnt(0)
	v_max3_f32 v187, v134, v151, v152
	v_sub_f32_e32 v37, v84, v187
	v_sub_f32_e32 v52, v52, v187
	s_nop 0
	v_max_f32_e32 v69, v69, v69
	v_max_f32_e32 v69, v53, v69
	s_nop 1
	v_mov_b32_dpp v84, v69 row_shl:4 row_mask:0xf bank_mask:0x5
	v_mov_b32_dpp v84, v69 row_shr:4 row_mask:0xf bank_mask:0xa
	v_mul_f32_e32 v52, 0x3fb8aa3b, v52
	v_exp_f32_e32 v53, v52
	v_sub_f32_e32 v52, v68, v187
	v_mul_f32_e32 v52, 0x3fb8aa3b, v52
	s_nop 0
	v_max_f32_e32 v68, v84, v84
	v_max_f32_e32 v68, v69, v68
	s_nop 1
	v_mov_b32_dpp v84, v68 quad_perm:[2,3,0,1] row_mask:0xf bank_mask:0xf
	v_exp_f32_e32 v85, v52
	v_sub_f32_e32 v52, v150, v187
	v_mul_f32_e32 v52, 0x3fb8aa3b, v52
	v_exp_f32_e32 v69, v52
	s_nop 0
	v_max_f32_e32 v52, v84, v84
	v_max_f32_e32 v52, v68, v52
	s_nop 1
	v_mov_b32_dpp v68, v52 quad_perm:[1,0,3,2] row_mask:0xf bank_mask:0xf
	v_sub_f32_e32 v36, v134, v187
	v_mul_f32_e32 v36, 0x3fb8aa3b, v36
	v_exp_f32_e32 v134, v36
	v_sub_u32_e32 v36, v96, v173
	v_cmp_gt_u32_e32 vcc, s58, v36
	s_nop 0
	v_max3_f32 v160, v135, v52, v68
	s_or_b64 vcc, s[2:3], vcc
	v_add_u32_e32 v52, 32, v36
	v_cndmask_b32_e32 v86, v204, v86, vcc
	v_cmp_gt_u32_e32 vcc, s58, v52
	s_or_b64 vcc, s[2:3], vcc
	v_add_u32_e32 v68, 64, v36
	v_cndmask_b32_e32 v54, v204, v54, vcc
	v_cmp_gt_u32_e32 vcc, s58, v68
	s_or_b64 vcc, s[2:3], vcc
	v_add_u32_e32 v36, 0x60, v36
	v_cndmask_b32_e32 v70, v204, v70, vcc
	v_cmp_gt_u32_e32 vcc, s58, v36
	s_or_b64 vcc, s[2:3], vcc
	v_max3_f32 v52, v86, s59, v54
	v_cndmask_b32_e32 v38, v204, v38, vcc
	v_max3_f32 v52, v52, v70, v38
	v_mov_b32_e32 v68, v52
	v_mov_b32_e32 v255, v52
	s_nop 1
	v_permlane16_swap_b32_e32 v68, v255
	s_nop 1
	v_mov_b32_dpp v68, v255 quad_perm:[0,1,2,3] row_mask:0x5 bank_mask:0xf
	v_sub_f32_e32 v36, v154, v160
	v_sub_u32_e32 v154, v96, v174
	v_cmp_gt_u32_e32 vcc, s58, v154
	s_or_b64 vcc, s[2:3], vcc
	s_nop 0
	v_max_f32_e32 v68, v68, v68
	v_max_f32_e32 v68, v52, v68
	s_nop 1
	v_mov_b32_dpp v150, v68 row_ror:8 row_mask:0xf bank_mask:0xf
	v_cndmask_b32_e32 v212, v204, v87, vcc
	v_add_u32_e32 v87, 32, v154
	v_cmp_gt_u32_e32 vcc, s58, v87
	s_or_b64 vcc, s[2:3], vcc
	s_nop 0
	v_max_f32_e32 v150, v150, v150
	v_add_u32_e32 v87, 64, v154
	v_max_f32_e32 v150, v68, v150
	v_cndmask_b32_e32 v213, v204, v55, vcc
	v_cmp_gt_u32_e32 vcc, s58, v87
	v_mov_b32_dpp v151, v150 row_shl:4 row_mask:0xf bank_mask:0x5
	v_mov_b32_dpp v151, v150 row_shr:4 row_mask:0xf bank_mask:0xa
	s_or_b64 vcc, s[2:3], vcc
	v_cndmask_b32_e32 v214, v204, v71, vcc
	v_add_u32_e32 v71, 0x60, v154
	v_cmp_gt_u32_e32 vcc, s58, v71
	s_or_b64 vcc, s[2:3], vcc
	v_max3_f32 v55, v212, s59, v213
	v_cndmask_b32_e32 v154, v204, v39, vcc
	s_nop 0
	v_max_f32_e32 v151, v151, v151
	v_max3_f32 v39, v55, v214, v154
	v_max_f32_e32 v152, v150, v151
	v_mov_b32_e32 v55, v39
	v_mov_b32_e32 v255, v39
	s_nop 1
	v_permlane16_swap_b32_e32 v55, v255
	s_nop 1
	v_mov_b32_dpp v55, v255 quad_perm:[0,1,2,3] row_mask:0x5 bank_mask:0xf
	v_sub_f32_e32 v68, v153, v160
	v_mov_b32_dpp v153, v152 quad_perm:[2,3,0,1] row_mask:0xf bank_mask:0xf
	v_sub_f32_e32 v84, v155, v160
	v_mul_f32_e32 v52, 0x3fb8aa3b, v84
	s_nop 0
	v_max_f32_e32 v55, v55, v55
	v_max_f32_e32 v55, v39, v55
	s_nop 0
	v_max_f32_e32 v153, v153, v153
	v_max_f32_e32 v152, v152, v153
	v_mov_b32_dpp v71, v55 row_ror:8 row_mask:0xf bank_mask:0xf
	s_nop 1
	v_mov_b32_dpp v153, v152 quad_perm:[1,0,3,2] row_mask:0xf bank_mask:0xf
	v_sub_f32_e32 v84, v156, v160
	v_mul_f32_e32 v37, 0x3fb8aa3b, v37
	v_mul_f32_e32 v36, 0x3fb8aa3b, v36
	s_nop 0
	v_max_f32_e32 v71, v71, v71
	s_nop 0
	v_max3_f32 v156, v136, v152, v153
	v_max_f32_e32 v71, v55, v71
	v_sub_f32_e32 v39, v86, v156
	s_nop 1
	v_mov_b32_dpp v86, v71 row_shl:4 row_mask:0xf bank_mask:0x5
	v_mov_b32_dpp v86, v71 row_shr:4 row_mask:0xf bank_mask:0xa
	v_sub_f32_e32 v54, v54, v156
	v_mul_f32_e32 v54, 0x3fb8aa3b, v54
	v_exp_f32_e32 v55, v54
	v_sub_f32_e32 v54, v70, v156
	s_nop 0
	v_max_f32_e32 v70, v86, v86
	v_max_f32_e32 v70, v71, v70
	s_nop 1
	v_mov_b32_dpp v86, v70 quad_perm:[2,3,0,1] row_mask:0xf bank_mask:0xf
	v_sub_f32_e32 v38, v38, v156
	v_mul_f32_e32 v38, 0x3fb8aa3b, v38
	v_exp_f32_e32 v71, v38
	v_mul_f32_e32 v54, 0x3fb8aa3b, v54
	s_nop 0
	v_max_f32_e32 v38, v86, v86
	v_max_f32_e32 v38, v70, v38
	v_exp_f32_e32 v87, v54
	s_nop 1
	v_mov_b32_dpp v54, v38 quad_perm:[1,0,3,2] row_mask:0xf bank_mask:0xf
	v_sub_f32_e32 v136, v136, v156
	v_mul_f32_e32 v84, 0x3fb8aa3b, v84
	v_mul_f32_e32 v68, 0x3fb8aa3b, v68
	v_mul_f32_e32 v70, 0x3fb8aa3b, v136
	s_nop 0
	v_max3_f32 v155, v137, v38, v54
	v_sub_u32_e32 v38, v96, v175
	v_cmp_gt_u32_e32 vcc, s58, v38
	s_or_b64 vcc, s[2:3], vcc
	v_add_u32_e32 v54, 32, v38
	v_cndmask_b32_e32 v88, v204, v88, vcc
	v_cmp_gt_u32_e32 vcc, s58, v54
	v_exp_f32_e32 v37, v37
	v_exp_f32_e32 v36, v36
	v_exp_f32_e32 v52, v52
	v_exp_f32_e32 v84, v84
	v_exp_f32_e32 v68, v68
	v_exp_f32_e32 v136, v70
	s_or_b64 vcc, s[2:3], vcc
	v_add_u32_e32 v70, 64, v38
	v_cndmask_b32_e32 v56, v204, v56, vcc
	v_cmp_gt_u32_e32 vcc, s58, v70
	s_or_b64 vcc, s[2:3], vcc
	v_add_u32_e32 v38, 0x60, v38
	v_cndmask_b32_e32 v72, v204, v72, vcc
	v_cmp_gt_u32_e32 vcc, s58, v38
	v_cvt_pk_bf16_f32 v148, v37, v53
	v_cvt_pk_bf16_f32 v149, v85, v69
	v_cvt_pk_bf16_f32 v150, v36, v52
	v_cvt_pk_bf16_f32 v151, v84, v68
	s_or_b64 vcc, s[2:3], vcc
	ds_write2_b64 v215, v[148:149], v[150:151] offset0:144 offset1:178
	v_max3_f32 v54, v88, s59, v56
	v_cndmask_b32_e32 v150, v204, v40, vcc
	v_max3_f32 v38, v54, v72, v150
	v_mov_b32_e32 v40, v38
	v_mov_b32_e32 v255, v38
	s_nop 1
	v_permlane16_swap_b32_e32 v40, v255
	s_nop 1
	v_mov_b32_dpp v40, v255 quad_perm:[0,1,2,3] row_mask:0x5 bank_mask:0xf
	v_sub_f32_e32 v151, v154, v155
	v_sub_f32_e32 v54, v137, v155
	v_mul_f32_e32 v137, 0x3fb8aa3b, v54
	v_sub_f32_e32 v54, v212, v155
	s_waitcnt lgkmcnt(0)
	v_max_f32_e32 v40, v40, v40
	v_max_f32_e32 v40, v38, v40
	s_nop 1
	v_mov_b32_dpp v70, v40 row_ror:8 row_mask:0xf bank_mask:0xf
	v_mul_f32_e32 v54, 0x3fb8aa3b, v54
	v_exp_f32_e32 v38, v54
	v_sub_f32_e32 v54, v213, v155
	v_sub_f32_e32 v86, v214, v155
	s_nop 0
	v_max_f32_e32 v70, v70, v70
	v_max_f32_e32 v40, v40, v70
	s_nop 1
	v_mov_b32_dpp v70, v40 row_shl:4 row_mask:0xf bank_mask:0x5
	v_mov_b32_dpp v70, v40 row_shr:4 row_mask:0xf bank_mask:0xa
	v_mul_f32_e32 v39, 0x3fb8aa3b, v39
	v_mul_f32_e32 v54, 0x3fb8aa3b, v54
	v_mul_f32_e32 v86, 0x3fb8aa3b, v86
	v_exp_f32_e32 v39, v39
	s_nop 0
	v_max_f32_e32 v70, v70, v70
	v_max_f32_e32 v152, v40, v70
	s_nop 1
	v_mov_b32_dpp v153, v152 quad_perm:[2,3,0,1] row_mask:0xf bank_mask:0xf
	v_mul_f32_e32 v40, 0x3fb8aa3b, v151
	v_exp_f32_e32 v54, v54
	v_exp_f32_e32 v86, v86
	v_exp_f32_e32 v70, v40
	s_nop 0
	v_max_f32_e32 v151, v153, v153
	v_sub_u32_e32 v153, v96, v176
	v_cmp_gt_u32_e32 vcc, s58, v153
	s_or_b64 vcc, s[2:3], vcc
	v_cvt_pk_bf16_f32 v148, v39, v55
	v_cndmask_b32_e32 v212, v204, v89, vcc
	v_add_u32_e32 v89, 32, v153
	v_cmp_gt_u32_e32 vcc, s58, v89
	s_or_b64 vcc, s[2:3], vcc
	v_add_u32_e32 v89, 64, v153
	v_cndmask_b32_e32 v213, v204, v57, vcc
	v_cmp_gt_u32_e32 vcc, s58, v89
	s_or_b64 vcc, s[2:3], vcc
	v_max3_f32 v57, v212, s59, v213
	v_cndmask_b32_e32 v214, v204, v73, vcc
	v_add_u32_e32 v73, 0x60, v153
	v_cmp_gt_u32_e32 vcc, s58, v73
	s_or_b64 vcc, s[2:3], vcc
	v_cvt_pk_bf16_f32 v149, v87, v71
	v_cndmask_b32_e32 v216, v204, v41, vcc
	v_max3_f32 v57, v57, v214, v216
	v_mov_b32_e32 v73, v57
	v_mov_b32_e32 v255, v57
	s_nop 1
	v_permlane16_swap_b32_e32 v73, v255
	s_nop 1
	v_mov_b32_dpp v73, v255 quad_perm:[0,1,2,3] row_mask:0x5 bank_mask:0xf
	v_cvt_pk_bf16_f32 v40, v38, v54
	v_cvt_pk_bf16_f32 v41, v86, v70
	ds_write2_b64 v215, v[148:149], v[40:41] offset0:212 offset1:246
	v_max_f32_e32 v151, v152, v151
	s_nop 0
	v_max_f32_e32 v41, v73, v73
	v_max_f32_e32 v57, v57, v41
	s_nop 1
	v_mov_b32_dpp v73, v57 row_ror:8 row_mask:0xf bank_mask:0xf
	v_mov_b32_dpp v152, v151 quad_perm:[1,0,3,2] row_mask:0xf bank_mask:0xf
	v_sub_f32_e32 v135, v135, v160
	v_mul_f32_e32 v131, 0x3fb8aa3b, v131
	v_mul_f32_e32 v135, 0x3fb8aa3b, v135
	s_waitcnt lgkmcnt(0)
	v_max_f32_e32 v73, v73, v73
	s_nop 0
	v_max3_f32 v154, v138, v151, v152
	v_max_f32_e32 v73, v57, v73
	v_sub_f32_e32 v41, v88, v154
	s_nop 1
	v_mov_b32_dpp v88, v73 row_shl:4 row_mask:0xf bank_mask:0x5
	v_mov_b32_dpp v88, v73 row_shr:4 row_mask:0xf bank_mask:0xa
	v_sub_f32_e32 v56, v56, v154
	v_mul_f32_e32 v56, 0x3fb8aa3b, v56
	v_exp_f32_e32 v57, v56
	v_sub_f32_e32 v56, v72, v154
	s_nop 0
	v_max_f32_e32 v72, v88, v88
	v_max_f32_e32 v72, v73, v72
	s_nop 1
	v_mov_b32_dpp v88, v72 quad_perm:[2,3,0,1] row_mask:0xf bank_mask:0xf
	v_mul_f32_e32 v56, 0x3fb8aa3b, v56
	v_exp_f32_e32 v89, v56
	v_sub_f32_e32 v56, v150, v154
	v_mul_f32_e32 v56, 0x3fb8aa3b, v56
	v_exp_f32_e32 v73, v56
	s_nop 0
	v_max_f32_e32 v56, v88, v88
	v_max_f32_e32 v56, v72, v56
	s_nop 1
	v_mov_b32_dpp v72, v56 quad_perm:[1,0,3,2] row_mask:0xf bank_mask:0xf
	v_sub_f32_e32 v40, v138, v154
	v_mul_f32_e32 v40, 0x3fb8aa3b, v40
	v_exp_f32_e32 v138, v40
	v_sub_u32_e32 v40, v96, v177
	v_cmp_gt_u32_e32 vcc, s58, v40
	s_nop 0
	v_max3_f32 v153, v139, v56, v72
	s_or_b64 vcc, s[2:3], vcc
	v_add_u32_e32 v56, 32, v40
	v_cndmask_b32_e32 v90, v204, v90, vcc
	v_cmp_gt_u32_e32 vcc, s58, v56
	s_or_b64 vcc, s[2:3], vcc
	v_add_u32_e32 v72, 64, v40
	v_cndmask_b32_e32 v58, v204, v58, vcc
	v_cmp_gt_u32_e32 vcc, s58, v72
	s_or_b64 vcc, s[2:3], vcc
	v_add_u32_e32 v40, 0x60, v40
	v_cndmask_b32_e32 v74, v204, v74, vcc
	v_cmp_gt_u32_e32 vcc, s58, v40
	s_or_b64 vcc, s[2:3], vcc
	v_max3_f32 v56, v90, s59, v58
	v_cndmask_b32_e32 v42, v204, v42, vcc
	v_max3_f32 v56, v56, v74, v42
	v_mov_b32_e32 v72, v56
	v_mov_b32_e32 v255, v56
	s_nop 1
	v_permlane16_swap_b32_e32 v72, v255
	s_nop 1
	v_mov_b32_dpp v72, v255 quad_perm:[0,1,2,3] row_mask:0x5 bank_mask:0xf
	v_sub_f32_e32 v88, v213, v153
	v_sub_u32_e32 v213, v96, v178
	v_cmp_gt_u32_e32 vcc, s58, v213
	s_or_b64 vcc, s[2:3], vcc
	s_nop 0
	v_max_f32_e32 v72, v72, v72
	v_max_f32_e32 v72, v56, v72
	s_nop 1
	v_mov_b32_dpp v150, v72 row_ror:8 row_mask:0xf bank_mask:0xf
	v_mul_f32_e32 v56, 0x3fb8aa3b, v88
	v_sub_f32_e32 v88, v214, v153
	v_cndmask_b32_e32 v214, v204, v91, vcc
	v_add_u32_e32 v91, 32, v213
	v_cmp_gt_u32_e32 vcc, s58, v91
	s_nop 0
	v_max_f32_e32 v150, v150, v150
	s_or_b64 vcc, s[2:3], vcc
	v_add_u32_e32 v91, 64, v213
	v_max_f32_e32 v150, v72, v150
	v_cndmask_b32_e32 v215, v204, v59, vcc
	v_cmp_gt_u32_e32 vcc, s58, v91
	v_mov_b32_dpp v151, v150 row_shl:4 row_mask:0xf bank_mask:0x5
	v_mov_b32_dpp v151, v150 row_shr:4 row_mask:0xf bank_mask:0xa
	s_or_b64 vcc, s[2:3], vcc
	v_sub_f32_e32 v72, v216, v153
	v_cndmask_b32_e32 v216, v204, v75, vcc
	v_add_u32_e32 v75, 0x60, v213
	v_cmp_gt_u32_e32 vcc, s58, v75
	s_or_b64 vcc, s[2:3], vcc
	v_max3_f32 v59, v214, s59, v215
	v_cndmask_b32_e32 v213, v204, v43, vcc
	s_nop 0
	v_max_f32_e32 v151, v151, v151
	v_max3_f32 v43, v59, v216, v213
	v_sub_f32_e32 v40, v212, v153
	v_max_f32_e32 v152, v150, v151
	v_mov_b32_e32 v59, v43
	v_mov_b32_e32 v255, v43
	s_nop 1
	v_permlane16_swap_b32_e32 v59, v255
	s_nop 1
	v_mov_b32_dpp v59, v255 quad_perm:[0,1,2,3] row_mask:0x5 bank_mask:0xf
	v_mul_f32_e32 v41, 0x3fb8aa3b, v41
	v_mul_f32_e32 v40, 0x3fb8aa3b, v40
	v_mul_f32_e32 v88, 0x3fb8aa3b, v88
	v_mul_f32_e32 v72, 0x3fb8aa3b, v72
	v_mov_b32_dpp v212, v152 quad_perm:[2,3,0,1] row_mask:0xf bank_mask:0xf
	v_exp_f32_e32 v41, v41
	v_exp_f32_e32 v40, v40
	v_exp_f32_e32 v56, v56
	v_exp_f32_e32 v88, v88
	v_exp_f32_e32 v72, v72
	s_nop 0
	v_max_f32_e32 v59, v59, v59
	v_cvt_pk_bf16_f32 v148, v41, v57
	v_cvt_pk_bf16_f32 v149, v89, v73
	v_cvt_pk_bf16_f32 v150, v40, v56
	v_cvt_pk_bf16_f32 v151, v88, v72
	s_nop 0
	v_max_f32_e32 v212, v212, v212
	v_add_u32_e32 v75, 0x9800, v186
	v_max_f32_e32 v59, v43, v59
	v_max_f32_e32 v152, v152, v212
	ds_write2_b64 v75, v[148:149], v[150:151] offset0:160 offset1:194
	v_mov_b32_dpp v75, v59 row_ror:8 row_mask:0xf bank_mask:0xf
	v_mov_b32_dpp v212, v152 quad_perm:[1,0,3,2] row_mask:0xf bank_mask:0xf
	v_sub_f32_e32 v139, v139, v153
	v_mul_f32_e32 v139, 0x3fb8aa3b, v139
	v_exp_f32_e32 v131, v131
	s_waitcnt lgkmcnt(0)
	v_max_f32_e32 v75, v75, v75
	s_nop 0
	v_max3_f32 v152, v140, v152, v212
	v_max_f32_e32 v75, v59, v75
	v_sub_f32_e32 v43, v90, v152
	s_nop 1
	v_mov_b32_dpp v90, v75 row_shl:4 row_mask:0xf bank_mask:0x5
	v_mov_b32_dpp v90, v75 row_shr:4 row_mask:0xf bank_mask:0xa
	v_sub_f32_e32 v58, v58, v152
	v_mul_f32_e32 v58, 0x3fb8aa3b, v58
	v_exp_f32_e32 v59, v58
	v_sub_f32_e32 v58, v74, v152
	s_nop 0
	v_max_f32_e32 v74, v90, v90
	v_max_f32_e32 v74, v75, v74
	s_nop 1
	v_mov_b32_dpp v90, v74 quad_perm:[2,3,0,1] row_mask:0xf bank_mask:0xf
	v_sub_f32_e32 v42, v42, v152
	v_mul_f32_e32 v42, 0x3fb8aa3b, v42
	v_exp_f32_e32 v75, v42
	v_mul_f32_e32 v58, 0x3fb8aa3b, v58
	s_nop 0
	v_max_f32_e32 v42, v90, v90
	v_max_f32_e32 v42, v74, v42
	v_exp_f32_e32 v91, v58
	s_nop 1
	v_mov_b32_dpp v58, v42 quad_perm:[1,0,3,2] row_mask:0xf bank_mask:0xf
	v_sub_f32_e32 v140, v140, v152
	v_mul_f32_e32 v74, 0x3fb8aa3b, v140
	v_exp_f32_e32 v140, v74
	v_mul_f32_e32 v43, 0x3fb8aa3b, v43
	s_nop 0
	v_max3_f32 v151, v141, v42, v58
	v_sub_u32_e32 v42, v96, v179
	v_cmp_gt_u32_e32 vcc, s58, v42
	s_or_b64 vcc, s[2:3], vcc
	v_add_u32_e32 v58, 32, v42
	v_cndmask_b32_e32 v92, v204, v92, vcc
	v_cmp_gt_u32_e32 vcc, s58, v58
	s_or_b64 vcc, s[2:3], vcc
	v_add_u32_e32 v74, 64, v42
	v_cndmask_b32_e32 v60, v204, v60, vcc
	v_cmp_gt_u32_e32 vcc, s58, v74
	s_or_b64 vcc, s[2:3], vcc
	v_add_u32_e32 v42, 0x60, v42
	v_cndmask_b32_e32 v76, v204, v76, vcc
	v_cmp_gt_u32_e32 vcc, s58, v42
	s_or_b64 vcc, s[2:3], vcc
	v_max3_f32 v58, v92, s59, v60
	v_cndmask_b32_e32 v44, v204, v44, vcc
	v_max3_f32 v58, v58, v76, v44
	v_mov_b32_e32 v74, v58
	v_mov_b32_e32 v255, v58
	s_nop 1
	v_permlane16_swap_b32_e32 v74, v255
	s_nop 1
	v_mov_b32_dpp v74, v255 quad_perm:[0,1,2,3] row_mask:0x5 bank_mask:0xf
	v_sub_f32_e32 v90, v215, v151
	v_sub_u32_e32 v215, v96, v180
	v_cmp_gt_u32_e32 vcc, s58, v215
	s_or_b64 vcc, s[2:3], vcc
	s_nop 0
	v_max_f32_e32 v74, v74, v74
	v_max_f32_e32 v74, v58, v74
	s_nop 1
	v_mov_b32_dpp v150, v74 row_ror:8 row_mask:0xf bank_mask:0xf
	v_mul_f32_e32 v58, 0x3fb8aa3b, v90
	v_sub_f32_e32 v90, v216, v151
	v_cndmask_b32_e32 v216, v204, v93, vcc
	v_add_u32_e32 v93, 32, v215
	v_cmp_gt_u32_e32 vcc, s58, v93
	s_nop 0
	v_max_f32_e32 v150, v150, v150
	s_or_b64 vcc, s[2:3], vcc
	v_add_u32_e32 v93, 64, v215
	v_max_f32_e32 v150, v74, v150
	v_cndmask_b32_e32 v217, v204, v61, vcc
	v_cmp_gt_u32_e32 vcc, s58, v93
	v_mov_b32_dpp v212, v150 row_shl:4 row_mask:0xf bank_mask:0x5
	v_mov_b32_dpp v212, v150 row_shr:4 row_mask:0xf bank_mask:0xa
	s_or_b64 vcc, s[2:3], vcc
	v_cndmask_b32_e32 v218, v204, v77, vcc
	v_add_u32_e32 v77, 0x60, v215
	v_cmp_gt_u32_e32 vcc, s58, v77
	s_or_b64 vcc, s[2:3], vcc
	v_max3_f32 v61, v216, s59, v217
	v_cndmask_b32_e32 v215, v204, v45, vcc
	s_nop 0
	v_max_f32_e32 v212, v212, v212
	v_max3_f32 v45, v61, v218, v215
	v_sub_f32_e32 v42, v214, v151
	v_sub_f32_e32 v74, v213, v151
	v_max_f32_e32 v150, v150, v212
	v_mov_b32_e32 v61, v45
	v_mov_b32_e32 v255, v45
	s_nop 1
	v_permlane16_swap_b32_e32 v61, v255
	s_nop 1
	v_mov_b32_dpp v61, v255 quad_perm:[0,1,2,3] row_mask:0x5 bank_mask:0xf
	v_mul_f32_e32 v42, 0x3fb8aa3b, v42
	v_mul_f32_e32 v90, 0x3fb8aa3b, v90
	v_mul_f32_e32 v74, 0x3fb8aa3b, v74
	v_mov_b32_dpp v214, v150 quad_perm:[2,3,0,1] row_mask:0xf bank_mask:0xf
	v_exp_f32_e32 v43, v43
	v_exp_f32_e32 v42, v42
	v_exp_f32_e32 v58, v58
	v_exp_f32_e32 v90, v90
	v_exp_f32_e32 v74, v74
	s_nop 0
	v_max_f32_e32 v61, v61, v61
	v_cvt_pk_bf16_f32 v148, v43, v59
	v_cvt_pk_bf16_f32 v149, v91, v75
	v_cvt_pk_bf16_f32 v212, v42, v58
	v_cvt_pk_bf16_f32 v213, v90, v74
	s_nop 0
	v_max_f32_e32 v214, v214, v214
	v_add_u32_e32 v77, 0x9c00, v186
	v_max_f32_e32 v61, v45, v61
	v_max_f32_e32 v150, v150, v214
	ds_write2_b64 v77, v[148:149], v[212:213] offset0:100 offset1:134
	v_mov_b32_dpp v77, v61 row_ror:8 row_mask:0xf bank_mask:0xf
	v_mov_b32_dpp v214, v150 quad_perm:[1,0,3,2] row_mask:0xf bank_mask:0xf
	v_sub_f32_e32 v141, v141, v151
	v_mul_f32_e32 v141, 0x3fb8aa3b, v141
	v_exp_f32_e32 v133, v133
	s_waitcnt lgkmcnt(0)
	v_max_f32_e32 v77, v77, v77
	s_nop 0
	v_max3_f32 v150, v142, v150, v214
	v_max_f32_e32 v77, v61, v77
	v_sub_f32_e32 v45, v92, v150
	s_nop 1
	v_mov_b32_dpp v92, v77 row_shl:4 row_mask:0xf bank_mask:0x5
	v_mov_b32_dpp v92, v77 row_shr:4 row_mask:0xf bank_mask:0xa
	v_sub_f32_e32 v60, v60, v150
	v_mul_f32_e32 v60, 0x3fb8aa3b, v60
	v_exp_f32_e32 v61, v60
	v_sub_f32_e32 v60, v76, v150
	s_nop 0
	v_max_f32_e32 v76, v92, v92
	v_max_f32_e32 v76, v77, v76
	s_nop 1
	v_mov_b32_dpp v92, v76 quad_perm:[2,3,0,1] row_mask:0xf bank_mask:0xf
	v_sub_f32_e32 v44, v44, v150
	v_mul_f32_e32 v44, 0x3fb8aa3b, v44
	v_exp_f32_e32 v77, v44
	v_mul_f32_e32 v60, 0x3fb8aa3b, v60
	s_nop 0
	v_max_f32_e32 v44, v92, v92
	v_max_f32_e32 v44, v76, v44
	v_exp_f32_e32 v93, v60
	s_nop 1
	v_mov_b32_dpp v60, v44 quad_perm:[1,0,3,2] row_mask:0xf bank_mask:0xf
	v_sub_f32_e32 v142, v142, v150
	v_mul_f32_e32 v76, 0x3fb8aa3b, v142
	v_exp_f32_e32 v142, v76
	v_mul_f32_e32 v45, 0x3fb8aa3b, v45
	s_nop 0
	v_max3_f32 v149, v143, v44, v60
	v_sub_u32_e32 v44, v96, v181
	v_cmp_gt_u32_e32 vcc, s58, v44
	s_or_b64 vcc, s[2:3], vcc
	v_add_u32_e32 v60, 32, v44
	v_cndmask_b32_e32 v94, v204, v94, vcc
	v_cmp_gt_u32_e32 vcc, s58, v60
	s_or_b64 vcc, s[2:3], vcc
	v_add_u32_e32 v76, 64, v44
	v_cndmask_b32_e32 v62, v204, v62, vcc
	v_cmp_gt_u32_e32 vcc, s58, v76
	s_or_b64 vcc, s[2:3], vcc
	v_add_u32_e32 v44, 0x60, v44
	v_cndmask_b32_e32 v78, v204, v78, vcc
	v_cmp_gt_u32_e32 vcc, s58, v44
	s_or_b64 vcc, s[2:3], vcc
	v_max3_f32 v60, v94, s59, v62
	v_cndmask_b32_e32 v46, v204, v46, vcc
	v_max3_f32 v60, v60, v78, v46
	v_mov_b32_e32 v76, v60
	v_mov_b32_e32 v255, v60
	s_nop 1
	v_permlane16_swap_b32_e32 v76, v255
	s_nop 1
	v_mov_b32_dpp v76, v255 quad_perm:[0,1,2,3] row_mask:0x5 bank_mask:0xf
	v_sub_u32_e32 v96, v96, v182
	v_cmp_gt_u32_e32 vcc, s58, v96
	s_or_b64 vcc, s[2:3], vcc
	v_sub_f32_e32 v92, v217, v149
	s_nop 0
	v_max_f32_e32 v76, v76, v76
	v_max_f32_e32 v76, v60, v76
	s_nop 1
	v_mov_b32_dpp v148, v76 row_ror:8 row_mask:0xf bank_mask:0xf
	v_cndmask_b32_e32 v217, v204, v95, vcc
	v_add_u32_e32 v95, 32, v96
	v_cmp_gt_u32_e32 vcc, s58, v95
	s_or_b64 vcc, s[2:3], vcc
	s_nop 0
	v_max_f32_e32 v148, v148, v148
	v_add_u32_e32 v95, 64, v96
	v_mul_f32_e32 v60, 0x3fb8aa3b, v92
	v_sub_f32_e32 v92, v218, v149
	v_max_f32_e32 v148, v76, v148
	v_cndmask_b32_e32 v218, v204, v63, vcc
	v_cmp_gt_u32_e32 vcc, s58, v95
	v_mov_b32_dpp v214, v148 row_shl:4 row_mask:0xf bank_mask:0x5
	v_mov_b32_dpp v214, v148 row_shr:4 row_mask:0xf bank_mask:0xa
	s_or_b64 vcc, s[2:3], vcc
	v_cndmask_b32_e32 v219, v204, v79, vcc
	v_add_u32_e32 v79, 0x60, v96
	v_cmp_gt_u32_e32 vcc, s58, v79
	s_or_b64 vcc, s[2:3], vcc
	v_max3_f32 v63, v217, s59, v218
	v_cndmask_b32_e32 v96, v204, v47, vcc
	s_nop 0
	v_max_f32_e32 v214, v214, v214
	v_max3_f32 v47, v63, v219, v96
	v_sub_f32_e32 v44, v216, v149
	v_sub_f32_e32 v76, v215, v149
	v_max_f32_e32 v148, v148, v214
	v_mov_b32_e32 v63, v47
	v_mov_b32_e32 v255, v47
	s_nop 1
	v_permlane16_swap_b32_e32 v63, v255
	s_nop 1
	v_mov_b32_dpp v63, v255 quad_perm:[0,1,2,3] row_mask:0x5 bank_mask:0xf
	v_mul_f32_e32 v44, 0x3fb8aa3b, v44
	v_mul_f32_e32 v92, 0x3fb8aa3b, v92
	v_mul_f32_e32 v76, 0x3fb8aa3b, v76
	v_mov_b32_dpp v216, v148 quad_perm:[2,3,0,1] row_mask:0xf bank_mask:0xf
	v_exp_f32_e32 v45, v45
	v_exp_f32_e32 v44, v44
	v_exp_f32_e32 v60, v60
	v_exp_f32_e32 v92, v92
	v_exp_f32_e32 v76, v76
	s_nop 0
	v_max_f32_e32 v63, v63, v63
	v_cvt_pk_bf16_f32 v212, v45, v61
	v_cvt_pk_bf16_f32 v213, v93, v77
	v_cvt_pk_bf16_f32 v214, v44, v60
	v_cvt_pk_bf16_f32 v215, v92, v76
	s_nop 0
	v_max_f32_e32 v216, v216, v216
	v_add_u32_e32 v79, 0xa000, v186
	v_max_f32_e32 v63, v47, v63
	v_max_f32_e32 v148, v148, v216
	ds_write2_b64 v79, v[212:213], v[214:215] offset0:176 offset1:210
	v_mov_b32_dpp v79, v63 row_ror:8 row_mask:0xf bank_mask:0xf
	v_mov_b32_dpp v216, v148 quad_perm:[1,0,3,2] row_mask:0xf bank_mask:0xf
	v_sub_f32_e32 v143, v143, v149
	v_mul_f32_e32 v143, 0x3fb8aa3b, v143
	v_exp_f32_e32 v135, v135
	s_waitcnt lgkmcnt(0)
	v_max_f32_e32 v79, v79, v79
	s_nop 0
	v_max3_f32 v148, v144, v148, v216
	v_max_f32_e32 v79, v63, v79
	v_sub_f32_e32 v47, v94, v148
	s_nop 1
	v_mov_b32_dpp v94, v79 row_shl:4 row_mask:0xf bank_mask:0x5
	v_mov_b32_dpp v94, v79 row_shr:4 row_mask:0xf bank_mask:0xa
	v_sub_f32_e32 v62, v62, v148
	v_mul_f32_e32 v62, 0x3fb8aa3b, v62
	v_exp_f32_e32 v63, v62
	v_sub_f32_e32 v62, v78, v148
	s_nop 0
	v_max_f32_e32 v78, v94, v94
	v_max_f32_e32 v78, v79, v78
	s_nop 1
	v_mov_b32_dpp v94, v78 quad_perm:[2,3,0,1] row_mask:0xf bank_mask:0xf
	v_sub_f32_e32 v46, v46, v148
	v_mul_f32_e32 v46, 0x3fb8aa3b, v46
	v_exp_f32_e32 v79, v46
	v_mul_f32_e32 v62, 0x3fb8aa3b, v62
	s_nop 0
	v_max_f32_e32 v46, v94, v94
	v_max_f32_e32 v46, v78, v46
	v_exp_f32_e32 v95, v62
	s_nop 1
	v_mov_b32_dpp v62, v46 quad_perm:[1,0,3,2] row_mask:0xf bank_mask:0xf
	v_sub_f32_e32 v144, v144, v148
	v_mul_f32_e32 v78, 0x3fb8aa3b, v144
	v_exp_f32_e32 v144, v78
	v_mul_f32_e32 v47, 0x3fb8aa3b, v47
	s_nop 0
	v_max3_f32 v147, v145, v46, v62
	v_sub_f32_e32 v78, v219, v147
	v_mul_f32_e32 v78, 0x3fb8aa3b, v78
	v_sub_f32_e32 v46, v217, v147
	v_sub_f32_e32 v62, v218, v147
	v_exp_f32_e32 v94, v78
	v_sub_f32_e32 v78, v96, v147
	v_sub_f32_e32 v145, v145, v147
	v_mul_f32_e32 v46, 0x3fb8aa3b, v46
	v_mul_f32_e32 v62, 0x3fb8aa3b, v62
	v_mul_f32_e32 v78, 0x3fb8aa3b, v78
	v_exp_f32_e32 v47, v47
	v_exp_f32_e32 v46, v46
	v_exp_f32_e32 v62, v62
	v_exp_f32_e32 v78, v78
	v_mul_f32_e32 v96, 0x3fb8aa3b, v145
	v_exp_f32_e32 v137, v137
	v_exp_f32_e32 v139, v139
	v_exp_f32_e32 v141, v141
	v_exp_f32_e32 v143, v143
	v_exp_f32_e32 v145, v96
	v_cvt_pk_bf16_f32 v208, v47, v63
	v_cvt_pk_bf16_f32 v209, v95, v79
	v_cvt_pk_bf16_f32 v210, v46, v62
	v_cvt_pk_bf16_f32 v211, v94, v78
	v_add_u32_e32 v96, 0xa400, v186
	ds_write2_b64 v96, v[208:209], v[210:211] offset0:116 offset1:150
	v_pk_mul_f32 v[14:15], v[14:15], v[144:145]
	v_pk_mul_f32 v[12:13], v[12:13], v[142:143]
	v_pk_mul_f32 v[10:11], v[10:11], v[140:141]
	v_pk_mul_f32 v[8:9], v[8:9], v[138:139]
	v_pk_mul_f32 v[6:7], v[6:7], v[136:137]
	v_pk_mul_f32 v[4:5], v[4:5], v[134:135]
	v_pk_mul_f32 v[2:3], v[2:3], v[132:133]
	v_pk_mul_f32 v[0:1], v[0:1], v[130:131]
	v_pk_mul_f32 v[30:31], v[30:31], v[144:145]
	v_pk_mul_f32 v[28:29], v[28:29], v[142:143]
	v_pk_mul_f32 v[26:27], v[26:27], v[140:141]
	v_pk_mul_f32 v[24:25], v[24:25], v[138:139]
	v_pk_mul_f32 v[22:23], v[22:23], v[136:137]
	v_pk_mul_f32 v[20:21], v[20:21], v[134:135]
	v_pk_mul_f32 v[18:19], v[18:19], v[132:133]
	v_pk_mul_f32 v[16:17], v[16:17], v[130:131]
	s_mov_b32 s2, -16
	v_mov_b32_e32 v96, v185
	v_mov_b32_e32 v208, v184
.Latt_join:
	s_waitcnt lgkmcnt(0)
	s_barrier
.LBB0_718:
	ds_read_b128 v[210:213], v96
	ds_read_b128 v[214:217], v208
	s_add_i32 s2, s2, 32
	s_cmpk_lt_u32 s2, 0x70
	s_waitcnt lgkmcnt(0)
	v_mfma_f32_32x32x16_bf16 v[0:15], v[210:213], v[214:217], v[0:15]
	ds_read_b128 v[214:217], v208 offset:8704
	s_waitcnt lgkmcnt(0)
	v_mfma_f32_32x32x16_bf16 v[16:31], v[210:213], v[214:217], v[16:31]
	ds_read_b128 v[210:213], v96 offset:32
	ds_read_b128 v[214:217], v208 offset:32
	v_add_u32_e32 v96, 64, v96
	s_waitcnt lgkmcnt(0)
	v_mfma_f32_32x32x16_bf16 v[0:15], v[210:213], v[214:217], v[0:15]
	ds_read_b128 v[214:217], v208 offset:8736
	v_add_u32_e32 v208, 64, v208
	s_waitcnt lgkmcnt(0)
	v_mfma_f32_32x32x16_bf16 v[16:31], v[210:213], v[214:217], v[16:31]
	s_cbranch_scc1 .LBB0_718
	v_pk_add_f32 v[32:33], v[32:33], 0 op_sel_hi:[1,0]
	v_mov_b32_e32 v208, v131
	v_pk_add_f32 v[32:33], v[48:49], v[32:33]
	v_mov_b32_e32 v209, v130
	v_pk_add_f32 v[32:33], v[80:81], v[32:33]
	v_mov_b32_e32 v130, v133
	v_pk_add_f32 v[32:33], v[64:65], v[32:33]
	v_mov_b32_e32 v131, v132
	v_pk_fma_f32 v[128:129], v[128:129], v[208:209], v[32:33]
	v_pk_add_f32 v[32:33], v[34:35], 0 op_sel_hi:[1,0]
	v_mov_b32_e32 v132, v135
	v_pk_add_f32 v[32:33], v[50:51], v[32:33]
	v_mov_b32_e32 v133, v134
	v_pk_add_f32 v[32:33], v[82:83], v[32:33]
	v_mov_b32_e32 v134, v137
	v_pk_add_f32 v[32:33], v[66:67], v[32:33]
	v_mov_b32_e32 v135, v136
	v_pk_fma_f32 v[126:127], v[126:127], v[130:131], v[32:33]
	v_pk_add_f32 v[32:33], v[36:37], 0 op_sel_hi:[1,0]
	v_mov_b32_e32 v136, v139
	v_pk_add_f32 v[32:33], v[52:53], v[32:33]
	v_mov_b32_e32 v137, v138
	v_pk_add_f32 v[32:33], v[84:85], v[32:33]
	v_mov_b32_e32 v138, v141
	v_pk_add_f32 v[32:33], v[68:69], v[32:33]
	v_mov_b32_e32 v139, v140
	v_pk_fma_f32 v[124:125], v[124:125], v[132:133], v[32:33]
	v_pk_add_f32 v[32:33], v[38:39], 0 op_sel_hi:[1,0]
	v_mov_b32_e32 v140, v143
	v_pk_add_f32 v[32:33], v[54:55], v[32:33]
	v_mov_b32_e32 v141, v142
	v_pk_add_f32 v[32:33], v[86:87], v[32:33]
	v_mov_b32_e32 v142, v145
	v_pk_add_f32 v[32:33], v[70:71], v[32:33]
	v_mov_b32_e32 v143, v144
	v_pk_fma_f32 v[122:123], v[122:123], v[134:135], v[32:33]
	v_pk_add_f32 v[32:33], v[40:41], 0 op_sel_hi:[1,0]
	s_nop 0
	v_pk_add_f32 v[32:33], v[56:57], v[32:33]
	s_nop 0
	v_pk_add_f32 v[32:33], v[88:89], v[32:33]
	s_nop 0
	v_pk_add_f32 v[32:33], v[72:73], v[32:33]
	s_nop 0
	v_pk_fma_f32 v[120:121], v[120:121], v[136:137], v[32:33]
	v_pk_add_f32 v[32:33], v[42:43], 0 op_sel_hi:[1,0]
	s_nop 0
	v_pk_add_f32 v[32:33], v[58:59], v[32:33]
	s_nop 0
	v_pk_add_f32 v[32:33], v[90:91], v[32:33]
	s_nop 0
	v_pk_add_f32 v[32:33], v[74:75], v[32:33]
	s_nop 0
	v_pk_fma_f32 v[118:119], v[118:119], v[138:139], v[32:33]
	v_pk_add_f32 v[32:33], v[44:45], 0 op_sel_hi:[1,0]
	s_nop 0
	v_pk_add_f32 v[32:33], v[60:61], v[32:33]
	s_nop 0
	v_pk_add_f32 v[32:33], v[92:93], v[32:33]
	s_nop 0
	v_pk_add_f32 v[32:33], v[76:77], v[32:33]
	s_nop 0
	v_pk_fma_f32 v[116:117], v[116:117], v[140:141], v[32:33]
	v_pk_add_f32 v[32:33], v[46:47], 0 op_sel_hi:[1,0]
	s_nop 0
	v_pk_add_f32 v[32:33], v[62:63], v[32:33]
	s_nop 0
	v_pk_add_f32 v[32:33], v[94:95], v[32:33]
	s_nop 0
	v_pk_add_f32 v[32:33], v[78:79], v[32:33]
	s_nop 0
	v_pk_fma_f32 v[114:115], v[114:115], v[142:143], v[32:33]
	s_add_i32 s53, s53, 1
	s_cmp_lg_u32 s53, 5
	s_cbranch_scc1 .LBB0_721
	s_branch .LBB0_722

.Latt_nm:
	s_nop 7
	s_nop 7
	s_nop 7
	s_add_i32 s6, s53, s49
	v_mbcnt_hi_u32_b32 v148, -1, v195
	v_lshl_add_u32 v96, s6, 7, v183
	v_and_b32_e32 v147, 64, v148
	v_add_u32_e32 v149, 64, v147
	v_xor_b32_e32 v147, 16, v148
	v_cmp_lt_i32_e32 vcc, v147, v149
	v_max3_f32 v150, v80, s59, v48
	v_max3_f32 v150, v150, v64, v32
	v_mov_b32_e32 v151, v150
	v_mov_b32_e32 v255, v150
	s_nop 1
	v_permlane16_swap_b32_e32 v151, v255
	s_nop 1
	v_mov_b32_dpp v151, v255 quad_perm:[0,1,2,3] row_mask:0x5 bank_mask:0xf
	v_add_u32_e32 v187, 0x8800, v186
	v_add_u32_e32 v215, 0x9000, v186
	s_nop 0
	s_nop 0
	v_max_f32_e32 v150, v150, v151
	v_xor_b32_e32 v151, 8, v148
	v_cmp_lt_i32_e32 vcc, v151, v149
	s_nop 1
	v_cndmask_b32_e32 v151, v148, v151, vcc
	s_nop 1
	v_mov_b32_dpp v151, v150 row_ror:8 row_mask:0xf bank_mask:0xf
	s_nop 0
	s_nop 0
	v_max_f32_e32 v150, v150, v151
	v_xor_b32_e32 v151, 4, v148
	v_cmp_lt_i32_e32 vcc, v151, v149
	s_nop 1
	v_cndmask_b32_e32 v151, v148, v151, vcc
	s_nop 1
	v_mov_b32_dpp v151, v150 row_shl:4 row_mask:0xf bank_mask:0x5
	s_nop 1
	v_mov_b32_dpp v151, v150 row_shr:4 row_mask:0xf bank_mask:0xa
	s_nop 0
	s_nop 0
	v_max_f32_e32 v150, v150, v151
	v_xor_b32_e32 v151, 2, v148
	v_cmp_lt_i32_e32 vcc, v151, v149
	s_nop 1
	v_cndmask_b32_e32 v151, v148, v151, vcc
	s_nop 1
	v_mov_b32_dpp v151, v150 quad_perm:[2,3,0,1] row_mask:0xf bank_mask:0xf
	s_nop 0
	s_nop 0
	v_max_f32_e32 v150, v150, v151
	v_xor_b32_e32 v151, 1, v148
	v_cmp_lt_i32_e32 vcc, v151, v149
	v_sub_u32_e32 v149, v96, v161
	s_nop 0
	v_cndmask_b32_e32 v148, v148, v151, vcc
	v_mov_b32_e32 v151, v81
	v_mov_b32_e32 v152, v49
	v_max3_f32 v49, v151, s59, v152
	v_mov_b32_e32 v153, v65
	v_add_u32_e32 v65, 0x60, v149
	v_mov_b32_dpp v148, v150 quad_perm:[1,0,3,2] row_mask:0xf bank_mask:0xf
	v_mov_b32_e32 v154, v33
	v_max3_f32 v33, v49, v153, v154
	v_mov_b32_e32 v49, v33
	v_mov_b32_e32 v255, v33
	s_nop 1
	v_permlane16_swap_b32_e32 v49, v255
	s_nop 1
	v_mov_b32_dpp v49, v255 quad_perm:[0,1,2,3] row_mask:0x5 bank_mask:0xf
	s_nop 0
	v_max3_f32 v207, v130, v150, v148
	v_sub_f32_e32 v48, v48, v207
	v_mul_f32_e32 v48, 0x3fb8aa3b, v48
	s_nop 0
	v_max_f32_e32 v49, v49, v49
	v_max_f32_e32 v49, v33, v49
	s_nop 1
	v_mov_b32_dpp v65, v49 row_ror:8 row_mask:0xf bank_mask:0xf
	v_sub_f32_e32 v33, v80, v207
	v_sub_f32_e32 v32, v32, v207
	v_mul_f32_e32 v32, 0x3fb8aa3b, v32
	v_sub_f32_e32 v130, v130, v207
	s_nop 0
	v_max_f32_e32 v65, v65, v65
	v_max_f32_e32 v65, v49, v65
	s_nop 1
	v_mov_b32_dpp v80, v65 row_shl:4 row_mask:0xf bank_mask:0x5
	s_nop 1
	v_mov_b32_dpp v80, v65 row_shr:4 row_mask:0xf bank_mask:0xa
	v_exp_f32_e32 v49, v48
	v_sub_f32_e32 v48, v64, v207
	v_mul_f32_e32 v48, 0x3fb8aa3b, v48
	v_exp_f32_e32 v81, v48
	s_nop 0
	v_max_f32_e32 v64, v80, v80
	v_max_f32_e32 v64, v65, v64
	s_nop 1
	v_mov_b32_dpp v80, v64 quad_perm:[2,3,0,1] row_mask:0xf bank_mask:0xf
	v_exp_f32_e32 v65, v32
	v_mul_f32_e32 v33, 0x3fb8aa3b, v33
	v_exp_f32_e32 v33, v33
	s_nop 0
	v_max_f32_e32 v32, v80, v80
	v_max_f32_e32 v32, v64, v32
	s_nop 1
	v_mov_b32_dpp v48, v32 quad_perm:[1,0,3,2] row_mask:0xf bank_mask:0xf
	v_mul_f32_e32 v64, 0x3fb8aa3b, v130
	v_exp_f32_e32 v130, v64
	v_cvt_pk_bf16_f32 v148, v33, v49
	v_cvt_pk_bf16_f32 v149, v81, v65
	s_nop 0
	v_max3_f32 v206, v131, v32, v48
	v_max3_f32 v48, v82, s59, v50
	v_max3_f32 v48, v48, v66, v34
	v_mov_b32_e32 v64, v48
	v_mov_b32_e32 v255, v48
	s_nop 1
	v_permlane16_swap_b32_e32 v64, v255
	s_nop 1
	v_mov_b32_dpp v64, v255 quad_perm:[0,1,2,3] row_mask:0x5 bank_mask:0xf
	v_sub_f32_e32 v32, v151, v206
	v_sub_f32_e32 v80, v152, v206
	v_mul_f32_e32 v32, 0x3fb8aa3b, v32
	v_exp_f32_e32 v32, v32
	s_nop 0
	v_max_f32_e32 v64, v64, v64
	v_max_f32_e32 v64, v48, v64
	s_nop 1
	v_mov_b32_dpp v150, v64 row_ror:8 row_mask:0xf bank_mask:0xf
	v_mul_f32_e32 v48, 0x3fb8aa3b, v80
	v_sub_f32_e32 v80, v153, v206
	v_mul_f32_e32 v80, 0x3fb8aa3b, v80
	v_exp_f32_e32 v48, v48
	s_nop 0
	v_max_f32_e32 v150, v150, v150
	v_max_f32_e32 v150, v64, v150
	v_sub_f32_e32 v64, v154, v206
	v_sub_u32_e32 v154, v96, v170
	v_mov_b32_dpp v151, v150 row_shl:4 row_mask:0xf bank_mask:0x5
	s_nop 1
	v_mov_b32_dpp v151, v150 row_shr:4 row_mask:0xf bank_mask:0xa
	v_mov_b32_e32 v155, v83
	v_mov_b32_e32 v156, v51
	v_max3_f32 v51, v155, s59, v156
	v_mov_b32_e32 v160, v67
	v_add_u32_e32 v67, 0x60, v154
	s_nop 0
	v_max_f32_e32 v151, v151, v151
	v_mov_b32_e32 v154, v35
	v_max3_f32 v35, v51, v160, v154
	v_max_f32_e32 v152, v150, v151
	v_mov_b32_e32 v51, v35
	v_mov_b32_e32 v255, v35
	s_nop 1
	v_permlane16_swap_b32_e32 v51, v255
	s_nop 1
	v_mov_b32_dpp v51, v255 quad_perm:[0,1,2,3] row_mask:0x5 bank_mask:0xf
	s_nop 1
	v_mov_b32_dpp v153, v152 quad_perm:[2,3,0,1] row_mask:0xf bank_mask:0xf
	v_mul_f32_e32 v64, 0x3fb8aa3b, v64
	v_exp_f32_e32 v80, v80
	v_exp_f32_e32 v64, v64
	s_nop 0
	v_max_f32_e32 v51, v51, v51
	s_nop 0
	v_max_f32_e32 v153, v153, v153
	v_max_f32_e32 v51, v35, v51
	v_max_f32_e32 v152, v152, v153
	s_nop 1
	v_mov_b32_dpp v67, v51 row_ror:8 row_mask:0xf bank_mask:0xf
	s_nop 1
	v_mov_b32_dpp v153, v152 quad_perm:[1,0,3,2] row_mask:0xf bank_mask:0xf
	v_cvt_pk_bf16_f32 v150, v32, v48
	v_cvt_pk_bf16_f32 v151, v80, v64
	ds_write2_b64 v187, v[148:149], v[150:151] offset0:128 offset1:162
	s_nop 0
	v_max_f32_e32 v67, v67, v67
	s_nop 0
	v_max3_f32 v189, v132, v152, v153
	v_max_f32_e32 v67, v51, v67
	v_sub_f32_e32 v35, v82, v189
	s_nop 1
	v_mov_b32_dpp v82, v67 row_shl:4 row_mask:0xf bank_mask:0x5
	s_nop 1
	v_mov_b32_dpp v82, v67 row_shr:4 row_mask:0xf bank_mask:0xa
	v_sub_f32_e32 v50, v50, v189
	v_mul_f32_e32 v50, 0x3fb8aa3b, v50
	v_exp_f32_e32 v51, v50
	v_sub_f32_e32 v50, v66, v189
	s_waitcnt lgkmcnt(0)
	v_max_f32_e32 v66, v82, v82
	v_max_f32_e32 v66, v67, v66
	s_nop 1
	v_mov_b32_dpp v82, v66 quad_perm:[2,3,0,1] row_mask:0xf bank_mask:0xf
	v_sub_f32_e32 v34, v34, v189
	v_mul_f32_e32 v34, 0x3fb8aa3b, v34
	v_exp_f32_e32 v67, v34
	v_mul_f32_e32 v50, 0x3fb8aa3b, v50
	s_nop 0
	v_max_f32_e32 v34, v82, v82
	v_max_f32_e32 v34, v66, v34
	v_exp_f32_e32 v83, v50
	s_nop 1
	v_mov_b32_dpp v50, v34 quad_perm:[1,0,3,2] row_mask:0xf bank_mask:0xf
	v_sub_f32_e32 v132, v132, v189
	v_mul_f32_e32 v66, 0x3fb8aa3b, v132
	v_exp_f32_e32 v132, v66
	v_mul_f32_e32 v35, 0x3fb8aa3b, v35
	s_nop 0
	v_max3_f32 v188, v133, v34, v50
	v_sub_u32_e32 v34, v96, v171
	v_add_u32_e32 v66, 64, v34
	v_max3_f32 v50, v84, s59, v52
	v_mov_b32_e32 v150, v36
	v_max3_f32 v34, v50, v68, v150
	v_mov_b32_e32 v36, v34
	v_mov_b32_e32 v255, v34
	s_nop 1
	v_permlane16_swap_b32_e32 v36, v255
	s_nop 1
	v_mov_b32_dpp v36, v255 quad_perm:[0,1,2,3] row_mask:0x5 bank_mask:0xf
	v_sub_f32_e32 v151, v154, v188
	v_sub_f32_e32 v50, v133, v188
	v_mul_f32_e32 v133, 0x3fb8aa3b, v50
	v_sub_f32_e32 v50, v155, v188
	s_nop 0
	v_max_f32_e32 v36, v36, v36
	v_max_f32_e32 v36, v34, v36
	s_nop 1
	v_mov_b32_dpp v66, v36 row_ror:8 row_mask:0xf bank_mask:0xf
	v_mul_f32_e32 v50, 0x3fb8aa3b, v50
	v_exp_f32_e32 v34, v50
	v_sub_f32_e32 v50, v156, v188
	v_sub_f32_e32 v82, v160, v188
	s_nop 0
	v_max_f32_e32 v66, v66, v66
	v_max_f32_e32 v36, v36, v66
	s_nop 1
	v_mov_b32_dpp v66, v36 row_shl:4 row_mask:0xf bank_mask:0x5
	s_nop 1
	v_mov_b32_dpp v66, v36 row_shr:4 row_mask:0xf bank_mask:0xa
	v_mul_f32_e32 v50, 0x3fb8aa3b, v50
	v_mul_f32_e32 v82, 0x3fb8aa3b, v82
	v_exp_f32_e32 v35, v35
	v_exp_f32_e32 v50, v50
	s_nop 0
	v_max_f32_e32 v66, v66, v66
	v_max_f32_e32 v152, v36, v66
	s_nop 1
	v_mov_b32_dpp v153, v152 quad_perm:[2,3,0,1] row_mask:0xf bank_mask:0xf
	v_mul_f32_e32 v36, 0x3fb8aa3b, v151
	v_exp_f32_e32 v82, v82
	v_exp_f32_e32 v66, v36
	v_cvt_pk_bf16_f32 v148, v35, v51
	s_nop 0
	v_max_f32_e32 v151, v153, v153
	v_cvt_pk_bf16_f32 v149, v83, v67
	v_mov_b32_e32 v154, v85
	v_mov_b32_e32 v155, v53
	v_max3_f32 v53, v154, s59, v155
	v_mov_b32_e32 v156, v69
	v_cvt_pk_bf16_f32 v36, v34, v50
	v_mov_b32_e32 v153, v37
	v_max3_f32 v53, v53, v156, v153
	v_mov_b32_e32 v69, v53
	v_mov_b32_e32 v255, v53
	s_nop 1
	v_permlane16_swap_b32_e32 v69, v255
	s_nop 1
	v_mov_b32_dpp v69, v255 quad_perm:[0,1,2,3] row_mask:0x5 bank_mask:0xf
	v_cvt_pk_bf16_f32 v37, v82, v66
	ds_write2_b64 v187, v[148:149], v[36:37] offset0:196 offset1:230
	v_max_f32_e32 v151, v152, v151
	s_nop 1
	v_mov_b32_dpp v152, v151 quad_perm:[1,0,3,2] row_mask:0xf bank_mask:0xf
	s_nop 0
	v_max_f32_e32 v37, v69, v69
	v_max_f32_e32 v53, v53, v37
	s_nop 1
	v_mov_b32_dpp v69, v53 row_ror:8 row_mask:0xf bank_mask:0xf
	v_sub_f32_e32 v131, v131, v206
	s_waitcnt lgkmcnt(0)
	v_max3_f32 v187, v134, v151, v152
	v_sub_f32_e32 v37, v84, v187
	v_sub_f32_e32 v52, v52, v187
	s_nop 0
	v_max_f32_e32 v69, v69, v69
	v_max_f32_e32 v69, v53, v69
	s_nop 1
	v_mov_b32_dpp v84, v69 row_shl:4 row_mask:0xf bank_mask:0x5
	s_nop 1
	v_mov_b32_dpp v84, v69 row_shr:4 row_mask:0xf bank_mask:0xa
	v_mul_f32_e32 v52, 0x3fb8aa3b, v52
	v_exp_f32_e32 v53, v52
	v_sub_f32_e32 v52, v68, v187
	v_mul_f32_e32 v52, 0x3fb8aa3b, v52
	s_nop 0
	v_max_f32_e32 v68, v84, v84
	v_max_f32_e32 v68, v69, v68
	s_nop 1
	v_mov_b32_dpp v84, v68 quad_perm:[2,3,0,1] row_mask:0xf bank_mask:0xf
	v_exp_f32_e32 v85, v52
	v_sub_f32_e32 v52, v150, v187
	v_mul_f32_e32 v52, 0x3fb8aa3b, v52
	v_exp_f32_e32 v69, v52
	s_nop 0
	v_max_f32_e32 v52, v84, v84
	v_max_f32_e32 v52, v68, v52
	s_nop 1
	v_mov_b32_dpp v68, v52 quad_perm:[1,0,3,2] row_mask:0xf bank_mask:0xf
	v_sub_f32_e32 v36, v134, v187
	v_mul_f32_e32 v36, 0x3fb8aa3b, v36
	v_exp_f32_e32 v134, v36
	s_nop 0
	v_max3_f32 v160, v135, v52, v68
	v_max3_f32 v52, v86, s59, v54
	v_max3_f32 v52, v52, v70, v38
	v_mov_b32_e32 v68, v52
	v_mov_b32_e32 v255, v52
	s_nop 1
	v_permlane16_swap_b32_e32 v68, v255
	s_nop 1
	v_mov_b32_dpp v68, v255 quad_perm:[0,1,2,3] row_mask:0x5 bank_mask:0xf
	v_sub_f32_e32 v36, v154, v160
	v_sub_u32_e32 v154, v96, v174
	s_nop 0
	s_nop 0
	v_max_f32_e32 v68, v52, v68
	s_nop 1
	v_mov_b32_dpp v150, v68 row_ror:8 row_mask:0xf bank_mask:0xf
	v_mov_b32_e32 v212, v87
	s_nop 0
	s_nop 0
	v_max_f32_e32 v150, v68, v150
	v_mov_b32_e32 v213, v55
	s_nop 0
	v_mov_b32_dpp v151, v150 row_shl:4 row_mask:0xf bank_mask:0x5
	s_nop 1
	v_mov_b32_dpp v151, v150 row_shr:4 row_mask:0xf bank_mask:0xa
	v_mov_b32_e32 v214, v71
	v_add_u32_e32 v71, 0x60, v154
	v_max3_f32 v55, v212, s59, v213
	v_mov_b32_e32 v154, v39
	s_nop 0
	v_max_f32_e32 v151, v151, v151
	v_max3_f32 v39, v55, v214, v154
	v_max_f32_e32 v152, v150, v151
	v_mov_b32_e32 v55, v39
	v_mov_b32_e32 v255, v39
	s_nop 1
	v_permlane16_swap_b32_e32 v55, v255
	s_nop 1
	v_mov_b32_dpp v55, v255 quad_perm:[0,1,2,3] row_mask:0x5 bank_mask:0xf
	v_sub_f32_e32 v68, v153, v160
	v_mov_b32_dpp v153, v152 quad_perm:[2,3,0,1] row_mask:0xf bank_mask:0xf
	v_sub_f32_e32 v84, v155, v160
	v_mul_f32_e32 v52, 0x3fb8aa3b, v84
	s_nop 0
	v_max_f32_e32 v55, v55, v55
	v_max_f32_e32 v55, v39, v55
	s_nop 0
	v_max_f32_e32 v153, v153, v153
	v_max_f32_e32 v152, v152, v153
	v_mov_b32_dpp v71, v55 row_ror:8 row_mask:0xf bank_mask:0xf
	s_nop 1
	v_mov_b32_dpp v153, v152 quad_perm:[1,0,3,2] row_mask:0xf bank_mask:0xf
	v_sub_f32_e32 v84, v156, v160
	v_mul_f32_e32 v37, 0x3fb8aa3b, v37
	v_mul_f32_e32 v36, 0x3fb8aa3b, v36
	s_nop 0
	v_max_f32_e32 v71, v71, v71
	s_nop 0
	v_max3_f32 v156, v136, v152, v153
	v_max_f32_e32 v71, v55, v71
	v_sub_f32_e32 v39, v86, v156
	s_nop 1
	v_mov_b32_dpp v86, v71 row_shl:4 row_mask:0xf bank_mask:0x5
	s_nop 1
	v_mov_b32_dpp v86, v71 row_shr:4 row_mask:0xf bank_mask:0xa
	v_sub_f32_e32 v54, v54, v156
	v_mul_f32_e32 v54, 0x3fb8aa3b, v54
	v_exp_f32_e32 v55, v54
	v_sub_f32_e32 v54, v70, v156
	s_nop 0
	v_max_f32_e32 v70, v86, v86
	v_max_f32_e32 v70, v71, v70
	s_nop 1
	v_mov_b32_dpp v86, v70 quad_perm:[2,3,0,1] row_mask:0xf bank_mask:0xf
	v_sub_f32_e32 v38, v38, v156
	v_mul_f32_e32 v38, 0x3fb8aa3b, v38
	v_exp_f32_e32 v71, v38
	v_mul_f32_e32 v54, 0x3fb8aa3b, v54
	s_nop 0
	v_max_f32_e32 v38, v86, v86
	v_max_f32_e32 v38, v70, v38
	v_exp_f32_e32 v87, v54
	s_nop 1
	v_mov_b32_dpp v54, v38 quad_perm:[1,0,3,2] row_mask:0xf bank_mask:0xf
	v_sub_f32_e32 v136, v136, v156
	v_mul_f32_e32 v84, 0x3fb8aa3b, v84
	v_mul_f32_e32 v68, 0x3fb8aa3b, v68
	v_mul_f32_e32 v70, 0x3fb8aa3b, v136
	s_nop 0
	v_max3_f32 v155, v137, v38, v54
	v_sub_u32_e32 v38, v96, v175
	v_exp_f32_e32 v37, v37
	v_exp_f32_e32 v36, v36
	v_exp_f32_e32 v52, v52
	v_exp_f32_e32 v84, v84
	v_exp_f32_e32 v68, v68
	v_exp_f32_e32 v136, v70
	v_add_u32_e32 v70, 64, v38
	v_cvt_pk_bf16_f32 v148, v37, v53
	v_cvt_pk_bf16_f32 v149, v85, v69
	v_cvt_pk_bf16_f32 v150, v36, v52
	v_cvt_pk_bf16_f32 v151, v84, v68
	ds_write2_b64 v215, v[148:149], v[150:151] offset0:144 offset1:178
	v_max3_f32 v54, v88, s59, v56
	v_mov_b32_e32 v150, v40
	v_max3_f32 v38, v54, v72, v150
	v_mov_b32_e32 v40, v38
	v_mov_b32_e32 v255, v38
	s_nop 1
	v_permlane16_swap_b32_e32 v40, v255
	s_nop 1
	v_mov_b32_dpp v40, v255 quad_perm:[0,1,2,3] row_mask:0x5 bank_mask:0xf
	v_sub_f32_e32 v151, v154, v155
	v_sub_f32_e32 v54, v137, v155
	v_mul_f32_e32 v137, 0x3fb8aa3b, v54
	v_sub_f32_e32 v54, v212, v155
	s_waitcnt lgkmcnt(0)
	v_max_f32_e32 v40, v40, v40
	v_max_f32_e32 v40, v38, v40
	s_nop 1
	v_mov_b32_dpp v70, v40 row_ror:8 row_mask:0xf bank_mask:0xf
	v_mul_f32_e32 v54, 0x3fb8aa3b, v54
	v_exp_f32_e32 v38, v54
	v_sub_f32_e32 v54, v213, v155
	v_sub_f32_e32 v86, v214, v155
	s_nop 0
	v_max_f32_e32 v70, v70, v70
	v_max_f32_e32 v40, v40, v70
	s_nop 1
	v_mov_b32_dpp v70, v40 row_shl:4 row_mask:0xf bank_mask:0x5
	s_nop 1
	v_mov_b32_dpp v70, v40 row_shr:4 row_mask:0xf bank_mask:0xa
	v_mul_f32_e32 v39, 0x3fb8aa3b, v39
	v_mul_f32_e32 v54, 0x3fb8aa3b, v54
	v_mul_f32_e32 v86, 0x3fb8aa3b, v86
	v_exp_f32_e32 v39, v39
	s_nop 0
	v_max_f32_e32 v70, v70, v70
	v_max_f32_e32 v152, v40, v70
	s_nop 1
	v_mov_b32_dpp v153, v152 quad_perm:[2,3,0,1] row_mask:0xf bank_mask:0xf
	v_mul_f32_e32 v40, 0x3fb8aa3b, v151
	v_exp_f32_e32 v54, v54
	v_exp_f32_e32 v86, v86
	v_exp_f32_e32 v70, v40
	s_nop 0
	v_max_f32_e32 v151, v153, v153
	v_cvt_pk_bf16_f32 v148, v39, v55
	v_mov_b32_e32 v212, v89
	v_mov_b32_e32 v213, v57
	v_max3_f32 v57, v212, s59, v213
	v_mov_b32_e32 v214, v73
	v_cvt_pk_bf16_f32 v149, v87, v71
	v_mov_b32_e32 v216, v41
	v_max3_f32 v57, v57, v214, v216
	v_mov_b32_e32 v73, v57
	v_mov_b32_e32 v255, v57
	s_nop 1
	v_permlane16_swap_b32_e32 v73, v255
	s_nop 1
	v_mov_b32_dpp v73, v255 quad_perm:[0,1,2,3] row_mask:0x5 bank_mask:0xf
	v_cvt_pk_bf16_f32 v40, v38, v54
	v_cvt_pk_bf16_f32 v41, v86, v70
	ds_write2_b64 v215, v[148:149], v[40:41] offset0:212 offset1:246
	v_max_f32_e32 v151, v152, v151
	s_nop 0
	v_max_f32_e32 v41, v73, v73
	v_max_f32_e32 v57, v57, v41
	s_nop 1
	v_mov_b32_dpp v73, v57 row_ror:8 row_mask:0xf bank_mask:0xf
	v_mov_b32_dpp v152, v151 quad_perm:[1,0,3,2] row_mask:0xf bank_mask:0xf
	v_sub_f32_e32 v135, v135, v160
	v_mul_f32_e32 v131, 0x3fb8aa3b, v131
	v_mul_f32_e32 v135, 0x3fb8aa3b, v135
	s_waitcnt lgkmcnt(0)
	v_max_f32_e32 v73, v73, v73
	s_nop 0
	v_max3_f32 v154, v138, v151, v152
	v_max_f32_e32 v73, v57, v73
	v_sub_f32_e32 v41, v88, v154
	s_nop 1
	v_mov_b32_dpp v88, v73 row_shl:4 row_mask:0xf bank_mask:0x5
	s_nop 1
	v_mov_b32_dpp v88, v73 row_shr:4 row_mask:0xf bank_mask:0xa
	v_sub_f32_e32 v56, v56, v154
	v_mul_f32_e32 v56, 0x3fb8aa3b, v56
	v_exp_f32_e32 v57, v56
	v_sub_f32_e32 v56, v72, v154
	s_nop 0
	v_max_f32_e32 v72, v88, v88
	v_max_f32_e32 v72, v73, v72
	s_nop 1
	v_mov_b32_dpp v88, v72 quad_perm:[2,3,0,1] row_mask:0xf bank_mask:0xf
	v_mul_f32_e32 v56, 0x3fb8aa3b, v56
	v_exp_f32_e32 v89, v56
	v_sub_f32_e32 v56, v150, v154
	v_mul_f32_e32 v56, 0x3fb8aa3b, v56
	v_exp_f32_e32 v73, v56
	s_nop 0
	v_max_f32_e32 v56, v88, v88
	v_max_f32_e32 v56, v72, v56
	s_nop 1
	v_mov_b32_dpp v72, v56 quad_perm:[1,0,3,2] row_mask:0xf bank_mask:0xf
	v_sub_f32_e32 v40, v138, v154
	v_mul_f32_e32 v40, 0x3fb8aa3b, v40
	v_exp_f32_e32 v138, v40
	s_nop 0
	v_max3_f32 v153, v139, v56, v72
	v_max3_f32 v56, v90, s59, v58
	v_max3_f32 v56, v56, v74, v42
	v_mov_b32_e32 v72, v56
	v_mov_b32_e32 v255, v56
	s_nop 1
	v_permlane16_swap_b32_e32 v72, v255
	s_nop 1
	v_mov_b32_dpp v72, v255 quad_perm:[0,1,2,3] row_mask:0x5 bank_mask:0xf
	v_sub_f32_e32 v88, v213, v153
	s_nop 0
	s_nop 0
	v_max_f32_e32 v72, v56, v72
	s_nop 1
	v_mov_b32_dpp v150, v72 row_ror:8 row_mask:0xf bank_mask:0xf
	v_mul_f32_e32 v56, 0x3fb8aa3b, v88
	v_sub_f32_e32 v88, v214, v153
	v_mov_b32_e32 v214, v91
	s_nop 0
	v_max_f32_e32 v150, v150, v150
	v_max_f32_e32 v150, v72, v150
	v_mov_b32_e32 v215, v59
	s_nop 0
	v_mov_b32_dpp v151, v150 row_shl:4 row_mask:0xf bank_mask:0x5
	s_nop 1
	v_mov_b32_dpp v151, v150 row_shr:4 row_mask:0xf bank_mask:0xa
	v_sub_f32_e32 v72, v216, v153
	v_mov_b32_e32 v216, v75
	v_max3_f32 v59, v214, s59, v215
	v_mov_b32_e32 v213, v43
	s_nop 0
	v_max_f32_e32 v151, v151, v151
	v_max3_f32 v43, v59, v216, v213
	v_sub_f32_e32 v40, v212, v153
	v_max_f32_e32 v152, v150, v151
	v_mov_b32_e32 v59, v43
	v_mov_b32_e32 v255, v43
	s_nop 1
	v_permlane16_swap_b32_e32 v59, v255
	s_nop 1
	v_mov_b32_dpp v59, v255 quad_perm:[0,1,2,3] row_mask:0x5 bank_mask:0xf
	v_mul_f32_e32 v41, 0x3fb8aa3b, v41
	v_mul_f32_e32 v40, 0x3fb8aa3b, v40
	v_mul_f32_e32 v88, 0x3fb8aa3b, v88
	v_mul_f32_e32 v72, 0x3fb8aa3b, v72
	v_mov_b32_dpp v212, v152 quad_perm:[2,3,0,1] row_mask:0xf bank_mask:0xf
	v_exp_f32_e32 v41, v41
	v_exp_f32_e32 v40, v40
	v_exp_f32_e32 v56, v56
	v_exp_f32_e32 v88, v88
	v_exp_f32_e32 v72, v72
	s_nop 0
	v_max_f32_e32 v59, v59, v59
	v_cvt_pk_bf16_f32 v148, v41, v57
	v_cvt_pk_bf16_f32 v149, v89, v73
	v_cvt_pk_bf16_f32 v150, v40, v56
	v_cvt_pk_bf16_f32 v151, v88, v72
	s_nop 0
	v_max_f32_e32 v212, v212, v212
	v_add_u32_e32 v75, 0x9800, v186
	v_max_f32_e32 v59, v43, v59
	v_max_f32_e32 v152, v152, v212
	ds_write2_b64 v75, v[148:149], v[150:151] offset0:160 offset1:194
	v_mov_b32_dpp v75, v59 row_ror:8 row_mask:0xf bank_mask:0xf
	v_mov_b32_dpp v212, v152 quad_perm:[1,0,3,2] row_mask:0xf bank_mask:0xf
	v_sub_f32_e32 v139, v139, v153
	v_mul_f32_e32 v139, 0x3fb8aa3b, v139
	v_exp_f32_e32 v131, v131
	s_waitcnt lgkmcnt(0)
	v_max_f32_e32 v75, v75, v75
	s_nop 0
	v_max3_f32 v152, v140, v152, v212
	v_max_f32_e32 v75, v59, v75
	v_sub_f32_e32 v43, v90, v152
	s_nop 1
	v_mov_b32_dpp v90, v75 row_shl:4 row_mask:0xf bank_mask:0x5
	s_nop 1
	v_mov_b32_dpp v90, v75 row_shr:4 row_mask:0xf bank_mask:0xa
	v_sub_f32_e32 v58, v58, v152
	v_mul_f32_e32 v58, 0x3fb8aa3b, v58
	v_exp_f32_e32 v59, v58
	v_sub_f32_e32 v58, v74, v152
	s_nop 0
	v_max_f32_e32 v74, v90, v90
	v_max_f32_e32 v74, v75, v74
	s_nop 1
	v_mov_b32_dpp v90, v74 quad_perm:[2,3,0,1] row_mask:0xf bank_mask:0xf
	v_sub_f32_e32 v42, v42, v152
	v_mul_f32_e32 v42, 0x3fb8aa3b, v42
	v_exp_f32_e32 v75, v42
	v_mul_f32_e32 v58, 0x3fb8aa3b, v58
	s_nop 0
	v_max_f32_e32 v42, v90, v90
	v_max_f32_e32 v42, v74, v42
	v_exp_f32_e32 v91, v58
	s_nop 1
	v_mov_b32_dpp v58, v42 quad_perm:[1,0,3,2] row_mask:0xf bank_mask:0xf
	v_sub_f32_e32 v140, v140, v152
	v_mul_f32_e32 v74, 0x3fb8aa3b, v140
	v_exp_f32_e32 v140, v74
	v_mul_f32_e32 v43, 0x3fb8aa3b, v43
	s_nop 0
	v_max3_f32 v151, v141, v42, v58
	v_max3_f32 v58, v92, s59, v60
	v_max3_f32 v58, v58, v76, v44
	v_mov_b32_e32 v74, v58
	v_mov_b32_e32 v255, v58
	s_nop 1
	v_permlane16_swap_b32_e32 v74, v255
	s_nop 1
	v_mov_b32_dpp v74, v255 quad_perm:[0,1,2,3] row_mask:0x5 bank_mask:0xf
	v_sub_f32_e32 v90, v215, v151
	s_nop 0
	s_nop 0
	v_max_f32_e32 v74, v58, v74
	s_nop 1
	v_mov_b32_dpp v150, v74 row_ror:8 row_mask:0xf bank_mask:0xf
	v_mul_f32_e32 v58, 0x3fb8aa3b, v90
	v_sub_f32_e32 v90, v216, v151
	v_mov_b32_e32 v216, v93
	s_nop 0
	v_max_f32_e32 v150, v150, v150
	v_max_f32_e32 v150, v74, v150
	v_mov_b32_e32 v217, v61
	s_nop 0
	v_mov_b32_dpp v212, v150 row_shl:4 row_mask:0xf bank_mask:0x5
	s_nop 1
	v_mov_b32_dpp v212, v150 row_shr:4 row_mask:0xf bank_mask:0xa
	v_mov_b32_e32 v218, v77
	v_max3_f32 v61, v216, s59, v217
	v_mov_b32_e32 v215, v45
	s_nop 0
	v_max_f32_e32 v212, v212, v212
	v_max3_f32 v45, v61, v218, v215
	v_sub_f32_e32 v42, v214, v151
	v_sub_f32_e32 v74, v213, v151
	v_max_f32_e32 v150, v150, v212
	v_mov_b32_e32 v61, v45
	v_mov_b32_e32 v255, v45
	s_nop 1
	v_permlane16_swap_b32_e32 v61, v255
	s_nop 1
	v_mov_b32_dpp v61, v255 quad_perm:[0,1,2,3] row_mask:0x5 bank_mask:0xf
	v_mul_f32_e32 v42, 0x3fb8aa3b, v42
	v_mul_f32_e32 v90, 0x3fb8aa3b, v90
	v_mul_f32_e32 v74, 0x3fb8aa3b, v74
	v_mov_b32_dpp v214, v150 quad_perm:[2,3,0,1] row_mask:0xf bank_mask:0xf
	v_exp_f32_e32 v43, v43
	v_exp_f32_e32 v42, v42
	v_exp_f32_e32 v58, v58
	v_exp_f32_e32 v90, v90
	v_exp_f32_e32 v74, v74
	s_nop 0
	v_max_f32_e32 v61, v61, v61
	v_cvt_pk_bf16_f32 v148, v43, v59
	v_cvt_pk_bf16_f32 v149, v91, v75
	v_cvt_pk_bf16_f32 v212, v42, v58
	v_cvt_pk_bf16_f32 v213, v90, v74
	s_nop 0
	v_max_f32_e32 v214, v214, v214
	v_add_u32_e32 v77, 0x9c00, v186
	v_max_f32_e32 v61, v45, v61
	v_max_f32_e32 v150, v150, v214
	ds_write2_b64 v77, v[148:149], v[212:213] offset0:100 offset1:134
	v_mov_b32_dpp v77, v61 row_ror:8 row_mask:0xf bank_mask:0xf
	v_mov_b32_dpp v214, v150 quad_perm:[1,0,3,2] row_mask:0xf bank_mask:0xf
	v_sub_f32_e32 v141, v141, v151
	v_mul_f32_e32 v141, 0x3fb8aa3b, v141
	v_exp_f32_e32 v133, v133
	s_waitcnt lgkmcnt(0)
	v_max_f32_e32 v77, v77, v77
	s_nop 0
	v_max3_f32 v150, v142, v150, v214
	v_max_f32_e32 v77, v61, v77
	v_sub_f32_e32 v45, v92, v150
	s_nop 1
	v_mov_b32_dpp v92, v77 row_shl:4 row_mask:0xf bank_mask:0x5
	s_nop 1
	v_mov_b32_dpp v92, v77 row_shr:4 row_mask:0xf bank_mask:0xa
	v_sub_f32_e32 v60, v60, v150
	v_mul_f32_e32 v60, 0x3fb8aa3b, v60
	v_exp_f32_e32 v61, v60
	v_sub_f32_e32 v60, v76, v150
	s_nop 0
	v_max_f32_e32 v76, v92, v92
	v_max_f32_e32 v76, v77, v76
	s_nop 1
	v_mov_b32_dpp v92, v76 quad_perm:[2,3,0,1] row_mask:0xf bank_mask:0xf
	v_sub_f32_e32 v44, v44, v150
	v_mul_f32_e32 v44, 0x3fb8aa3b, v44
	v_exp_f32_e32 v77, v44
	v_mul_f32_e32 v60, 0x3fb8aa3b, v60
	s_nop 0
	v_max_f32_e32 v44, v92, v92
	v_max_f32_e32 v44, v76, v44
	v_exp_f32_e32 v93, v60
	s_nop 1
	v_mov_b32_dpp v60, v44 quad_perm:[1,0,3,2] row_mask:0xf bank_mask:0xf
	v_sub_f32_e32 v142, v142, v150
	v_mul_f32_e32 v76, 0x3fb8aa3b, v142
	v_exp_f32_e32 v142, v76
	v_mul_f32_e32 v45, 0x3fb8aa3b, v45
	s_nop 0
	v_max3_f32 v149, v143, v44, v60
	v_max3_f32 v60, v94, s59, v62
	v_max3_f32 v60, v60, v78, v46
	v_mov_b32_e32 v76, v60
	v_mov_b32_e32 v255, v60
	s_nop 1
	v_permlane16_swap_b32_e32 v76, v255
	s_nop 1
	v_mov_b32_dpp v76, v255 quad_perm:[0,1,2,3] row_mask:0x5 bank_mask:0xf
	v_sub_f32_e32 v92, v217, v149
	s_nop 0
	s_nop 0
	v_max_f32_e32 v76, v60, v76
	s_nop 1
	v_mov_b32_dpp v148, v76 row_ror:8 row_mask:0xf bank_mask:0xf
	v_mov_b32_e32 v217, v95
	s_nop 0
	s_nop 0
	v_mul_f32_e32 v60, 0x3fb8aa3b, v92
	v_sub_f32_e32 v92, v218, v149
	v_max_f32_e32 v148, v76, v148
	v_mov_b32_e32 v218, v63
	s_nop 0
	v_mov_b32_dpp v214, v148 row_shl:4 row_mask:0xf bank_mask:0x5
	s_nop 1
	v_mov_b32_dpp v214, v148 row_shr:4 row_mask:0xf bank_mask:0xa
	v_mov_b32_e32 v219, v79
	v_max3_f32 v63, v217, s59, v218
	v_mov_b32_e32 v96, v47
	s_nop 0
	v_max_f32_e32 v214, v214, v214
	v_max3_f32 v47, v63, v219, v96
	v_sub_f32_e32 v44, v216, v149
	v_sub_f32_e32 v76, v215, v149
	v_max_f32_e32 v148, v148, v214
	v_mov_b32_e32 v63, v47
	v_mov_b32_e32 v255, v47
	s_nop 1
	v_permlane16_swap_b32_e32 v63, v255
	s_nop 1
	v_mov_b32_dpp v63, v255 quad_perm:[0,1,2,3] row_mask:0x5 bank_mask:0xf
	v_mul_f32_e32 v44, 0x3fb8aa3b, v44
	v_mul_f32_e32 v92, 0x3fb8aa3b, v92
	v_mul_f32_e32 v76, 0x3fb8aa3b, v76
	v_mov_b32_dpp v216, v148 quad_perm:[2,3,0,1] row_mask:0xf bank_mask:0xf
	v_exp_f32_e32 v45, v45
	v_exp_f32_e32 v44, v44
	v_exp_f32_e32 v60, v60
	v_exp_f32_e32 v92, v92
	v_exp_f32_e32 v76, v76
	s_nop 0
	v_max_f32_e32 v63, v63, v63
	v_cvt_pk_bf16_f32 v212, v45, v61
	v_cvt_pk_bf16_f32 v213, v93, v77
	v_cvt_pk_bf16_f32 v214, v44, v60
	v_cvt_pk_bf16_f32 v215, v92, v76
	s_nop 0
	v_max_f32_e32 v216, v216, v216
	v_add_u32_e32 v79, 0xa000, v186
	v_max_f32_e32 v63, v47, v63
	v_max_f32_e32 v148, v148, v216
	ds_write2_b64 v79, v[212:213], v[214:215] offset0:176 offset1:210
	v_mov_b32_dpp v79, v63 row_ror:8 row_mask:0xf bank_mask:0xf
	v_mov_b32_dpp v216, v148 quad_perm:[1,0,3,2] row_mask:0xf bank_mask:0xf
	v_sub_f32_e32 v143, v143, v149
	v_mul_f32_e32 v143, 0x3fb8aa3b, v143
	v_exp_f32_e32 v135, v135
	s_waitcnt lgkmcnt(0)
	v_max_f32_e32 v79, v79, v79
	s_nop 0
	v_max3_f32 v148, v144, v148, v216
	v_max_f32_e32 v79, v63, v79
	v_sub_f32_e32 v47, v94, v148
	s_nop 1
	v_mov_b32_dpp v94, v79 row_shl:4 row_mask:0xf bank_mask:0x5
	s_nop 1
	v_mov_b32_dpp v94, v79 row_shr:4 row_mask:0xf bank_mask:0xa
	v_sub_f32_e32 v62, v62, v148
	v_mul_f32_e32 v62, 0x3fb8aa3b, v62
	v_exp_f32_e32 v63, v62
	v_sub_f32_e32 v62, v78, v148
	s_nop 0
	v_max_f32_e32 v78, v94, v94
	v_max_f32_e32 v78, v79, v78
	s_nop 1
	v_mov_b32_dpp v94, v78 quad_perm:[2,3,0,1] row_mask:0xf bank_mask:0xf
	v_sub_f32_e32 v46, v46, v148
	v_mul_f32_e32 v46, 0x3fb8aa3b, v46
	v_exp_f32_e32 v79, v46
	v_mul_f32_e32 v62, 0x3fb8aa3b, v62
	s_nop 0
	v_max_f32_e32 v46, v94, v94
	v_max_f32_e32 v46, v78, v46
	v_exp_f32_e32 v95, v62
	s_nop 1
	v_mov_b32_dpp v62, v46 quad_perm:[1,0,3,2] row_mask:0xf bank_mask:0xf
	v_sub_f32_e32 v144, v144, v148
	v_mul_f32_e32 v78, 0x3fb8aa3b, v144
	v_exp_f32_e32 v144, v78
	v_mul_f32_e32 v47, 0x3fb8aa3b, v47
	s_nop 0
	v_max3_f32 v147, v145, v46, v62
	v_sub_f32_e32 v78, v219, v147
	v_mul_f32_e32 v78, 0x3fb8aa3b, v78
	v_sub_f32_e32 v46, v217, v147
	v_sub_f32_e32 v62, v218, v147
	v_exp_f32_e32 v94, v78
	v_sub_f32_e32 v78, v96, v147
	v_sub_f32_e32 v145, v145, v147
	v_mul_f32_e32 v46, 0x3fb8aa3b, v46
	v_mul_f32_e32 v62, 0x3fb8aa3b, v62
	v_mul_f32_e32 v78, 0x3fb8aa3b, v78
	v_exp_f32_e32 v47, v47
	v_exp_f32_e32 v46, v46
	v_exp_f32_e32 v62, v62
	v_exp_f32_e32 v78, v78
	v_mul_f32_e32 v96, 0x3fb8aa3b, v145
	v_exp_f32_e32 v137, v137
	v_exp_f32_e32 v139, v139
	v_exp_f32_e32 v141, v141
	v_exp_f32_e32 v143, v143
	v_exp_f32_e32 v145, v96
	v_cvt_pk_bf16_f32 v208, v47, v63
	v_cvt_pk_bf16_f32 v209, v95, v79
	v_cvt_pk_bf16_f32 v210, v46, v62
	v_cvt_pk_bf16_f32 v211, v94, v78
	v_add_u32_e32 v96, 0xa400, v186
	ds_write2_b64 v96, v[208:209], v[210:211] offset0:116 offset1:150
	v_pk_mul_f32 v[14:15], v[14:15], v[144:145]
	v_pk_mul_f32 v[12:13], v[12:13], v[142:143]
	v_pk_mul_f32 v[10:11], v[10:11], v[140:141]
	v_pk_mul_f32 v[8:9], v[8:9], v[138:139]
	v_pk_mul_f32 v[6:7], v[6:7], v[136:137]
	v_pk_mul_f32 v[4:5], v[4:5], v[134:135]
	v_pk_mul_f32 v[2:3], v[2:3], v[132:133]
	v_pk_mul_f32 v[0:1], v[0:1], v[130:131]
	v_pk_mul_f32 v[30:31], v[30:31], v[144:145]
	v_pk_mul_f32 v[28:29], v[28:29], v[142:143]
	v_pk_mul_f32 v[26:27], v[26:27], v[140:141]
	v_pk_mul_f32 v[24:25], v[24:25], v[138:139]
	v_pk_mul_f32 v[22:23], v[22:23], v[136:137]
	v_pk_mul_f32 v[20:21], v[20:21], v[134:135]
	v_pk_mul_f32 v[18:19], v[18:19], v[132:133]
	v_pk_mul_f32 v[16:17], v[16:17], v[130:131]
	s_mov_b32 s2, -16
	v_mov_b32_e32 v96, v185
	v_mov_b32_e32 v208, v184
	s_branch .Latt_join

.LBB0_859:
	v_add_u32_e32 v67, v65, v64
	ds_read_b128 v[76:79], v65 offset:18432
	ds_read_b128 v[80:83], v67
	s_add_i32 s0, s0, 32
	s_cmp_lt_u32 s0, 48
	s_waitcnt lgkmcnt(0)
	v_mfma_f32_32x32x16_bf16 v[48:63], v[80:83], v[76:79], v[48:63]
	ds_read_b128 v[76:79], v65 offset:23040
	s_waitcnt lgkmcnt(0)
	v_mfma_f32_32x32x16_bf16 v[16:31], v[80:83], v[76:79], v[16:31]
	ds_read_b128 v[76:79], v65 offset:27648
	s_waitcnt lgkmcnt(0)
	v_mfma_f32_32x32x16_bf16 v[32:47], v[80:83], v[76:79], v[32:47]
	ds_read_b128 v[76:79], v65 offset:32256
	ds_read_b128 v[84:87], v65 offset:18464
	s_waitcnt lgkmcnt(1)
	v_mfma_f32_32x32x16_bf16 v[0:15], v[80:83], v[76:79], v[0:15]
	ds_read_b128 v[76:79], v67 offset:32
	ds_read_b128 v[80:83], v65 offset:23072
	s_waitcnt lgkmcnt(0)
	v_mfma_f32_32x32x16_bf16 v[16:31], v[76:79], v[80:83], v[16:31]
	ds_read_b128 v[80:83], v65 offset:27680
	s_waitcnt lgkmcnt(0)
	v_mfma_f32_32x32x16_bf16 v[32:47], v[76:79], v[80:83], v[32:47]
	ds_read_b128 v[80:83], v65 offset:32288
	v_add_u32_e32 v65, 64, v65
	v_mfma_f32_32x32x16_bf16 v[48:63], v[76:79], v[84:87], v[48:63]
	s_waitcnt lgkmcnt(0)
	v_mfma_f32_32x32x16_bf16 v[0:15], v[76:79], v[80:83], v[0:15]
	s_cbranch_scc1 .LBB0_859
	v_and_b32_e32 v141, 63, v72
	v_or_b32_e32 v140, s13, v141
	v_readlane_b32 s0, v249, 15
	v_lshlrev_b32_e32 v96, 3, v140
	v_readlane_b32 s1, v249, 16
	v_readlane_b32 s16, v251, 20
	v_lshlrev_b32_e32 v69, 11, v66
	v_lshl_add_u64 v[64:65], s[0:1], 0, v[96:97]
	v_readlane_b32 s0, v248, 25
	s_or_b32 s3, s13, s0
	v_or_b32_e32 v96, s3, v74
	v_lshlrev_b64 v[66:67], 2, v[96:97]
	v_readlane_b32 s18, v251, 22
	v_readlane_b32 s19, v251, 23
	s_barrier
	s_nop 0
	v_lshl_add_u64 v[70:71], s[18:19], 0, v[66:67]
	v_readlane_b32 s100, v251, 16
	v_readlane_b32 s101, v251, 17
	s_nop 1
	v_lshl_add_u64 v[220:221], s[100:101], 0, v[66:67]
	v_readlane_b32 s100, v251, 20
	v_readlane_b32 s101, v251, 21
	s_nop 1
	v_lshl_add_u64 v[222:223], s[100:101], 0, v[66:67]
	global_load_dword v224, v[220:221], off
	global_load_dword v225, v[222:223], off
	global_load_dword v226, v[70:71], off offset:128
	global_load_dword v227, v[222:223], off offset:128
	global_load_dword v228, v[220:221], off offset:128
	global_load_dword v70, v[70:71], off
	s_mov_b32 s4, 0x3f2aaaab
	s_mov_b32 s8, 0x3f317218
	v_readlane_b32 s40, v251, 4
	v_readlane_b32 s52, v251, 16
	v_readlane_b32 s53, v251, 17
	v_readlane_b32 s17, v251, 21
	s_mov_b32 s9, 0x7f800000
	s_mov_b32 s10, 0x33800000
	v_readlane_b32 s20, v251, 24
	s_mov_b32 s20, 0x43000000
	v_readlane_b32 s21, v251, 25
	s_mov_b32 s21, 0x42b17217
	v_readlane_b32 s22, v251, 26
	s_mov_b32 s22, 0xf800000
	v_readlane_b32 s23, v251, 27
	s_mov_b32 s23, 0xc1880000
	v_add_u32_e32 v96, s3, v74
	s_mov_b32 s2, 0
	s_cmp_eq_u32 s12, 0
	v_readlane_b32 s24, v251, 28
	v_readlane_b32 s25, v251, 29
	v_readlane_b32 s26, v251, 30
	v_readlane_b32 s27, v251, 31
	v_readlane_b32 s28, v251, 32
	v_readlane_b32 s29, v251, 33
	v_readlane_b32 s30, v251, 34
	v_readlane_b32 s31, v251, 35
	v_readlane_b32 s41, v251, 5
	v_readlane_b32 s42, v251, 6
	v_readlane_b32 s43, v251, 7
	v_readlane_b32 s44, v251, 8
	v_readlane_b32 s45, v251, 9
	v_readlane_b32 s46, v251, 10
	v_readlane_b32 s47, v251, 11
	v_readlane_b32 s48, v251, 12
	v_readlane_b32 s49, v251, 13
	v_readlane_b32 s50, v251, 14
	v_readlane_b32 s51, v251, 15
	v_readlane_b32 s54, v251, 18
	v_readlane_b32 s55, v251, 19
	s_waitcnt vmcnt(0)
	v_mul_f32_e32 v70, 0xbfb8aa3b, v70
	v_exp_f32_e32 v73, v70
	s_nop 0
	v_add_f32_e32 v75, 1.0, v73
	v_add_f32_e32 v70, -1.0, v75
	v_sub_f32_e32 v71, v70, v75
	v_add_f32_e32 v71, 1.0, v71
	v_sub_f32_e32 v70, v73, v70
	v_add_f32_e32 v76, v70, v71
	v_frexp_mant_f32_e32 v70, v75
	v_cmp_gt_f32_e32 vcc, s4, v70
	v_cvt_f64_f32_e32 v[70:71], v75
	v_frexp_exp_i32_f64_e32 v70, v[70:71]
	v_subbrev_co_u32_e32 v82, vcc, 0, v70, vcc
	v_sub_u32_e32 v70, 0, v82
	v_ldexp_f32 v71, v75, v70
	v_add_f32_e32 v75, -1.0, v71
	v_add_f32_e32 v77, 1.0, v71
	v_ldexp_f32 v70, v76, v70
	v_add_f32_e32 v76, 1.0, v75
	v_add_f32_e32 v78, -1.0, v77
	v_sub_f32_e32 v76, v71, v76
	v_sub_f32_e32 v71, v71, v78
	v_add_f32_e32 v76, v70, v76
	v_add_f32_e32 v70, v70, v71
	v_add_f32_e32 v83, v77, v70
	v_rcp_f32_e32 v85, v83
	v_sub_f32_e32 v71, v83, v77
	v_sub_f32_e32 v84, v70, v71
	v_add_f32_e32 v71, v75, v76
	v_sub_f32_e32 v70, v71, v75
	v_mul_f32_e32 v86, v71, v85
	v_sub_f32_e32 v75, v76, v70
	v_mul_f32_e32 v76, v83, v86
	v_fma_f32 v78, v86, v83, -v76
	v_fmac_f32_e32 v78, v86, v84
	v_add_f32_e32 v70, v76, v78
	v_sub_f32_e32 v77, v71, v70
	v_pk_add_f32 v[80:81], v[70:71], v[76:77] neg_lo:[0,1] neg_hi:[0,1]
	v_mov_b32_e32 v79, v70
	v_pk_add_f32 v[70:71], v[80:81], v[78:79] neg_lo:[0,1] neg_hi:[0,1]
	v_cmp_neq_f32_e32 vcc, s9, v73
	v_add_f32_e32 v71, v75, v71
	v_add_f32_e32 v70, v70, v71
	v_add_f32_e32 v71, v77, v70
	v_mul_f32_e32 v75, v85, v71
	v_mul_f32_e32 v76, v83, v75
	v_fma_f32 v78, v75, v83, -v76
	v_fmac_f32_e32 v78, v75, v84
	v_sub_f32_e32 v77, v77, v71
	v_add_f32_e32 v83, v70, v77
	v_add_f32_e32 v70, v76, v78
	v_sub_f32_e32 v77, v71, v70
	v_pk_add_f32 v[80:81], v[70:71], v[76:77] neg_lo:[0,1] neg_hi:[0,1]
	v_mov_b32_e32 v79, v70
	v_pk_add_f32 v[70:71], v[80:81], v[78:79] neg_lo:[0,1] neg_hi:[0,1]
	s_nop 0
	v_add_f32_e32 v71, v83, v71
	v_add_f32_e32 v70, v70, v71
	v_add_f32_e32 v71, v86, v75
	v_add_f32_e32 v70, v77, v70
	v_sub_f32_e32 v76, v71, v86
	v_mul_f32_e32 v70, v85, v70
	v_sub_f32_e32 v75, v75, v76
	v_add_f32_e32 v75, v75, v70
	v_add_f32_e32 v76, v71, v75
	v_mul_f32_e32 v78, v76, v76
	v_fmamk_f32 v70, v78, 0x3e9b6dac, v191
	v_fmaak_f32 v169, v78, v70, 0x3f2aaada
	v_cvt_f32_i32_e32 v70, v82
	v_sub_f32_e32 v71, v76, v71
	v_sub_f32_e32 v71, v75, v71
	v_ldexp_f32 v75, v71, 1
	v_mul_f32_e32 v71, v76, v78
	v_pk_mul_f32 v[78:79], v[70:71], v[168:169]
	v_ldexp_f32 v77, v76, 1
	v_fma_f32 v76, v70, s8, -v78
	v_fmac_f32_e32 v76, 0xb102e308, v70
	v_pk_add_f32 v[70:71], v[78:79], v[76:77]
	v_mov_b32_e32 v80, v78
	v_sub_f32_e32 v77, v71, v77
	v_sub_f32_e32 v77, v79, v77
	v_add_f32_e32 v81, v75, v77
	v_pk_add_f32 v[78:79], v[70:71], v[78:79] neg_lo:[0,1] neg_hi:[0,1]
	v_pk_add_f32 v[82:83], v[70:71], v[80:81]
	v_mov_b32_e32 v77, v70
	v_mov_b32_e32 v79, v83
	v_pk_add_f32 v[84:85], v[76:77], v[78:79] neg_lo:[0,1] neg_hi:[0,1]
	v_pk_add_f32 v[76:77], v[76:77], v[78:79]
	v_mov_b32_e32 v80, v81
	v_pk_add_f32 v[78:79], v[76:77], v[70:71] op_sel:[1,0] op_sel_hi:[0,1] neg_lo:[0,1] neg_hi:[0,1]
	v_pk_add_f32 v[86:87], v[82:83], v[78:79] op_sel_hi:[1,0] neg_lo:[0,1] neg_hi:[0,1]
	v_mov_b32_e32 v82, v83
	v_mov_b32_e32 v83, v77
	v_pk_mov_b32 v[78:79], v[70:71], v[78:79] op_sel:[1,0]
	v_mov_b32_e32 v81, v70
	v_pk_add_f32 v[78:79], v[82:83], v[78:79] neg_lo:[0,1] neg_hi:[0,1]
	v_mov_b32_e32 v86, v84
	v_pk_add_f32 v[70:71], v[80:81], v[78:79] neg_lo:[0,1] neg_hi:[0,1]
	v_mov_b32_e32 v85, v77
	v_pk_add_f32 v[78:79], v[86:87], v[70:71]
	s_nop 0
	v_pk_add_f32 v[80:81], v[78:79], v[78:79] op_sel:[0,1] op_sel_hi:[1,0]
	s_nop 0
	v_pk_add_f32 v[76:77], v[76:77], v[80:81] op_sel:[1,0] op_sel_hi:[0,1]
	v_mov_b32_e32 v79, v76
	v_pk_add_f32 v[82:83], v[78:79], v[84:85] neg_lo:[0,1] neg_hi:[0,1]
	v_mov_b32_e32 v71, v80
	v_sub_f32_e32 v75, v78, v82
	v_pk_add_f32 v[70:71], v[70:71], v[82:83] neg_lo:[0,1] neg_hi:[0,1]
	v_sub_f32_e32 v75, v84, v75
	v_add_f32_e32 v70, v70, v75
	v_add_f32_e32 v70, v70, v71
	v_add_f32_e32 v70, v76, v70
	v_lshl_add_u64 v[76:77], s[52:53], 0, v[66:67]
	v_mov_b32_e32 v77, v224
	v_lshl_add_u64 v[66:67], s[16:17], 0, v[66:67]
	v_mov_b32_e32 v76, v225
	v_cndmask_b32_e32 v70, v199, v70, vcc
	v_cmp_ngt_f32_e32 vcc, -1.0, v73
	s_waitcnt vmcnt(1)
	v_add_f32_e32 v48, v48, v77
	v_mul_f32_e32 v48, 0xbfb8aa3b, v48
	v_exp_f32_e32 v48, v48
	v_cndmask_b32_e32 v70, v200, v70, vcc
	v_cmp_neq_f32_e32 vcc, -1.0, v73
	s_waitcnt vmcnt(0)
	v_add_f32_e32 v32, v32, v76
	v_add_f32_e32 v48, 1.0, v48
	v_rcp_f32_e32 v48, v48
	v_cndmask_b32_e32 v70, v201, v70, vcc
	v_cmp_lt_f32_e64 vcc, |v73|, s10
	v_mul_f32_e32 v32, 0xbfb8aa3b, v32
	v_exp_f32_e32 v32, v32
	v_cndmask_b32_e32 v70, v70, v73, vcc
	v_mul_f32_e32 v75, 0xc1000000, v70
	v_mul_f32_e32 v48, v48, v75
	v_mul_f32_e32 v66, 0x3fb8aa3b, v48
	v_add_f32_e32 v48, v48, v48
	v_exp_f32_e32 v70, v66
	v_mul_f32_e32 v66, 0x3fb8aa3b, v48
	v_rndne_f32_e32 v66, v66
	v_fmamk_f32 v67, v66, 0xbf317218, v48
	v_fmac_f32_e32 v67, 0x3102e308, v66
	v_fmamk_f32 v71, v67, 0x395133b1, v192
	v_cmp_eq_f32_e32 vcc, s20, v66
	v_cvt_i32_f32_e32 v66, v66
	v_fmaak_f32 v71, v67, v71, 0x3c0887f9
	v_fmaak_f32 v71, v67, v71, 0x3d2aaa81
	v_fmaak_f32 v71, v67, v71, 0x3e2aaaab
	v_fma_f32 v71, v67, v71, 0.5
	v_ldexp_f32 v66, 1.0, v66
	v_mul_f32_e32 v71, v67, v71
	v_cndmask_b32_e32 v66, v66, v202, vcc
	v_fmac_f32_e32 v67, v67, v71
	v_add_f32_e32 v71, -1.0, v66
	v_fmac_f32_e32 v71, v66, v67
	v_add_f32_e32 v66, v71, v71
	v_cndmask_b32_e32 v66, v71, v66, vcc
	v_cmp_nlt_f32_e32 vcc, s21, v48
	v_add_f32_e32 v32, 1.0, v32
	v_rcp_f32_e32 v32, v32
	v_cndmask_b32_e64 v66, v201, -v66, vcc
	v_cmp_gt_f32_e32 vcc, s22, v66
	v_mul_f32_e32 v67, 0x4f800000, v66
	v_add_f32_e32 v33, v33, v76
	v_cndmask_b32_e32 v66, v66, v67, vcc
	v_sqrt_f32_e32 v67, v66
	v_mul_f32_e32 v33, 0xbfb8aa3b, v33
	v_exp_f32_e32 v33, v33
	v_add_f32_e32 v34, v34, v76
	v_add_u32_e32 v71, -1, v67
	v_fma_f32 v73, -v71, v67, v66
	v_cmp_ge_f32_e64 s[0:1], 0, v73
	v_add_u32_e32 v73, 1, v67
	v_add_f32_e32 v33, 1.0, v33
	v_cndmask_b32_e64 v71, v67, v71, s[0:1]
	v_fma_f32 v67, -v73, v67, v66
	v_cmp_lt_f32_e64 s[0:1], 0, v67
	v_rcp_f32_e32 v33, v33
	v_mul_f32_e32 v34, 0xbfb8aa3b, v34
	v_cndmask_b32_e64 v67, v71, v73, s[0:1]
	v_mul_f32_e32 v71, 0x37800000, v67
	v_cndmask_b32_e32 v67, v67, v71, vcc
	v_cmp_class_f32_e32 vcc, v66, v193
	v_exp_f32_e32 v34, v34
	s_nop 0
	v_cndmask_b32_e32 v66, v67, v66, vcc
	v_cmp_ngt_f32_e32 vcc, s23, v48
	v_add_f32_e32 v34, 1.0, v34
	v_rcp_f32_e32 v34, v34
	v_cndmask_b32_e32 v48, 1.0, v66, vcc
	v_mul_f32_e32 v48, v32, v48
	v_and_b32_e32 v32, 0x100, v68
	v_or3_b32 v32, v69, v74, v32
	v_lshl_add_u32 v73, v32, 2, 0
	v_add_u32_e32 v32, 0x9000, v73
	ds_read2_b32 v[66:67], v32 offset1:32
	s_waitcnt lgkmcnt(0)
	v_mul_f32_e32 v48, v66, v48
	ds_write_b32 v73, v70
	ds_write_b32 v73, v48 offset:36864
	v_add_f32_e32 v48, v49, v77
	v_mul_f32_e32 v48, 0xbfb8aa3b, v48
	v_exp_f32_e32 v48, v48
	s_nop 0
	v_add_f32_e32 v48, 1.0, v48
	v_rcp_f32_e32 v48, v48
	s_nop 0
	v_mul_f32_e32 v48, v48, v75
	v_mul_f32_e32 v49, 0x3fb8aa3b, v48
	v_add_f32_e32 v48, v48, v48
	v_exp_f32_e32 v66, v49
	v_mul_f32_e32 v49, 0x3fb8aa3b, v48
	v_rndne_f32_e32 v49, v49
	v_fmamk_f32 v68, v49, 0xbf317218, v48
	v_fmac_f32_e32 v68, 0x3102e308, v49
	v_fmamk_f32 v69, v68, 0x395133b1, v192
	v_cmp_eq_f32_e32 vcc, s20, v49
	v_cvt_i32_f32_e32 v49, v49
	v_fmaak_f32 v69, v68, v69, 0x3c0887f9
	v_fmaak_f32 v69, v68, v69, 0x3d2aaa81
	v_fmaak_f32 v69, v68, v69, 0x3e2aaaab
	v_fma_f32 v69, v68, v69, 0.5
	v_ldexp_f32 v49, 1.0, v49
	v_mul_f32_e32 v69, v68, v69
	v_cndmask_b32_e32 v49, v49, v202, vcc
	v_fmac_f32_e32 v68, v68, v69
	v_add_f32_e32 v69, -1.0, v49
	v_fmac_f32_e32 v69, v49, v68
	v_add_f32_e32 v49, v69, v69
	v_cndmask_b32_e32 v49, v69, v49, vcc
	v_cmp_nlt_f32_e32 vcc, s21, v48
	s_nop 1
	v_cndmask_b32_e64 v49, v201, -v49, vcc
	v_cmp_gt_f32_e32 vcc, s22, v49
	v_mul_f32_e32 v68, 0x4f800000, v49
	s_nop 0
	v_cndmask_b32_e32 v49, v49, v68, vcc
	v_sqrt_f32_e32 v68, v49
	s_nop 0
	v_add_u32_e32 v69, -1, v68
	v_fma_f32 v70, -v69, v68, v49
	v_cmp_ge_f32_e64 s[0:1], 0, v70
	v_add_u32_e32 v70, 1, v68
	s_nop 0
	v_cndmask_b32_e64 v69, v68, v69, s[0:1]
	v_fma_f32 v68, -v70, v68, v49
	v_cmp_lt_f32_e64 s[0:1], 0, v68
	s_nop 1
	v_cndmask_b32_e64 v68, v69, v70, s[0:1]
	v_mul_f32_e32 v69, 0x37800000, v68
	v_cndmask_b32_e32 v68, v68, v69, vcc
	v_cmp_class_f32_e32 vcc, v49, v193
	s_nop 1
	v_cndmask_b32_e32 v49, v68, v49, vcc
	v_cmp_ngt_f32_e32 vcc, s23, v48
	s_nop 1
	v_cndmask_b32_e32 v48, 1.0, v49, vcc
	v_mul_f32_e32 v33, v33, v48
	ds_read2_b32 v[48:49], v32 offset0:64 offset1:96
	s_waitcnt lgkmcnt(0)
	v_mul_f32_e32 v33, v48, v33
	ds_write_b32 v73, v66 offset:256
	ds_write_b32 v73, v33 offset:37120
	v_add_f32_e32 v33, v50, v77
	v_mul_f32_e32 v33, 0xbfb8aa3b, v33
	v_exp_f32_e32 v33, v33
	s_nop 0
	v_add_f32_e32 v33, 1.0, v33
	v_rcp_f32_e32 v33, v33
	s_nop 0
	v_mul_f32_e32 v33, v33, v75
	v_mul_f32_e32 v48, 0x3fb8aa3b, v33
	v_add_f32_e32 v33, v33, v33
	v_mul_f32_e32 v50, 0x3fb8aa3b, v33
	v_rndne_f32_e32 v50, v50
	v_fmamk_f32 v66, v50, 0xbf317218, v33
	v_fmac_f32_e32 v66, 0x3102e308, v50
	v_fmamk_f32 v68, v66, 0x395133b1, v192
	v_cmp_eq_f32_e32 vcc, s20, v50
	v_cvt_i32_f32_e32 v50, v50
	v_fmaak_f32 v68, v66, v68, 0x3c0887f9
	v_fmaak_f32 v68, v66, v68, 0x3d2aaa81
	v_fmaak_f32 v68, v66, v68, 0x3e2aaaab
	v_fma_f32 v68, v66, v68, 0.5
	v_ldexp_f32 v50, 1.0, v50
	v_mul_f32_e32 v68, v66, v68
	v_cndmask_b32_e32 v50, v50, v202, vcc
	v_fmac_f32_e32 v66, v66, v68
	v_add_f32_e32 v68, -1.0, v50
	v_fmac_f32_e32 v68, v50, v66
	v_add_f32_e32 v50, v68, v68
	v_cndmask_b32_e32 v50, v68, v50, vcc
	v_cmp_nlt_f32_e32 vcc, s21, v33
	v_exp_f32_e32 v48, v48
	s_nop 0
	v_cndmask_b32_e64 v50, v201, -v50, vcc
	v_cmp_gt_f32_e32 vcc, s22, v50
	v_mul_f32_e32 v66, 0x4f800000, v50
	s_nop 0
	v_cndmask_b32_e32 v50, v50, v66, vcc
	v_sqrt_f32_e32 v66, v50
	s_nop 0
	v_add_u32_e32 v68, -1, v66
	v_fma_f32 v69, -v68, v66, v50
	v_cmp_ge_f32_e64 s[0:1], 0, v69
	v_add_u32_e32 v69, 1, v66
	s_nop 0
	v_cndmask_b32_e64 v68, v66, v68, s[0:1]
	v_fma_f32 v66, -v69, v66, v50
	v_cmp_lt_f32_e64 s[0:1], 0, v66
	s_nop 1
	v_cndmask_b32_e64 v66, v68, v69, s[0:1]
	v_mul_f32_e32 v68, 0x37800000, v66
	v_cndmask_b32_e32 v66, v66, v68, vcc
	ds_read2_b32 v[68:69], v32 offset0:128 offset1:160
	v_cmp_class_f32_e32 vcc, v50, v193
	s_nop 1
	v_cndmask_b32_e32 v50, v66, v50, vcc
	v_cmp_ngt_f32_e32 vcc, s23, v33
	s_nop 1
	v_cndmask_b32_e32 v33, 1.0, v50, vcc
	v_mul_f32_e32 v33, v34, v33
	s_waitcnt lgkmcnt(0)
	v_mul_f32_e32 v33, v68, v33
	ds_write_b32 v73, v48 offset:512
	ds_write_b32 v73, v33 offset:37376
	v_add_f32_e32 v33, v51, v77
	v_mul_f32_e32 v33, 0xbfb8aa3b, v33
	v_exp_f32_e32 v33, v33
	v_add_f32_e32 v34, v35, v76
	v_mul_f32_e32 v34, 0xbfb8aa3b, v34
	v_exp_f32_e32 v34, v34
	v_add_f32_e32 v33, 1.0, v33
	v_rcp_f32_e32 v33, v33
	v_add_f32_e32 v34, 1.0, v34
	v_rcp_f32_e32 v34, v34
	v_mul_f32_e32 v33, v33, v75
	v_mul_f32_e32 v35, 0x3fb8aa3b, v33
	v_add_f32_e32 v33, v33, v33
	v_mul_f32_e32 v48, 0x3fb8aa3b, v33
	v_rndne_f32_e32 v48, v48
	v_fmamk_f32 v50, v48, 0xbf317218, v33
	v_fmac_f32_e32 v50, 0x3102e308, v48
	v_fmamk_f32 v51, v50, 0x395133b1, v192
	v_cmp_eq_f32_e32 vcc, s20, v48
	v_cvt_i32_f32_e32 v48, v48
	v_fmaak_f32 v51, v50, v51, 0x3c0887f9
	v_fmaak_f32 v51, v50, v51, 0x3d2aaa81
	v_fmaak_f32 v51, v50, v51, 0x3e2aaaab
	v_fma_f32 v51, v50, v51, 0.5
	v_ldexp_f32 v48, 1.0, v48
	v_mul_f32_e32 v51, v50, v51
	v_cndmask_b32_e32 v48, v48, v202, vcc
	v_fmac_f32_e32 v50, v50, v51
	v_add_f32_e32 v51, -1.0, v48
	v_fmac_f32_e32 v51, v48, v50
	v_add_f32_e32 v48, v51, v51
	v_cndmask_b32_e32 v48, v51, v48, vcc
	v_cmp_nlt_f32_e32 vcc, s21, v33
	v_exp_f32_e32 v35, v35
	s_nop 0
	v_cndmask_b32_e64 v48, v201, -v48, vcc
	v_cmp_gt_f32_e32 vcc, s22, v48
	v_mul_f32_e32 v50, 0x4f800000, v48
	s_nop 0
	v_cndmask_b32_e32 v48, v48, v50, vcc
	v_sqrt_f32_e32 v50, v48
	s_nop 0
	v_add_u32_e32 v51, -1, v50
	v_fma_f32 v66, -v51, v50, v48
	v_cmp_ge_f32_e64 s[0:1], 0, v66
	v_add_u32_e32 v66, 1, v50
	s_nop 0
	v_cndmask_b32_e64 v51, v50, v51, s[0:1]
	v_fma_f32 v50, -v66, v50, v48
	v_cmp_lt_f32_e64 s[0:1], 0, v50
	s_nop 1
	v_cndmask_b32_e64 v50, v51, v66, s[0:1]
	v_mul_f32_e32 v51, 0x37800000, v50
	v_cndmask_b32_e32 v50, v50, v51, vcc
	v_cmp_class_f32_e32 vcc, v48, v193
	s_nop 1
	v_cndmask_b32_e32 v48, v50, v48, vcc
	ds_read2_b32 v[50:51], v32 offset0:192 offset1:224
	v_cmp_ngt_f32_e32 vcc, s23, v33
	s_nop 1
	v_cndmask_b32_e32 v33, 1.0, v48, vcc
	v_mul_f32_e32 v33, v34, v33
	s_waitcnt lgkmcnt(0)
	v_mul_f32_e32 v32, v50, v33
	ds_write_b32 v73, v35 offset:768
	ds_write_b32 v73, v32 offset:37632
	v_add_f32_e32 v32, v52, v77
	v_mul_f32_e32 v32, 0xbfb8aa3b, v32
	v_exp_f32_e32 v32, v32
	v_add_f32_e32 v33, v36, v76
	v_mul_f32_e32 v33, 0xbfb8aa3b, v33
	v_exp_f32_e32 v33, v33
	v_add_f32_e32 v32, 1.0, v32
	v_rcp_f32_e32 v32, v32
	v_add_f32_e32 v33, 1.0, v33
	v_rcp_f32_e32 v33, v33
	v_mul_f32_e32 v32, v32, v75
	v_mul_f32_e32 v34, 0x3fb8aa3b, v32
	v_add_f32_e32 v32, v32, v32
	v_mul_f32_e32 v35, 0x3fb8aa3b, v32
	v_rndne_f32_e32 v35, v35
	v_fmamk_f32 v36, v35, 0xbf317218, v32
	v_fmac_f32_e32 v36, 0x3102e308, v35
	v_fmamk_f32 v48, v36, 0x395133b1, v192
	v_cmp_eq_f32_e32 vcc, s20, v35
	v_cvt_i32_f32_e32 v35, v35
	v_fmaak_f32 v48, v36, v48, 0x3c0887f9
	v_fmaak_f32 v48, v36, v48, 0x3d2aaa81
	v_fmaak_f32 v48, v36, v48, 0x3e2aaaab
	v_fma_f32 v48, v36, v48, 0.5
	v_ldexp_f32 v35, 1.0, v35
	v_mul_f32_e32 v48, v36, v48
	v_cndmask_b32_e32 v35, v35, v202, vcc
	v_fmac_f32_e32 v36, v36, v48
	v_add_f32_e32 v48, -1.0, v35
	v_fmac_f32_e32 v48, v35, v36
	v_add_f32_e32 v35, v48, v48
	v_cndmask_b32_e32 v35, v48, v35, vcc
	v_cmp_nlt_f32_e32 vcc, s21, v32
	v_exp_f32_e32 v34, v34
	s_nop 0
	v_cndmask_b32_e64 v35, v201, -v35, vcc
	v_cmp_gt_f32_e32 vcc, s22, v35
	v_mul_f32_e32 v36, 0x4f800000, v35
	s_nop 0
	v_cndmask_b32_e32 v35, v35, v36, vcc
	v_sqrt_f32_e32 v36, v35
	s_nop 0
	v_add_u32_e32 v48, -1, v36
	v_fma_f32 v50, -v48, v36, v35
	v_cmp_ge_f32_e64 s[0:1], 0, v50
	v_add_u32_e32 v50, 1, v36
	s_nop 0
	v_cndmask_b32_e64 v48, v36, v48, s[0:1]
	v_fma_f32 v36, -v50, v36, v35
	v_cmp_lt_f32_e64 s[0:1], 0, v36
	s_nop 1
	v_cndmask_b32_e64 v36, v48, v50, s[0:1]
	v_mul_f32_e32 v48, 0x37800000, v36
	v_cndmask_b32_e32 v36, v36, v48, vcc
	v_cmp_class_f32_e32 vcc, v35, v193
	s_nop 1
	v_cndmask_b32_e32 v35, v36, v35, vcc
	v_cmp_ngt_f32_e32 vcc, s23, v32
	s_nop 1
	v_cndmask_b32_e32 v32, 1.0, v35, vcc
	v_mul_f32_e32 v33, v33, v32
	v_add_u32_e32 v32, 0x9800, v73
	ds_read2_b32 v[70:71], v32 offset1:32
	s_waitcnt lgkmcnt(0)
	v_mul_f32_e32 v33, v70, v33
	ds_write_b32 v73, v34 offset:2048
	ds_write_b32 v73, v33 offset:38912
	v_add_f32_e32 v33, v53, v77
	v_mul_f32_e32 v33, 0xbfb8aa3b, v33
	v_exp_f32_e32 v33, v33
	v_add_f32_e32 v34, v37, v76
	v_mul_f32_e32 v34, 0xbfb8aa3b, v34
	v_exp_f32_e32 v34, v34
	v_add_f32_e32 v33, 1.0, v33
	v_rcp_f32_e32 v33, v33
	v_add_f32_e32 v34, 1.0, v34
	v_rcp_f32_e32 v34, v34
	v_mul_f32_e32 v33, v33, v75
	v_mul_f32_e32 v35, 0x3fb8aa3b, v33
	v_add_f32_e32 v33, v33, v33
	v_mul_f32_e32 v36, 0x3fb8aa3b, v33
	v_rndne_f32_e32 v36, v36
	v_fmamk_f32 v37, v36, 0xbf317218, v33
	v_fmac_f32_e32 v37, 0x3102e308, v36
	v_fmamk_f32 v48, v37, 0x395133b1, v192
	v_cmp_eq_f32_e32 vcc, s20, v36
	v_cvt_i32_f32_e32 v36, v36
	v_fmaak_f32 v48, v37, v48, 0x3c0887f9
	v_fmaak_f32 v48, v37, v48, 0x3d2aaa81
	v_fmaak_f32 v48, v37, v48, 0x3e2aaaab
	v_fma_f32 v48, v37, v48, 0.5
	v_ldexp_f32 v36, 1.0, v36
	v_mul_f32_e32 v48, v37, v48
	v_cndmask_b32_e32 v36, v36, v202, vcc
	v_fmac_f32_e32 v37, v37, v48
	v_add_f32_e32 v48, -1.0, v36
	v_fmac_f32_e32 v48, v36, v37
	v_add_f32_e32 v36, v48, v48
	v_cndmask_b32_e32 v36, v48, v36, vcc
	v_cmp_nlt_f32_e32 vcc, s21, v33
	v_exp_f32_e32 v35, v35
	s_nop 0
	v_cndmask_b32_e64 v36, v201, -v36, vcc
	v_cmp_gt_f32_e32 vcc, s22, v36
	v_mul_f32_e32 v37, 0x4f800000, v36
	s_nop 0
	v_cndmask_b32_e32 v36, v36, v37, vcc
	v_sqrt_f32_e32 v37, v36
	s_nop 0
	v_add_u32_e32 v48, -1, v37
	v_fma_f32 v50, -v48, v37, v36
	v_cmp_ge_f32_e64 s[0:1], 0, v50
	v_add_u32_e32 v50, 1, v37
	s_nop 0
	v_cndmask_b32_e64 v48, v37, v48, s[0:1]
	v_fma_f32 v37, -v50, v37, v36
	v_cmp_lt_f32_e64 s[0:1], 0, v37
	s_nop 1
	v_cndmask_b32_e64 v37, v48, v50, s[0:1]
	v_mul_f32_e32 v48, 0x37800000, v37
	v_cndmask_b32_e32 v37, v37, v48, vcc
	v_cmp_class_f32_e32 vcc, v36, v193
	s_nop 1
	v_cndmask_b32_e32 v36, v37, v36, vcc
	v_cmp_ngt_f32_e32 vcc, s23, v33
	s_nop 1
	v_cndmask_b32_e32 v33, 1.0, v36, vcc
	ds_read2_b32 v[36:37], v32 offset0:64 offset1:96
	v_mul_f32_e32 v33, v34, v33
	v_add_f32_e32 v34, v38, v76
	v_mul_f32_e32 v34, 0xbfb8aa3b, v34
	v_exp_f32_e32 v34, v34
	s_waitcnt lgkmcnt(0)
	v_mul_f32_e32 v33, v36, v33
	ds_write_b32 v73, v35 offset:2304
	ds_write_b32 v73, v33 offset:39168
	v_add_f32_e32 v33, v54, v77
	v_mul_f32_e32 v33, 0xbfb8aa3b, v33
	v_exp_f32_e32 v33, v33
	v_add_f32_e32 v34, 1.0, v34
	v_rcp_f32_e32 v34, v34
	ds_read2_b32 v[52:53], v32 offset0:128 offset1:160
	v_add_f32_e32 v33, 1.0, v33
	v_rcp_f32_e32 v33, v33
	s_nop 0
	v_mul_f32_e32 v33, v33, v75
	v_mul_f32_e32 v35, 0x3fb8aa3b, v33
	v_add_f32_e32 v33, v33, v33
	v_mul_f32_e32 v36, 0x3fb8aa3b, v33
	v_rndne_f32_e32 v36, v36
	v_fmamk_f32 v38, v36, 0xbf317218, v33
	v_fmac_f32_e32 v38, 0x3102e308, v36
	v_fmamk_f32 v48, v38, 0x395133b1, v192
	v_cmp_eq_f32_e32 vcc, s20, v36
	v_cvt_i32_f32_e32 v36, v36
	v_fmaak_f32 v48, v38, v48, 0x3c0887f9
	v_fmaak_f32 v48, v38, v48, 0x3d2aaa81
	v_fmaak_f32 v48, v38, v48, 0x3e2aaaab
	v_fma_f32 v48, v38, v48, 0.5
	v_ldexp_f32 v36, 1.0, v36
	v_mul_f32_e32 v48, v38, v48
	v_cndmask_b32_e32 v36, v36, v202, vcc
	v_fmac_f32_e32 v38, v38, v48
	v_add_f32_e32 v48, -1.0, v36
	v_fmac_f32_e32 v48, v36, v38
	v_add_f32_e32 v36, v48, v48
	v_cndmask_b32_e32 v36, v48, v36, vcc
	v_cmp_nlt_f32_e32 vcc, s21, v33
	v_exp_f32_e32 v35, v35
	s_nop 0
	v_cndmask_b32_e64 v36, v201, -v36, vcc
	v_cmp_gt_f32_e32 vcc, s22, v36
	v_mul_f32_e32 v38, 0x4f800000, v36
	s_nop 0
	v_cndmask_b32_e32 v36, v36, v38, vcc
	v_sqrt_f32_e32 v38, v36
	s_nop 0
	v_add_u32_e32 v48, -1, v38
	v_fma_f32 v50, -v48, v38, v36
	v_cmp_ge_f32_e64 s[0:1], 0, v50
	v_add_u32_e32 v50, 1, v38
	s_nop 0
	v_cndmask_b32_e64 v48, v38, v48, s[0:1]
	v_fma_f32 v38, -v50, v38, v36
	v_cmp_lt_f32_e64 s[0:1], 0, v38
	s_nop 1
	v_cndmask_b32_e64 v38, v48, v50, s[0:1]
	v_mul_f32_e32 v48, 0x37800000, v38
	v_cndmask_b32_e32 v38, v38, v48, vcc
	v_cmp_class_f32_e32 vcc, v36, v193
	s_nop 1
	v_cndmask_b32_e32 v36, v38, v36, vcc
	v_cmp_ngt_f32_e32 vcc, s23, v33
	s_nop 1
	v_cndmask_b32_e32 v33, 1.0, v36, vcc
	v_mul_f32_e32 v33, v34, v33
	s_waitcnt lgkmcnt(0)
	v_mul_f32_e32 v33, v52, v33
	ds_write_b32 v73, v35 offset:2560
	ds_write_b32 v73, v33 offset:39424
	v_add_f32_e32 v33, v55, v77
	v_mul_f32_e32 v33, 0xbfb8aa3b, v33
	v_exp_f32_e32 v33, v33
	v_add_f32_e32 v34, v39, v76
	v_mul_f32_e32 v34, 0xbfb8aa3b, v34
	v_exp_f32_e32 v34, v34
	v_add_f32_e32 v33, 1.0, v33
	v_rcp_f32_e32 v33, v33
	v_add_f32_e32 v34, 1.0, v34
	v_rcp_f32_e32 v34, v34
	v_mul_f32_e32 v33, v33, v75
	v_mul_f32_e32 v35, 0x3fb8aa3b, v33
	v_add_f32_e32 v33, v33, v33
	v_mul_f32_e32 v36, 0x3fb8aa3b, v33
	v_rndne_f32_e32 v36, v36
	v_fmamk_f32 v38, v36, 0xbf317218, v33
	v_fmac_f32_e32 v38, 0x3102e308, v36
	v_fmamk_f32 v39, v38, 0x395133b1, v192
	v_cmp_eq_f32_e32 vcc, s20, v36
	v_cvt_i32_f32_e32 v36, v36
	v_fmaak_f32 v39, v38, v39, 0x3c0887f9
	v_fmaak_f32 v39, v38, v39, 0x3d2aaa81
	v_fmaak_f32 v39, v38, v39, 0x3e2aaaab
	v_fma_f32 v39, v38, v39, 0.5
	v_ldexp_f32 v36, 1.0, v36
	v_mul_f32_e32 v39, v38, v39
	v_cndmask_b32_e32 v36, v36, v202, vcc
	v_fmac_f32_e32 v38, v38, v39
	v_add_f32_e32 v39, -1.0, v36
	v_fmac_f32_e32 v39, v36, v38
	v_add_f32_e32 v36, v39, v39
	v_cndmask_b32_e32 v36, v39, v36, vcc
	v_cmp_nlt_f32_e32 vcc, s21, v33
	v_exp_f32_e32 v35, v35
	s_nop 0
	v_cndmask_b32_e64 v36, v201, -v36, vcc
	v_cmp_gt_f32_e32 vcc, s22, v36
	v_mul_f32_e32 v38, 0x4f800000, v36
	s_nop 0
	v_cndmask_b32_e32 v36, v36, v38, vcc
	v_sqrt_f32_e32 v38, v36
	s_nop 0
	v_add_u32_e32 v39, -1, v38
	v_fma_f32 v48, -v39, v38, v36
	v_cmp_ge_f32_e64 s[0:1], 0, v48
	v_add_u32_e32 v48, 1, v38
	s_nop 0
	v_cndmask_b32_e64 v39, v38, v39, s[0:1]
	v_fma_f32 v38, -v48, v38, v36
	v_cmp_lt_f32_e64 s[0:1], 0, v38
	s_nop 1
	v_cndmask_b32_e64 v38, v39, v48, s[0:1]
	v_mul_f32_e32 v39, 0x37800000, v38
	v_cndmask_b32_e32 v38, v38, v39, vcc
	v_cmp_class_f32_e32 vcc, v36, v193
	s_nop 1
	v_cndmask_b32_e32 v36, v38, v36, vcc
	ds_read2_b32 v[38:39], v32 offset0:192 offset1:224
	v_cmp_ngt_f32_e32 vcc, s23, v33
	s_nop 1
	v_cndmask_b32_e32 v33, 1.0, v36, vcc
	v_mul_f32_e32 v33, v34, v33
	s_waitcnt lgkmcnt(0)
	v_mul_f32_e32 v32, v38, v33
	ds_write_b32 v73, v35 offset:2816
	ds_write_b32 v73, v32 offset:39680
	v_add_f32_e32 v32, v56, v77
	v_mul_f32_e32 v32, 0xbfb8aa3b, v32
	v_exp_f32_e32 v32, v32
	v_add_f32_e32 v33, v40, v76
	v_mul_f32_e32 v33, 0xbfb8aa3b, v33
	v_exp_f32_e32 v33, v33
	v_add_f32_e32 v32, 1.0, v32
	v_rcp_f32_e32 v32, v32
	v_add_f32_e32 v33, 1.0, v33
	v_rcp_f32_e32 v33, v33
	v_mul_f32_e32 v32, v32, v75
	v_mul_f32_e32 v34, 0x3fb8aa3b, v32
	v_add_f32_e32 v32, v32, v32
	v_mul_f32_e32 v35, 0x3fb8aa3b, v32
	v_rndne_f32_e32 v35, v35
	v_fmamk_f32 v36, v35, 0xbf317218, v32
	v_fmac_f32_e32 v36, 0x3102e308, v35
	v_fmamk_f32 v38, v36, 0x395133b1, v192
	v_cmp_eq_f32_e32 vcc, s20, v35
	v_cvt_i32_f32_e32 v35, v35
	v_fmaak_f32 v38, v36, v38, 0x3c0887f9
	v_fmaak_f32 v38, v36, v38, 0x3d2aaa81
	v_fmaak_f32 v38, v36, v38, 0x3e2aaaab
	v_fma_f32 v38, v36, v38, 0.5
	v_ldexp_f32 v35, 1.0, v35
	v_mul_f32_e32 v38, v36, v38
	v_cndmask_b32_e32 v35, v35, v202, vcc
	v_fmac_f32_e32 v36, v36, v38
	v_add_f32_e32 v38, -1.0, v35
	v_fmac_f32_e32 v38, v35, v36
	v_add_f32_e32 v35, v38, v38
	v_cndmask_b32_e32 v35, v38, v35, vcc
	v_cmp_nlt_f32_e32 vcc, s21, v32
	v_exp_f32_e32 v34, v34
	s_nop 0
	v_cndmask_b32_e64 v35, v201, -v35, vcc
	v_cmp_gt_f32_e32 vcc, s22, v35
	v_mul_f32_e32 v36, 0x4f800000, v35
	s_nop 0
	v_cndmask_b32_e32 v35, v35, v36, vcc
	v_sqrt_f32_e32 v36, v35
	s_nop 0
	v_add_u32_e32 v38, -1, v36
	v_fma_f32 v40, -v38, v36, v35
	v_cmp_ge_f32_e64 s[0:1], 0, v40
	v_add_u32_e32 v40, 1, v36
	s_nop 0
	v_cndmask_b32_e64 v38, v36, v38, s[0:1]
	v_fma_f32 v36, -v40, v36, v35
	v_cmp_lt_f32_e64 s[0:1], 0, v36
	s_nop 1
	v_cndmask_b32_e64 v36, v38, v40, s[0:1]
	v_mul_f32_e32 v38, 0x37800000, v36
	v_cndmask_b32_e32 v36, v36, v38, vcc
	v_cmp_class_f32_e32 vcc, v35, v193
	s_nop 1
	v_cndmask_b32_e32 v35, v36, v35, vcc
	v_cmp_ngt_f32_e32 vcc, s23, v32
	s_nop 1
	v_cndmask_b32_e32 v32, 1.0, v35, vcc
	v_mul_f32_e32 v33, v33, v32
	v_add_u32_e32 v32, 0xa000, v73
	ds_read2_b32 v[54:55], v32 offset1:32
	s_waitcnt lgkmcnt(0)
	v_mul_f32_e32 v33, v54, v33
	ds_write_b32 v73, v34 offset:4096
	ds_write_b32 v73, v33 offset:40960
	v_add_f32_e32 v33, v57, v77
	v_mul_f32_e32 v33, 0xbfb8aa3b, v33
	v_exp_f32_e32 v33, v33
	v_add_f32_e32 v34, v41, v76
	v_mul_f32_e32 v34, 0xbfb8aa3b, v34
	v_exp_f32_e32 v34, v34
	v_add_f32_e32 v33, 1.0, v33
	v_rcp_f32_e32 v33, v33
	v_add_f32_e32 v34, 1.0, v34
	v_rcp_f32_e32 v34, v34
	v_mul_f32_e32 v33, v33, v75
	v_mul_f32_e32 v35, 0x3fb8aa3b, v33
	v_add_f32_e32 v33, v33, v33
	v_mul_f32_e32 v36, 0x3fb8aa3b, v33
	v_rndne_f32_e32 v36, v36
	v_fmamk_f32 v38, v36, 0xbf317218, v33
	v_fmac_f32_e32 v38, 0x3102e308, v36
	v_fmamk_f32 v40, v38, 0x395133b1, v192
	v_cmp_eq_f32_e32 vcc, s20, v36
	v_cvt_i32_f32_e32 v36, v36
	v_fmaak_f32 v40, v38, v40, 0x3c0887f9
	v_fmaak_f32 v40, v38, v40, 0x3d2aaa81
	v_fmaak_f32 v40, v38, v40, 0x3e2aaaab
	v_fma_f32 v40, v38, v40, 0.5
	v_ldexp_f32 v36, 1.0, v36
	v_mul_f32_e32 v40, v38, v40
	v_cndmask_b32_e32 v36, v36, v202, vcc
	v_fmac_f32_e32 v38, v38, v40
	v_add_f32_e32 v40, -1.0, v36
	v_fmac_f32_e32 v40, v36, v38
	v_add_f32_e32 v36, v40, v40
	v_cndmask_b32_e32 v36, v40, v36, vcc
	v_cmp_nlt_f32_e32 vcc, s21, v33
	v_exp_f32_e32 v35, v35
	s_nop 0
	v_cndmask_b32_e64 v36, v201, -v36, vcc
	v_cmp_gt_f32_e32 vcc, s22, v36
	v_mul_f32_e32 v38, 0x4f800000, v36
	s_nop 0
	v_cndmask_b32_e32 v36, v36, v38, vcc
	v_sqrt_f32_e32 v38, v36
	s_nop 0
	v_add_u32_e32 v40, -1, v38
	v_fma_f32 v41, -v40, v38, v36
	v_cmp_ge_f32_e64 s[0:1], 0, v41
	v_add_u32_e32 v41, 1, v38
	s_nop 0
	v_cndmask_b32_e64 v40, v38, v40, s[0:1]
	v_fma_f32 v38, -v41, v38, v36
	v_cmp_lt_f32_e64 s[0:1], 0, v38
	s_nop 1
	v_cndmask_b32_e64 v38, v40, v41, s[0:1]
	v_mul_f32_e32 v40, 0x37800000, v38
	v_cndmask_b32_e32 v38, v38, v40, vcc
	ds_read2_b32 v[40:41], v32 offset0:64 offset1:96
	v_cmp_class_f32_e32 vcc, v36, v193
	s_nop 1
	v_cndmask_b32_e32 v36, v38, v36, vcc
	v_cmp_ngt_f32_e32 vcc, s23, v33
	s_nop 1
	v_cndmask_b32_e32 v33, 1.0, v36, vcc
	v_mul_f32_e32 v33, v34, v33
	s_waitcnt lgkmcnt(0)
	v_mul_f32_e32 v33, v40, v33
	ds_write_b32 v73, v35 offset:4352
	ds_write_b32 v73, v33 offset:41216
	v_add_f32_e32 v33, v58, v77
	v_mul_f32_e32 v33, 0xbfb8aa3b, v33
	v_exp_f32_e32 v33, v33
	v_add_f32_e32 v34, v42, v76
	v_mul_f32_e32 v34, 0xbfb8aa3b, v34
	v_exp_f32_e32 v34, v34
	v_add_f32_e32 v33, 1.0, v33
	v_rcp_f32_e32 v33, v33
	ds_read2_b32 v[56:57], v32 offset0:128 offset1:160
	v_add_f32_e32 v34, 1.0, v34
	v_rcp_f32_e32 v34, v34
	v_mul_f32_e32 v33, v33, v75
	v_mul_f32_e32 v35, 0x3fb8aa3b, v33
	v_add_f32_e32 v33, v33, v33
	v_mul_f32_e32 v36, 0x3fb8aa3b, v33
	v_rndne_f32_e32 v36, v36
	v_fmamk_f32 v38, v36, 0xbf317218, v33
	v_fmac_f32_e32 v38, 0x3102e308, v36
	v_fmamk_f32 v40, v38, 0x395133b1, v192
	v_cmp_eq_f32_e32 vcc, s20, v36
	v_cvt_i32_f32_e32 v36, v36
	v_fmaak_f32 v40, v38, v40, 0x3c0887f9
	v_fmaak_f32 v40, v38, v40, 0x3d2aaa81
	v_fmaak_f32 v40, v38, v40, 0x3e2aaaab
	v_fma_f32 v40, v38, v40, 0.5
	v_ldexp_f32 v36, 1.0, v36
	v_mul_f32_e32 v40, v38, v40
	v_cndmask_b32_e32 v36, v36, v202, vcc
	v_fmac_f32_e32 v38, v38, v40
	v_add_f32_e32 v40, -1.0, v36
	v_fmac_f32_e32 v40, v36, v38
	v_add_f32_e32 v36, v40, v40
	v_cndmask_b32_e32 v36, v40, v36, vcc
	v_cmp_nlt_f32_e32 vcc, s21, v33
	v_exp_f32_e32 v35, v35
	s_nop 0
	v_cndmask_b32_e64 v36, v201, -v36, vcc
	v_cmp_gt_f32_e32 vcc, s22, v36
	v_mul_f32_e32 v38, 0x4f800000, v36
	s_nop 0
	v_cndmask_b32_e32 v36, v36, v38, vcc
	v_sqrt_f32_e32 v38, v36
	s_nop 0
	v_add_u32_e32 v40, -1, v38
	v_fma_f32 v42, -v40, v38, v36
	v_cmp_ge_f32_e64 s[0:1], 0, v42
	v_add_u32_e32 v42, 1, v38
	s_nop 0
	v_cndmask_b32_e64 v40, v38, v40, s[0:1]
	v_fma_f32 v38, -v42, v38, v36
	v_cmp_lt_f32_e64 s[0:1], 0, v38
	s_nop 1
	v_cndmask_b32_e64 v38, v40, v42, s[0:1]
	v_mul_f32_e32 v40, 0x37800000, v38
	v_cndmask_b32_e32 v38, v38, v40, vcc
	v_cmp_class_f32_e32 vcc, v36, v193
	s_nop 1
	v_cndmask_b32_e32 v36, v38, v36, vcc
	v_cmp_ngt_f32_e32 vcc, s23, v33
	s_nop 1
	v_cndmask_b32_e32 v33, 1.0, v36, vcc
	v_mul_f32_e32 v33, v34, v33
	s_waitcnt lgkmcnt(0)
	v_mul_f32_e32 v33, v56, v33
	ds_write_b32 v73, v35 offset:4608
	ds_write_b32 v73, v33 offset:41472
	v_add_f32_e32 v33, v59, v77
	v_mul_f32_e32 v33, 0xbfb8aa3b, v33
	v_exp_f32_e32 v33, v33
	v_add_f32_e32 v34, v43, v76
	v_mul_f32_e32 v34, 0xbfb8aa3b, v34
	v_exp_f32_e32 v34, v34
	v_add_f32_e32 v33, 1.0, v33
	v_rcp_f32_e32 v33, v33
	v_add_f32_e32 v34, 1.0, v34
	v_rcp_f32_e32 v34, v34
	v_mul_f32_e32 v33, v33, v75
	v_mul_f32_e32 v35, 0x3fb8aa3b, v33
	v_add_f32_e32 v33, v33, v33
	v_mul_f32_e32 v36, 0x3fb8aa3b, v33
	v_rndne_f32_e32 v36, v36
	v_fmamk_f32 v38, v36, 0xbf317218, v33
	v_fmac_f32_e32 v38, 0x3102e308, v36
	v_fmamk_f32 v40, v38, 0x395133b1, v192
	v_cmp_eq_f32_e32 vcc, s20, v36
	v_cvt_i32_f32_e32 v36, v36
	v_fmaak_f32 v40, v38, v40, 0x3c0887f9
	v_fmaak_f32 v40, v38, v40, 0x3d2aaa81
	v_fmaak_f32 v40, v38, v40, 0x3e2aaaab
	v_fma_f32 v40, v38, v40, 0.5
	v_ldexp_f32 v36, 1.0, v36
	v_mul_f32_e32 v40, v38, v40
	v_cndmask_b32_e32 v36, v36, v202, vcc
	v_fmac_f32_e32 v38, v38, v40
	v_add_f32_e32 v40, -1.0, v36
	v_fmac_f32_e32 v40, v36, v38
	v_add_f32_e32 v36, v40, v40
	v_cndmask_b32_e32 v36, v40, v36, vcc
	v_cmp_nlt_f32_e32 vcc, s21, v33
	v_exp_f32_e32 v35, v35
	s_nop 0
	v_cndmask_b32_e64 v36, v201, -v36, vcc
	v_cmp_gt_f32_e32 vcc, s22, v36
	v_mul_f32_e32 v38, 0x4f800000, v36
	s_nop 0
	v_cndmask_b32_e32 v36, v36, v38, vcc
	v_sqrt_f32_e32 v38, v36
	s_nop 0
	v_add_u32_e32 v40, -1, v38
	v_fma_f32 v42, -v40, v38, v36
	v_cmp_ge_f32_e64 s[0:1], 0, v42
	v_add_u32_e32 v42, 1, v38
	s_nop 0
	v_cndmask_b32_e64 v40, v38, v40, s[0:1]
	v_fma_f32 v38, -v42, v38, v36
	v_cmp_lt_f32_e64 s[0:1], 0, v38
	s_nop 1
	v_cndmask_b32_e64 v38, v40, v42, s[0:1]
	v_mul_f32_e32 v40, 0x37800000, v38
	ds_read2_b32 v[42:43], v32 offset0:192 offset1:224
	v_cndmask_b32_e32 v38, v38, v40, vcc
	v_cmp_class_f32_e32 vcc, v36, v193
	s_nop 1
	v_cndmask_b32_e32 v36, v38, v36, vcc
	v_cmp_ngt_f32_e32 vcc, s23, v33
	s_nop 1
	v_cndmask_b32_e32 v33, 1.0, v36, vcc
	v_mul_f32_e32 v33, v34, v33
	s_waitcnt lgkmcnt(0)
	v_mul_f32_e32 v32, v42, v33
	ds_write_b32 v73, v35 offset:4864
	ds_write_b32 v73, v32 offset:41728
	v_add_f32_e32 v32, v60, v77
	v_mul_f32_e32 v32, 0xbfb8aa3b, v32
	v_exp_f32_e32 v32, v32
	v_add_f32_e32 v33, v44, v76
	v_mul_f32_e32 v33, 0xbfb8aa3b, v33
	v_exp_f32_e32 v33, v33
	v_add_f32_e32 v32, 1.0, v32
	v_rcp_f32_e32 v32, v32
	v_add_f32_e32 v33, 1.0, v33
	v_rcp_f32_e32 v33, v33
	v_mul_f32_e32 v32, v32, v75
	v_mul_f32_e32 v34, 0x3fb8aa3b, v32
	v_add_f32_e32 v32, v32, v32
	v_mul_f32_e32 v35, 0x3fb8aa3b, v32
	v_rndne_f32_e32 v35, v35
	v_fmamk_f32 v36, v35, 0xbf317218, v32
	v_fmac_f32_e32 v36, 0x3102e308, v35
	v_fmamk_f32 v38, v36, 0x395133b1, v192
	v_cmp_eq_f32_e32 vcc, s20, v35
	v_cvt_i32_f32_e32 v35, v35
	v_fmaak_f32 v38, v36, v38, 0x3c0887f9
	v_fmaak_f32 v38, v36, v38, 0x3d2aaa81
	v_fmaak_f32 v38, v36, v38, 0x3e2aaaab
	v_fma_f32 v38, v36, v38, 0.5
	v_ldexp_f32 v35, 1.0, v35
	v_mul_f32_e32 v38, v36, v38
	v_cndmask_b32_e32 v35, v35, v202, vcc
	v_fmac_f32_e32 v36, v36, v38
	v_add_f32_e32 v38, -1.0, v35
	v_fmac_f32_e32 v38, v35, v36
	v_add_f32_e32 v35, v38, v38
	v_cndmask_b32_e32 v35, v38, v35, vcc
	v_cmp_nlt_f32_e32 vcc, s21, v32
	v_exp_f32_e32 v34, v34
	s_nop 0
	v_cndmask_b32_e64 v35, v201, -v35, vcc
	v_cmp_gt_f32_e32 vcc, s22, v35
	v_mul_f32_e32 v36, 0x4f800000, v35
	s_nop 0
	v_cndmask_b32_e32 v35, v35, v36, vcc
	v_sqrt_f32_e32 v36, v35
	s_nop 0
	v_add_u32_e32 v38, -1, v36
	v_fma_f32 v40, -v38, v36, v35
	v_cmp_ge_f32_e64 s[0:1], 0, v40
	v_add_u32_e32 v40, 1, v36
	s_nop 0
	v_cndmask_b32_e64 v38, v36, v38, s[0:1]
	v_fma_f32 v36, -v40, v36, v35
	v_cmp_lt_f32_e64 s[0:1], 0, v36
	s_nop 1
	v_cndmask_b32_e64 v36, v38, v40, s[0:1]
	v_mul_f32_e32 v38, 0x37800000, v36
	v_cndmask_b32_e32 v36, v36, v38, vcc
	v_cmp_class_f32_e32 vcc, v35, v193
	s_nop 1
	v_cndmask_b32_e32 v35, v36, v35, vcc
	v_cmp_ngt_f32_e32 vcc, s23, v32
	s_nop 1
	v_cndmask_b32_e32 v32, 1.0, v35, vcc
	v_mul_f32_e32 v32, v33, v32
	v_add_u32_e32 v33, 0xa800, v73
	ds_read2_b32 v[58:59], v33 offset1:32
	s_waitcnt lgkmcnt(0)
	v_mul_f32_e32 v32, v58, v32
	ds_write_b32 v73, v34 offset:6144
	ds_write_b32 v73, v32 offset:43008
	v_add_f32_e32 v32, v61, v77
	v_mul_f32_e32 v32, 0xbfb8aa3b, v32
	v_exp_f32_e32 v32, v32
	v_add_f32_e32 v34, v45, v76
	v_mul_f32_e32 v34, 0xbfb8aa3b, v34
	v_exp_f32_e32 v34, v34
	v_add_f32_e32 v32, 1.0, v32
	v_rcp_f32_e32 v32, v32
	ds_read2_b32 v[44:45], v33 offset0:64 offset1:96
	v_add_f32_e32 v34, 1.0, v34
	v_rcp_f32_e32 v34, v34
	v_mul_f32_e32 v32, v32, v75
	v_mul_f32_e32 v35, 0x3fb8aa3b, v32
	v_add_f32_e32 v32, v32, v32
	v_mul_f32_e32 v36, 0x3fb8aa3b, v32
	v_rndne_f32_e32 v36, v36
	v_fmamk_f32 v38, v36, 0xbf317218, v32
	v_fmac_f32_e32 v38, 0x3102e308, v36
	v_fmamk_f32 v40, v38, 0x395133b1, v192
	v_cmp_eq_f32_e32 vcc, s20, v36
	v_cvt_i32_f32_e32 v36, v36
	v_fmaak_f32 v40, v38, v40, 0x3c0887f9
	v_fmaak_f32 v40, v38, v40, 0x3d2aaa81
	v_fmaak_f32 v40, v38, v40, 0x3e2aaaab
	v_fma_f32 v40, v38, v40, 0.5
	v_ldexp_f32 v36, 1.0, v36
	v_mul_f32_e32 v40, v38, v40
	v_cndmask_b32_e32 v36, v36, v202, vcc
	v_fmac_f32_e32 v38, v38, v40
	v_add_f32_e32 v40, -1.0, v36
	v_fmac_f32_e32 v40, v36, v38
	v_add_f32_e32 v36, v40, v40
	v_cndmask_b32_e32 v36, v40, v36, vcc
	v_cmp_nlt_f32_e32 vcc, s21, v32
	v_exp_f32_e32 v35, v35
	s_nop 0
	v_cndmask_b32_e64 v36, v201, -v36, vcc
	v_cmp_gt_f32_e32 vcc, s22, v36
	v_mul_f32_e32 v38, 0x4f800000, v36
	s_nop 0
	v_cndmask_b32_e32 v36, v36, v38, vcc
	v_sqrt_f32_e32 v38, v36
	s_nop 0
	v_add_u32_e32 v40, -1, v38
	v_fma_f32 v42, -v40, v38, v36
	v_cmp_ge_f32_e64 s[0:1], 0, v42
	v_add_u32_e32 v42, 1, v38
	s_nop 0
	v_cndmask_b32_e64 v40, v38, v40, s[0:1]
	v_fma_f32 v38, -v42, v38, v36
	v_cmp_lt_f32_e64 s[0:1], 0, v38
	s_nop 1
	v_cndmask_b32_e64 v38, v40, v42, s[0:1]
	v_mul_f32_e32 v40, 0x37800000, v38
	v_cndmask_b32_e32 v38, v38, v40, vcc
	v_cmp_class_f32_e32 vcc, v36, v193
	s_nop 1
	v_cndmask_b32_e32 v36, v38, v36, vcc
	v_cmp_ngt_f32_e32 vcc, s23, v32
	s_nop 1
	v_cndmask_b32_e32 v32, 1.0, v36, vcc
	v_mul_f32_e32 v32, v34, v32
	s_waitcnt lgkmcnt(0)
	v_mul_f32_e32 v32, v44, v32
	ds_write_b32 v73, v35 offset:6400
	ds_write_b32 v73, v32 offset:43264
	v_add_f32_e32 v32, v62, v77
	v_mul_f32_e32 v32, 0xbfb8aa3b, v32
	v_exp_f32_e32 v32, v32
	v_add_f32_e32 v34, v46, v76
	v_mul_f32_e32 v34, 0xbfb8aa3b, v34
	v_exp_f32_e32 v34, v34
	v_add_f32_e32 v32, 1.0, v32
	v_rcp_f32_e32 v32, v32
	v_add_f32_e32 v34, 1.0, v34
	v_rcp_f32_e32 v34, v34
	v_mul_f32_e32 v32, v32, v75
	v_mul_f32_e32 v35, 0x3fb8aa3b, v32
	v_add_f32_e32 v32, v32, v32
	v_exp_f32_e32 v36, v35
	v_mul_f32_e32 v35, 0x3fb8aa3b, v32
	v_rndne_f32_e32 v35, v35
	v_fmamk_f32 v38, v35, 0xbf317218, v32
	v_fmac_f32_e32 v38, 0x3102e308, v35
	v_fmamk_f32 v40, v38, 0x395133b1, v192
	v_cmp_eq_f32_e32 vcc, s20, v35
	v_cvt_i32_f32_e32 v35, v35
	v_fmaak_f32 v40, v38, v40, 0x3c0887f9
	v_fmaak_f32 v40, v38, v40, 0x3d2aaa81
	v_fmaak_f32 v40, v38, v40, 0x3e2aaaab
	v_fma_f32 v40, v38, v40, 0.5
	v_ldexp_f32 v35, 1.0, v35
	v_mul_f32_e32 v40, v38, v40
	v_cndmask_b32_e32 v35, v35, v202, vcc
	v_fmac_f32_e32 v38, v38, v40
	v_add_f32_e32 v40, -1.0, v35
	v_fmac_f32_e32 v40, v35, v38
	v_add_f32_e32 v35, v40, v40
	v_cndmask_b32_e32 v35, v40, v35, vcc
	v_cmp_nlt_f32_e32 vcc, s21, v32
	s_nop 1
	v_cndmask_b32_e64 v35, v201, -v35, vcc
	v_cmp_gt_f32_e32 vcc, s22, v35
	v_mul_f32_e32 v38, 0x4f800000, v35
	s_nop 0
	v_cndmask_b32_e32 v35, v35, v38, vcc
	v_sqrt_f32_e32 v38, v35
	s_nop 0
	v_add_u32_e32 v40, -1, v38
	v_fma_f32 v42, -v40, v38, v35
	v_cmp_ge_f32_e64 s[0:1], 0, v42
	v_add_u32_e32 v42, 1, v38
	s_nop 0
	v_cndmask_b32_e64 v40, v38, v40, s[0:1]
	v_fma_f32 v38, -v42, v38, v35
	v_cmp_lt_f32_e64 s[0:1], 0, v38
	s_nop 1
	v_cndmask_b32_e64 v38, v40, v42, s[0:1]
	v_mul_f32_e32 v40, 0x37800000, v38
	v_cndmask_b32_e32 v38, v38, v40, vcc
	v_cmp_class_f32_e32 vcc, v35, v193
	s_nop 1
	v_cndmask_b32_e32 v35, v38, v35, vcc
	v_cmp_ngt_f32_e32 vcc, s23, v32
	s_nop 1
	v_cndmask_b32_e32 v32, 1.0, v35, vcc
	v_mul_f32_e32 v32, v34, v32
	ds_read2_b32 v[34:35], v33 offset0:128 offset1:160
	s_waitcnt lgkmcnt(0)
	v_mul_f32_e32 v32, v34, v32
	ds_write_b32 v73, v36 offset:6656
	ds_write_b32 v73, v32 offset:43520
	v_add_f32_e32 v32, v63, v77
	v_mul_f32_e32 v32, 0xbfb8aa3b, v32
	v_exp_f32_e32 v32, v32
	v_add_f32_e32 v34, v47, v76
	v_mul_f32_e32 v34, 0xbfb8aa3b, v34
	v_exp_f32_e32 v34, v34
	v_add_f32_e32 v32, 1.0, v32
	v_rcp_f32_e32 v32, v32
	v_lshlrev_b64 v[46:47], 2, v[96:97]
	v_add_f32_e32 v34, 1.0, v34
	v_rcp_f32_e32 v36, v34
	v_mul_f32_e32 v32, v32, v75
	v_mul_f32_e32 v34, 0x3fb8aa3b, v32
	v_add_f32_e32 v32, v32, v32
	v_mul_f32_e32 v38, 0x3fb8aa3b, v32
	v_rndne_f32_e32 v38, v38
	v_fmamk_f32 v40, v38, 0xbf317218, v32
	v_fmac_f32_e32 v40, 0x3102e308, v38
	v_fmamk_f32 v42, v40, 0x395133b1, v192
	v_cmp_eq_f32_e32 vcc, s20, v38
	v_cvt_i32_f32_e32 v38, v38
	v_fmaak_f32 v42, v40, v42, 0x3c0887f9
	v_fmaak_f32 v42, v40, v42, 0x3d2aaa81
	v_fmaak_f32 v42, v40, v42, 0x3e2aaaab
	v_fma_f32 v42, v40, v42, 0.5
	v_ldexp_f32 v38, 1.0, v38
	v_mul_f32_e32 v42, v40, v42
	v_cndmask_b32_e32 v38, v38, v202, vcc
	v_fmac_f32_e32 v40, v40, v42
	v_add_f32_e32 v42, -1.0, v38
	v_fmac_f32_e32 v42, v38, v40
	v_add_f32_e32 v38, v42, v42
	v_cndmask_b32_e32 v38, v42, v38, vcc
	v_cmp_nlt_f32_e32 vcc, s21, v32
	v_lshl_add_u64 v[60:61], s[18:19], 0, v[46:47]
	v_exp_f32_e32 v34, v34
	v_cndmask_b32_e64 v38, v201, -v38, vcc
	v_cmp_gt_f32_e32 vcc, s22, v38
	v_mul_f32_e32 v40, 0x4f800000, v38
	s_nop 0
	v_cndmask_b32_e32 v38, v38, v40, vcc
	v_sqrt_f32_e32 v40, v38
	s_nop 0
	v_add_u32_e32 v42, -1, v40
	v_fma_f32 v44, -v42, v40, v38
	v_cmp_ge_f32_e64 s[0:1], 0, v44
	v_add_u32_e32 v44, 1, v40
	s_nop 0
	v_cndmask_b32_e64 v42, v40, v42, s[0:1]
	v_fma_f32 v40, -v44, v40, v38
	v_cmp_lt_f32_e64 s[0:1], 0, v40
	s_nop 1
	v_cndmask_b32_e64 v40, v42, v44, s[0:1]
	v_mul_f32_e32 v42, 0x37800000, v40
	v_cndmask_b32_e32 v40, v40, v42, vcc
	v_cmp_class_f32_e32 vcc, v38, v193
	s_nop 1
	v_cndmask_b32_e32 v38, v40, v38, vcc
	v_cmp_ngt_f32_e32 vcc, s23, v32
	s_nop 1
	v_cndmask_b32_e32 v32, 1.0, v38, vcc
	v_mul_f32_e32 v36, v36, v32
	ds_read2_b32 v[32:33], v33 offset0:192 offset1:224
	s_waitcnt lgkmcnt(0)
	v_mul_f32_e32 v32, v32, v36
	ds_write_b32 v73, v32 offset:43776
	v_mov_b32_e32 v32, v226
	s_waitcnt vmcnt(0)
	v_mul_f32_e32 v32, 0xbfb8aa3b, v32
	v_exp_f32_e32 v32, v32
	s_nop 0
	v_add_f32_e32 v36, 1.0, v32
	v_add_f32_e32 v38, -1.0, v36
	v_sub_f32_e32 v40, v38, v36
	v_add_f32_e32 v40, 1.0, v40
	v_sub_f32_e32 v38, v32, v38
	v_add_f32_e32 v38, v38, v40
	v_frexp_mant_f32_e32 v40, v36
	v_cvt_f64_f32_e32 v[60:61], v36
	v_cmp_gt_f32_e32 vcc, s4, v40
	v_frexp_exp_i32_f64_e32 v40, v[60:61]
	s_mul_i32 s4, s11, 0x24000
	v_subbrev_co_u32_e32 v40, vcc, 0, v40, vcc
	v_sub_u32_e32 v42, 0, v40
	v_ldexp_f32 v36, v36, v42
	v_ldexp_f32 v38, v38, v42
	v_add_f32_e32 v42, -1.0, v36
	v_add_f32_e32 v48, 1.0, v36
	v_add_f32_e32 v44, 1.0, v42
	v_add_f32_e32 v50, -1.0, v48
	v_sub_f32_e32 v44, v36, v44
	v_sub_f32_e32 v36, v36, v50
	v_add_f32_e32 v36, v38, v36
	v_add_f32_e32 v44, v38, v44
	v_add_f32_e32 v38, v48, v36
	v_sub_f32_e32 v48, v38, v48
	v_sub_f32_e32 v36, v36, v48
	v_rcp_f32_e32 v48, v38
	v_add_f32_e32 v61, v42, v44
	v_sub_f32_e32 v42, v61, v42
	v_sub_f32_e32 v42, v44, v42
	v_mul_f32_e32 v44, v61, v48
	v_mul_f32_e32 v62, v38, v44
	v_fma_f32 v74, v44, v38, -v62
	v_fmac_f32_e32 v74, v44, v36
	v_add_f32_e32 v60, v62, v74
	v_sub_f32_e32 v63, v61, v60
	v_pk_add_f32 v[76:77], v[60:61], v[62:63] neg_lo:[0,1] neg_hi:[0,1]
	v_mov_b32_e32 v75, v60
	v_pk_add_f32 v[60:61], v[76:77], v[74:75] neg_lo:[0,1] neg_hi:[0,1]
	v_cmp_neq_f32_e32 vcc, s9, v32
	v_add_f32_e32 v42, v42, v61
	v_add_f32_e32 v42, v60, v42
	v_add_f32_e32 v61, v63, v42
	v_mul_f32_e32 v50, v48, v61
	v_mul_f32_e32 v62, v38, v50
	v_fma_f32 v74, v50, v38, -v62
	v_fmac_f32_e32 v74, v50, v36
	v_add_f32_e32 v60, v62, v74
	v_sub_f32_e32 v36, v63, v61
	v_sub_f32_e32 v63, v61, v60
	v_pk_add_f32 v[76:77], v[60:61], v[62:63] neg_lo:[0,1] neg_hi:[0,1]
	v_mov_b32_e32 v75, v60
	v_add_f32_e32 v36, v42, v36
	v_pk_add_f32 v[60:61], v[76:77], v[74:75] neg_lo:[0,1] neg_hi:[0,1]
	v_add_f32_e32 v38, v44, v50
	v_add_f32_e32 v36, v36, v61
	v_add_f32_e32 v36, v60, v36
	v_add_f32_e32 v36, v63, v36
	v_sub_f32_e32 v42, v38, v44
	v_mul_f32_e32 v36, v48, v36
	v_sub_f32_e32 v42, v50, v42
	v_add_f32_e32 v36, v42, v36
	v_add_f32_e32 v42, v38, v36
	v_cvt_f32_i32_e32 v60, v40
	v_mul_f32_e32 v44, v42, v42
	v_fmamk_f32 v48, v44, 0x3e9b6dac, v191
	v_fmaak_f32 v169, v44, v48, 0x3f2aaada
	v_mul_f32_e32 v61, v42, v44
	v_pk_mul_f32 v[74:75], v[60:61], v[168:169]
	v_ldexp_f32 v63, v42, 1
	v_fma_f32 v62, v60, s8, -v74
	v_fmac_f32_e32 v62, 0xb102e308, v60
	v_sub_f32_e32 v38, v42, v38
	v_pk_add_f32 v[60:61], v[74:75], v[62:63]
	v_sub_f32_e32 v36, v36, v38
	v_sub_f32_e32 v38, v61, v63
	v_ldexp_f32 v36, v36, 1
	v_sub_f32_e32 v38, v75, v38
	v_add_f32_e32 v77, v36, v38
	v_mov_b32_e32 v76, v74
	v_pk_add_f32 v[74:75], v[60:61], v[74:75] neg_lo:[0,1] neg_hi:[0,1]
	v_pk_add_f32 v[78:79], v[60:61], v[76:77]
	v_mov_b32_e32 v63, v60
	v_mov_b32_e32 v75, v79
	v_pk_add_f32 v[80:81], v[62:63], v[74:75] neg_lo:[0,1] neg_hi:[0,1]
	v_pk_add_f32 v[62:63], v[62:63], v[74:75]
	v_mov_b32_e32 v76, v77
	v_pk_add_f32 v[74:75], v[62:63], v[60:61] op_sel:[1,0] op_sel_hi:[0,1] neg_lo:[0,1] neg_hi:[0,1]
	v_pk_add_f32 v[82:83], v[78:79], v[74:75] op_sel_hi:[1,0] neg_lo:[0,1] neg_hi:[0,1]
	v_mov_b32_e32 v78, v79
	v_mov_b32_e32 v79, v63
	v_pk_mov_b32 v[74:75], v[60:61], v[74:75] op_sel:[1,0]
	v_mov_b32_e32 v77, v60
	v_pk_add_f32 v[74:75], v[78:79], v[74:75] neg_lo:[0,1] neg_hi:[0,1]
	v_mov_b32_e32 v82, v80
	v_pk_add_f32 v[60:61], v[76:77], v[74:75] neg_lo:[0,1] neg_hi:[0,1]
	v_mov_b32_e32 v81, v63
	v_pk_add_f32 v[74:75], v[82:83], v[60:61]
	s_nop 0
	v_pk_add_f32 v[76:77], v[74:75], v[74:75] op_sel:[0,1] op_sel_hi:[1,0]
	s_nop 0
	v_pk_add_f32 v[62:63], v[62:63], v[76:77] op_sel:[1,0] op_sel_hi:[0,1]
	v_mov_b32_e32 v75, v62
	v_pk_add_f32 v[78:79], v[74:75], v[80:81] neg_lo:[0,1] neg_hi:[0,1]
	v_mov_b32_e32 v61, v76
	v_sub_f32_e32 v36, v74, v78
	v_pk_add_f32 v[60:61], v[60:61], v[78:79] neg_lo:[0,1] neg_hi:[0,1]
	v_sub_f32_e32 v36, v80, v36
	v_add_f32_e32 v36, v60, v36
	v_add_f32_e32 v36, v36, v61
	v_add_f32_e32 v36, v62, v36
	v_cndmask_b32_e32 v36, v199, v36, vcc
	v_cmp_ngt_f32_e32 vcc, -1.0, v32
	v_lshl_add_u64 v[60:61], s[52:53], 0, v[46:47]
	v_lshl_add_u64 v[46:47], s[16:17], 0, v[46:47]
	v_cndmask_b32_e32 v36, v200, v36, vcc
	v_cmp_neq_f32_e32 vcc, -1.0, v32
	v_mov_b32_e32 v38, v227
	s_waitcnt vmcnt(0)
	v_add_f32_e32 v0, v0, v38
	v_cndmask_b32_e32 v36, v201, v36, vcc
	v_cmp_lt_f32_e64 vcc, |v32|, s10
	v_mul_f32_e32 v0, 0xbfb8aa3b, v0
	v_exp_f32_e32 v0, v0
	v_cndmask_b32_e32 v32, v36, v32, vcc
	v_mov_b32_e32 v36, v228
	v_mul_f32_e32 v32, 0xc1000000, v32
	v_add_f32_e32 v0, 1.0, v0
	v_rcp_f32_e32 v0, v0
	v_add_f32_e32 v1, v1, v38
	v_mul_f32_e32 v1, 0xbfb8aa3b, v1
	v_exp_f32_e32 v1, v1
	s_waitcnt vmcnt(0)
	v_add_f32_e32 v16, v16, v36
	v_mul_f32_e32 v16, 0xbfb8aa3b, v16
	v_exp_f32_e32 v16, v16
	v_add_f32_e32 v1, 1.0, v1
	v_rcp_f32_e32 v1, v1
	v_add_f32_e32 v16, 1.0, v16
	v_rcp_f32_e32 v16, v16
	s_nop 0
	v_mul_f32_e32 v16, v16, v32
	v_mul_f32_e32 v40, 0x3fb8aa3b, v16
	v_add_f32_e32 v16, v16, v16
	v_mul_f32_e32 v42, 0x3fb8aa3b, v16
	v_rndne_f32_e32 v42, v42
	v_fmamk_f32 v44, v42, 0xbf317218, v16
	v_fmac_f32_e32 v44, 0x3102e308, v42
	v_fmamk_f32 v46, v44, 0x395133b1, v192
	v_cmp_eq_f32_e32 vcc, s20, v42
	v_cvt_i32_f32_e32 v42, v42
	v_fmaak_f32 v46, v44, v46, 0x3c0887f9
	v_fmaak_f32 v46, v44, v46, 0x3d2aaa81
	v_fmaak_f32 v46, v44, v46, 0x3e2aaaab
	v_fma_f32 v46, v44, v46, 0.5
	v_ldexp_f32 v42, 1.0, v42
	v_mul_f32_e32 v46, v44, v46
	v_cndmask_b32_e32 v42, v42, v202, vcc
	v_fmac_f32_e32 v44, v44, v46
	v_add_f32_e32 v46, -1.0, v42
	v_fmac_f32_e32 v46, v42, v44
	v_add_f32_e32 v42, v46, v46
	v_cndmask_b32_e32 v42, v46, v42, vcc
	v_cmp_nlt_f32_e32 vcc, s21, v16
	v_exp_f32_e32 v40, v40
	s_nop 0
	v_cndmask_b32_e64 v42, v201, -v42, vcc
	v_cmp_gt_f32_e32 vcc, s22, v42
	v_mul_f32_e32 v44, 0x4f800000, v42
	s_nop 0
	v_cndmask_b32_e32 v42, v42, v44, vcc
	v_sqrt_f32_e32 v44, v42
	s_nop 0
	v_add_u32_e32 v46, -1, v44
	v_fma_f32 v47, -v46, v44, v42
	v_cmp_ge_f32_e64 s[0:1], 0, v47
	v_add_u32_e32 v47, 1, v44
	s_nop 0
	v_cndmask_b32_e64 v46, v44, v46, s[0:1]
	v_fma_f32 v44, -v47, v44, v42
	v_cmp_lt_f32_e64 s[0:1], 0, v44
	s_nop 1
	v_cndmask_b32_e64 v44, v46, v47, s[0:1]
	v_mul_f32_e32 v46, 0x37800000, v44
	v_cndmask_b32_e32 v44, v44, v46, vcc
	v_cmp_class_f32_e32 vcc, v42, v193
	s_nop 1
	v_cndmask_b32_e32 v42, v44, v42, vcc
	v_cmp_ngt_f32_e32 vcc, s23, v16
	s_nop 1
	v_cndmask_b32_e32 v16, 1.0, v42, vcc
	v_mul_f32_e32 v0, v0, v16
	v_mul_f32_e32 v0, v67, v0
	ds_write_b32 v73, v40 offset:128
	ds_write_b32 v73, v0 offset:36992
	v_add_f32_e32 v0, v17, v36
	v_mul_f32_e32 v0, 0xbfb8aa3b, v0
	v_exp_f32_e32 v0, v0
	s_nop 0
	v_add_f32_e32 v0, 1.0, v0
	v_rcp_f32_e32 v0, v0
	s_nop 0
	v_mul_f32_e32 v0, v0, v32
	v_mul_f32_e32 v16, 0x3fb8aa3b, v0
	v_add_f32_e32 v0, v0, v0
	v_mul_f32_e32 v17, 0x3fb8aa3b, v0
	v_rndne_f32_e32 v17, v17
	v_fmamk_f32 v40, v17, 0xbf317218, v0
	v_fmac_f32_e32 v40, 0x3102e308, v17
	v_fmamk_f32 v42, v40, 0x395133b1, v192
	v_cmp_eq_f32_e32 vcc, s20, v17
	v_cvt_i32_f32_e32 v17, v17
	v_fmaak_f32 v42, v40, v42, 0x3c0887f9
	v_fmaak_f32 v42, v40, v42, 0x3d2aaa81
	v_fmaak_f32 v42, v40, v42, 0x3e2aaaab
	v_fma_f32 v42, v40, v42, 0.5
	v_ldexp_f32 v17, 1.0, v17
	v_mul_f32_e32 v42, v40, v42
	v_cndmask_b32_e32 v17, v17, v202, vcc
	v_fmac_f32_e32 v40, v40, v42
	v_add_f32_e32 v42, -1.0, v17
	v_fmac_f32_e32 v42, v17, v40
	v_add_f32_e32 v17, v42, v42
	v_cndmask_b32_e32 v17, v42, v17, vcc
	v_cmp_nlt_f32_e32 vcc, s21, v0
	v_exp_f32_e32 v16, v16
	s_nop 0
	v_cndmask_b32_e64 v17, v201, -v17, vcc
	v_cmp_gt_f32_e32 vcc, s22, v17
	v_mul_f32_e32 v40, 0x4f800000, v17
	s_nop 0
	v_cndmask_b32_e32 v17, v17, v40, vcc
	v_sqrt_f32_e32 v40, v17
	s_nop 0
	v_add_u32_e32 v42, -1, v40
	v_fma_f32 v44, -v42, v40, v17
	v_cmp_ge_f32_e64 s[0:1], 0, v44
	v_add_u32_e32 v44, 1, v40
	s_nop 0
	v_cndmask_b32_e64 v42, v40, v42, s[0:1]
	v_fma_f32 v40, -v44, v40, v17
	v_cmp_lt_f32_e64 s[0:1], 0, v40
	s_nop 1
	v_cndmask_b32_e64 v40, v42, v44, s[0:1]
	v_mul_f32_e32 v42, 0x37800000, v40
	v_cndmask_b32_e32 v40, v40, v42, vcc
	v_cmp_class_f32_e32 vcc, v17, v193
	s_nop 1
	v_cndmask_b32_e32 v17, v40, v17, vcc
	v_cmp_ngt_f32_e32 vcc, s23, v0
	s_nop 1
	v_cndmask_b32_e32 v0, 1.0, v17, vcc
	v_mul_f32_e32 v0, v1, v0
	v_mul_f32_e32 v0, v49, v0
	ds_write_b32 v73, v16 offset:384
	ds_write_b32 v73, v0 offset:37248
	v_add_f32_e32 v0, v18, v36
	v_mul_f32_e32 v0, 0xbfb8aa3b, v0
	v_exp_f32_e32 v0, v0
	v_add_f32_e32 v1, v2, v38
	v_mul_f32_e32 v1, 0xbfb8aa3b, v1
	v_exp_f32_e32 v1, v1
	v_add_f32_e32 v0, 1.0, v0
	v_rcp_f32_e32 v0, v0
	v_add_f32_e32 v1, 1.0, v1
	v_rcp_f32_e32 v1, v1
	v_mul_f32_e32 v0, v0, v32
	v_mul_f32_e32 v2, 0x3fb8aa3b, v0
	v_add_f32_e32 v0, v0, v0
	v_mul_f32_e32 v16, 0x3fb8aa3b, v0
	v_rndne_f32_e32 v16, v16
	v_fmamk_f32 v17, v16, 0xbf317218, v0
	v_fmac_f32_e32 v17, 0x3102e308, v16
	v_fmamk_f32 v18, v17, 0x395133b1, v192
	v_cmp_eq_f32_e32 vcc, s20, v16
	v_cvt_i32_f32_e32 v16, v16
	v_fmaak_f32 v18, v17, v18, 0x3c0887f9
	v_fmaak_f32 v18, v17, v18, 0x3d2aaa81
	v_fmaak_f32 v18, v17, v18, 0x3e2aaaab
	v_fma_f32 v18, v17, v18, 0.5
	v_ldexp_f32 v16, 1.0, v16
	v_mul_f32_e32 v18, v17, v18
	v_cndmask_b32_e32 v16, v16, v202, vcc
	v_fmac_f32_e32 v17, v17, v18
	v_add_f32_e32 v18, -1.0, v16
	v_fmac_f32_e32 v18, v16, v17
	v_add_f32_e32 v16, v18, v18
	v_cndmask_b32_e32 v16, v18, v16, vcc
	v_cmp_nlt_f32_e32 vcc, s21, v0
	v_exp_f32_e32 v2, v2
	s_nop 0
	v_cndmask_b32_e64 v16, v201, -v16, vcc
	v_cmp_gt_f32_e32 vcc, s22, v16
	v_mul_f32_e32 v17, 0x4f800000, v16
	s_nop 0
	v_cndmask_b32_e32 v16, v16, v17, vcc
	v_sqrt_f32_e32 v17, v16
	s_nop 0
	v_add_u32_e32 v18, -1, v17
	v_fma_f32 v40, -v18, v17, v16
	v_cmp_ge_f32_e64 s[0:1], 0, v40
	v_add_u32_e32 v40, 1, v17
	s_nop 0
	v_cndmask_b32_e64 v18, v17, v18, s[0:1]
	v_fma_f32 v17, -v40, v17, v16
	v_cmp_lt_f32_e64 s[0:1], 0, v17
	s_nop 1
	v_cndmask_b32_e64 v17, v18, v40, s[0:1]
	v_mul_f32_e32 v18, 0x37800000, v17
	v_cndmask_b32_e32 v17, v17, v18, vcc
	v_cmp_class_f32_e32 vcc, v16, v193
	s_nop 1
	v_cndmask_b32_e32 v16, v17, v16, vcc
	v_cmp_ngt_f32_e32 vcc, s23, v0
	s_nop 1
	v_cndmask_b32_e32 v0, 1.0, v16, vcc
	v_mul_f32_e32 v0, v1, v0
	v_mul_f32_e32 v0, v69, v0
	ds_write_b32 v73, v2 offset:640
	ds_write_b32 v73, v0 offset:37504
	v_add_f32_e32 v0, v19, v36
	v_mul_f32_e32 v0, 0xbfb8aa3b, v0
	v_exp_f32_e32 v0, v0
	v_add_f32_e32 v1, v3, v38
	v_mul_f32_e32 v1, 0xbfb8aa3b, v1
	v_exp_f32_e32 v1, v1
	v_add_f32_e32 v0, 1.0, v0
	v_rcp_f32_e32 v0, v0
	v_add_f32_e32 v1, 1.0, v1
	v_rcp_f32_e32 v1, v1
	v_mul_f32_e32 v0, v0, v32
	v_mul_f32_e32 v2, 0x3fb8aa3b, v0
	v_add_f32_e32 v0, v0, v0
	v_mul_f32_e32 v3, 0x3fb8aa3b, v0
	v_rndne_f32_e32 v3, v3
	v_fmamk_f32 v16, v3, 0xbf317218, v0
	v_fmac_f32_e32 v16, 0x3102e308, v3
	v_fmamk_f32 v17, v16, 0x395133b1, v192
	v_cmp_eq_f32_e32 vcc, s20, v3
	v_cvt_i32_f32_e32 v3, v3
	v_fmaak_f32 v17, v16, v17, 0x3c0887f9
	v_fmaak_f32 v17, v16, v17, 0x3d2aaa81
	v_fmaak_f32 v17, v16, v17, 0x3e2aaaab
	v_fma_f32 v17, v16, v17, 0.5
	v_ldexp_f32 v3, 1.0, v3
	v_mul_f32_e32 v17, v16, v17
	v_cndmask_b32_e32 v3, v3, v202, vcc
	v_fmac_f32_e32 v16, v16, v17
	v_add_f32_e32 v17, -1.0, v3
	v_fmac_f32_e32 v17, v3, v16
	v_add_f32_e32 v3, v17, v17
	v_cndmask_b32_e32 v3, v17, v3, vcc
	v_cmp_nlt_f32_e32 vcc, s21, v0
	v_exp_f32_e32 v2, v2
	s_nop 0
	v_cndmask_b32_e64 v3, v201, -v3, vcc
	v_cmp_gt_f32_e32 vcc, s22, v3
	v_mul_f32_e32 v16, 0x4f800000, v3
	s_nop 0
	v_cndmask_b32_e32 v3, v3, v16, vcc
	v_sqrt_f32_e32 v16, v3
	s_nop 0
	v_add_u32_e32 v17, -1, v16
	v_fma_f32 v18, -v17, v16, v3
	v_cmp_ge_f32_e64 s[0:1], 0, v18
	v_add_u32_e32 v18, 1, v16
	s_nop 0
	v_cndmask_b32_e64 v17, v16, v17, s[0:1]
	v_fma_f32 v16, -v18, v16, v3
	v_cmp_lt_f32_e64 s[0:1], 0, v16
	s_nop 1
	v_cndmask_b32_e64 v16, v17, v18, s[0:1]
	v_mul_f32_e32 v17, 0x37800000, v16
	v_cndmask_b32_e32 v16, v16, v17, vcc
	v_cmp_class_f32_e32 vcc, v3, v193
	s_nop 1
	v_cndmask_b32_e32 v3, v16, v3, vcc
	v_cmp_ngt_f32_e32 vcc, s23, v0
	s_nop 1
	v_cndmask_b32_e32 v0, 1.0, v3, vcc
	v_mul_f32_e32 v0, v1, v0
	v_mul_f32_e32 v0, v51, v0
	ds_write_b32 v73, v2 offset:896
	ds_write_b32 v73, v0 offset:37760
	v_add_f32_e32 v0, v20, v36
	v_mul_f32_e32 v0, 0xbfb8aa3b, v0
	v_exp_f32_e32 v0, v0
	v_add_f32_e32 v1, v4, v38
	v_mul_f32_e32 v1, 0xbfb8aa3b, v1
	v_exp_f32_e32 v1, v1
	v_add_f32_e32 v0, 1.0, v0
	v_rcp_f32_e32 v0, v0
	v_add_f32_e32 v1, 1.0, v1
	v_rcp_f32_e32 v1, v1
	v_mul_f32_e32 v0, v0, v32
	v_mul_f32_e32 v2, 0x3fb8aa3b, v0
	v_add_f32_e32 v0, v0, v0
	v_mul_f32_e32 v3, 0x3fb8aa3b, v0
	v_rndne_f32_e32 v3, v3
	v_fmamk_f32 v4, v3, 0xbf317218, v0
	v_fmac_f32_e32 v4, 0x3102e308, v3
	v_fmamk_f32 v16, v4, 0x395133b1, v192
	v_cmp_eq_f32_e32 vcc, s20, v3
	v_cvt_i32_f32_e32 v3, v3
	v_fmaak_f32 v16, v4, v16, 0x3c0887f9
	v_fmaak_f32 v16, v4, v16, 0x3d2aaa81
	v_fmaak_f32 v16, v4, v16, 0x3e2aaaab
	v_fma_f32 v16, v4, v16, 0.5
	v_ldexp_f32 v3, 1.0, v3
	v_mul_f32_e32 v16, v4, v16
	v_cndmask_b32_e32 v3, v3, v202, vcc
	v_fmac_f32_e32 v4, v4, v16
	v_add_f32_e32 v16, -1.0, v3
	v_fmac_f32_e32 v16, v3, v4
	v_add_f32_e32 v3, v16, v16
	v_cndmask_b32_e32 v3, v16, v3, vcc
	v_cmp_nlt_f32_e32 vcc, s21, v0
	v_exp_f32_e32 v2, v2
	s_nop 0
	v_cndmask_b32_e64 v3, v201, -v3, vcc
	v_cmp_gt_f32_e32 vcc, s22, v3
	v_mul_f32_e32 v4, 0x4f800000, v3
	s_nop 0
	v_cndmask_b32_e32 v3, v3, v4, vcc
	v_sqrt_f32_e32 v4, v3
	s_nop 0
	v_add_u32_e32 v16, -1, v4
	v_fma_f32 v17, -v16, v4, v3
	v_cmp_ge_f32_e64 s[0:1], 0, v17
	v_add_u32_e32 v17, 1, v4
	s_nop 0
	v_cndmask_b32_e64 v16, v4, v16, s[0:1]
	v_fma_f32 v4, -v17, v4, v3
	v_cmp_lt_f32_e64 s[0:1], 0, v4
	s_nop 1
	v_cndmask_b32_e64 v4, v16, v17, s[0:1]
	v_mul_f32_e32 v16, 0x37800000, v4
	v_cndmask_b32_e32 v4, v4, v16, vcc
	v_cmp_class_f32_e32 vcc, v3, v193
	s_nop 1
	v_cndmask_b32_e32 v3, v4, v3, vcc
	v_cmp_ngt_f32_e32 vcc, s23, v0
	s_nop 1
	v_cndmask_b32_e32 v0, 1.0, v3, vcc
	v_mul_f32_e32 v0, v1, v0
	v_mul_f32_e32 v0, v71, v0
	ds_write_b32 v73, v2 offset:2176
	ds_write_b32 v73, v0 offset:39040
	v_add_f32_e32 v0, v21, v36
	v_mul_f32_e32 v0, 0xbfb8aa3b, v0
	v_exp_f32_e32 v0, v0
	v_add_f32_e32 v1, v5, v38
	v_mul_f32_e32 v1, 0xbfb8aa3b, v1
	v_exp_f32_e32 v1, v1
	v_add_f32_e32 v0, 1.0, v0
	v_rcp_f32_e32 v0, v0
	v_add_f32_e32 v1, 1.0, v1
	v_rcp_f32_e32 v1, v1
	v_mul_f32_e32 v0, v0, v32
	v_mul_f32_e32 v2, 0x3fb8aa3b, v0
	v_add_f32_e32 v0, v0, v0
	v_mul_f32_e32 v3, 0x3fb8aa3b, v0
	v_rndne_f32_e32 v3, v3
	v_fmamk_f32 v4, v3, 0xbf317218, v0
	v_fmac_f32_e32 v4, 0x3102e308, v3
	v_fmamk_f32 v5, v4, 0x395133b1, v192
	v_cmp_eq_f32_e32 vcc, s20, v3
	v_cvt_i32_f32_e32 v3, v3
	v_fmaak_f32 v5, v4, v5, 0x3c0887f9
	v_fmaak_f32 v5, v4, v5, 0x3d2aaa81
	v_fmaak_f32 v5, v4, v5, 0x3e2aaaab
	v_fma_f32 v5, v4, v5, 0.5
	v_ldexp_f32 v3, 1.0, v3
	v_mul_f32_e32 v5, v4, v5
	v_cndmask_b32_e32 v3, v3, v202, vcc
	v_fmac_f32_e32 v4, v4, v5
	v_add_f32_e32 v5, -1.0, v3
	v_fmac_f32_e32 v5, v3, v4
	v_add_f32_e32 v3, v5, v5
	v_cndmask_b32_e32 v3, v5, v3, vcc
	v_cmp_nlt_f32_e32 vcc, s21, v0
	v_exp_f32_e32 v2, v2
	s_nop 0
	v_cndmask_b32_e64 v3, v201, -v3, vcc
	v_cmp_gt_f32_e32 vcc, s22, v3
	v_mul_f32_e32 v4, 0x4f800000, v3
	s_nop 0
	v_cndmask_b32_e32 v3, v3, v4, vcc
	v_sqrt_f32_e32 v4, v3
	s_nop 0
	v_add_u32_e32 v5, -1, v4
	v_fma_f32 v16, -v5, v4, v3
	v_cmp_ge_f32_e64 s[0:1], 0, v16
	v_add_u32_e32 v16, 1, v4
	s_nop 0
	v_cndmask_b32_e64 v5, v4, v5, s[0:1]
	v_fma_f32 v4, -v16, v4, v3
	v_cmp_lt_f32_e64 s[0:1], 0, v4
	s_nop 1
	v_cndmask_b32_e64 v4, v5, v16, s[0:1]
	v_mul_f32_e32 v5, 0x37800000, v4
	v_cndmask_b32_e32 v4, v4, v5, vcc
	v_cmp_class_f32_e32 vcc, v3, v193
	s_nop 1
	v_cndmask_b32_e32 v3, v4, v3, vcc
	v_cmp_ngt_f32_e32 vcc, s23, v0
	s_nop 1
	v_cndmask_b32_e32 v0, 1.0, v3, vcc
	v_mul_f32_e32 v0, v1, v0
	v_mul_f32_e32 v0, v37, v0
	ds_write_b32 v73, v2 offset:2432
	ds_write_b32 v73, v0 offset:39296
	v_add_f32_e32 v0, v22, v36
	v_mul_f32_e32 v0, 0xbfb8aa3b, v0
	v_exp_f32_e32 v0, v0
	v_add_f32_e32 v1, v6, v38
	v_mul_f32_e32 v1, 0xbfb8aa3b, v1
	v_exp_f32_e32 v1, v1
	v_add_f32_e32 v0, 1.0, v0
	v_rcp_f32_e32 v0, v0
	v_add_f32_e32 v1, 1.0, v1
	v_rcp_f32_e32 v1, v1
	v_mul_f32_e32 v0, v0, v32
	v_mul_f32_e32 v2, 0x3fb8aa3b, v0
	v_add_f32_e32 v0, v0, v0
	v_mul_f32_e32 v3, 0x3fb8aa3b, v0
	v_rndne_f32_e32 v3, v3
	v_fmamk_f32 v4, v3, 0xbf317218, v0
	v_fmac_f32_e32 v4, 0x3102e308, v3
	v_fmamk_f32 v5, v4, 0x395133b1, v192
	v_cmp_eq_f32_e32 vcc, s20, v3
	v_cvt_i32_f32_e32 v3, v3
	v_fmaak_f32 v5, v4, v5, 0x3c0887f9
	v_fmaak_f32 v5, v4, v5, 0x3d2aaa81
	v_fmaak_f32 v5, v4, v5, 0x3e2aaaab
	v_fma_f32 v5, v4, v5, 0.5
	v_ldexp_f32 v3, 1.0, v3
	v_mul_f32_e32 v5, v4, v5
	v_cndmask_b32_e32 v3, v3, v202, vcc
	v_fmac_f32_e32 v4, v4, v5
	v_add_f32_e32 v5, -1.0, v3
	v_fmac_f32_e32 v5, v3, v4
	v_add_f32_e32 v3, v5, v5
	v_cndmask_b32_e32 v3, v5, v3, vcc
	v_cmp_nlt_f32_e32 vcc, s21, v0
	v_exp_f32_e32 v2, v2
	s_nop 0
	v_cndmask_b32_e64 v3, v201, -v3, vcc
	v_cmp_gt_f32_e32 vcc, s22, v3
	v_mul_f32_e32 v4, 0x4f800000, v3
	s_nop 0
	v_cndmask_b32_e32 v3, v3, v4, vcc
	v_sqrt_f32_e32 v4, v3
	s_nop 0
	v_add_u32_e32 v5, -1, v4
	v_fma_f32 v6, -v5, v4, v3
	v_cmp_ge_f32_e64 s[0:1], 0, v6
	v_add_u32_e32 v6, 1, v4
	s_nop 0
	v_cndmask_b32_e64 v5, v4, v5, s[0:1]
	v_fma_f32 v4, -v6, v4, v3
	v_cmp_lt_f32_e64 s[0:1], 0, v4
	s_nop 1
	v_cndmask_b32_e64 v4, v5, v6, s[0:1]
	v_mul_f32_e32 v5, 0x37800000, v4
	v_cndmask_b32_e32 v4, v4, v5, vcc
	v_cmp_class_f32_e32 vcc, v3, v193
	s_nop 1
	v_cndmask_b32_e32 v3, v4, v3, vcc
	v_cmp_ngt_f32_e32 vcc, s23, v0
	s_nop 1
	v_cndmask_b32_e32 v0, 1.0, v3, vcc
	v_mul_f32_e32 v0, v1, v0
	v_mul_f32_e32 v0, v53, v0
	ds_write_b32 v73, v2 offset:2688
	ds_write_b32 v73, v0 offset:39552
	v_add_f32_e32 v0, v23, v36
	v_mul_f32_e32 v0, 0xbfb8aa3b, v0
	v_exp_f32_e32 v0, v0
	v_add_f32_e32 v1, v7, v38
	v_mul_f32_e32 v1, 0xbfb8aa3b, v1
	v_exp_f32_e32 v1, v1
	v_add_f32_e32 v0, 1.0, v0
	v_rcp_f32_e32 v0, v0
	v_add_f32_e32 v1, 1.0, v1
	v_rcp_f32_e32 v1, v1
	v_mul_f32_e32 v0, v0, v32
	v_mul_f32_e32 v2, 0x3fb8aa3b, v0
	v_add_f32_e32 v0, v0, v0
	v_mul_f32_e32 v3, 0x3fb8aa3b, v0
	v_rndne_f32_e32 v3, v3
	v_fmamk_f32 v4, v3, 0xbf317218, v0
	v_fmac_f32_e32 v4, 0x3102e308, v3
	v_fmamk_f32 v5, v4, 0x395133b1, v192
	v_cmp_eq_f32_e32 vcc, s20, v3
	v_cvt_i32_f32_e32 v3, v3
	v_fmaak_f32 v5, v4, v5, 0x3c0887f9
	v_fmaak_f32 v5, v4, v5, 0x3d2aaa81
	v_fmaak_f32 v5, v4, v5, 0x3e2aaaab
	v_fma_f32 v5, v4, v5, 0.5
	v_ldexp_f32 v3, 1.0, v3
	v_mul_f32_e32 v5, v4, v5
	v_cndmask_b32_e32 v3, v3, v202, vcc
	v_fmac_f32_e32 v4, v4, v5
	v_add_f32_e32 v5, -1.0, v3
	v_fmac_f32_e32 v5, v3, v4
	v_add_f32_e32 v3, v5, v5
	v_cndmask_b32_e32 v3, v5, v3, vcc
	v_cmp_nlt_f32_e32 vcc, s21, v0
	v_exp_f32_e32 v2, v2
	s_nop 0
	v_cndmask_b32_e64 v3, v201, -v3, vcc
	v_cmp_gt_f32_e32 vcc, s22, v3
	v_mul_f32_e32 v4, 0x4f800000, v3
	s_nop 0
	v_cndmask_b32_e32 v3, v3, v4, vcc
	v_sqrt_f32_e32 v4, v3
	s_nop 0
	v_add_u32_e32 v5, -1, v4
	v_fma_f32 v6, -v5, v4, v3
	v_cmp_ge_f32_e64 s[0:1], 0, v6
	v_add_u32_e32 v6, 1, v4
	s_nop 0
	v_cndmask_b32_e64 v5, v4, v5, s[0:1]
	v_fma_f32 v4, -v6, v4, v3
	v_cmp_lt_f32_e64 s[0:1], 0, v4
	s_nop 1
	v_cndmask_b32_e64 v4, v5, v6, s[0:1]
	v_mul_f32_e32 v5, 0x37800000, v4
	v_cndmask_b32_e32 v4, v4, v5, vcc
	v_cmp_class_f32_e32 vcc, v3, v193
	s_nop 1
	v_cndmask_b32_e32 v3, v4, v3, vcc
	v_cmp_ngt_f32_e32 vcc, s23, v0
	s_nop 1
	v_cndmask_b32_e32 v0, 1.0, v3, vcc
	v_mul_f32_e32 v0, v1, v0
	v_mul_f32_e32 v0, v39, v0
	ds_write_b32 v73, v2 offset:2944
	ds_write_b32 v73, v0 offset:39808
	v_add_f32_e32 v0, v24, v36
	v_mul_f32_e32 v0, 0xbfb8aa3b, v0
	v_exp_f32_e32 v0, v0
	v_add_f32_e32 v1, v8, v38
	v_mul_f32_e32 v1, 0xbfb8aa3b, v1
	v_exp_f32_e32 v1, v1
	v_add_f32_e32 v0, 1.0, v0
	v_rcp_f32_e32 v0, v0
	v_add_f32_e32 v1, 1.0, v1
	v_rcp_f32_e32 v1, v1
	v_mul_f32_e32 v0, v0, v32
	v_mul_f32_e32 v2, 0x3fb8aa3b, v0
	v_add_f32_e32 v0, v0, v0
	v_mul_f32_e32 v3, 0x3fb8aa3b, v0
	v_rndne_f32_e32 v3, v3
	v_fmamk_f32 v4, v3, 0xbf317218, v0
	v_fmac_f32_e32 v4, 0x3102e308, v3
	v_fmamk_f32 v5, v4, 0x395133b1, v192
	v_cmp_eq_f32_e32 vcc, s20, v3
	v_cvt_i32_f32_e32 v3, v3
	v_fmaak_f32 v5, v4, v5, 0x3c0887f9
	v_fmaak_f32 v5, v4, v5, 0x3d2aaa81
	v_fmaak_f32 v5, v4, v5, 0x3e2aaaab
	v_fma_f32 v5, v4, v5, 0.5
	v_ldexp_f32 v3, 1.0, v3
	v_mul_f32_e32 v5, v4, v5
	v_cndmask_b32_e32 v3, v3, v202, vcc
	v_fmac_f32_e32 v4, v4, v5
	v_add_f32_e32 v5, -1.0, v3
	v_fmac_f32_e32 v5, v3, v4
	v_add_f32_e32 v3, v5, v5
	v_cndmask_b32_e32 v3, v5, v3, vcc
	v_cmp_nlt_f32_e32 vcc, s21, v0
	v_exp_f32_e32 v2, v2
	s_nop 0
	v_cndmask_b32_e64 v3, v201, -v3, vcc
	v_cmp_gt_f32_e32 vcc, s22, v3
	v_mul_f32_e32 v4, 0x4f800000, v3
	s_nop 0
	v_cndmask_b32_e32 v3, v3, v4, vcc
	v_sqrt_f32_e32 v4, v3
	s_nop 0
	v_add_u32_e32 v5, -1, v4
	v_fma_f32 v6, -v5, v4, v3
	v_cmp_ge_f32_e64 s[0:1], 0, v6
	v_add_u32_e32 v6, 1, v4
	s_nop 0
	v_cndmask_b32_e64 v5, v4, v5, s[0:1]
	v_fma_f32 v4, -v6, v4, v3
	v_cmp_lt_f32_e64 s[0:1], 0, v4
	s_nop 1
	v_cndmask_b32_e64 v4, v5, v6, s[0:1]
	v_mul_f32_e32 v5, 0x37800000, v4
	v_cndmask_b32_e32 v4, v4, v5, vcc
	v_cmp_class_f32_e32 vcc, v3, v193
	s_nop 1
	v_cndmask_b32_e32 v3, v4, v3, vcc
	v_cmp_ngt_f32_e32 vcc, s23, v0
	s_nop 1
	v_cndmask_b32_e32 v0, 1.0, v3, vcc
	v_mul_f32_e32 v0, v1, v0
	v_mul_f32_e32 v0, v55, v0
	ds_write_b32 v73, v2 offset:4224
	ds_write_b32 v73, v0 offset:41088
	v_add_f32_e32 v0, v25, v36
	v_mul_f32_e32 v0, 0xbfb8aa3b, v0
	v_exp_f32_e32 v0, v0
	v_add_f32_e32 v1, v9, v38
	v_mul_f32_e32 v1, 0xbfb8aa3b, v1
	v_exp_f32_e32 v1, v1
	v_add_f32_e32 v0, 1.0, v0
	v_rcp_f32_e32 v0, v0
	v_add_f32_e32 v1, 1.0, v1
	v_rcp_f32_e32 v1, v1
	v_mul_f32_e32 v0, v0, v32
	v_mul_f32_e32 v2, 0x3fb8aa3b, v0
	v_add_f32_e32 v0, v0, v0
	v_mul_f32_e32 v3, 0x3fb8aa3b, v0
	v_rndne_f32_e32 v3, v3
	v_fmamk_f32 v4, v3, 0xbf317218, v0
	v_fmac_f32_e32 v4, 0x3102e308, v3
	v_fmamk_f32 v5, v4, 0x395133b1, v192
	v_cmp_eq_f32_e32 vcc, s20, v3
	v_cvt_i32_f32_e32 v3, v3
	v_fmaak_f32 v5, v4, v5, 0x3c0887f9
	v_fmaak_f32 v5, v4, v5, 0x3d2aaa81
	v_fmaak_f32 v5, v4, v5, 0x3e2aaaab
	v_fma_f32 v5, v4, v5, 0.5
	v_ldexp_f32 v3, 1.0, v3
	v_mul_f32_e32 v5, v4, v5
	v_cndmask_b32_e32 v3, v3, v202, vcc
	v_fmac_f32_e32 v4, v4, v5
	v_add_f32_e32 v5, -1.0, v3
	v_fmac_f32_e32 v5, v3, v4
	v_add_f32_e32 v3, v5, v5
	v_cndmask_b32_e32 v3, v5, v3, vcc
	v_cmp_nlt_f32_e32 vcc, s21, v0
	v_exp_f32_e32 v2, v2
	s_nop 0
	v_cndmask_b32_e64 v3, v201, -v3, vcc
	v_cmp_gt_f32_e32 vcc, s22, v3
	v_mul_f32_e32 v4, 0x4f800000, v3
	s_nop 0
	v_cndmask_b32_e32 v3, v3, v4, vcc
	v_sqrt_f32_e32 v4, v3
	s_nop 0
	v_add_u32_e32 v5, -1, v4
	v_fma_f32 v6, -v5, v4, v3
	v_cmp_ge_f32_e64 s[0:1], 0, v6
	v_add_u32_e32 v6, 1, v4
	s_nop 0
	v_cndmask_b32_e64 v5, v4, v5, s[0:1]
	v_fma_f32 v4, -v6, v4, v3
	v_cmp_lt_f32_e64 s[0:1], 0, v4
	s_nop 1
	v_cndmask_b32_e64 v4, v5, v6, s[0:1]
	v_mul_f32_e32 v5, 0x37800000, v4
	v_cndmask_b32_e32 v4, v4, v5, vcc
	v_cmp_class_f32_e32 vcc, v3, v193
	s_nop 1
	v_cndmask_b32_e32 v3, v4, v3, vcc
	v_cmp_ngt_f32_e32 vcc, s23, v0
	s_nop 1
	v_cndmask_b32_e32 v0, 1.0, v3, vcc
	v_mul_f32_e32 v0, v1, v0
	v_mul_f32_e32 v0, v41, v0
	ds_write_b32 v73, v2 offset:4480
	ds_write_b32 v73, v0 offset:41344
	v_add_f32_e32 v0, v26, v36
	v_mul_f32_e32 v0, 0xbfb8aa3b, v0
	v_exp_f32_e32 v0, v0
	v_add_f32_e32 v1, v10, v38
	v_mul_f32_e32 v1, 0xbfb8aa3b, v1
	v_exp_f32_e32 v1, v1
	v_add_f32_e32 v0, 1.0, v0
	v_rcp_f32_e32 v0, v0
	v_add_f32_e32 v1, 1.0, v1
	v_rcp_f32_e32 v1, v1
	v_mul_f32_e32 v0, v0, v32
	v_mul_f32_e32 v2, 0x3fb8aa3b, v0
	v_add_f32_e32 v0, v0, v0
	v_mul_f32_e32 v3, 0x3fb8aa3b, v0
	v_rndne_f32_e32 v3, v3
	v_fmamk_f32 v4, v3, 0xbf317218, v0
	v_fmac_f32_e32 v4, 0x3102e308, v3
	v_fmamk_f32 v5, v4, 0x395133b1, v192
	v_cmp_eq_f32_e32 vcc, s20, v3
	v_cvt_i32_f32_e32 v3, v3
	v_fmaak_f32 v5, v4, v5, 0x3c0887f9
	v_fmaak_f32 v5, v4, v5, 0x3d2aaa81
	v_fmaak_f32 v5, v4, v5, 0x3e2aaaab
	v_fma_f32 v5, v4, v5, 0.5
	v_ldexp_f32 v3, 1.0, v3
	v_mul_f32_e32 v5, v4, v5
	v_cndmask_b32_e32 v3, v3, v202, vcc
	v_fmac_f32_e32 v4, v4, v5
	v_add_f32_e32 v5, -1.0, v3
	v_fmac_f32_e32 v5, v3, v4
	v_add_f32_e32 v3, v5, v5
	v_cndmask_b32_e32 v3, v5, v3, vcc
	v_cmp_nlt_f32_e32 vcc, s21, v0
	v_exp_f32_e32 v2, v2
	s_nop 0
	v_cndmask_b32_e64 v3, v201, -v3, vcc
	v_cmp_gt_f32_e32 vcc, s22, v3
	v_mul_f32_e32 v4, 0x4f800000, v3
	s_nop 0
	v_cndmask_b32_e32 v3, v3, v4, vcc
	v_sqrt_f32_e32 v4, v3
	s_nop 0
	v_add_u32_e32 v5, -1, v4
	v_fma_f32 v6, -v5, v4, v3
	v_cmp_ge_f32_e64 s[0:1], 0, v6
	v_add_u32_e32 v6, 1, v4
	s_nop 0
	v_cndmask_b32_e64 v5, v4, v5, s[0:1]
	v_fma_f32 v4, -v6, v4, v3
	v_cmp_lt_f32_e64 s[0:1], 0, v4
	s_nop 1
	v_cndmask_b32_e64 v4, v5, v6, s[0:1]
	v_mul_f32_e32 v5, 0x37800000, v4
	v_cndmask_b32_e32 v4, v4, v5, vcc
	v_cmp_class_f32_e32 vcc, v3, v193
	s_nop 1
	v_cndmask_b32_e32 v3, v4, v3, vcc
	v_cmp_ngt_f32_e32 vcc, s23, v0
	s_nop 1
	v_cndmask_b32_e32 v0, 1.0, v3, vcc
	v_mul_f32_e32 v0, v1, v0
	v_mul_f32_e32 v0, v57, v0
	ds_write_b32 v73, v2 offset:4736
	ds_write_b32 v73, v0 offset:41600
	v_add_f32_e32 v0, v27, v36
	v_mul_f32_e32 v0, 0xbfb8aa3b, v0
	v_exp_f32_e32 v0, v0
	v_add_f32_e32 v1, v11, v38
	v_mul_f32_e32 v1, 0xbfb8aa3b, v1
	v_exp_f32_e32 v1, v1
	v_add_f32_e32 v0, 1.0, v0
	v_rcp_f32_e32 v0, v0
	v_add_f32_e32 v1, 1.0, v1
	v_rcp_f32_e32 v1, v1
	v_mul_f32_e32 v0, v0, v32
	v_mul_f32_e32 v2, 0x3fb8aa3b, v0
	v_add_f32_e32 v0, v0, v0
	v_mul_f32_e32 v3, 0x3fb8aa3b, v0
	v_rndne_f32_e32 v3, v3
	v_fmamk_f32 v4, v3, 0xbf317218, v0
	v_fmac_f32_e32 v4, 0x3102e308, v3
	v_fmamk_f32 v5, v4, 0x395133b1, v192
	v_cmp_eq_f32_e32 vcc, s20, v3
	v_cvt_i32_f32_e32 v3, v3
	v_fmaak_f32 v5, v4, v5, 0x3c0887f9
	v_fmaak_f32 v5, v4, v5, 0x3d2aaa81
	v_fmaak_f32 v5, v4, v5, 0x3e2aaaab
	v_fma_f32 v5, v4, v5, 0.5
	v_ldexp_f32 v3, 1.0, v3
	v_mul_f32_e32 v5, v4, v5
	v_cndmask_b32_e32 v3, v3, v202, vcc
	v_fmac_f32_e32 v4, v4, v5
	v_add_f32_e32 v5, -1.0, v3
	v_fmac_f32_e32 v5, v3, v4
	v_add_f32_e32 v3, v5, v5
	v_cndmask_b32_e32 v3, v5, v3, vcc
	v_cmp_nlt_f32_e32 vcc, s21, v0
	v_exp_f32_e32 v2, v2
	s_nop 0
	v_cndmask_b32_e64 v3, v201, -v3, vcc
	v_cmp_gt_f32_e32 vcc, s22, v3
	v_mul_f32_e32 v4, 0x4f800000, v3
	s_nop 0
	v_cndmask_b32_e32 v3, v3, v4, vcc
	v_sqrt_f32_e32 v4, v3
	s_nop 0
	v_add_u32_e32 v5, -1, v4
	v_fma_f32 v6, -v5, v4, v3
	v_cmp_ge_f32_e64 s[0:1], 0, v6
	v_add_u32_e32 v6, 1, v4
	s_nop 0
	v_cndmask_b32_e64 v5, v4, v5, s[0:1]
	v_fma_f32 v4, -v6, v4, v3
	v_cmp_lt_f32_e64 s[0:1], 0, v4
	s_nop 1
	v_cndmask_b32_e64 v4, v5, v6, s[0:1]
	v_mul_f32_e32 v5, 0x37800000, v4
	v_cndmask_b32_e32 v4, v4, v5, vcc
	v_cmp_class_f32_e32 vcc, v3, v193
	s_nop 1
	v_cndmask_b32_e32 v3, v4, v3, vcc
	v_cmp_ngt_f32_e32 vcc, s23, v0
	s_nop 1
	v_cndmask_b32_e32 v0, 1.0, v3, vcc
	v_mul_f32_e32 v0, v1, v0
	v_mul_f32_e32 v0, v43, v0
	ds_write_b32 v73, v2 offset:4992
	ds_write_b32 v73, v0 offset:41856
	v_add_f32_e32 v0, v28, v36
	v_mul_f32_e32 v0, 0xbfb8aa3b, v0
	v_exp_f32_e32 v0, v0
	v_add_f32_e32 v1, v12, v38
	v_mul_f32_e32 v1, 0xbfb8aa3b, v1
	v_exp_f32_e32 v1, v1
	v_add_f32_e32 v0, 1.0, v0
	v_rcp_f32_e32 v0, v0
	v_add_f32_e32 v1, 1.0, v1
	v_rcp_f32_e32 v1, v1
	v_mul_f32_e32 v0, v0, v32
	v_mul_f32_e32 v2, 0x3fb8aa3b, v0
	v_add_f32_e32 v0, v0, v0
	v_mul_f32_e32 v3, 0x3fb8aa3b, v0
	v_rndne_f32_e32 v3, v3
	v_fmamk_f32 v4, v3, 0xbf317218, v0
	v_fmac_f32_e32 v4, 0x3102e308, v3
	v_fmamk_f32 v5, v4, 0x395133b1, v192
	v_cmp_eq_f32_e32 vcc, s20, v3
	v_cvt_i32_f32_e32 v3, v3
	v_fmaak_f32 v5, v4, v5, 0x3c0887f9
	v_fmaak_f32 v5, v4, v5, 0x3d2aaa81
	v_fmaak_f32 v5, v4, v5, 0x3e2aaaab
	v_fma_f32 v5, v4, v5, 0.5
	v_ldexp_f32 v3, 1.0, v3
	v_mul_f32_e32 v5, v4, v5
	v_cndmask_b32_e32 v3, v3, v202, vcc
	v_fmac_f32_e32 v4, v4, v5
	v_add_f32_e32 v5, -1.0, v3
	v_fmac_f32_e32 v5, v3, v4
	v_add_f32_e32 v3, v5, v5
	v_cndmask_b32_e32 v3, v5, v3, vcc
	v_cmp_nlt_f32_e32 vcc, s21, v0
	v_exp_f32_e32 v2, v2
	s_nop 0
	v_cndmask_b32_e64 v3, v201, -v3, vcc
	v_cmp_gt_f32_e32 vcc, s22, v3
	v_mul_f32_e32 v4, 0x4f800000, v3
	s_nop 0
	v_cndmask_b32_e32 v3, v3, v4, vcc
	v_sqrt_f32_e32 v4, v3
	s_nop 0
	v_add_u32_e32 v5, -1, v4
	v_fma_f32 v6, -v5, v4, v3
	v_cmp_ge_f32_e64 s[0:1], 0, v6
	v_add_u32_e32 v6, 1, v4
	s_nop 0
	v_cndmask_b32_e64 v5, v4, v5, s[0:1]
	v_fma_f32 v4, -v6, v4, v3
	v_cmp_lt_f32_e64 s[0:1], 0, v4
	s_nop 1
	v_cndmask_b32_e64 v4, v5, v6, s[0:1]
	v_mul_f32_e32 v5, 0x37800000, v4
	v_cndmask_b32_e32 v4, v4, v5, vcc
	v_cmp_class_f32_e32 vcc, v3, v193
	s_nop 1
	v_cndmask_b32_e32 v3, v4, v3, vcc
	v_cmp_ngt_f32_e32 vcc, s23, v0
	s_nop 1
	v_cndmask_b32_e32 v0, 1.0, v3, vcc
	v_mul_f32_e32 v0, v1, v0
	v_mul_f32_e32 v0, v59, v0
	ds_write_b32 v73, v2 offset:6272
	ds_write_b32 v73, v0 offset:43136
	v_add_f32_e32 v0, v29, v36
	v_mul_f32_e32 v0, 0xbfb8aa3b, v0
	v_exp_f32_e32 v0, v0
	v_add_f32_e32 v1, v13, v38
	v_mul_f32_e32 v1, 0xbfb8aa3b, v1
	v_exp_f32_e32 v1, v1
	v_add_f32_e32 v0, 1.0, v0
	v_rcp_f32_e32 v0, v0
	v_add_f32_e32 v1, 1.0, v1
	v_rcp_f32_e32 v1, v1
	v_mul_f32_e32 v0, v0, v32
	v_mul_f32_e32 v2, 0x3fb8aa3b, v0
	v_add_f32_e32 v0, v0, v0
	v_mul_f32_e32 v3, 0x3fb8aa3b, v0
	v_rndne_f32_e32 v3, v3
	v_fmamk_f32 v4, v3, 0xbf317218, v0
	v_fmac_f32_e32 v4, 0x3102e308, v3
	v_fmamk_f32 v5, v4, 0x395133b1, v192
	v_cmp_eq_f32_e32 vcc, s20, v3
	v_cvt_i32_f32_e32 v3, v3
	v_fmaak_f32 v5, v4, v5, 0x3c0887f9
	v_fmaak_f32 v5, v4, v5, 0x3d2aaa81
	v_fmaak_f32 v5, v4, v5, 0x3e2aaaab
	v_fma_f32 v5, v4, v5, 0.5
	v_ldexp_f32 v3, 1.0, v3
	v_mul_f32_e32 v5, v4, v5
	v_cndmask_b32_e32 v3, v3, v202, vcc
	v_fmac_f32_e32 v4, v4, v5
	v_add_f32_e32 v5, -1.0, v3
	v_fmac_f32_e32 v5, v3, v4
	v_add_f32_e32 v3, v5, v5
	v_cndmask_b32_e32 v3, v5, v3, vcc
	v_cmp_nlt_f32_e32 vcc, s21, v0
	v_exp_f32_e32 v2, v2
	s_nop 0
	v_cndmask_b32_e64 v3, v201, -v3, vcc
	v_cmp_gt_f32_e32 vcc, s22, v3
	v_mul_f32_e32 v4, 0x4f800000, v3
	s_nop 0
	v_cndmask_b32_e32 v3, v3, v4, vcc
	v_sqrt_f32_e32 v4, v3
	s_nop 0
	v_add_u32_e32 v5, -1, v4
	v_fma_f32 v6, -v5, v4, v3
	v_cmp_ge_f32_e64 s[0:1], 0, v6
	v_add_u32_e32 v6, 1, v4
	s_nop 0
	v_cndmask_b32_e64 v5, v4, v5, s[0:1]
	v_fma_f32 v4, -v6, v4, v3
	v_cmp_lt_f32_e64 s[0:1], 0, v4
	s_nop 1
	v_cndmask_b32_e64 v4, v5, v6, s[0:1]
	v_mul_f32_e32 v5, 0x37800000, v4
	v_cndmask_b32_e32 v4, v4, v5, vcc
	v_cmp_class_f32_e32 vcc, v3, v193
	s_nop 1
	v_cndmask_b32_e32 v3, v4, v3, vcc
	v_cmp_ngt_f32_e32 vcc, s23, v0
	s_nop 1
	v_cndmask_b32_e32 v0, 1.0, v3, vcc
	v_mul_f32_e32 v0, v1, v0
	v_mul_f32_e32 v0, v45, v0
	ds_write_b32 v73, v2 offset:6528
	ds_write_b32 v73, v0 offset:43392
	v_add_f32_e32 v0, v30, v36
	v_mul_f32_e32 v0, 0xbfb8aa3b, v0
	v_exp_f32_e32 v0, v0
	v_add_f32_e32 v1, v14, v38
	v_mul_f32_e32 v1, 0xbfb8aa3b, v1
	v_exp_f32_e32 v1, v1
	v_add_f32_e32 v0, 1.0, v0
	v_rcp_f32_e32 v0, v0
	v_add_f32_e32 v1, 1.0, v1
	v_rcp_f32_e32 v1, v1
	v_mul_f32_e32 v0, v0, v32
	v_mul_f32_e32 v2, 0x3fb8aa3b, v0
	v_add_f32_e32 v0, v0, v0
	v_mul_f32_e32 v3, 0x3fb8aa3b, v0
	v_rndne_f32_e32 v3, v3
	v_fmamk_f32 v4, v3, 0xbf317218, v0
	v_fmac_f32_e32 v4, 0x3102e308, v3
	v_fmamk_f32 v5, v4, 0x395133b1, v192
	v_cmp_eq_f32_e32 vcc, s20, v3
	v_cvt_i32_f32_e32 v3, v3
	v_fmaak_f32 v5, v4, v5, 0x3c0887f9
	v_fmaak_f32 v5, v4, v5, 0x3d2aaa81
	v_fmaak_f32 v5, v4, v5, 0x3e2aaaab
	v_fma_f32 v5, v4, v5, 0.5
	v_ldexp_f32 v3, 1.0, v3
	v_mul_f32_e32 v5, v4, v5
	v_cndmask_b32_e32 v3, v3, v202, vcc
	v_fmac_f32_e32 v4, v4, v5
	v_add_f32_e32 v5, -1.0, v3
	v_fmac_f32_e32 v5, v3, v4
	v_add_f32_e32 v3, v5, v5
	v_cndmask_b32_e32 v3, v5, v3, vcc
	v_cmp_nlt_f32_e32 vcc, s21, v0
	v_exp_f32_e32 v2, v2
	s_nop 0
	v_cndmask_b32_e64 v3, v201, -v3, vcc
	v_cmp_gt_f32_e32 vcc, s22, v3
	v_mul_f32_e32 v4, 0x4f800000, v3
	s_nop 0
	v_cndmask_b32_e32 v3, v3, v4, vcc
	v_sqrt_f32_e32 v4, v3
	s_nop 0
	v_add_u32_e32 v5, -1, v4
	v_fma_f32 v6, -v5, v4, v3
	v_cmp_ge_f32_e64 s[0:1], 0, v6
	v_add_u32_e32 v6, 1, v4
	s_nop 0
	v_cndmask_b32_e64 v5, v4, v5, s[0:1]
	v_fma_f32 v4, -v6, v4, v3
	v_cmp_lt_f32_e64 s[0:1], 0, v4
	s_nop 1
	v_cndmask_b32_e64 v4, v5, v6, s[0:1]
	v_mul_f32_e32 v5, 0x37800000, v4
	v_cndmask_b32_e32 v4, v4, v5, vcc
	v_cmp_class_f32_e32 vcc, v3, v193
	s_nop 1
	v_cndmask_b32_e32 v3, v4, v3, vcc
	v_cmp_ngt_f32_e32 vcc, s23, v0
	s_nop 1
	v_cndmask_b32_e32 v0, 1.0, v3, vcc
	v_mul_f32_e32 v0, v1, v0
	v_mul_f32_e32 v0, v35, v0
	v_add_u32_e32 v1, 0x1800, v73
	ds_write2_b32 v1, v2, v34 offset0:160 offset1:192
	ds_write_b32 v73, v0 offset:43648
	v_add_f32_e32 v0, v31, v36
	v_mul_f32_e32 v0, 0xbfb8aa3b, v0
	v_exp_f32_e32 v0, v0
	v_add_f32_e32 v1, v15, v38
	v_mul_f32_e32 v1, 0xbfb8aa3b, v1
	v_exp_f32_e32 v1, v1
	v_add_f32_e32 v0, 1.0, v0
	v_rcp_f32_e32 v0, v0
	v_add_f32_e32 v1, 1.0, v1
	v_rcp_f32_e32 v1, v1
	v_mul_f32_e32 v0, v0, v32
	v_mul_f32_e32 v2, 0x3fb8aa3b, v0
	v_add_f32_e32 v0, v0, v0
	v_mul_f32_e32 v3, 0x3fb8aa3b, v0
	v_rndne_f32_e32 v3, v3
	v_fmamk_f32 v4, v3, 0xbf317218, v0
	v_fmac_f32_e32 v4, 0x3102e308, v3
	v_fmamk_f32 v5, v4, 0x395133b1, v192
	v_cmp_eq_f32_e32 vcc, s20, v3
	v_cvt_i32_f32_e32 v3, v3
	v_fmaak_f32 v5, v4, v5, 0x3c0887f9
	v_fmaak_f32 v5, v4, v5, 0x3d2aaa81
	v_fmaak_f32 v5, v4, v5, 0x3e2aaaab
	v_fma_f32 v5, v4, v5, 0.5
	v_ldexp_f32 v3, 1.0, v3
	v_mul_f32_e32 v5, v4, v5
	v_cndmask_b32_e32 v3, v3, v202, vcc
	v_fmac_f32_e32 v4, v4, v5
	v_add_f32_e32 v5, -1.0, v3
	v_fmac_f32_e32 v5, v3, v4
	v_add_f32_e32 v3, v5, v5
	v_cndmask_b32_e32 v3, v5, v3, vcc
	v_cmp_nlt_f32_e32 vcc, s21, v0
	v_exp_f32_e32 v2, v2
	s_nop 0
	v_cndmask_b32_e64 v3, v201, -v3, vcc
	v_cmp_gt_f32_e32 vcc, s22, v3
	v_mul_f32_e32 v4, 0x4f800000, v3
	s_nop 0
	v_cndmask_b32_e32 v3, v3, v4, vcc
	v_sqrt_f32_e32 v4, v3
	s_nop 0
	v_add_u32_e32 v5, -1, v4
	v_fma_f32 v6, -v5, v4, v3
	v_cmp_ge_f32_e64 s[0:1], 0, v6
	v_add_u32_e32 v6, 1, v4
	s_nop 0
	v_cndmask_b32_e64 v5, v4, v5, s[0:1]
	v_fma_f32 v4, -v6, v4, v3
	v_cmp_lt_f32_e64 s[0:1], 0, v4
	s_nop 1
	v_cndmask_b32_e64 v4, v5, v6, s[0:1]
	v_mul_f32_e32 v5, 0x37800000, v4
	v_cndmask_b32_e32 v4, v4, v5, vcc
	v_cmp_class_f32_e32 vcc, v3, v193
	s_nop 1
	v_cndmask_b32_e32 v3, v4, v3, vcc
	v_cmp_ngt_f32_e32 vcc, s23, v0
	s_nop 1
	v_cndmask_b32_e32 v0, 1.0, v3, vcc
	v_mul_f32_e32 v0, v1, v0
	v_mul_f32_e32 v0, v33, v0
	ds_write_b32 v73, v2 offset:7040
	ds_write_b32 v73, v0 offset:43904
	s_waitcnt lgkmcnt(0)
	s_barrier
	s_cbranch_scc1 .LBB0_866
	v_lshl_add_u64 v[0:1], v[64:65], 0, s[4:5]
	global_load_dwordx2 v[98:99], v[0:1], off
	s_cmp_eq_u32 s12, 1
	s_waitcnt vmcnt(0)
	v_fmac_f32_e32 v99, 0, v98
	s_cbranch_scc1 .LBB0_867
	v_add_co_u32_e32 v0, vcc, 0x1000, v0
	s_cmp_eq_u32 s12, 2
	s_nop 0
	v_addc_co_u32_e32 v1, vcc, 0, v1, vcc
	global_load_dwordx2 v[0:1], v[0:1], off
	s_waitcnt vmcnt(0)
	v_fmac_f32_e32 v1, v99, v0
	s_cbranch_scc1 .LBB0_865
	v_readlane_b32 s0, v248, 32
	s_mul_i32 s46, s11, 36
	s_add_i32 s0, s0, s75
	s_mov_b32 s47, s5
	s_sub_i32 s0, s0, s70
	s_lshl_b64 s[44:45], s[46:47], 12
	v_readlane_b32 s1, v249, 45
	s_add_u32 s44, s1, s44
	v_readlane_b32 s1, v249, 46
	v_add_lshl_u32 v96, s13, v141, 3
	s_addc_u32 s45, s1, s45
	v_lshl_add_u64 v[2:3], s[44:45], 0, v[96:97]
	s_mov_b64 s[8:9], 0x1000

.LBB0_908:
	v_add_u32_e32 v137, v135, v134
	ds_read_b128 v[146:149], v135 offset:18432
	ds_read_b128 v[150:153], v137
	s_add_i32 s0, s0, 32
	s_cmp_lt_u32 s0, 48
	s_waitcnt lgkmcnt(0)
	v_mfma_f32_32x32x16_bf16 v[48:63], v[150:153], v[146:149], v[48:63]
	ds_read_b128 v[146:149], v135 offset:23040
	s_waitcnt lgkmcnt(0)
	v_mfma_f32_32x32x16_bf16 v[16:31], v[150:153], v[146:149], v[16:31]
	ds_read_b128 v[146:149], v135 offset:27648
	s_waitcnt lgkmcnt(0)
	v_mfma_f32_32x32x16_bf16 v[32:47], v[150:153], v[146:149], v[32:47]
	ds_read_b128 v[146:149], v135 offset:32256
	ds_read_b128 v[154:157], v135 offset:18464
	s_waitcnt lgkmcnt(1)
	v_mfma_f32_32x32x16_bf16 v[0:15], v[150:153], v[146:149], v[0:15]
	ds_read_b128 v[146:149], v137 offset:32
	ds_read_b128 v[150:153], v135 offset:23072
	s_waitcnt lgkmcnt(0)
	v_mfma_f32_32x32x16_bf16 v[16:31], v[146:149], v[150:153], v[16:31]
	ds_read_b128 v[150:153], v135 offset:27680
	s_waitcnt lgkmcnt(0)
	v_mfma_f32_32x32x16_bf16 v[32:47], v[146:149], v[150:153], v[32:47]
	ds_read_b128 v[150:153], v135 offset:32288
	v_add_u32_e32 v135, 64, v135
	v_mfma_f32_32x32x16_bf16 v[48:63], v[146:149], v[154:157], v[48:63]
	s_waitcnt lgkmcnt(0)
	v_mfma_f32_32x32x16_bf16 v[0:15], v[146:149], v[150:153], v[0:15]
	s_cbranch_scc1 .LBB0_908
	s_cmp_gt_u32 s12, 1
	v_readlane_b32 s0, v248, 27
	s_cselect_b32 s2, 19, 1
	s_or_b32 s3, s13, s0
	v_lshlrev_b32_e32 v137, 11, v96
	v_or_b32_e32 v96, s3, v145
	v_readlane_b32 s16, v251, 20
	v_lshlrev_b64 v[134:135], 2, v[96:97]
	v_readlane_b32 s18, v251, 22
	v_readlane_b32 s19, v251, 23
	s_barrier
	s_nop 0
	v_lshl_add_u64 v[138:139], s[18:19], 0, v[134:135]
	v_readlane_b32 s100, v251, 16
	v_readlane_b32 s101, v251, 17
	s_nop 1
	v_lshl_add_u64 v[220:221], s[100:101], 0, v[134:135]
	v_readlane_b32 s100, v251, 20
	v_readlane_b32 s101, v251, 21
	s_nop 1
	v_lshl_add_u64 v[222:223], s[100:101], 0, v[134:135]
	global_load_dword v224, v[220:221], off
	global_load_dword v225, v[222:223], off
	global_load_dword v226, v[138:139], off offset:128
	global_load_dword v227, v[222:223], off offset:128
	global_load_dword v228, v[220:221], off offset:128
	global_load_dword v96, v[138:139], off
	s_mov_b32 s8, 0x3f2aaaab
	s_mov_b32 s9, 0x3f317218
	s_mov_b32 s10, 0x7f800000
	v_readlane_b32 s20, v251, 24
	s_mov_b32 s20, 0x33800000
	v_readlane_b32 s40, v251, 4
	v_readlane_b32 s52, v251, 16
	v_readlane_b32 s53, v251, 17
	v_readlane_b32 s17, v251, 21
	v_readlane_b32 s21, v251, 25
	s_mov_b32 s21, 0x43000000
	v_readlane_b32 s22, v251, 26
	s_mov_b32 s22, 0x42b17217
	v_readlane_b32 s23, v251, 27
	s_mov_b32 s23, 0xf800000
	v_readlane_b32 s24, v251, 28
	s_mov_b32 s24, 0xc1880000
	v_readlane_b32 s30, v251, 34
	v_readlane_b32 s31, v251, 35
	v_readlane_b32 s25, v251, 29
	v_readlane_b32 s27, v251, 31
	v_readlane_b32 s28, v251, 32
	v_readlane_b32 s29, v251, 33
	v_readlane_b32 s30, v248, 2
	s_cmp_eq_u32 s2, s12
	v_readlane_b32 s31, v248, 3
	s_mov_b32 s28, 0x4800000
	s_movk_i32 s29, 0x47ff
	s_mov_b32 s25, 0x85000
	v_readlane_b32 s27, v248, 10
	v_readlane_b32 s26, v251, 30
	v_readlane_b32 s41, v251, 5
	v_readlane_b32 s42, v251, 6
	v_readlane_b32 s43, v251, 7
	v_readlane_b32 s44, v251, 8
	v_readlane_b32 s45, v251, 9
	v_readlane_b32 s46, v251, 10
	v_readlane_b32 s47, v251, 11
	v_readlane_b32 s48, v251, 12
	v_readlane_b32 s49, v251, 13
	v_readlane_b32 s50, v251, 14
	v_readlane_b32 s51, v251, 15
	v_readlane_b32 s54, v251, 18
	v_readlane_b32 s55, v251, 19
	s_waitcnt vmcnt(0)
	v_mul_f32_e32 v96, 0xbfb8aa3b, v96
	v_exp_f32_e32 v96, v96
	s_nop 0
	v_add_f32_e32 v144, 1.0, v96
	v_add_f32_e32 v138, -1.0, v144
	v_sub_f32_e32 v139, v138, v144
	v_add_f32_e32 v139, 1.0, v139
	v_sub_f32_e32 v138, v96, v138
	v_add_f32_e32 v146, v138, v139
	v_frexp_mant_f32_e32 v138, v144
	v_cmp_gt_f32_e32 vcc, s8, v138
	v_cvt_f64_f32_e32 v[138:139], v144
	v_frexp_exp_i32_f64_e32 v138, v[138:139]
	v_subbrev_co_u32_e32 v152, vcc, 0, v138, vcc
	v_sub_u32_e32 v138, 0, v152
	v_ldexp_f32 v139, v144, v138
	v_add_f32_e32 v144, -1.0, v139
	v_add_f32_e32 v147, 1.0, v139
	v_ldexp_f32 v138, v146, v138
	v_add_f32_e32 v146, 1.0, v144
	v_add_f32_e32 v148, -1.0, v147
	v_sub_f32_e32 v146, v139, v146
	v_sub_f32_e32 v139, v139, v148
	v_add_f32_e32 v146, v138, v146
	v_add_f32_e32 v138, v138, v139
	v_add_f32_e32 v153, v147, v138
	v_rcp_f32_e32 v155, v153
	v_sub_f32_e32 v139, v153, v147
	v_sub_f32_e32 v154, v138, v139
	v_add_f32_e32 v139, v144, v146
	v_sub_f32_e32 v138, v139, v144
	v_mul_f32_e32 v156, v139, v155
	v_sub_f32_e32 v144, v146, v138
	v_mul_f32_e32 v146, v153, v156
	v_fma_f32 v148, v156, v153, -v146
	v_fmac_f32_e32 v148, v156, v154
	v_add_f32_e32 v138, v146, v148
	v_sub_f32_e32 v147, v139, v138
	v_pk_add_f32 v[150:151], v[138:139], v[146:147] neg_lo:[0,1] neg_hi:[0,1]
	v_mov_b32_e32 v149, v138
	v_pk_add_f32 v[138:139], v[150:151], v[148:149] neg_lo:[0,1] neg_hi:[0,1]
	v_cmp_neq_f32_e32 vcc, s10, v96
	v_add_f32_e32 v139, v144, v139
	v_add_f32_e32 v138, v138, v139
	v_add_f32_e32 v139, v147, v138
	v_mul_f32_e32 v144, v155, v139
	v_mul_f32_e32 v146, v153, v144
	v_fma_f32 v148, v144, v153, -v146
	v_fmac_f32_e32 v148, v144, v154
	v_sub_f32_e32 v147, v147, v139
	v_add_f32_e32 v153, v138, v147
	v_add_f32_e32 v138, v146, v148
	v_sub_f32_e32 v147, v139, v138
	v_pk_add_f32 v[150:151], v[138:139], v[146:147] neg_lo:[0,1] neg_hi:[0,1]
	v_mov_b32_e32 v149, v138
	v_pk_add_f32 v[138:139], v[150:151], v[148:149] neg_lo:[0,1] neg_hi:[0,1]
	s_nop 0
	v_add_f32_e32 v139, v153, v139
	v_add_f32_e32 v138, v138, v139
	v_add_f32_e32 v139, v156, v144
	v_add_f32_e32 v138, v147, v138
	v_sub_f32_e32 v146, v139, v156
	v_mul_f32_e32 v138, v155, v138
	v_sub_f32_e32 v144, v144, v146
	v_add_f32_e32 v144, v144, v138
	v_add_f32_e32 v146, v139, v144
	v_mul_f32_e32 v148, v146, v146
	v_fmamk_f32 v138, v148, 0x3e9b6dac, v191
	v_fmaak_f32 v169, v148, v138, 0x3f2aaada
	v_cvt_f32_i32_e32 v138, v152
	v_sub_f32_e32 v139, v146, v139
	v_sub_f32_e32 v139, v144, v139
	v_ldexp_f32 v144, v139, 1
	v_mul_f32_e32 v139, v146, v148
	v_pk_mul_f32 v[148:149], v[138:139], v[168:169]
	v_ldexp_f32 v147, v146, 1
	v_fma_f32 v146, v138, s9, -v148
	v_fmac_f32_e32 v146, 0xb102e308, v138
	v_pk_add_f32 v[138:139], v[148:149], v[146:147]
	v_mov_b32_e32 v150, v148
	v_sub_f32_e32 v147, v139, v147
	v_sub_f32_e32 v147, v149, v147
	v_add_f32_e32 v151, v144, v147
	v_pk_add_f32 v[148:149], v[138:139], v[148:149] neg_lo:[0,1] neg_hi:[0,1]
	v_pk_add_f32 v[152:153], v[138:139], v[150:151]
	v_mov_b32_e32 v147, v138
	v_mov_b32_e32 v149, v153
	v_pk_add_f32 v[154:155], v[146:147], v[148:149] neg_lo:[0,1] neg_hi:[0,1]
	v_pk_add_f32 v[146:147], v[146:147], v[148:149]
	v_mov_b32_e32 v150, v151
	v_pk_add_f32 v[148:149], v[146:147], v[138:139] op_sel:[1,0] op_sel_hi:[0,1] neg_lo:[0,1] neg_hi:[0,1]
	v_pk_add_f32 v[156:157], v[152:153], v[148:149] op_sel_hi:[1,0] neg_lo:[0,1] neg_hi:[0,1]
	v_mov_b32_e32 v152, v153
	v_mov_b32_e32 v153, v147
	v_pk_mov_b32 v[148:149], v[138:139], v[148:149] op_sel:[1,0]
	v_mov_b32_e32 v151, v138
	v_pk_add_f32 v[148:149], v[152:153], v[148:149] neg_lo:[0,1] neg_hi:[0,1]
	v_mov_b32_e32 v156, v154
	v_pk_add_f32 v[138:139], v[150:151], v[148:149] neg_lo:[0,1] neg_hi:[0,1]
	v_mov_b32_e32 v155, v147
	v_pk_add_f32 v[148:149], v[156:157], v[138:139]
	s_nop 0
	v_pk_add_f32 v[150:151], v[148:149], v[148:149] op_sel:[0,1] op_sel_hi:[1,0]
	s_nop 0
	v_pk_add_f32 v[146:147], v[146:147], v[150:151] op_sel:[1,0] op_sel_hi:[0,1]
	v_mov_b32_e32 v149, v146
	v_pk_add_f32 v[152:153], v[148:149], v[154:155] neg_lo:[0,1] neg_hi:[0,1]
	v_mov_b32_e32 v139, v150
	v_sub_f32_e32 v144, v148, v152
	v_pk_add_f32 v[138:139], v[138:139], v[152:153] neg_lo:[0,1] neg_hi:[0,1]
	v_sub_f32_e32 v144, v154, v144
	v_add_f32_e32 v138, v138, v144
	v_add_f32_e32 v138, v138, v139
	v_add_f32_e32 v138, v146, v138
	v_cndmask_b32_e32 v138, v199, v138, vcc
	v_cmp_ngt_f32_e32 vcc, -1.0, v96
	s_nop 1
	v_cndmask_b32_e32 v138, v200, v138, vcc
	v_cmp_neq_f32_e32 vcc, -1.0, v96
	s_nop 1
	v_cndmask_b32_e32 v138, v201, v138, vcc
	v_cmp_lt_f32_e64 vcc, |v96|, s20
	s_nop 1
	v_cndmask_b32_e32 v96, v138, v96, vcc
	v_lshl_add_u64 v[138:139], s[52:53], 0, v[134:135]
	v_mov_b32_e32 v147, v224
	v_lshl_add_u64 v[134:135], s[16:17], 0, v[134:135]
	v_mov_b32_e32 v146, v225
	v_mul_f32_e32 v96, 0xc1000000, v96
	s_waitcnt vmcnt(1)
	v_add_f32_e32 v48, v48, v147
	v_mul_f32_e32 v48, 0xbfb8aa3b, v48
	v_exp_f32_e32 v48, v48
	s_waitcnt vmcnt(0)
	v_add_f32_e32 v32, v32, v146
	v_mul_f32_e32 v32, 0xbfb8aa3b, v32
	v_exp_f32_e32 v32, v32
	v_add_f32_e32 v48, 1.0, v48
	v_rcp_f32_e32 v48, v48
	v_add_f32_e32 v33, v33, v146
	v_add_f32_e32 v32, 1.0, v32
	v_rcp_f32_e32 v32, v32
	v_mul_f32_e32 v48, v48, v96
	v_mul_f32_e32 v134, 0x3fb8aa3b, v48
	v_add_f32_e32 v48, v48, v48
	v_exp_f32_e32 v138, v134
	v_mul_f32_e32 v134, 0x3fb8aa3b, v48
	v_rndne_f32_e32 v134, v134
	v_fmamk_f32 v135, v134, 0xbf317218, v48
	v_fmac_f32_e32 v135, 0x3102e308, v134
	v_fmamk_f32 v139, v135, 0x395133b1, v192
	v_cmp_eq_f32_e32 vcc, s21, v134
	v_cvt_i32_f32_e32 v134, v134
	v_fmaak_f32 v139, v135, v139, 0x3c0887f9
	v_fmaak_f32 v139, v135, v139, 0x3d2aaa81
	v_fmaak_f32 v139, v135, v139, 0x3e2aaaab
	v_fma_f32 v139, v135, v139, 0.5
	v_ldexp_f32 v134, 1.0, v134
	v_mul_f32_e32 v139, v135, v139
	v_cndmask_b32_e32 v134, v134, v202, vcc
	v_fmac_f32_e32 v135, v135, v139
	v_add_f32_e32 v139, -1.0, v134
	v_fmac_f32_e32 v139, v134, v135
	v_add_f32_e32 v134, v139, v139
	v_cndmask_b32_e32 v134, v139, v134, vcc
	v_cmp_nlt_f32_e32 vcc, s22, v48
	v_mul_f32_e32 v33, 0xbfb8aa3b, v33
	v_exp_f32_e32 v33, v33
	v_cndmask_b32_e64 v134, v201, -v134, vcc
	v_cmp_gt_f32_e32 vcc, s23, v134
	v_mul_f32_e32 v135, 0x4f800000, v134
	v_add_f32_e32 v33, 1.0, v33
	v_cndmask_b32_e32 v134, v134, v135, vcc
	v_sqrt_f32_e32 v135, v134
	v_rcp_f32_e32 v33, v33
	v_add_f32_e32 v34, v34, v146
	v_mul_f32_e32 v34, 0xbfb8aa3b, v34
	v_add_u32_e32 v139, -1, v135
	v_fma_f32 v144, -v139, v135, v134
	v_cmp_ge_f32_e64 s[0:1], 0, v144
	v_add_u32_e32 v144, 1, v135
	v_exp_f32_e32 v34, v34
	v_cndmask_b32_e64 v139, v135, v139, s[0:1]
	v_fma_f32 v135, -v144, v135, v134
	v_cmp_lt_f32_e64 s[0:1], 0, v135
	v_add_f32_e32 v34, 1.0, v34
	v_rcp_f32_e32 v34, v34
	v_cndmask_b32_e64 v135, v139, v144, s[0:1]
	v_mul_f32_e32 v139, 0x37800000, v135
	v_cndmask_b32_e32 v135, v135, v139, vcc
	v_cmp_class_f32_e32 vcc, v134, v193
	s_nop 1
	v_cndmask_b32_e32 v134, v135, v134, vcc
	v_cmp_ngt_f32_e32 vcc, s24, v48
	s_nop 1
	v_cndmask_b32_e32 v48, 1.0, v134, vcc
	v_mul_f32_e32 v48, v32, v48
	v_and_b32_e32 v32, 0x100, v136
	v_or3_b32 v32, v137, v145, v32
	v_lshl_add_u32 v144, v32, 2, 0
	v_add_u32_e32 v32, 0x9000, v144
	ds_read2_b32 v[134:135], v32 offset1:32
	s_waitcnt lgkmcnt(0)
	v_mul_f32_e32 v48, v134, v48
	ds_write_b32 v144, v138
	ds_write_b32 v144, v48 offset:36864
	v_add_f32_e32 v48, v49, v147
	v_mul_f32_e32 v48, 0xbfb8aa3b, v48
	v_exp_f32_e32 v48, v48
	s_nop 0
	v_add_f32_e32 v48, 1.0, v48
	v_rcp_f32_e32 v48, v48
	s_nop 0
	v_mul_f32_e32 v48, v48, v96
	v_mul_f32_e32 v49, 0x3fb8aa3b, v48
	v_add_f32_e32 v48, v48, v48
	v_exp_f32_e32 v134, v49
	v_mul_f32_e32 v49, 0x3fb8aa3b, v48
	v_rndne_f32_e32 v49, v49
	v_fmamk_f32 v136, v49, 0xbf317218, v48
	v_fmac_f32_e32 v136, 0x3102e308, v49
	v_fmamk_f32 v137, v136, 0x395133b1, v192
	v_cmp_eq_f32_e32 vcc, s21, v49
	v_cvt_i32_f32_e32 v49, v49
	v_fmaak_f32 v137, v136, v137, 0x3c0887f9
	v_fmaak_f32 v137, v136, v137, 0x3d2aaa81
	v_fmaak_f32 v137, v136, v137, 0x3e2aaaab
	v_fma_f32 v137, v136, v137, 0.5
	v_ldexp_f32 v49, 1.0, v49
	v_mul_f32_e32 v137, v136, v137
	v_cndmask_b32_e32 v49, v49, v202, vcc
	v_fmac_f32_e32 v136, v136, v137
	v_add_f32_e32 v137, -1.0, v49
	v_fmac_f32_e32 v137, v49, v136
	v_add_f32_e32 v49, v137, v137
	v_cndmask_b32_e32 v49, v137, v49, vcc
	v_cmp_nlt_f32_e32 vcc, s22, v48
	s_nop 1
	v_cndmask_b32_e64 v49, v201, -v49, vcc
	v_cmp_gt_f32_e32 vcc, s23, v49
	v_mul_f32_e32 v136, 0x4f800000, v49
	s_nop 0
	v_cndmask_b32_e32 v49, v49, v136, vcc
	v_sqrt_f32_e32 v136, v49
	s_nop 0
	v_add_u32_e32 v137, -1, v136
	v_fma_f32 v138, -v137, v136, v49
	v_cmp_ge_f32_e64 s[0:1], 0, v138
	v_add_u32_e32 v138, 1, v136
	s_nop 0
	v_cndmask_b32_e64 v137, v136, v137, s[0:1]
	v_fma_f32 v136, -v138, v136, v49
	v_cmp_lt_f32_e64 s[0:1], 0, v136
	s_nop 1
	v_cndmask_b32_e64 v136, v137, v138, s[0:1]
	v_mul_f32_e32 v137, 0x37800000, v136
	v_cndmask_b32_e32 v136, v136, v137, vcc
	v_cmp_class_f32_e32 vcc, v49, v193
	s_nop 1
	v_cndmask_b32_e32 v49, v136, v49, vcc
	v_cmp_ngt_f32_e32 vcc, s24, v48
	s_nop 1
	v_cndmask_b32_e32 v48, 1.0, v49, vcc
	v_mul_f32_e32 v33, v33, v48
	ds_read2_b32 v[48:49], v32 offset0:64 offset1:96
	s_waitcnt lgkmcnt(0)
	v_mul_f32_e32 v33, v48, v33
	ds_write_b32 v144, v134 offset:256
	ds_write_b32 v144, v33 offset:37120
	v_add_f32_e32 v33, v50, v147
	v_mul_f32_e32 v33, 0xbfb8aa3b, v33
	v_exp_f32_e32 v33, v33
	s_nop 0
	v_add_f32_e32 v33, 1.0, v33
	v_rcp_f32_e32 v33, v33
	s_nop 0
	v_mul_f32_e32 v33, v33, v96
	v_mul_f32_e32 v48, 0x3fb8aa3b, v33
	v_add_f32_e32 v33, v33, v33
	v_mul_f32_e32 v50, 0x3fb8aa3b, v33
	v_rndne_f32_e32 v50, v50
	v_fmamk_f32 v134, v50, 0xbf317218, v33
	v_fmac_f32_e32 v134, 0x3102e308, v50
	v_fmamk_f32 v136, v134, 0x395133b1, v192
	v_cmp_eq_f32_e32 vcc, s21, v50
	v_cvt_i32_f32_e32 v50, v50
	v_fmaak_f32 v136, v134, v136, 0x3c0887f9
	v_fmaak_f32 v136, v134, v136, 0x3d2aaa81
	v_fmaak_f32 v136, v134, v136, 0x3e2aaaab
	v_fma_f32 v136, v134, v136, 0.5
	v_ldexp_f32 v50, 1.0, v50
	v_mul_f32_e32 v136, v134, v136
	v_cndmask_b32_e32 v50, v50, v202, vcc
	v_fmac_f32_e32 v134, v134, v136
	v_add_f32_e32 v136, -1.0, v50
	v_fmac_f32_e32 v136, v50, v134
	v_add_f32_e32 v50, v136, v136
	v_cndmask_b32_e32 v50, v136, v50, vcc
	v_cmp_nlt_f32_e32 vcc, s22, v33
	v_exp_f32_e32 v48, v48
	s_nop 0
	v_cndmask_b32_e64 v50, v201, -v50, vcc
	v_cmp_gt_f32_e32 vcc, s23, v50
	v_mul_f32_e32 v134, 0x4f800000, v50
	s_nop 0
	v_cndmask_b32_e32 v50, v50, v134, vcc
	v_sqrt_f32_e32 v134, v50
	s_nop 0
	v_add_u32_e32 v136, -1, v134
	v_fma_f32 v137, -v136, v134, v50
	v_cmp_ge_f32_e64 s[0:1], 0, v137
	v_add_u32_e32 v137, 1, v134
	s_nop 0
	v_cndmask_b32_e64 v136, v134, v136, s[0:1]
	v_fma_f32 v134, -v137, v134, v50
	v_cmp_lt_f32_e64 s[0:1], 0, v134
	s_nop 1
	v_cndmask_b32_e64 v134, v136, v137, s[0:1]
	v_mul_f32_e32 v136, 0x37800000, v134
	v_cndmask_b32_e32 v134, v134, v136, vcc
	ds_read2_b32 v[136:137], v32 offset0:128 offset1:160
	v_cmp_class_f32_e32 vcc, v50, v193
	s_nop 1
	v_cndmask_b32_e32 v50, v134, v50, vcc
	v_cmp_ngt_f32_e32 vcc, s24, v33
	s_nop 1
	v_cndmask_b32_e32 v33, 1.0, v50, vcc
	v_mul_f32_e32 v33, v34, v33
	s_waitcnt lgkmcnt(0)
	v_mul_f32_e32 v33, v136, v33
	ds_write_b32 v144, v48 offset:512
	ds_write_b32 v144, v33 offset:37376
	v_add_f32_e32 v33, v51, v147
	v_mul_f32_e32 v33, 0xbfb8aa3b, v33
	v_exp_f32_e32 v33, v33
	v_add_f32_e32 v34, v35, v146
	v_mul_f32_e32 v34, 0xbfb8aa3b, v34
	v_exp_f32_e32 v34, v34
	v_add_f32_e32 v33, 1.0, v33
	v_rcp_f32_e32 v33, v33
	v_add_f32_e32 v34, 1.0, v34
	v_rcp_f32_e32 v34, v34
	v_mul_f32_e32 v33, v33, v96
	v_mul_f32_e32 v35, 0x3fb8aa3b, v33
	v_add_f32_e32 v33, v33, v33
	v_mul_f32_e32 v48, 0x3fb8aa3b, v33
	v_rndne_f32_e32 v48, v48
	v_fmamk_f32 v50, v48, 0xbf317218, v33
	v_fmac_f32_e32 v50, 0x3102e308, v48
	v_fmamk_f32 v51, v50, 0x395133b1, v192
	v_cmp_eq_f32_e32 vcc, s21, v48
	v_cvt_i32_f32_e32 v48, v48
	v_fmaak_f32 v51, v50, v51, 0x3c0887f9
	v_fmaak_f32 v51, v50, v51, 0x3d2aaa81
	v_fmaak_f32 v51, v50, v51, 0x3e2aaaab
	v_fma_f32 v51, v50, v51, 0.5
	v_ldexp_f32 v48, 1.0, v48
	v_mul_f32_e32 v51, v50, v51
	v_cndmask_b32_e32 v48, v48, v202, vcc
	v_fmac_f32_e32 v50, v50, v51
	v_add_f32_e32 v51, -1.0, v48
	v_fmac_f32_e32 v51, v48, v50
	v_add_f32_e32 v48, v51, v51
	v_cndmask_b32_e32 v48, v51, v48, vcc
	v_cmp_nlt_f32_e32 vcc, s22, v33
	v_exp_f32_e32 v35, v35
	s_nop 0
	v_cndmask_b32_e64 v48, v201, -v48, vcc
	v_cmp_gt_f32_e32 vcc, s23, v48
	v_mul_f32_e32 v50, 0x4f800000, v48
	s_nop 0
	v_cndmask_b32_e32 v48, v48, v50, vcc
	v_sqrt_f32_e32 v50, v48
	s_nop 0
	v_add_u32_e32 v51, -1, v50
	v_fma_f32 v134, -v51, v50, v48
	v_cmp_ge_f32_e64 s[0:1], 0, v134
	v_add_u32_e32 v134, 1, v50
	s_nop 0
	v_cndmask_b32_e64 v51, v50, v51, s[0:1]
	v_fma_f32 v50, -v134, v50, v48
	v_cmp_lt_f32_e64 s[0:1], 0, v50
	s_nop 1
	v_cndmask_b32_e64 v50, v51, v134, s[0:1]
	v_mul_f32_e32 v51, 0x37800000, v50
	v_cndmask_b32_e32 v50, v50, v51, vcc
	v_cmp_class_f32_e32 vcc, v48, v193
	s_nop 1
	v_cndmask_b32_e32 v48, v50, v48, vcc
	ds_read2_b32 v[50:51], v32 offset0:192 offset1:224
	v_cmp_ngt_f32_e32 vcc, s24, v33
	s_nop 1
	v_cndmask_b32_e32 v33, 1.0, v48, vcc
	v_mul_f32_e32 v33, v34, v33
	s_waitcnt lgkmcnt(0)
	v_mul_f32_e32 v32, v50, v33
	ds_write_b32 v144, v35 offset:768
	ds_write_b32 v144, v32 offset:37632
	v_add_f32_e32 v32, v52, v147
	v_mul_f32_e32 v32, 0xbfb8aa3b, v32
	v_exp_f32_e32 v32, v32
	v_add_f32_e32 v33, v36, v146
	v_mul_f32_e32 v33, 0xbfb8aa3b, v33
	v_exp_f32_e32 v33, v33
	v_add_f32_e32 v32, 1.0, v32
	v_rcp_f32_e32 v32, v32
	v_add_f32_e32 v33, 1.0, v33
	v_rcp_f32_e32 v33, v33
	v_mul_f32_e32 v32, v32, v96
	v_mul_f32_e32 v34, 0x3fb8aa3b, v32
	v_add_f32_e32 v32, v32, v32
	v_mul_f32_e32 v35, 0x3fb8aa3b, v32
	v_rndne_f32_e32 v35, v35
	v_fmamk_f32 v36, v35, 0xbf317218, v32
	v_fmac_f32_e32 v36, 0x3102e308, v35
	v_fmamk_f32 v48, v36, 0x395133b1, v192
	v_cmp_eq_f32_e32 vcc, s21, v35
	v_cvt_i32_f32_e32 v35, v35
	v_fmaak_f32 v48, v36, v48, 0x3c0887f9
	v_fmaak_f32 v48, v36, v48, 0x3d2aaa81
	v_fmaak_f32 v48, v36, v48, 0x3e2aaaab
	v_fma_f32 v48, v36, v48, 0.5
	v_ldexp_f32 v35, 1.0, v35
	v_mul_f32_e32 v48, v36, v48
	v_cndmask_b32_e32 v35, v35, v202, vcc
	v_fmac_f32_e32 v36, v36, v48
	v_add_f32_e32 v48, -1.0, v35
	v_fmac_f32_e32 v48, v35, v36
	v_add_f32_e32 v35, v48, v48
	v_cndmask_b32_e32 v35, v48, v35, vcc
	v_cmp_nlt_f32_e32 vcc, s22, v32
	v_exp_f32_e32 v34, v34
	s_nop 0
	v_cndmask_b32_e64 v35, v201, -v35, vcc
	v_cmp_gt_f32_e32 vcc, s23, v35
	v_mul_f32_e32 v36, 0x4f800000, v35
	s_nop 0
	v_cndmask_b32_e32 v35, v35, v36, vcc
	v_sqrt_f32_e32 v36, v35
	s_nop 0
	v_add_u32_e32 v48, -1, v36
	v_fma_f32 v50, -v48, v36, v35
	v_cmp_ge_f32_e64 s[0:1], 0, v50
	v_add_u32_e32 v50, 1, v36
	s_nop 0
	v_cndmask_b32_e64 v48, v36, v48, s[0:1]
	v_fma_f32 v36, -v50, v36, v35
	v_cmp_lt_f32_e64 s[0:1], 0, v36
	s_nop 1
	v_cndmask_b32_e64 v36, v48, v50, s[0:1]
	v_mul_f32_e32 v48, 0x37800000, v36
	v_cndmask_b32_e32 v36, v36, v48, vcc
	v_cmp_class_f32_e32 vcc, v35, v193
	s_nop 1
	v_cndmask_b32_e32 v35, v36, v35, vcc
	v_cmp_ngt_f32_e32 vcc, s24, v32
	s_nop 1
	v_cndmask_b32_e32 v32, 1.0, v35, vcc
	v_mul_f32_e32 v33, v33, v32
	v_add_u32_e32 v32, 0x9800, v144
	ds_read2_b32 v[138:139], v32 offset1:32
	s_waitcnt lgkmcnt(0)
	v_mul_f32_e32 v33, v138, v33
	ds_write_b32 v144, v34 offset:2048
	ds_write_b32 v144, v33 offset:38912
	v_add_f32_e32 v33, v53, v147
	v_mul_f32_e32 v33, 0xbfb8aa3b, v33
	v_exp_f32_e32 v33, v33
	v_add_f32_e32 v34, v37, v146
	v_mul_f32_e32 v34, 0xbfb8aa3b, v34
	v_exp_f32_e32 v34, v34
	v_add_f32_e32 v33, 1.0, v33
	v_rcp_f32_e32 v33, v33
	v_add_f32_e32 v34, 1.0, v34
	v_rcp_f32_e32 v34, v34
	v_mul_f32_e32 v33, v33, v96
	v_mul_f32_e32 v35, 0x3fb8aa3b, v33
	v_add_f32_e32 v33, v33, v33
	v_mul_f32_e32 v36, 0x3fb8aa3b, v33
	v_rndne_f32_e32 v36, v36
	v_fmamk_f32 v37, v36, 0xbf317218, v33
	v_fmac_f32_e32 v37, 0x3102e308, v36
	v_fmamk_f32 v48, v37, 0x395133b1, v192
	v_cmp_eq_f32_e32 vcc, s21, v36
	v_cvt_i32_f32_e32 v36, v36
	v_fmaak_f32 v48, v37, v48, 0x3c0887f9
	v_fmaak_f32 v48, v37, v48, 0x3d2aaa81
	v_fmaak_f32 v48, v37, v48, 0x3e2aaaab
	v_fma_f32 v48, v37, v48, 0.5
	v_ldexp_f32 v36, 1.0, v36
	v_mul_f32_e32 v48, v37, v48
	v_cndmask_b32_e32 v36, v36, v202, vcc
	v_fmac_f32_e32 v37, v37, v48
	v_add_f32_e32 v48, -1.0, v36
	v_fmac_f32_e32 v48, v36, v37
	v_add_f32_e32 v36, v48, v48
	v_cndmask_b32_e32 v36, v48, v36, vcc
	v_cmp_nlt_f32_e32 vcc, s22, v33
	v_exp_f32_e32 v35, v35
	s_nop 0
	v_cndmask_b32_e64 v36, v201, -v36, vcc
	v_cmp_gt_f32_e32 vcc, s23, v36
	v_mul_f32_e32 v37, 0x4f800000, v36
	s_nop 0
	v_cndmask_b32_e32 v36, v36, v37, vcc
	v_sqrt_f32_e32 v37, v36
	s_nop 0
	v_add_u32_e32 v48, -1, v37
	v_fma_f32 v50, -v48, v37, v36
	v_cmp_ge_f32_e64 s[0:1], 0, v50
	v_add_u32_e32 v50, 1, v37
	s_nop 0
	v_cndmask_b32_e64 v48, v37, v48, s[0:1]
	v_fma_f32 v37, -v50, v37, v36
	v_cmp_lt_f32_e64 s[0:1], 0, v37
	s_nop 1
	v_cndmask_b32_e64 v37, v48, v50, s[0:1]
	v_mul_f32_e32 v48, 0x37800000, v37
	v_cndmask_b32_e32 v37, v37, v48, vcc
	v_cmp_class_f32_e32 vcc, v36, v193
	s_nop 1
	v_cndmask_b32_e32 v36, v37, v36, vcc
	v_cmp_ngt_f32_e32 vcc, s24, v33
	s_nop 1
	v_cndmask_b32_e32 v33, 1.0, v36, vcc
	ds_read2_b32 v[36:37], v32 offset0:64 offset1:96
	v_mul_f32_e32 v33, v34, v33
	v_add_f32_e32 v34, v38, v146
	v_mul_f32_e32 v34, 0xbfb8aa3b, v34
	v_exp_f32_e32 v34, v34
	s_waitcnt lgkmcnt(0)
	v_mul_f32_e32 v33, v36, v33
	ds_write_b32 v144, v35 offset:2304
	ds_write_b32 v144, v33 offset:39168
	v_add_f32_e32 v33, v54, v147
	v_mul_f32_e32 v33, 0xbfb8aa3b, v33
	v_exp_f32_e32 v33, v33
	v_add_f32_e32 v34, 1.0, v34
	v_rcp_f32_e32 v34, v34
	ds_read2_b32 v[52:53], v32 offset0:128 offset1:160
	v_add_f32_e32 v33, 1.0, v33
	v_rcp_f32_e32 v33, v33
	s_nop 0
	v_mul_f32_e32 v33, v33, v96
	v_mul_f32_e32 v35, 0x3fb8aa3b, v33
	v_add_f32_e32 v33, v33, v33
	v_mul_f32_e32 v36, 0x3fb8aa3b, v33
	v_rndne_f32_e32 v36, v36
	v_fmamk_f32 v38, v36, 0xbf317218, v33
	v_fmac_f32_e32 v38, 0x3102e308, v36
	v_fmamk_f32 v48, v38, 0x395133b1, v192
	v_cmp_eq_f32_e32 vcc, s21, v36
	v_cvt_i32_f32_e32 v36, v36
	v_fmaak_f32 v48, v38, v48, 0x3c0887f9
	v_fmaak_f32 v48, v38, v48, 0x3d2aaa81
	v_fmaak_f32 v48, v38, v48, 0x3e2aaaab
	v_fma_f32 v48, v38, v48, 0.5
	v_ldexp_f32 v36, 1.0, v36
	v_mul_f32_e32 v48, v38, v48
	v_cndmask_b32_e32 v36, v36, v202, vcc
	v_fmac_f32_e32 v38, v38, v48
	v_add_f32_e32 v48, -1.0, v36
	v_fmac_f32_e32 v48, v36, v38
	v_add_f32_e32 v36, v48, v48
	v_cndmask_b32_e32 v36, v48, v36, vcc
	v_cmp_nlt_f32_e32 vcc, s22, v33
	v_exp_f32_e32 v35, v35
	s_nop 0
	v_cndmask_b32_e64 v36, v201, -v36, vcc
	v_cmp_gt_f32_e32 vcc, s23, v36
	v_mul_f32_e32 v38, 0x4f800000, v36
	s_nop 0
	v_cndmask_b32_e32 v36, v36, v38, vcc
	v_sqrt_f32_e32 v38, v36
	s_nop 0
	v_add_u32_e32 v48, -1, v38
	v_fma_f32 v50, -v48, v38, v36
	v_cmp_ge_f32_e64 s[0:1], 0, v50
	v_add_u32_e32 v50, 1, v38
	s_nop 0
	v_cndmask_b32_e64 v48, v38, v48, s[0:1]
	v_fma_f32 v38, -v50, v38, v36
	v_cmp_lt_f32_e64 s[0:1], 0, v38
	s_nop 1
	v_cndmask_b32_e64 v38, v48, v50, s[0:1]
	v_mul_f32_e32 v48, 0x37800000, v38
	v_cndmask_b32_e32 v38, v38, v48, vcc
	v_cmp_class_f32_e32 vcc, v36, v193
	s_nop 1
	v_cndmask_b32_e32 v36, v38, v36, vcc
	v_cmp_ngt_f32_e32 vcc, s24, v33
	s_nop 1
	v_cndmask_b32_e32 v33, 1.0, v36, vcc
	v_mul_f32_e32 v33, v34, v33
	s_waitcnt lgkmcnt(0)
	v_mul_f32_e32 v33, v52, v33
	ds_write_b32 v144, v35 offset:2560
	ds_write_b32 v144, v33 offset:39424
	v_add_f32_e32 v33, v55, v147
	v_mul_f32_e32 v33, 0xbfb8aa3b, v33
	v_exp_f32_e32 v33, v33
	v_add_f32_e32 v34, v39, v146
	v_mul_f32_e32 v34, 0xbfb8aa3b, v34
	v_exp_f32_e32 v34, v34
	v_add_f32_e32 v33, 1.0, v33
	v_rcp_f32_e32 v33, v33
	v_add_f32_e32 v34, 1.0, v34
	v_rcp_f32_e32 v34, v34
	v_mul_f32_e32 v33, v33, v96
	v_mul_f32_e32 v35, 0x3fb8aa3b, v33
	v_add_f32_e32 v33, v33, v33
	v_mul_f32_e32 v36, 0x3fb8aa3b, v33
	v_rndne_f32_e32 v36, v36
	v_fmamk_f32 v38, v36, 0xbf317218, v33
	v_fmac_f32_e32 v38, 0x3102e308, v36
	v_fmamk_f32 v39, v38, 0x395133b1, v192
	v_cmp_eq_f32_e32 vcc, s21, v36
	v_cvt_i32_f32_e32 v36, v36
	v_fmaak_f32 v39, v38, v39, 0x3c0887f9
	v_fmaak_f32 v39, v38, v39, 0x3d2aaa81
	v_fmaak_f32 v39, v38, v39, 0x3e2aaaab
	v_fma_f32 v39, v38, v39, 0.5
	v_ldexp_f32 v36, 1.0, v36
	v_mul_f32_e32 v39, v38, v39
	v_cndmask_b32_e32 v36, v36, v202, vcc
	v_fmac_f32_e32 v38, v38, v39
	v_add_f32_e32 v39, -1.0, v36
	v_fmac_f32_e32 v39, v36, v38
	v_add_f32_e32 v36, v39, v39
	v_cndmask_b32_e32 v36, v39, v36, vcc
	v_cmp_nlt_f32_e32 vcc, s22, v33
	v_exp_f32_e32 v35, v35
	s_nop 0
	v_cndmask_b32_e64 v36, v201, -v36, vcc
	v_cmp_gt_f32_e32 vcc, s23, v36
	v_mul_f32_e32 v38, 0x4f800000, v36
	s_nop 0
	v_cndmask_b32_e32 v36, v36, v38, vcc
	v_sqrt_f32_e32 v38, v36
	s_nop 0
	v_add_u32_e32 v39, -1, v38
	v_fma_f32 v48, -v39, v38, v36
	v_cmp_ge_f32_e64 s[0:1], 0, v48
	v_add_u32_e32 v48, 1, v38
	s_nop 0
	v_cndmask_b32_e64 v39, v38, v39, s[0:1]
	v_fma_f32 v38, -v48, v38, v36
	v_cmp_lt_f32_e64 s[0:1], 0, v38
	s_nop 1
	v_cndmask_b32_e64 v38, v39, v48, s[0:1]
	v_mul_f32_e32 v39, 0x37800000, v38
	v_cndmask_b32_e32 v38, v38, v39, vcc
	v_cmp_class_f32_e32 vcc, v36, v193
	s_nop 1
	v_cndmask_b32_e32 v36, v38, v36, vcc
	ds_read2_b32 v[38:39], v32 offset0:192 offset1:224
	v_cmp_ngt_f32_e32 vcc, s24, v33
	s_nop 1
	v_cndmask_b32_e32 v33, 1.0, v36, vcc
	v_mul_f32_e32 v33, v34, v33
	s_waitcnt lgkmcnt(0)
	v_mul_f32_e32 v32, v38, v33
	ds_write_b32 v144, v35 offset:2816
	ds_write_b32 v144, v32 offset:39680
	v_add_f32_e32 v32, v56, v147
	v_mul_f32_e32 v32, 0xbfb8aa3b, v32
	v_exp_f32_e32 v32, v32
	v_add_f32_e32 v33, v40, v146
	v_mul_f32_e32 v33, 0xbfb8aa3b, v33
	v_exp_f32_e32 v33, v33
	v_add_f32_e32 v32, 1.0, v32
	v_rcp_f32_e32 v32, v32
	v_add_f32_e32 v33, 1.0, v33
	v_rcp_f32_e32 v33, v33
	v_mul_f32_e32 v32, v32, v96
	v_mul_f32_e32 v34, 0x3fb8aa3b, v32
	v_add_f32_e32 v32, v32, v32
	v_mul_f32_e32 v35, 0x3fb8aa3b, v32
	v_rndne_f32_e32 v35, v35
	v_fmamk_f32 v36, v35, 0xbf317218, v32
	v_fmac_f32_e32 v36, 0x3102e308, v35
	v_fmamk_f32 v38, v36, 0x395133b1, v192
	v_cmp_eq_f32_e32 vcc, s21, v35
	v_cvt_i32_f32_e32 v35, v35
	v_fmaak_f32 v38, v36, v38, 0x3c0887f9
	v_fmaak_f32 v38, v36, v38, 0x3d2aaa81
	v_fmaak_f32 v38, v36, v38, 0x3e2aaaab
	v_fma_f32 v38, v36, v38, 0.5
	v_ldexp_f32 v35, 1.0, v35
	v_mul_f32_e32 v38, v36, v38
	v_cndmask_b32_e32 v35, v35, v202, vcc
	v_fmac_f32_e32 v36, v36, v38
	v_add_f32_e32 v38, -1.0, v35
	v_fmac_f32_e32 v38, v35, v36
	v_add_f32_e32 v35, v38, v38
	v_cndmask_b32_e32 v35, v38, v35, vcc
	v_cmp_nlt_f32_e32 vcc, s22, v32
	v_exp_f32_e32 v34, v34
	s_nop 0
	v_cndmask_b32_e64 v35, v201, -v35, vcc
	v_cmp_gt_f32_e32 vcc, s23, v35
	v_mul_f32_e32 v36, 0x4f800000, v35
	s_nop 0
	v_cndmask_b32_e32 v35, v35, v36, vcc
	v_sqrt_f32_e32 v36, v35
	s_nop 0
	v_add_u32_e32 v38, -1, v36
	v_fma_f32 v40, -v38, v36, v35
	v_cmp_ge_f32_e64 s[0:1], 0, v40
	v_add_u32_e32 v40, 1, v36
	s_nop 0
	v_cndmask_b32_e64 v38, v36, v38, s[0:1]
	v_fma_f32 v36, -v40, v36, v35
	v_cmp_lt_f32_e64 s[0:1], 0, v36
	s_nop 1
	v_cndmask_b32_e64 v36, v38, v40, s[0:1]
	v_mul_f32_e32 v38, 0x37800000, v36
	v_cndmask_b32_e32 v36, v36, v38, vcc
	v_cmp_class_f32_e32 vcc, v35, v193
	s_nop 1
	v_cndmask_b32_e32 v35, v36, v35, vcc
	v_cmp_ngt_f32_e32 vcc, s24, v32
	s_nop 1
	v_cndmask_b32_e32 v32, 1.0, v35, vcc
	v_mul_f32_e32 v33, v33, v32
	v_add_u32_e32 v32, 0xa000, v144
	ds_read2_b32 v[54:55], v32 offset1:32
	s_waitcnt lgkmcnt(0)
	v_mul_f32_e32 v33, v54, v33
	ds_write_b32 v144, v34 offset:4096
	ds_write_b32 v144, v33 offset:40960
	v_add_f32_e32 v33, v57, v147
	v_mul_f32_e32 v33, 0xbfb8aa3b, v33
	v_exp_f32_e32 v33, v33
	v_add_f32_e32 v34, v41, v146
	v_mul_f32_e32 v34, 0xbfb8aa3b, v34
	v_exp_f32_e32 v34, v34
	v_add_f32_e32 v33, 1.0, v33
	v_rcp_f32_e32 v33, v33
	v_add_f32_e32 v34, 1.0, v34
	v_rcp_f32_e32 v34, v34
	v_mul_f32_e32 v33, v33, v96
	v_mul_f32_e32 v35, 0x3fb8aa3b, v33
	v_add_f32_e32 v33, v33, v33
	v_mul_f32_e32 v36, 0x3fb8aa3b, v33
	v_rndne_f32_e32 v36, v36
	v_fmamk_f32 v38, v36, 0xbf317218, v33
	v_fmac_f32_e32 v38, 0x3102e308, v36
	v_fmamk_f32 v40, v38, 0x395133b1, v192
	v_cmp_eq_f32_e32 vcc, s21, v36
	v_cvt_i32_f32_e32 v36, v36
	v_fmaak_f32 v40, v38, v40, 0x3c0887f9
	v_fmaak_f32 v40, v38, v40, 0x3d2aaa81
	v_fmaak_f32 v40, v38, v40, 0x3e2aaaab
	v_fma_f32 v40, v38, v40, 0.5
	v_ldexp_f32 v36, 1.0, v36
	v_mul_f32_e32 v40, v38, v40
	v_cndmask_b32_e32 v36, v36, v202, vcc
	v_fmac_f32_e32 v38, v38, v40
	v_add_f32_e32 v40, -1.0, v36
	v_fmac_f32_e32 v40, v36, v38
	v_add_f32_e32 v36, v40, v40
	v_cndmask_b32_e32 v36, v40, v36, vcc
	v_cmp_nlt_f32_e32 vcc, s22, v33
	v_exp_f32_e32 v35, v35
	s_nop 0
	v_cndmask_b32_e64 v36, v201, -v36, vcc
	v_cmp_gt_f32_e32 vcc, s23, v36
	v_mul_f32_e32 v38, 0x4f800000, v36
	s_nop 0
	v_cndmask_b32_e32 v36, v36, v38, vcc
	v_sqrt_f32_e32 v38, v36
	s_nop 0
	v_add_u32_e32 v40, -1, v38
	v_fma_f32 v41, -v40, v38, v36
	v_cmp_ge_f32_e64 s[0:1], 0, v41
	v_add_u32_e32 v41, 1, v38
	s_nop 0
	v_cndmask_b32_e64 v40, v38, v40, s[0:1]
	v_fma_f32 v38, -v41, v38, v36
	v_cmp_lt_f32_e64 s[0:1], 0, v38
	s_nop 1
	v_cndmask_b32_e64 v38, v40, v41, s[0:1]
	v_mul_f32_e32 v40, 0x37800000, v38
	v_cndmask_b32_e32 v38, v38, v40, vcc
	ds_read2_b32 v[40:41], v32 offset0:64 offset1:96
	v_cmp_class_f32_e32 vcc, v36, v193
	s_nop 1
	v_cndmask_b32_e32 v36, v38, v36, vcc
	v_cmp_ngt_f32_e32 vcc, s24, v33
	s_nop 1
	v_cndmask_b32_e32 v33, 1.0, v36, vcc
	v_mul_f32_e32 v33, v34, v33
	s_waitcnt lgkmcnt(0)
	v_mul_f32_e32 v33, v40, v33
	ds_write_b32 v144, v35 offset:4352
	ds_write_b32 v144, v33 offset:41216
	v_add_f32_e32 v33, v58, v147
	v_mul_f32_e32 v33, 0xbfb8aa3b, v33
	v_exp_f32_e32 v33, v33
	v_add_f32_e32 v34, v42, v146
	v_mul_f32_e32 v34, 0xbfb8aa3b, v34
	v_exp_f32_e32 v34, v34
	v_add_f32_e32 v33, 1.0, v33
	v_rcp_f32_e32 v33, v33
	ds_read2_b32 v[56:57], v32 offset0:128 offset1:160
	v_add_f32_e32 v34, 1.0, v34
	v_rcp_f32_e32 v34, v34
	v_mul_f32_e32 v33, v33, v96
	v_mul_f32_e32 v35, 0x3fb8aa3b, v33
	v_add_f32_e32 v33, v33, v33
	v_mul_f32_e32 v36, 0x3fb8aa3b, v33
	v_rndne_f32_e32 v36, v36
	v_fmamk_f32 v38, v36, 0xbf317218, v33
	v_fmac_f32_e32 v38, 0x3102e308, v36
	v_fmamk_f32 v40, v38, 0x395133b1, v192
	v_cmp_eq_f32_e32 vcc, s21, v36
	v_cvt_i32_f32_e32 v36, v36
	v_fmaak_f32 v40, v38, v40, 0x3c0887f9
	v_fmaak_f32 v40, v38, v40, 0x3d2aaa81
	v_fmaak_f32 v40, v38, v40, 0x3e2aaaab
	v_fma_f32 v40, v38, v40, 0.5
	v_ldexp_f32 v36, 1.0, v36
	v_mul_f32_e32 v40, v38, v40
	v_cndmask_b32_e32 v36, v36, v202, vcc
	v_fmac_f32_e32 v38, v38, v40
	v_add_f32_e32 v40, -1.0, v36
	v_fmac_f32_e32 v40, v36, v38
	v_add_f32_e32 v36, v40, v40
	v_cndmask_b32_e32 v36, v40, v36, vcc
	v_cmp_nlt_f32_e32 vcc, s22, v33
	v_exp_f32_e32 v35, v35
	s_nop 0
	v_cndmask_b32_e64 v36, v201, -v36, vcc
	v_cmp_gt_f32_e32 vcc, s23, v36
	v_mul_f32_e32 v38, 0x4f800000, v36
	s_nop 0
	v_cndmask_b32_e32 v36, v36, v38, vcc
	v_sqrt_f32_e32 v38, v36
	s_nop 0
	v_add_u32_e32 v40, -1, v38
	v_fma_f32 v42, -v40, v38, v36
	v_cmp_ge_f32_e64 s[0:1], 0, v42
	v_add_u32_e32 v42, 1, v38
	s_nop 0
	v_cndmask_b32_e64 v40, v38, v40, s[0:1]
	v_fma_f32 v38, -v42, v38, v36
	v_cmp_lt_f32_e64 s[0:1], 0, v38
	s_nop 1
	v_cndmask_b32_e64 v38, v40, v42, s[0:1]
	v_mul_f32_e32 v40, 0x37800000, v38
	v_cndmask_b32_e32 v38, v38, v40, vcc
	v_cmp_class_f32_e32 vcc, v36, v193
	s_nop 1
	v_cndmask_b32_e32 v36, v38, v36, vcc
	v_cmp_ngt_f32_e32 vcc, s24, v33
	s_nop 1
	v_cndmask_b32_e32 v33, 1.0, v36, vcc
	v_mul_f32_e32 v33, v34, v33
	s_waitcnt lgkmcnt(0)
	v_mul_f32_e32 v33, v56, v33
	ds_write_b32 v144, v35 offset:4608
	ds_write_b32 v144, v33 offset:41472
	v_add_f32_e32 v33, v59, v147
	v_mul_f32_e32 v33, 0xbfb8aa3b, v33
	v_exp_f32_e32 v33, v33
	v_add_f32_e32 v34, v43, v146
	v_mul_f32_e32 v34, 0xbfb8aa3b, v34
	v_exp_f32_e32 v34, v34
	v_add_f32_e32 v33, 1.0, v33
	v_rcp_f32_e32 v33, v33
	v_add_f32_e32 v34, 1.0, v34
	v_rcp_f32_e32 v34, v34
	v_mul_f32_e32 v33, v33, v96
	v_mul_f32_e32 v35, 0x3fb8aa3b, v33
	v_add_f32_e32 v33, v33, v33
	v_mul_f32_e32 v36, 0x3fb8aa3b, v33
	v_rndne_f32_e32 v36, v36
	v_fmamk_f32 v38, v36, 0xbf317218, v33
	v_fmac_f32_e32 v38, 0x3102e308, v36
	v_fmamk_f32 v40, v38, 0x395133b1, v192
	v_cmp_eq_f32_e32 vcc, s21, v36
	v_cvt_i32_f32_e32 v36, v36
	v_fmaak_f32 v40, v38, v40, 0x3c0887f9
	v_fmaak_f32 v40, v38, v40, 0x3d2aaa81
	v_fmaak_f32 v40, v38, v40, 0x3e2aaaab
	v_fma_f32 v40, v38, v40, 0.5
	v_ldexp_f32 v36, 1.0, v36
	v_mul_f32_e32 v40, v38, v40
	v_cndmask_b32_e32 v36, v36, v202, vcc
	v_fmac_f32_e32 v38, v38, v40
	v_add_f32_e32 v40, -1.0, v36
	v_fmac_f32_e32 v40, v36, v38
	v_add_f32_e32 v36, v40, v40
	v_cndmask_b32_e32 v36, v40, v36, vcc
	v_cmp_nlt_f32_e32 vcc, s22, v33
	v_exp_f32_e32 v35, v35
	s_nop 0
	v_cndmask_b32_e64 v36, v201, -v36, vcc
	v_cmp_gt_f32_e32 vcc, s23, v36
	v_mul_f32_e32 v38, 0x4f800000, v36
	s_nop 0
	v_cndmask_b32_e32 v36, v36, v38, vcc
	v_sqrt_f32_e32 v38, v36
	s_nop 0
	v_add_u32_e32 v40, -1, v38
	v_fma_f32 v42, -v40, v38, v36
	v_cmp_ge_f32_e64 s[0:1], 0, v42
	v_add_u32_e32 v42, 1, v38
	s_nop 0
	v_cndmask_b32_e64 v40, v38, v40, s[0:1]
	v_fma_f32 v38, -v42, v38, v36
	v_cmp_lt_f32_e64 s[0:1], 0, v38
	s_nop 1
	v_cndmask_b32_e64 v38, v40, v42, s[0:1]
	v_mul_f32_e32 v40, 0x37800000, v38
	ds_read2_b32 v[42:43], v32 offset0:192 offset1:224
	v_cndmask_b32_e32 v38, v38, v40, vcc
	v_cmp_class_f32_e32 vcc, v36, v193
	s_nop 1
	v_cndmask_b32_e32 v36, v38, v36, vcc
	v_cmp_ngt_f32_e32 vcc, s24, v33
	s_nop 1
	v_cndmask_b32_e32 v33, 1.0, v36, vcc
	v_mul_f32_e32 v33, v34, v33
	s_waitcnt lgkmcnt(0)
	v_mul_f32_e32 v32, v42, v33
	ds_write_b32 v144, v35 offset:4864
	ds_write_b32 v144, v32 offset:41728
	v_add_f32_e32 v32, v60, v147
	v_mul_f32_e32 v32, 0xbfb8aa3b, v32
	v_exp_f32_e32 v32, v32
	v_add_f32_e32 v33, v44, v146
	v_mul_f32_e32 v33, 0xbfb8aa3b, v33
	v_exp_f32_e32 v33, v33
	v_add_f32_e32 v32, 1.0, v32
	v_rcp_f32_e32 v32, v32
	v_add_f32_e32 v33, 1.0, v33
	v_rcp_f32_e32 v33, v33
	v_mul_f32_e32 v32, v32, v96
	v_mul_f32_e32 v34, 0x3fb8aa3b, v32
	v_add_f32_e32 v32, v32, v32
	v_mul_f32_e32 v35, 0x3fb8aa3b, v32
	v_rndne_f32_e32 v35, v35
	v_fmamk_f32 v36, v35, 0xbf317218, v32
	v_fmac_f32_e32 v36, 0x3102e308, v35
	v_fmamk_f32 v38, v36, 0x395133b1, v192
	v_cmp_eq_f32_e32 vcc, s21, v35
	v_cvt_i32_f32_e32 v35, v35
	v_fmaak_f32 v38, v36, v38, 0x3c0887f9
	v_fmaak_f32 v38, v36, v38, 0x3d2aaa81
	v_fmaak_f32 v38, v36, v38, 0x3e2aaaab
	v_fma_f32 v38, v36, v38, 0.5
	v_ldexp_f32 v35, 1.0, v35
	v_mul_f32_e32 v38, v36, v38
	v_cndmask_b32_e32 v35, v35, v202, vcc
	v_fmac_f32_e32 v36, v36, v38
	v_add_f32_e32 v38, -1.0, v35
	v_fmac_f32_e32 v38, v35, v36
	v_add_f32_e32 v35, v38, v38
	v_cndmask_b32_e32 v35, v38, v35, vcc
	v_cmp_nlt_f32_e32 vcc, s22, v32
	v_exp_f32_e32 v34, v34
	s_nop 0
	v_cndmask_b32_e64 v35, v201, -v35, vcc
	v_cmp_gt_f32_e32 vcc, s23, v35
	v_mul_f32_e32 v36, 0x4f800000, v35
	s_nop 0
	v_cndmask_b32_e32 v35, v35, v36, vcc
	v_sqrt_f32_e32 v36, v35
	s_nop 0
	v_add_u32_e32 v38, -1, v36
	v_fma_f32 v40, -v38, v36, v35
	v_cmp_ge_f32_e64 s[0:1], 0, v40
	v_add_u32_e32 v40, 1, v36
	s_nop 0
	v_cndmask_b32_e64 v38, v36, v38, s[0:1]
	v_fma_f32 v36, -v40, v36, v35
	v_cmp_lt_f32_e64 s[0:1], 0, v36
	s_nop 1
	v_cndmask_b32_e64 v36, v38, v40, s[0:1]
	v_mul_f32_e32 v38, 0x37800000, v36
	v_cndmask_b32_e32 v36, v36, v38, vcc
	v_cmp_class_f32_e32 vcc, v35, v193
	s_nop 1
	v_cndmask_b32_e32 v35, v36, v35, vcc
	v_cmp_ngt_f32_e32 vcc, s24, v32
	s_nop 1
	v_cndmask_b32_e32 v32, 1.0, v35, vcc
	v_mul_f32_e32 v32, v33, v32
	v_add_u32_e32 v33, 0xa800, v144
	ds_read2_b32 v[58:59], v33 offset1:32
	s_waitcnt lgkmcnt(0)
	v_mul_f32_e32 v32, v58, v32
	ds_write_b32 v144, v34 offset:6144
	ds_write_b32 v144, v32 offset:43008
	v_add_f32_e32 v32, v61, v147
	v_mul_f32_e32 v32, 0xbfb8aa3b, v32
	v_exp_f32_e32 v32, v32
	v_add_f32_e32 v34, v45, v146
	v_mul_f32_e32 v34, 0xbfb8aa3b, v34
	v_exp_f32_e32 v34, v34
	v_add_f32_e32 v32, 1.0, v32
	v_rcp_f32_e32 v32, v32
	ds_read2_b32 v[44:45], v33 offset0:64 offset1:96
	v_add_f32_e32 v34, 1.0, v34
	v_rcp_f32_e32 v34, v34
	v_mul_f32_e32 v32, v32, v96
	v_mul_f32_e32 v35, 0x3fb8aa3b, v32
	v_add_f32_e32 v32, v32, v32
	v_mul_f32_e32 v36, 0x3fb8aa3b, v32
	v_rndne_f32_e32 v36, v36
	v_fmamk_f32 v38, v36, 0xbf317218, v32
	v_fmac_f32_e32 v38, 0x3102e308, v36
	v_fmamk_f32 v40, v38, 0x395133b1, v192
	v_cmp_eq_f32_e32 vcc, s21, v36
	v_cvt_i32_f32_e32 v36, v36
	v_fmaak_f32 v40, v38, v40, 0x3c0887f9
	v_fmaak_f32 v40, v38, v40, 0x3d2aaa81
	v_fmaak_f32 v40, v38, v40, 0x3e2aaaab
	v_fma_f32 v40, v38, v40, 0.5
	v_ldexp_f32 v36, 1.0, v36
	v_mul_f32_e32 v40, v38, v40
	v_cndmask_b32_e32 v36, v36, v202, vcc
	v_fmac_f32_e32 v38, v38, v40
	v_add_f32_e32 v40, -1.0, v36
	v_fmac_f32_e32 v40, v36, v38
	v_add_f32_e32 v36, v40, v40
	v_cndmask_b32_e32 v36, v40, v36, vcc
	v_cmp_nlt_f32_e32 vcc, s22, v32
	v_exp_f32_e32 v35, v35
	s_nop 0
	v_cndmask_b32_e64 v36, v201, -v36, vcc
	v_cmp_gt_f32_e32 vcc, s23, v36
	v_mul_f32_e32 v38, 0x4f800000, v36
	s_nop 0
	v_cndmask_b32_e32 v36, v36, v38, vcc
	v_sqrt_f32_e32 v38, v36
	s_nop 0
	v_add_u32_e32 v40, -1, v38
	v_fma_f32 v42, -v40, v38, v36
	v_cmp_ge_f32_e64 s[0:1], 0, v42
	v_add_u32_e32 v42, 1, v38
	s_nop 0
	v_cndmask_b32_e64 v40, v38, v40, s[0:1]
	v_fma_f32 v38, -v42, v38, v36
	v_cmp_lt_f32_e64 s[0:1], 0, v38
	s_nop 1
	v_cndmask_b32_e64 v38, v40, v42, s[0:1]
	v_mul_f32_e32 v40, 0x37800000, v38
	v_cndmask_b32_e32 v38, v38, v40, vcc
	v_cmp_class_f32_e32 vcc, v36, v193
	s_nop 1
	v_cndmask_b32_e32 v36, v38, v36, vcc
	v_cmp_ngt_f32_e32 vcc, s24, v32
	s_nop 1
	v_cndmask_b32_e32 v32, 1.0, v36, vcc
	v_mul_f32_e32 v32, v34, v32
	s_waitcnt lgkmcnt(0)
	v_mul_f32_e32 v32, v44, v32
	ds_write_b32 v144, v35 offset:6400
	ds_write_b32 v144, v32 offset:43264
	v_add_f32_e32 v32, v62, v147
	v_mul_f32_e32 v32, 0xbfb8aa3b, v32
	v_exp_f32_e32 v32, v32
	v_add_f32_e32 v34, v46, v146
	v_mul_f32_e32 v34, 0xbfb8aa3b, v34
	v_exp_f32_e32 v34, v34
	v_add_f32_e32 v32, 1.0, v32
	v_rcp_f32_e32 v32, v32
	v_add_f32_e32 v34, 1.0, v34
	v_rcp_f32_e32 v34, v34
	v_mul_f32_e32 v32, v32, v96
	v_mul_f32_e32 v35, 0x3fb8aa3b, v32
	v_add_f32_e32 v32, v32, v32
	v_exp_f32_e32 v36, v35
	v_mul_f32_e32 v35, 0x3fb8aa3b, v32
	v_rndne_f32_e32 v35, v35
	v_fmamk_f32 v38, v35, 0xbf317218, v32
	v_fmac_f32_e32 v38, 0x3102e308, v35
	v_fmamk_f32 v40, v38, 0x395133b1, v192
	v_cmp_eq_f32_e32 vcc, s21, v35
	v_cvt_i32_f32_e32 v35, v35
	v_fmaak_f32 v40, v38, v40, 0x3c0887f9
	v_fmaak_f32 v40, v38, v40, 0x3d2aaa81
	v_fmaak_f32 v40, v38, v40, 0x3e2aaaab
	v_fma_f32 v40, v38, v40, 0.5
	v_ldexp_f32 v35, 1.0, v35
	v_mul_f32_e32 v40, v38, v40
	v_cndmask_b32_e32 v35, v35, v202, vcc
	v_fmac_f32_e32 v38, v38, v40
	v_add_f32_e32 v40, -1.0, v35
	v_fmac_f32_e32 v40, v35, v38
	v_add_f32_e32 v35, v40, v40
	v_cndmask_b32_e32 v35, v40, v35, vcc
	v_cmp_nlt_f32_e32 vcc, s22, v32
	s_nop 1
	v_cndmask_b32_e64 v35, v201, -v35, vcc
	v_cmp_gt_f32_e32 vcc, s23, v35
	v_mul_f32_e32 v38, 0x4f800000, v35
	s_nop 0
	v_cndmask_b32_e32 v35, v35, v38, vcc
	v_sqrt_f32_e32 v38, v35
	s_nop 0
	v_add_u32_e32 v40, -1, v38
	v_fma_f32 v42, -v40, v38, v35
	v_cmp_ge_f32_e64 s[0:1], 0, v42
	v_add_u32_e32 v42, 1, v38
	s_nop 0
	v_cndmask_b32_e64 v40, v38, v40, s[0:1]
	v_fma_f32 v38, -v42, v38, v35
	v_cmp_lt_f32_e64 s[0:1], 0, v38
	s_nop 1
	v_cndmask_b32_e64 v38, v40, v42, s[0:1]
	v_mul_f32_e32 v40, 0x37800000, v38
	v_cndmask_b32_e32 v38, v38, v40, vcc
	v_cmp_class_f32_e32 vcc, v35, v193
	s_nop 1
	v_cndmask_b32_e32 v35, v38, v35, vcc
	v_cmp_ngt_f32_e32 vcc, s24, v32
	s_nop 1
	v_cndmask_b32_e32 v32, 1.0, v35, vcc
	v_mul_f32_e32 v32, v34, v32
	ds_read2_b32 v[34:35], v33 offset0:128 offset1:160
	s_waitcnt lgkmcnt(0)
	v_mul_f32_e32 v32, v34, v32
	ds_write_b32 v144, v36 offset:6656
	ds_write_b32 v144, v32 offset:43520
	v_add_f32_e32 v32, v63, v147
	v_mul_f32_e32 v32, 0xbfb8aa3b, v32
	v_exp_f32_e32 v32, v32
	v_add_f32_e32 v34, v47, v146
	v_mul_f32_e32 v34, 0xbfb8aa3b, v34
	v_exp_f32_e32 v34, v34
	v_add_f32_e32 v32, 1.0, v32
	v_rcp_f32_e32 v32, v32
	v_add_f32_e32 v34, 1.0, v34
	v_rcp_f32_e32 v36, v34
	v_mul_f32_e32 v32, v32, v96
	v_mul_f32_e32 v34, 0x3fb8aa3b, v32
	v_add_f32_e32 v32, v32, v32
	v_mul_f32_e32 v38, 0x3fb8aa3b, v32
	v_rndne_f32_e32 v38, v38
	v_fmamk_f32 v40, v38, 0xbf317218, v32
	v_fmac_f32_e32 v40, 0x3102e308, v38
	v_fmamk_f32 v42, v40, 0x395133b1, v192
	v_cmp_eq_f32_e32 vcc, s21, v38
	v_cvt_i32_f32_e32 v38, v38
	v_fmaak_f32 v42, v40, v42, 0x3c0887f9
	v_fmaak_f32 v42, v40, v42, 0x3d2aaa81
	v_fmaak_f32 v42, v40, v42, 0x3e2aaaab
	v_fma_f32 v42, v40, v42, 0.5
	v_ldexp_f32 v38, 1.0, v38
	v_mul_f32_e32 v42, v40, v42
	v_cndmask_b32_e32 v38, v38, v202, vcc
	v_fmac_f32_e32 v40, v40, v42
	v_add_f32_e32 v42, -1.0, v38
	v_fmac_f32_e32 v42, v38, v40
	v_add_f32_e32 v38, v42, v42
	v_cndmask_b32_e32 v38, v42, v38, vcc
	v_cmp_nlt_f32_e32 vcc, s22, v32
	v_add_u32_e32 v96, s3, v145
	v_lshlrev_b64 v[46:47], 2, v[96:97]
	v_cndmask_b32_e64 v38, v201, -v38, vcc
	v_cmp_gt_f32_e32 vcc, s23, v38
	v_mul_f32_e32 v40, 0x4f800000, v38
	v_lshl_add_u64 v[60:61], s[18:19], 0, v[46:47]
	v_cndmask_b32_e32 v38, v38, v40, vcc
	v_sqrt_f32_e32 v40, v38
	v_exp_f32_e32 v34, v34
	s_movk_i32 s18, 0x1600
	s_mov_b32 s19, 0x2c000
	v_add_u32_e32 v42, -1, v40
	v_fma_f32 v44, -v42, v40, v38
	v_cmp_ge_f32_e64 s[0:1], 0, v44
	v_add_u32_e32 v44, 1, v40
	s_nop 0
	v_cndmask_b32_e64 v42, v40, v42, s[0:1]
	v_fma_f32 v40, -v44, v40, v38
	v_cmp_lt_f32_e64 s[0:1], 0, v40
	s_nop 1
	v_cndmask_b32_e64 v40, v42, v44, s[0:1]
	v_mul_f32_e32 v42, 0x37800000, v40
	v_cndmask_b32_e32 v40, v40, v42, vcc
	v_cmp_class_f32_e32 vcc, v38, v193
	s_nop 1
	v_cndmask_b32_e32 v38, v40, v38, vcc
	v_cmp_ngt_f32_e32 vcc, s24, v32
	s_nop 1
	v_cndmask_b32_e32 v32, 1.0, v38, vcc
	v_mul_f32_e32 v36, v36, v32
	ds_read2_b32 v[32:33], v33 offset0:192 offset1:224
	s_waitcnt lgkmcnt(0)
	v_mul_f32_e32 v32, v32, v36
	ds_write_b32 v144, v32 offset:43776
	v_mov_b32_e32 v32, v226
	s_waitcnt vmcnt(0)
	v_mul_f32_e32 v32, 0xbfb8aa3b, v32
	v_exp_f32_e32 v32, v32
	s_nop 0
	v_add_f32_e32 v36, 1.0, v32
	v_add_f32_e32 v38, -1.0, v36
	v_sub_f32_e32 v40, v38, v36
	v_add_f32_e32 v40, 1.0, v40
	v_sub_f32_e32 v38, v32, v38
	v_add_f32_e32 v38, v38, v40
	v_frexp_mant_f32_e32 v40, v36
	v_cvt_f64_f32_e32 v[60:61], v36
	v_cmp_gt_f32_e32 vcc, s8, v40
	v_frexp_exp_i32_f64_e32 v40, v[60:61]
	s_nop 0
	v_subbrev_co_u32_e32 v40, vcc, 0, v40, vcc
	v_sub_u32_e32 v42, 0, v40
	v_ldexp_f32 v36, v36, v42
	v_ldexp_f32 v38, v38, v42
	v_add_f32_e32 v42, -1.0, v36
	v_add_f32_e32 v48, 1.0, v36
	v_add_f32_e32 v44, 1.0, v42
	v_add_f32_e32 v50, -1.0, v48
	v_sub_f32_e32 v44, v36, v44
	v_sub_f32_e32 v36, v36, v50
	v_add_f32_e32 v36, v38, v36
	v_add_f32_e32 v44, v38, v44
	v_add_f32_e32 v38, v48, v36
	v_sub_f32_e32 v48, v38, v48
	v_sub_f32_e32 v36, v36, v48
	v_rcp_f32_e32 v48, v38
	v_add_f32_e32 v61, v42, v44
	v_sub_f32_e32 v42, v61, v42
	v_sub_f32_e32 v42, v44, v42
	v_mul_f32_e32 v44, v61, v48
	v_mul_f32_e32 v62, v38, v44
	v_fma_f32 v146, v44, v38, -v62
	v_fmac_f32_e32 v146, v44, v36
	v_add_f32_e32 v60, v62, v146
	v_sub_f32_e32 v63, v61, v60
	v_pk_add_f32 v[148:149], v[60:61], v[62:63] neg_lo:[0,1] neg_hi:[0,1]
	v_mov_b32_e32 v147, v60
	v_pk_add_f32 v[60:61], v[148:149], v[146:147] neg_lo:[0,1] neg_hi:[0,1]
	v_cmp_neq_f32_e32 vcc, s10, v32
	v_add_f32_e32 v42, v42, v61
	v_add_f32_e32 v42, v60, v42
	v_add_f32_e32 v61, v63, v42
	v_mul_f32_e32 v50, v48, v61
	v_mul_f32_e32 v62, v38, v50
	v_fma_f32 v146, v50, v38, -v62
	v_fmac_f32_e32 v146, v50, v36
	v_add_f32_e32 v60, v62, v146
	v_sub_f32_e32 v36, v63, v61
	v_sub_f32_e32 v63, v61, v60
	v_pk_add_f32 v[148:149], v[60:61], v[62:63] neg_lo:[0,1] neg_hi:[0,1]
	v_mov_b32_e32 v147, v60
	v_add_f32_e32 v36, v42, v36
	v_pk_add_f32 v[60:61], v[148:149], v[146:147] neg_lo:[0,1] neg_hi:[0,1]
	v_add_f32_e32 v38, v44, v50
	v_add_f32_e32 v36, v36, v61
	v_add_f32_e32 v36, v60, v36
	v_add_f32_e32 v36, v63, v36
	v_sub_f32_e32 v42, v38, v44
	v_mul_f32_e32 v36, v48, v36
	v_sub_f32_e32 v42, v50, v42
	v_add_f32_e32 v36, v42, v36
	v_add_f32_e32 v42, v38, v36
	v_cvt_f32_i32_e32 v60, v40
	v_mul_f32_e32 v44, v42, v42
	v_fmamk_f32 v48, v44, 0x3e9b6dac, v191
	v_fmaak_f32 v169, v44, v48, 0x3f2aaada
	v_mul_f32_e32 v61, v42, v44
	v_pk_mul_f32 v[146:147], v[60:61], v[168:169]
	v_ldexp_f32 v63, v42, 1
	v_fma_f32 v62, v60, s9, -v146
	v_fmac_f32_e32 v62, 0xb102e308, v60
	v_sub_f32_e32 v38, v42, v38
	v_pk_add_f32 v[60:61], v[146:147], v[62:63]
	v_sub_f32_e32 v36, v36, v38
	v_sub_f32_e32 v38, v61, v63
	v_ldexp_f32 v36, v36, 1
	v_sub_f32_e32 v38, v147, v38
	v_add_f32_e32 v149, v36, v38
	v_mov_b32_e32 v148, v146
	v_pk_add_f32 v[146:147], v[60:61], v[146:147] neg_lo:[0,1] neg_hi:[0,1]
	v_pk_add_f32 v[150:151], v[60:61], v[148:149]
	v_mov_b32_e32 v63, v60
	v_mov_b32_e32 v147, v151
	v_pk_add_f32 v[152:153], v[62:63], v[146:147] neg_lo:[0,1] neg_hi:[0,1]
	v_pk_add_f32 v[62:63], v[62:63], v[146:147]
	v_mov_b32_e32 v148, v149
	v_pk_add_f32 v[146:147], v[62:63], v[60:61] op_sel:[1,0] op_sel_hi:[0,1] neg_lo:[0,1] neg_hi:[0,1]
	v_pk_add_f32 v[154:155], v[150:151], v[146:147] op_sel_hi:[1,0] neg_lo:[0,1] neg_hi:[0,1]
	v_mov_b32_e32 v150, v151
	v_mov_b32_e32 v151, v63
	v_pk_mov_b32 v[146:147], v[60:61], v[146:147] op_sel:[1,0]
	v_mov_b32_e32 v149, v60
	v_pk_add_f32 v[146:147], v[150:151], v[146:147] neg_lo:[0,1] neg_hi:[0,1]
	v_mov_b32_e32 v154, v152
	v_pk_add_f32 v[60:61], v[148:149], v[146:147] neg_lo:[0,1] neg_hi:[0,1]
	v_mov_b32_e32 v153, v63
	v_pk_add_f32 v[146:147], v[154:155], v[60:61]
	v_readlane_b32 s10, v248, 33
	v_pk_add_f32 v[148:149], v[146:147], v[146:147] op_sel:[0,1] op_sel_hi:[1,0]
	s_nop 0
	v_pk_add_f32 v[62:63], v[62:63], v[148:149] op_sel:[1,0] op_sel_hi:[0,1]
	v_mov_b32_e32 v147, v62
	v_pk_add_f32 v[150:151], v[146:147], v[152:153] neg_lo:[0,1] neg_hi:[0,1]
	v_mov_b32_e32 v61, v148
	v_sub_f32_e32 v36, v146, v150
	v_pk_add_f32 v[60:61], v[60:61], v[150:151] neg_lo:[0,1] neg_hi:[0,1]
	v_sub_f32_e32 v36, v152, v36
	v_add_f32_e32 v36, v60, v36
	v_add_f32_e32 v36, v36, v61
	v_add_f32_e32 v36, v62, v36
	v_cndmask_b32_e32 v36, v199, v36, vcc
	v_cmp_ngt_f32_e32 vcc, -1.0, v32
	v_lshl_add_u64 v[60:61], s[52:53], 0, v[46:47]
	v_lshl_add_u64 v[46:47], s[16:17], 0, v[46:47]
	v_cndmask_b32_e32 v36, v200, v36, vcc
	v_cmp_neq_f32_e32 vcc, -1.0, v32
	v_mov_b32_e32 v38, v227
	s_mov_b64 s[16:17], s[82:83]
	v_cndmask_b32_e32 v36, v201, v36, vcc
	v_cmp_lt_f32_e64 vcc, |v32|, s20
	s_mov_b32 s20, 0x58000
	s_waitcnt vmcnt(0)
	v_add_f32_e32 v0, v0, v38
	v_cndmask_b32_e32 v32, v36, v32, vcc
	v_mov_b32_e32 v36, v228
	v_mul_f32_e32 v32, 0xc1000000, v32
	v_mul_f32_e32 v0, 0xbfb8aa3b, v0
	v_exp_f32_e32 v0, v0
	v_add_f32_e32 v1, v1, v38
	v_mul_f32_e32 v1, 0xbfb8aa3b, v1
	v_exp_f32_e32 v1, v1
	v_add_f32_e32 v0, 1.0, v0
	v_rcp_f32_e32 v0, v0
	v_add_f32_e32 v1, 1.0, v1
	v_rcp_f32_e32 v1, v1
	s_waitcnt vmcnt(0)
	v_add_f32_e32 v16, v16, v36
	v_mul_f32_e32 v16, 0xbfb8aa3b, v16
	v_exp_f32_e32 v16, v16
	s_nop 0
	v_add_f32_e32 v16, 1.0, v16
	v_rcp_f32_e32 v16, v16
	s_nop 0
	v_mul_f32_e32 v16, v16, v32
	v_mul_f32_e32 v40, 0x3fb8aa3b, v16
	v_add_f32_e32 v16, v16, v16
	v_mul_f32_e32 v42, 0x3fb8aa3b, v16
	v_rndne_f32_e32 v42, v42
	v_fmamk_f32 v44, v42, 0xbf317218, v16
	v_fmac_f32_e32 v44, 0x3102e308, v42
	v_fmamk_f32 v46, v44, 0x395133b1, v192
	v_cmp_eq_f32_e32 vcc, s21, v42
	v_cvt_i32_f32_e32 v42, v42
	v_fmaak_f32 v46, v44, v46, 0x3c0887f9
	v_fmaak_f32 v46, v44, v46, 0x3d2aaa81
	v_fmaak_f32 v46, v44, v46, 0x3e2aaaab
	v_fma_f32 v46, v44, v46, 0.5
	v_ldexp_f32 v42, 1.0, v42
	v_mul_f32_e32 v46, v44, v46
	v_cndmask_b32_e32 v42, v42, v202, vcc
	v_fmac_f32_e32 v44, v44, v46
	v_add_f32_e32 v46, -1.0, v42
	v_fmac_f32_e32 v46, v42, v44
	v_add_f32_e32 v42, v46, v46
	v_cndmask_b32_e32 v42, v46, v42, vcc
	v_cmp_nlt_f32_e32 vcc, s22, v16
	v_exp_f32_e32 v40, v40
	s_nop 0
	v_cndmask_b32_e64 v42, v201, -v42, vcc
	v_cmp_gt_f32_e32 vcc, s23, v42
	v_mul_f32_e32 v44, 0x4f800000, v42
	s_nop 0
	v_cndmask_b32_e32 v42, v42, v44, vcc
	v_sqrt_f32_e32 v44, v42
	s_nop 0
	v_add_u32_e32 v46, -1, v44
	v_fma_f32 v47, -v46, v44, v42
	v_cmp_ge_f32_e64 s[0:1], 0, v47
	v_add_u32_e32 v47, 1, v44
	s_nop 0
	v_cndmask_b32_e64 v46, v44, v46, s[0:1]
	v_fma_f32 v44, -v47, v44, v42
	v_cmp_lt_f32_e64 s[0:1], 0, v44
	s_nop 1
	v_cndmask_b32_e64 v44, v46, v47, s[0:1]
	v_mul_f32_e32 v46, 0x37800000, v44
	v_cndmask_b32_e32 v44, v44, v46, vcc
	v_cmp_class_f32_e32 vcc, v42, v193
	s_nop 1
	v_cndmask_b32_e32 v42, v44, v42, vcc
	v_cmp_ngt_f32_e32 vcc, s24, v16
	s_nop 1
	v_cndmask_b32_e32 v16, 1.0, v42, vcc
	v_mul_f32_e32 v0, v0, v16
	v_mul_f32_e32 v0, v135, v0
	ds_write_b32 v144, v40 offset:128
	ds_write_b32 v144, v0 offset:36992
	v_add_f32_e32 v0, v17, v36
	v_mul_f32_e32 v0, 0xbfb8aa3b, v0
	v_exp_f32_e32 v0, v0
	s_nop 0
	v_add_f32_e32 v0, 1.0, v0
	v_rcp_f32_e32 v0, v0
	s_nop 0
	v_mul_f32_e32 v0, v0, v32
	v_mul_f32_e32 v16, 0x3fb8aa3b, v0
	v_add_f32_e32 v0, v0, v0
	v_mul_f32_e32 v17, 0x3fb8aa3b, v0
	v_rndne_f32_e32 v17, v17
	v_fmamk_f32 v40, v17, 0xbf317218, v0
	v_fmac_f32_e32 v40, 0x3102e308, v17
	v_fmamk_f32 v42, v40, 0x395133b1, v192
	v_cmp_eq_f32_e32 vcc, s21, v17
	v_cvt_i32_f32_e32 v17, v17
	v_fmaak_f32 v42, v40, v42, 0x3c0887f9
	v_fmaak_f32 v42, v40, v42, 0x3d2aaa81
	v_fmaak_f32 v42, v40, v42, 0x3e2aaaab
	v_fma_f32 v42, v40, v42, 0.5
	v_ldexp_f32 v17, 1.0, v17
	v_mul_f32_e32 v42, v40, v42
	v_cndmask_b32_e32 v17, v17, v202, vcc
	v_fmac_f32_e32 v40, v40, v42
	v_add_f32_e32 v42, -1.0, v17
	v_fmac_f32_e32 v42, v17, v40
	v_add_f32_e32 v17, v42, v42
	v_cndmask_b32_e32 v17, v42, v17, vcc
	v_cmp_nlt_f32_e32 vcc, s22, v0
	v_exp_f32_e32 v16, v16
	s_nop 0
	v_cndmask_b32_e64 v17, v201, -v17, vcc
	v_cmp_gt_f32_e32 vcc, s23, v17
	v_mul_f32_e32 v40, 0x4f800000, v17
	s_nop 0
	v_cndmask_b32_e32 v17, v17, v40, vcc
	v_sqrt_f32_e32 v40, v17
	s_nop 0
	v_add_u32_e32 v42, -1, v40
	v_fma_f32 v44, -v42, v40, v17
	v_cmp_ge_f32_e64 s[0:1], 0, v44
	v_add_u32_e32 v44, 1, v40
	s_nop 0
	v_cndmask_b32_e64 v42, v40, v42, s[0:1]
	v_fma_f32 v40, -v44, v40, v17
	v_cmp_lt_f32_e64 s[0:1], 0, v40
	s_nop 1
	v_cndmask_b32_e64 v40, v42, v44, s[0:1]
	v_mul_f32_e32 v42, 0x37800000, v40
	v_cndmask_b32_e32 v40, v40, v42, vcc
	v_cmp_class_f32_e32 vcc, v17, v193
	s_nop 1
	v_cndmask_b32_e32 v17, v40, v17, vcc
	v_cmp_ngt_f32_e32 vcc, s24, v0
	s_nop 1
	v_cndmask_b32_e32 v0, 1.0, v17, vcc
	v_mul_f32_e32 v0, v1, v0
	v_mul_f32_e32 v0, v49, v0
	ds_write_b32 v144, v16 offset:384
	ds_write_b32 v144, v0 offset:37248
	v_add_f32_e32 v0, v18, v36
	v_mul_f32_e32 v0, 0xbfb8aa3b, v0
	v_exp_f32_e32 v0, v0
	v_add_f32_e32 v1, v2, v38
	v_mul_f32_e32 v1, 0xbfb8aa3b, v1
	v_exp_f32_e32 v1, v1
	v_add_f32_e32 v0, 1.0, v0
	v_rcp_f32_e32 v0, v0
	v_add_f32_e32 v1, 1.0, v1
	v_rcp_f32_e32 v1, v1
	v_mul_f32_e32 v0, v0, v32
	v_mul_f32_e32 v2, 0x3fb8aa3b, v0
	v_add_f32_e32 v0, v0, v0
	v_mul_f32_e32 v16, 0x3fb8aa3b, v0
	v_rndne_f32_e32 v16, v16
	v_fmamk_f32 v17, v16, 0xbf317218, v0
	v_fmac_f32_e32 v17, 0x3102e308, v16
	v_fmamk_f32 v18, v17, 0x395133b1, v192
	v_cmp_eq_f32_e32 vcc, s21, v16
	v_cvt_i32_f32_e32 v16, v16
	v_fmaak_f32 v18, v17, v18, 0x3c0887f9
	v_fmaak_f32 v18, v17, v18, 0x3d2aaa81
	v_fmaak_f32 v18, v17, v18, 0x3e2aaaab
	v_fma_f32 v18, v17, v18, 0.5
	v_ldexp_f32 v16, 1.0, v16
	v_mul_f32_e32 v18, v17, v18
	v_cndmask_b32_e32 v16, v16, v202, vcc
	v_fmac_f32_e32 v17, v17, v18
	v_add_f32_e32 v18, -1.0, v16
	v_fmac_f32_e32 v18, v16, v17
	v_add_f32_e32 v16, v18, v18
	v_cndmask_b32_e32 v16, v18, v16, vcc
	v_cmp_nlt_f32_e32 vcc, s22, v0
	v_exp_f32_e32 v2, v2
	s_nop 0
	v_cndmask_b32_e64 v16, v201, -v16, vcc
	v_cmp_gt_f32_e32 vcc, s23, v16
	v_mul_f32_e32 v17, 0x4f800000, v16
	s_nop 0
	v_cndmask_b32_e32 v16, v16, v17, vcc
	v_sqrt_f32_e32 v17, v16
	s_nop 0
	v_add_u32_e32 v18, -1, v17
	v_fma_f32 v40, -v18, v17, v16
	v_cmp_ge_f32_e64 s[0:1], 0, v40
	v_add_u32_e32 v40, 1, v17
	s_nop 0
	v_cndmask_b32_e64 v18, v17, v18, s[0:1]
	v_fma_f32 v17, -v40, v17, v16
	v_cmp_lt_f32_e64 s[0:1], 0, v17
	s_nop 1
	v_cndmask_b32_e64 v17, v18, v40, s[0:1]
	v_mul_f32_e32 v18, 0x37800000, v17
	v_cndmask_b32_e32 v17, v17, v18, vcc
	v_cmp_class_f32_e32 vcc, v16, v193
	s_nop 1
	v_cndmask_b32_e32 v16, v17, v16, vcc
	v_cmp_ngt_f32_e32 vcc, s24, v0
	s_nop 1
	v_cndmask_b32_e32 v0, 1.0, v16, vcc
	v_mul_f32_e32 v0, v1, v0
	v_mul_f32_e32 v0, v137, v0
	ds_write_b32 v144, v2 offset:640
	ds_write_b32 v144, v0 offset:37504
	v_add_f32_e32 v0, v19, v36
	v_mul_f32_e32 v0, 0xbfb8aa3b, v0
	v_exp_f32_e32 v0, v0
	v_add_f32_e32 v1, v3, v38
	v_mul_f32_e32 v1, 0xbfb8aa3b, v1
	v_exp_f32_e32 v1, v1
	v_add_f32_e32 v0, 1.0, v0
	v_rcp_f32_e32 v0, v0
	v_add_f32_e32 v1, 1.0, v1
	v_rcp_f32_e32 v1, v1
	v_mul_f32_e32 v0, v0, v32
	v_mul_f32_e32 v2, 0x3fb8aa3b, v0
	v_add_f32_e32 v0, v0, v0
	v_mul_f32_e32 v3, 0x3fb8aa3b, v0
	v_rndne_f32_e32 v3, v3
	v_fmamk_f32 v16, v3, 0xbf317218, v0
	v_fmac_f32_e32 v16, 0x3102e308, v3
	v_fmamk_f32 v17, v16, 0x395133b1, v192
	v_cmp_eq_f32_e32 vcc, s21, v3
	v_cvt_i32_f32_e32 v3, v3
	v_fmaak_f32 v17, v16, v17, 0x3c0887f9
	v_fmaak_f32 v17, v16, v17, 0x3d2aaa81
	v_fmaak_f32 v17, v16, v17, 0x3e2aaaab
	v_fma_f32 v17, v16, v17, 0.5
	v_ldexp_f32 v3, 1.0, v3
	v_mul_f32_e32 v17, v16, v17
	v_cndmask_b32_e32 v3, v3, v202, vcc
	v_fmac_f32_e32 v16, v16, v17
	v_add_f32_e32 v17, -1.0, v3
	v_fmac_f32_e32 v17, v3, v16
	v_add_f32_e32 v3, v17, v17
	v_cndmask_b32_e32 v3, v17, v3, vcc
	v_cmp_nlt_f32_e32 vcc, s22, v0
	v_exp_f32_e32 v2, v2
	s_nop 0
	v_cndmask_b32_e64 v3, v201, -v3, vcc
	v_cmp_gt_f32_e32 vcc, s23, v3
	v_mul_f32_e32 v16, 0x4f800000, v3
	s_nop 0
	v_cndmask_b32_e32 v3, v3, v16, vcc
	v_sqrt_f32_e32 v16, v3
	s_nop 0
	v_add_u32_e32 v17, -1, v16
	v_fma_f32 v18, -v17, v16, v3
	v_cmp_ge_f32_e64 s[0:1], 0, v18
	v_add_u32_e32 v18, 1, v16
	s_nop 0
	v_cndmask_b32_e64 v17, v16, v17, s[0:1]
	v_fma_f32 v16, -v18, v16, v3
	v_cmp_lt_f32_e64 s[0:1], 0, v16
	s_nop 1
	v_cndmask_b32_e64 v16, v17, v18, s[0:1]
	v_mul_f32_e32 v17, 0x37800000, v16
	v_cndmask_b32_e32 v16, v16, v17, vcc
	v_cmp_class_f32_e32 vcc, v3, v193
	s_nop 1
	v_cndmask_b32_e32 v3, v16, v3, vcc
	v_cmp_ngt_f32_e32 vcc, s24, v0
	s_nop 1
	v_cndmask_b32_e32 v0, 1.0, v3, vcc
	v_mul_f32_e32 v0, v1, v0
	v_mul_f32_e32 v0, v51, v0
	ds_write_b32 v144, v2 offset:896
	ds_write_b32 v144, v0 offset:37760
	v_add_f32_e32 v0, v20, v36
	v_mul_f32_e32 v0, 0xbfb8aa3b, v0
	v_exp_f32_e32 v0, v0
	v_add_f32_e32 v1, v4, v38
	v_mul_f32_e32 v1, 0xbfb8aa3b, v1
	v_exp_f32_e32 v1, v1
	v_add_f32_e32 v0, 1.0, v0
	v_rcp_f32_e32 v0, v0
	v_add_f32_e32 v1, 1.0, v1
	v_rcp_f32_e32 v1, v1
	v_mul_f32_e32 v0, v0, v32
	v_mul_f32_e32 v2, 0x3fb8aa3b, v0
	v_add_f32_e32 v0, v0, v0
	v_mul_f32_e32 v3, 0x3fb8aa3b, v0
	v_rndne_f32_e32 v3, v3
	v_fmamk_f32 v4, v3, 0xbf317218, v0
	v_fmac_f32_e32 v4, 0x3102e308, v3
	v_fmamk_f32 v16, v4, 0x395133b1, v192
	v_cmp_eq_f32_e32 vcc, s21, v3
	v_cvt_i32_f32_e32 v3, v3
	v_fmaak_f32 v16, v4, v16, 0x3c0887f9
	v_fmaak_f32 v16, v4, v16, 0x3d2aaa81
	v_fmaak_f32 v16, v4, v16, 0x3e2aaaab
	v_fma_f32 v16, v4, v16, 0.5
	v_ldexp_f32 v3, 1.0, v3
	v_mul_f32_e32 v16, v4, v16
	v_cndmask_b32_e32 v3, v3, v202, vcc
	v_fmac_f32_e32 v4, v4, v16
	v_add_f32_e32 v16, -1.0, v3
	v_fmac_f32_e32 v16, v3, v4
	v_add_f32_e32 v3, v16, v16
	v_cndmask_b32_e32 v3, v16, v3, vcc
	v_cmp_nlt_f32_e32 vcc, s22, v0
	v_exp_f32_e32 v2, v2
	s_nop 0
	v_cndmask_b32_e64 v3, v201, -v3, vcc
	v_cmp_gt_f32_e32 vcc, s23, v3
	v_mul_f32_e32 v4, 0x4f800000, v3
	s_nop 0
	v_cndmask_b32_e32 v3, v3, v4, vcc
	v_sqrt_f32_e32 v4, v3
	s_nop 0
	v_add_u32_e32 v16, -1, v4
	v_fma_f32 v17, -v16, v4, v3
	v_cmp_ge_f32_e64 s[0:1], 0, v17
	v_add_u32_e32 v17, 1, v4
	s_nop 0
	v_cndmask_b32_e64 v16, v4, v16, s[0:1]
	v_fma_f32 v4, -v17, v4, v3
	v_cmp_lt_f32_e64 s[0:1], 0, v4
	s_nop 1
	v_cndmask_b32_e64 v4, v16, v17, s[0:1]
	v_mul_f32_e32 v16, 0x37800000, v4
	v_cndmask_b32_e32 v4, v4, v16, vcc
	v_cmp_class_f32_e32 vcc, v3, v193
	s_nop 1
	v_cndmask_b32_e32 v3, v4, v3, vcc
	v_cmp_ngt_f32_e32 vcc, s24, v0
	s_nop 1
	v_cndmask_b32_e32 v0, 1.0, v3, vcc
	v_mul_f32_e32 v0, v1, v0
	v_mul_f32_e32 v0, v139, v0
	ds_write_b32 v144, v2 offset:2176
	ds_write_b32 v144, v0 offset:39040
	v_add_f32_e32 v0, v21, v36
	v_mul_f32_e32 v0, 0xbfb8aa3b, v0
	v_exp_f32_e32 v0, v0
	v_add_f32_e32 v1, v5, v38
	v_mul_f32_e32 v1, 0xbfb8aa3b, v1
	v_exp_f32_e32 v1, v1
	v_add_f32_e32 v0, 1.0, v0
	v_rcp_f32_e32 v0, v0
	v_add_f32_e32 v1, 1.0, v1
	v_rcp_f32_e32 v1, v1
	v_mul_f32_e32 v0, v0, v32
	v_mul_f32_e32 v2, 0x3fb8aa3b, v0
	v_add_f32_e32 v0, v0, v0
	v_mul_f32_e32 v3, 0x3fb8aa3b, v0
	v_rndne_f32_e32 v3, v3
	v_fmamk_f32 v4, v3, 0xbf317218, v0
	v_fmac_f32_e32 v4, 0x3102e308, v3
	v_fmamk_f32 v5, v4, 0x395133b1, v192
	v_cmp_eq_f32_e32 vcc, s21, v3
	v_cvt_i32_f32_e32 v3, v3
	v_fmaak_f32 v5, v4, v5, 0x3c0887f9
	v_fmaak_f32 v5, v4, v5, 0x3d2aaa81
	v_fmaak_f32 v5, v4, v5, 0x3e2aaaab
	v_fma_f32 v5, v4, v5, 0.5
	v_ldexp_f32 v3, 1.0, v3
	v_mul_f32_e32 v5, v4, v5
	v_cndmask_b32_e32 v3, v3, v202, vcc
	v_fmac_f32_e32 v4, v4, v5
	v_add_f32_e32 v5, -1.0, v3
	v_fmac_f32_e32 v5, v3, v4
	v_add_f32_e32 v3, v5, v5
	v_cndmask_b32_e32 v3, v5, v3, vcc
	v_cmp_nlt_f32_e32 vcc, s22, v0
	v_exp_f32_e32 v2, v2
	s_nop 0
	v_cndmask_b32_e64 v3, v201, -v3, vcc
	v_cmp_gt_f32_e32 vcc, s23, v3
	v_mul_f32_e32 v4, 0x4f800000, v3
	s_nop 0
	v_cndmask_b32_e32 v3, v3, v4, vcc
	v_sqrt_f32_e32 v4, v3
	s_nop 0
	v_add_u32_e32 v5, -1, v4
	v_fma_f32 v16, -v5, v4, v3
	v_cmp_ge_f32_e64 s[0:1], 0, v16
	v_add_u32_e32 v16, 1, v4
	s_nop 0
	v_cndmask_b32_e64 v5, v4, v5, s[0:1]
	v_fma_f32 v4, -v16, v4, v3
	v_cmp_lt_f32_e64 s[0:1], 0, v4
	s_nop 1
	v_cndmask_b32_e64 v4, v5, v16, s[0:1]
	v_mul_f32_e32 v5, 0x37800000, v4
	v_cndmask_b32_e32 v4, v4, v5, vcc
	v_cmp_class_f32_e32 vcc, v3, v193
	s_nop 1
	v_cndmask_b32_e32 v3, v4, v3, vcc
	v_cmp_ngt_f32_e32 vcc, s24, v0
	s_nop 1
	v_cndmask_b32_e32 v0, 1.0, v3, vcc
	v_mul_f32_e32 v0, v1, v0
	v_mul_f32_e32 v0, v37, v0
	ds_write_b32 v144, v2 offset:2432
	ds_write_b32 v144, v0 offset:39296
	v_add_f32_e32 v0, v22, v36
	v_mul_f32_e32 v0, 0xbfb8aa3b, v0
	v_exp_f32_e32 v0, v0
	v_add_f32_e32 v1, v6, v38
	v_mul_f32_e32 v1, 0xbfb8aa3b, v1
	v_exp_f32_e32 v1, v1
	v_add_f32_e32 v0, 1.0, v0
	v_rcp_f32_e32 v0, v0
	v_add_f32_e32 v1, 1.0, v1
	v_rcp_f32_e32 v1, v1
	v_mul_f32_e32 v0, v0, v32
	v_mul_f32_e32 v2, 0x3fb8aa3b, v0
	v_add_f32_e32 v0, v0, v0
	v_mul_f32_e32 v3, 0x3fb8aa3b, v0
	v_rndne_f32_e32 v3, v3
	v_fmamk_f32 v4, v3, 0xbf317218, v0
	v_fmac_f32_e32 v4, 0x3102e308, v3
	v_fmamk_f32 v5, v4, 0x395133b1, v192
	v_cmp_eq_f32_e32 vcc, s21, v3
	v_cvt_i32_f32_e32 v3, v3
	v_fmaak_f32 v5, v4, v5, 0x3c0887f9
	v_fmaak_f32 v5, v4, v5, 0x3d2aaa81
	v_fmaak_f32 v5, v4, v5, 0x3e2aaaab
	v_fma_f32 v5, v4, v5, 0.5
	v_ldexp_f32 v3, 1.0, v3
	v_mul_f32_e32 v5, v4, v5
	v_cndmask_b32_e32 v3, v3, v202, vcc
	v_fmac_f32_e32 v4, v4, v5
	v_add_f32_e32 v5, -1.0, v3
	v_fmac_f32_e32 v5, v3, v4
	v_add_f32_e32 v3, v5, v5
	v_cndmask_b32_e32 v3, v5, v3, vcc
	v_cmp_nlt_f32_e32 vcc, s22, v0
	v_exp_f32_e32 v2, v2
	s_nop 0
	v_cndmask_b32_e64 v3, v201, -v3, vcc
	v_cmp_gt_f32_e32 vcc, s23, v3
	v_mul_f32_e32 v4, 0x4f800000, v3
	s_nop 0
	v_cndmask_b32_e32 v3, v3, v4, vcc
	v_sqrt_f32_e32 v4, v3
	s_nop 0
	v_add_u32_e32 v5, -1, v4
	v_fma_f32 v6, -v5, v4, v3
	v_cmp_ge_f32_e64 s[0:1], 0, v6
	v_add_u32_e32 v6, 1, v4
	s_nop 0
	v_cndmask_b32_e64 v5, v4, v5, s[0:1]
	v_fma_f32 v4, -v6, v4, v3
	v_cmp_lt_f32_e64 s[0:1], 0, v4
	s_nop 1
	v_cndmask_b32_e64 v4, v5, v6, s[0:1]
	v_mul_f32_e32 v5, 0x37800000, v4
	v_cndmask_b32_e32 v4, v4, v5, vcc
	v_cmp_class_f32_e32 vcc, v3, v193
	s_nop 1
	v_cndmask_b32_e32 v3, v4, v3, vcc
	v_cmp_ngt_f32_e32 vcc, s24, v0
	s_nop 1
	v_cndmask_b32_e32 v0, 1.0, v3, vcc
	v_mul_f32_e32 v0, v1, v0
	v_mul_f32_e32 v0, v53, v0
	ds_write_b32 v144, v2 offset:2688
	ds_write_b32 v144, v0 offset:39552
	v_add_f32_e32 v0, v23, v36
	v_mul_f32_e32 v0, 0xbfb8aa3b, v0
	v_exp_f32_e32 v0, v0
	v_add_f32_e32 v1, v7, v38
	v_mul_f32_e32 v1, 0xbfb8aa3b, v1
	v_exp_f32_e32 v1, v1
	v_add_f32_e32 v0, 1.0, v0
	v_rcp_f32_e32 v0, v0
	v_add_f32_e32 v1, 1.0, v1
	v_rcp_f32_e32 v1, v1
	v_mul_f32_e32 v0, v0, v32
	v_mul_f32_e32 v2, 0x3fb8aa3b, v0
	v_add_f32_e32 v0, v0, v0
	v_mul_f32_e32 v3, 0x3fb8aa3b, v0
	v_rndne_f32_e32 v3, v3
	v_fmamk_f32 v4, v3, 0xbf317218, v0
	v_fmac_f32_e32 v4, 0x3102e308, v3
	v_fmamk_f32 v5, v4, 0x395133b1, v192
	v_cmp_eq_f32_e32 vcc, s21, v3
	v_cvt_i32_f32_e32 v3, v3
	v_fmaak_f32 v5, v4, v5, 0x3c0887f9
	v_fmaak_f32 v5, v4, v5, 0x3d2aaa81
	v_fmaak_f32 v5, v4, v5, 0x3e2aaaab
	v_fma_f32 v5, v4, v5, 0.5
	v_ldexp_f32 v3, 1.0, v3
	v_mul_f32_e32 v5, v4, v5
	v_cndmask_b32_e32 v3, v3, v202, vcc
	v_fmac_f32_e32 v4, v4, v5
	v_add_f32_e32 v5, -1.0, v3
	v_fmac_f32_e32 v5, v3, v4
	v_add_f32_e32 v3, v5, v5
	v_cndmask_b32_e32 v3, v5, v3, vcc
	v_cmp_nlt_f32_e32 vcc, s22, v0
	v_exp_f32_e32 v2, v2
	s_nop 0
	v_cndmask_b32_e64 v3, v201, -v3, vcc
	v_cmp_gt_f32_e32 vcc, s23, v3
	v_mul_f32_e32 v4, 0x4f800000, v3
	s_nop 0
	v_cndmask_b32_e32 v3, v3, v4, vcc
	v_sqrt_f32_e32 v4, v3
	s_nop 0
	v_add_u32_e32 v5, -1, v4
	v_fma_f32 v6, -v5, v4, v3
	v_cmp_ge_f32_e64 s[0:1], 0, v6
	v_add_u32_e32 v6, 1, v4
	s_nop 0
	v_cndmask_b32_e64 v5, v4, v5, s[0:1]
	v_fma_f32 v4, -v6, v4, v3
	v_cmp_lt_f32_e64 s[0:1], 0, v4
	s_nop 1
	v_cndmask_b32_e64 v4, v5, v6, s[0:1]
	v_mul_f32_e32 v5, 0x37800000, v4
	v_cndmask_b32_e32 v4, v4, v5, vcc
	v_cmp_class_f32_e32 vcc, v3, v193
	s_nop 1
	v_cndmask_b32_e32 v3, v4, v3, vcc
	v_cmp_ngt_f32_e32 vcc, s24, v0
	s_nop 1
	v_cndmask_b32_e32 v0, 1.0, v3, vcc
	v_mul_f32_e32 v0, v1, v0
	v_mul_f32_e32 v0, v39, v0
	ds_write_b32 v144, v2 offset:2944
	ds_write_b32 v144, v0 offset:39808
	v_add_f32_e32 v0, v24, v36
	v_mul_f32_e32 v0, 0xbfb8aa3b, v0
	v_exp_f32_e32 v0, v0
	v_add_f32_e32 v1, v8, v38
	v_mul_f32_e32 v1, 0xbfb8aa3b, v1
	v_exp_f32_e32 v1, v1
	v_add_f32_e32 v0, 1.0, v0
	v_rcp_f32_e32 v0, v0
	v_add_f32_e32 v1, 1.0, v1
	v_rcp_f32_e32 v1, v1
	v_mul_f32_e32 v0, v0, v32
	v_mul_f32_e32 v2, 0x3fb8aa3b, v0
	v_add_f32_e32 v0, v0, v0
	v_mul_f32_e32 v3, 0x3fb8aa3b, v0
	v_rndne_f32_e32 v3, v3
	v_fmamk_f32 v4, v3, 0xbf317218, v0
	v_fmac_f32_e32 v4, 0x3102e308, v3
	v_fmamk_f32 v5, v4, 0x395133b1, v192
	v_cmp_eq_f32_e32 vcc, s21, v3
	v_cvt_i32_f32_e32 v3, v3
	v_fmaak_f32 v5, v4, v5, 0x3c0887f9
	v_fmaak_f32 v5, v4, v5, 0x3d2aaa81
	v_fmaak_f32 v5, v4, v5, 0x3e2aaaab
	v_fma_f32 v5, v4, v5, 0.5
	v_ldexp_f32 v3, 1.0, v3
	v_mul_f32_e32 v5, v4, v5
	v_cndmask_b32_e32 v3, v3, v202, vcc
	v_fmac_f32_e32 v4, v4, v5
	v_add_f32_e32 v5, -1.0, v3
	v_fmac_f32_e32 v5, v3, v4
	v_add_f32_e32 v3, v5, v5
	v_cndmask_b32_e32 v3, v5, v3, vcc
	v_cmp_nlt_f32_e32 vcc, s22, v0
	v_exp_f32_e32 v2, v2
	s_nop 0
	v_cndmask_b32_e64 v3, v201, -v3, vcc
	v_cmp_gt_f32_e32 vcc, s23, v3
	v_mul_f32_e32 v4, 0x4f800000, v3
	s_nop 0
	v_cndmask_b32_e32 v3, v3, v4, vcc
	v_sqrt_f32_e32 v4, v3
	s_nop 0
	v_add_u32_e32 v5, -1, v4
	v_fma_f32 v6, -v5, v4, v3
	v_cmp_ge_f32_e64 s[0:1], 0, v6
	v_add_u32_e32 v6, 1, v4
	s_nop 0
	v_cndmask_b32_e64 v5, v4, v5, s[0:1]
	v_fma_f32 v4, -v6, v4, v3
	v_cmp_lt_f32_e64 s[0:1], 0, v4
	s_nop 1
	v_cndmask_b32_e64 v4, v5, v6, s[0:1]
	v_mul_f32_e32 v5, 0x37800000, v4
	v_cndmask_b32_e32 v4, v4, v5, vcc
	v_cmp_class_f32_e32 vcc, v3, v193
	s_nop 1
	v_cndmask_b32_e32 v3, v4, v3, vcc
	v_cmp_ngt_f32_e32 vcc, s24, v0
	s_nop 1
	v_cndmask_b32_e32 v0, 1.0, v3, vcc
	v_mul_f32_e32 v0, v1, v0
	v_mul_f32_e32 v0, v55, v0
	ds_write_b32 v144, v2 offset:4224
	ds_write_b32 v144, v0 offset:41088
	v_add_f32_e32 v0, v25, v36
	v_mul_f32_e32 v0, 0xbfb8aa3b, v0
	v_exp_f32_e32 v0, v0
	v_add_f32_e32 v1, v9, v38
	v_mul_f32_e32 v1, 0xbfb8aa3b, v1
	v_exp_f32_e32 v1, v1
	v_add_f32_e32 v0, 1.0, v0
	v_rcp_f32_e32 v0, v0
	v_add_f32_e32 v1, 1.0, v1
	v_rcp_f32_e32 v1, v1
	v_mul_f32_e32 v0, v0, v32
	v_mul_f32_e32 v2, 0x3fb8aa3b, v0
	v_add_f32_e32 v0, v0, v0
	v_mul_f32_e32 v3, 0x3fb8aa3b, v0
	v_rndne_f32_e32 v3, v3
	v_fmamk_f32 v4, v3, 0xbf317218, v0
	v_fmac_f32_e32 v4, 0x3102e308, v3
	v_fmamk_f32 v5, v4, 0x395133b1, v192
	v_cmp_eq_f32_e32 vcc, s21, v3
	v_cvt_i32_f32_e32 v3, v3
	v_fmaak_f32 v5, v4, v5, 0x3c0887f9
	v_fmaak_f32 v5, v4, v5, 0x3d2aaa81
	v_fmaak_f32 v5, v4, v5, 0x3e2aaaab
	v_fma_f32 v5, v4, v5, 0.5
	v_ldexp_f32 v3, 1.0, v3
	v_mul_f32_e32 v5, v4, v5
	v_cndmask_b32_e32 v3, v3, v202, vcc
	v_fmac_f32_e32 v4, v4, v5
	v_add_f32_e32 v5, -1.0, v3
	v_fmac_f32_e32 v5, v3, v4
	v_add_f32_e32 v3, v5, v5
	v_cndmask_b32_e32 v3, v5, v3, vcc
	v_cmp_nlt_f32_e32 vcc, s22, v0
	v_exp_f32_e32 v2, v2
	s_nop 0
	v_cndmask_b32_e64 v3, v201, -v3, vcc
	v_cmp_gt_f32_e32 vcc, s23, v3
	v_mul_f32_e32 v4, 0x4f800000, v3
	s_nop 0
	v_cndmask_b32_e32 v3, v3, v4, vcc
	v_sqrt_f32_e32 v4, v3
	s_nop 0
	v_add_u32_e32 v5, -1, v4
	v_fma_f32 v6, -v5, v4, v3
	v_cmp_ge_f32_e64 s[0:1], 0, v6
	v_add_u32_e32 v6, 1, v4
	s_nop 0
	v_cndmask_b32_e64 v5, v4, v5, s[0:1]
	v_fma_f32 v4, -v6, v4, v3
	v_cmp_lt_f32_e64 s[0:1], 0, v4
	s_nop 1
	v_cndmask_b32_e64 v4, v5, v6, s[0:1]
	v_mul_f32_e32 v5, 0x37800000, v4
	v_cndmask_b32_e32 v4, v4, v5, vcc
	v_cmp_class_f32_e32 vcc, v3, v193
	s_nop 1
	v_cndmask_b32_e32 v3, v4, v3, vcc
	v_cmp_ngt_f32_e32 vcc, s24, v0
	s_nop 1
	v_cndmask_b32_e32 v0, 1.0, v3, vcc
	v_mul_f32_e32 v0, v1, v0
	v_mul_f32_e32 v0, v41, v0
	ds_write_b32 v144, v2 offset:4480
	ds_write_b32 v144, v0 offset:41344
	v_add_f32_e32 v0, v26, v36
	v_mul_f32_e32 v0, 0xbfb8aa3b, v0
	v_exp_f32_e32 v0, v0
	v_add_f32_e32 v1, v10, v38
	v_mul_f32_e32 v1, 0xbfb8aa3b, v1
	v_exp_f32_e32 v1, v1
	v_add_f32_e32 v0, 1.0, v0
	v_rcp_f32_e32 v0, v0
	v_add_f32_e32 v1, 1.0, v1
	v_rcp_f32_e32 v1, v1
	v_mul_f32_e32 v0, v0, v32
	v_mul_f32_e32 v2, 0x3fb8aa3b, v0
	v_add_f32_e32 v0, v0, v0
	v_mul_f32_e32 v3, 0x3fb8aa3b, v0
	v_rndne_f32_e32 v3, v3
	v_fmamk_f32 v4, v3, 0xbf317218, v0
	v_fmac_f32_e32 v4, 0x3102e308, v3
	v_fmamk_f32 v5, v4, 0x395133b1, v192
	v_cmp_eq_f32_e32 vcc, s21, v3
	v_cvt_i32_f32_e32 v3, v3
	v_fmaak_f32 v5, v4, v5, 0x3c0887f9
	v_fmaak_f32 v5, v4, v5, 0x3d2aaa81
	v_fmaak_f32 v5, v4, v5, 0x3e2aaaab
	v_fma_f32 v5, v4, v5, 0.5
	v_ldexp_f32 v3, 1.0, v3
	v_mul_f32_e32 v5, v4, v5
	v_cndmask_b32_e32 v3, v3, v202, vcc
	v_fmac_f32_e32 v4, v4, v5
	v_add_f32_e32 v5, -1.0, v3
	v_fmac_f32_e32 v5, v3, v4
	v_add_f32_e32 v3, v5, v5
	v_cndmask_b32_e32 v3, v5, v3, vcc
	v_cmp_nlt_f32_e32 vcc, s22, v0
	v_exp_f32_e32 v2, v2
	s_nop 0
	v_cndmask_b32_e64 v3, v201, -v3, vcc
	v_cmp_gt_f32_e32 vcc, s23, v3
	v_mul_f32_e32 v4, 0x4f800000, v3
	s_nop 0
	v_cndmask_b32_e32 v3, v3, v4, vcc
	v_sqrt_f32_e32 v4, v3
	s_nop 0
	v_add_u32_e32 v5, -1, v4
	v_fma_f32 v6, -v5, v4, v3
	v_cmp_ge_f32_e64 s[0:1], 0, v6
	v_add_u32_e32 v6, 1, v4
	s_nop 0
	v_cndmask_b32_e64 v5, v4, v5, s[0:1]
	v_fma_f32 v4, -v6, v4, v3
	v_cmp_lt_f32_e64 s[0:1], 0, v4
	s_nop 1
	v_cndmask_b32_e64 v4, v5, v6, s[0:1]
	v_mul_f32_e32 v5, 0x37800000, v4
	v_cndmask_b32_e32 v4, v4, v5, vcc
	v_cmp_class_f32_e32 vcc, v3, v193
	s_nop 1
	v_cndmask_b32_e32 v3, v4, v3, vcc
	v_cmp_ngt_f32_e32 vcc, s24, v0
	s_nop 1
	v_cndmask_b32_e32 v0, 1.0, v3, vcc
	v_mul_f32_e32 v0, v1, v0
	v_mul_f32_e32 v0, v57, v0
	ds_write_b32 v144, v2 offset:4736
	ds_write_b32 v144, v0 offset:41600
	v_add_f32_e32 v0, v27, v36
	v_mul_f32_e32 v0, 0xbfb8aa3b, v0
	v_exp_f32_e32 v0, v0
	v_add_f32_e32 v1, v11, v38
	v_mul_f32_e32 v1, 0xbfb8aa3b, v1
	v_exp_f32_e32 v1, v1
	v_add_f32_e32 v0, 1.0, v0
	v_rcp_f32_e32 v0, v0
	v_add_f32_e32 v1, 1.0, v1
	v_rcp_f32_e32 v1, v1
	v_mul_f32_e32 v0, v0, v32
	v_mul_f32_e32 v2, 0x3fb8aa3b, v0
	v_add_f32_e32 v0, v0, v0
	v_mul_f32_e32 v3, 0x3fb8aa3b, v0
	v_rndne_f32_e32 v3, v3
	v_fmamk_f32 v4, v3, 0xbf317218, v0
	v_fmac_f32_e32 v4, 0x3102e308, v3
	v_fmamk_f32 v5, v4, 0x395133b1, v192
	v_cmp_eq_f32_e32 vcc, s21, v3
	v_cvt_i32_f32_e32 v3, v3
	v_fmaak_f32 v5, v4, v5, 0x3c0887f9
	v_fmaak_f32 v5, v4, v5, 0x3d2aaa81
	v_fmaak_f32 v5, v4, v5, 0x3e2aaaab
	v_fma_f32 v5, v4, v5, 0.5
	v_ldexp_f32 v3, 1.0, v3
	v_mul_f32_e32 v5, v4, v5
	v_cndmask_b32_e32 v3, v3, v202, vcc
	v_fmac_f32_e32 v4, v4, v5
	v_add_f32_e32 v5, -1.0, v3
	v_fmac_f32_e32 v5, v3, v4
	v_add_f32_e32 v3, v5, v5
	v_cndmask_b32_e32 v3, v5, v3, vcc
	v_cmp_nlt_f32_e32 vcc, s22, v0
	v_exp_f32_e32 v2, v2
	s_nop 0
	v_cndmask_b32_e64 v3, v201, -v3, vcc
	v_cmp_gt_f32_e32 vcc, s23, v3
	v_mul_f32_e32 v4, 0x4f800000, v3
	s_nop 0
	v_cndmask_b32_e32 v3, v3, v4, vcc
	v_sqrt_f32_e32 v4, v3
	s_nop 0
	v_add_u32_e32 v5, -1, v4
	v_fma_f32 v6, -v5, v4, v3
	v_cmp_ge_f32_e64 s[0:1], 0, v6
	v_add_u32_e32 v6, 1, v4
	s_nop 0
	v_cndmask_b32_e64 v5, v4, v5, s[0:1]
	v_fma_f32 v4, -v6, v4, v3
	v_cmp_lt_f32_e64 s[0:1], 0, v4
	s_nop 1
	v_cndmask_b32_e64 v4, v5, v6, s[0:1]
	v_mul_f32_e32 v5, 0x37800000, v4
	v_cndmask_b32_e32 v4, v4, v5, vcc
	v_cmp_class_f32_e32 vcc, v3, v193
	s_nop 1
	v_cndmask_b32_e32 v3, v4, v3, vcc
	v_cmp_ngt_f32_e32 vcc, s24, v0
	s_nop 1
	v_cndmask_b32_e32 v0, 1.0, v3, vcc
	v_mul_f32_e32 v0, v1, v0
	v_mul_f32_e32 v0, v43, v0
	ds_write_b32 v144, v2 offset:4992
	ds_write_b32 v144, v0 offset:41856
	v_add_f32_e32 v0, v28, v36
	v_mul_f32_e32 v0, 0xbfb8aa3b, v0
	v_exp_f32_e32 v0, v0
	v_add_f32_e32 v1, v12, v38
	v_mul_f32_e32 v1, 0xbfb8aa3b, v1
	v_exp_f32_e32 v1, v1
	v_add_f32_e32 v0, 1.0, v0
	v_rcp_f32_e32 v0, v0
	v_add_f32_e32 v1, 1.0, v1
	v_rcp_f32_e32 v1, v1
	v_mul_f32_e32 v0, v0, v32
	v_mul_f32_e32 v2, 0x3fb8aa3b, v0
	v_add_f32_e32 v0, v0, v0
	v_mul_f32_e32 v3, 0x3fb8aa3b, v0
	v_rndne_f32_e32 v3, v3
	v_fmamk_f32 v4, v3, 0xbf317218, v0
	v_fmac_f32_e32 v4, 0x3102e308, v3
	v_fmamk_f32 v5, v4, 0x395133b1, v192
	v_cmp_eq_f32_e32 vcc, s21, v3
	v_cvt_i32_f32_e32 v3, v3
	v_fmaak_f32 v5, v4, v5, 0x3c0887f9
	v_fmaak_f32 v5, v4, v5, 0x3d2aaa81
	v_fmaak_f32 v5, v4, v5, 0x3e2aaaab
	v_fma_f32 v5, v4, v5, 0.5
	v_ldexp_f32 v3, 1.0, v3
	v_mul_f32_e32 v5, v4, v5
	v_cndmask_b32_e32 v3, v3, v202, vcc
	v_fmac_f32_e32 v4, v4, v5
	v_add_f32_e32 v5, -1.0, v3
	v_fmac_f32_e32 v5, v3, v4
	v_add_f32_e32 v3, v5, v5
	v_cndmask_b32_e32 v3, v5, v3, vcc
	v_cmp_nlt_f32_e32 vcc, s22, v0
	v_exp_f32_e32 v2, v2
	s_nop 0
	v_cndmask_b32_e64 v3, v201, -v3, vcc
	v_cmp_gt_f32_e32 vcc, s23, v3
	v_mul_f32_e32 v4, 0x4f800000, v3
	s_nop 0
	v_cndmask_b32_e32 v3, v3, v4, vcc
	v_sqrt_f32_e32 v4, v3
	s_nop 0
	v_add_u32_e32 v5, -1, v4
	v_fma_f32 v6, -v5, v4, v3
	v_cmp_ge_f32_e64 s[0:1], 0, v6
	v_add_u32_e32 v6, 1, v4
	s_nop 0
	v_cndmask_b32_e64 v5, v4, v5, s[0:1]
	v_fma_f32 v4, -v6, v4, v3
	v_cmp_lt_f32_e64 s[0:1], 0, v4
	s_nop 1
	v_cndmask_b32_e64 v4, v5, v6, s[0:1]
	v_mul_f32_e32 v5, 0x37800000, v4
	v_cndmask_b32_e32 v4, v4, v5, vcc
	v_cmp_class_f32_e32 vcc, v3, v193
	s_nop 1
	v_cndmask_b32_e32 v3, v4, v3, vcc
	v_cmp_ngt_f32_e32 vcc, s24, v0
	s_nop 1
	v_cndmask_b32_e32 v0, 1.0, v3, vcc
	v_mul_f32_e32 v0, v1, v0
	v_mul_f32_e32 v0, v59, v0
	ds_write_b32 v144, v2 offset:6272
	ds_write_b32 v144, v0 offset:43136
	v_add_f32_e32 v0, v29, v36
	v_mul_f32_e32 v0, 0xbfb8aa3b, v0
	v_exp_f32_e32 v0, v0
	v_add_f32_e32 v1, v13, v38
	v_mul_f32_e32 v1, 0xbfb8aa3b, v1
	v_exp_f32_e32 v1, v1
	v_add_f32_e32 v0, 1.0, v0
	v_rcp_f32_e32 v0, v0
	v_add_f32_e32 v1, 1.0, v1
	v_rcp_f32_e32 v1, v1
	v_mul_f32_e32 v0, v0, v32
	v_mul_f32_e32 v2, 0x3fb8aa3b, v0
	v_add_f32_e32 v0, v0, v0
	v_mul_f32_e32 v3, 0x3fb8aa3b, v0
	v_rndne_f32_e32 v3, v3
	v_fmamk_f32 v4, v3, 0xbf317218, v0
	v_fmac_f32_e32 v4, 0x3102e308, v3
	v_fmamk_f32 v5, v4, 0x395133b1, v192
	v_cmp_eq_f32_e32 vcc, s21, v3
	v_cvt_i32_f32_e32 v3, v3
	v_fmaak_f32 v5, v4, v5, 0x3c0887f9
	v_fmaak_f32 v5, v4, v5, 0x3d2aaa81
	v_fmaak_f32 v5, v4, v5, 0x3e2aaaab
	v_fma_f32 v5, v4, v5, 0.5
	v_ldexp_f32 v3, 1.0, v3
	v_mul_f32_e32 v5, v4, v5
	v_cndmask_b32_e32 v3, v3, v202, vcc
	v_fmac_f32_e32 v4, v4, v5
	v_add_f32_e32 v5, -1.0, v3
	v_fmac_f32_e32 v5, v3, v4
	v_add_f32_e32 v3, v5, v5
	v_cndmask_b32_e32 v3, v5, v3, vcc
	v_cmp_nlt_f32_e32 vcc, s22, v0
	v_exp_f32_e32 v2, v2
	s_nop 0
	v_cndmask_b32_e64 v3, v201, -v3, vcc
	v_cmp_gt_f32_e32 vcc, s23, v3
	v_mul_f32_e32 v4, 0x4f800000, v3
	s_nop 0
	v_cndmask_b32_e32 v3, v3, v4, vcc
	v_sqrt_f32_e32 v4, v3
	s_nop 0
	v_add_u32_e32 v5, -1, v4
	v_fma_f32 v6, -v5, v4, v3
	v_cmp_ge_f32_e64 s[0:1], 0, v6
	v_add_u32_e32 v6, 1, v4
	s_nop 0
	v_cndmask_b32_e64 v5, v4, v5, s[0:1]
	v_fma_f32 v4, -v6, v4, v3
	v_cmp_lt_f32_e64 s[0:1], 0, v4
	s_nop 1
	v_cndmask_b32_e64 v4, v5, v6, s[0:1]
	v_mul_f32_e32 v5, 0x37800000, v4
	v_cndmask_b32_e32 v4, v4, v5, vcc
	v_cmp_class_f32_e32 vcc, v3, v193
	s_nop 1
	v_cndmask_b32_e32 v3, v4, v3, vcc
	v_cmp_ngt_f32_e32 vcc, s24, v0
	s_nop 1
	v_cndmask_b32_e32 v0, 1.0, v3, vcc
	v_mul_f32_e32 v0, v1, v0
	v_mul_f32_e32 v0, v45, v0
	ds_write_b32 v144, v2 offset:6528
	ds_write_b32 v144, v0 offset:43392
	v_add_f32_e32 v0, v30, v36
	v_mul_f32_e32 v0, 0xbfb8aa3b, v0
	v_exp_f32_e32 v0, v0
	v_add_f32_e32 v1, v14, v38
	v_mul_f32_e32 v1, 0xbfb8aa3b, v1
	v_exp_f32_e32 v1, v1
	v_add_f32_e32 v0, 1.0, v0
	v_rcp_f32_e32 v0, v0
	v_add_f32_e32 v1, 1.0, v1
	v_rcp_f32_e32 v1, v1
	v_mul_f32_e32 v0, v0, v32
	v_mul_f32_e32 v2, 0x3fb8aa3b, v0
	v_add_f32_e32 v0, v0, v0
	v_mul_f32_e32 v3, 0x3fb8aa3b, v0
	v_rndne_f32_e32 v3, v3
	v_fmamk_f32 v4, v3, 0xbf317218, v0
	v_fmac_f32_e32 v4, 0x3102e308, v3
	v_fmamk_f32 v5, v4, 0x395133b1, v192
	v_cmp_eq_f32_e32 vcc, s21, v3
	v_cvt_i32_f32_e32 v3, v3
	v_fmaak_f32 v5, v4, v5, 0x3c0887f9
	v_fmaak_f32 v5, v4, v5, 0x3d2aaa81
	v_fmaak_f32 v5, v4, v5, 0x3e2aaaab
	v_fma_f32 v5, v4, v5, 0.5
	v_ldexp_f32 v3, 1.0, v3
	v_mul_f32_e32 v5, v4, v5
	v_cndmask_b32_e32 v3, v3, v202, vcc
	v_fmac_f32_e32 v4, v4, v5
	v_add_f32_e32 v5, -1.0, v3
	v_fmac_f32_e32 v5, v3, v4
	v_add_f32_e32 v3, v5, v5
	v_cndmask_b32_e32 v3, v5, v3, vcc
	v_cmp_nlt_f32_e32 vcc, s22, v0
	v_exp_f32_e32 v2, v2
	s_nop 0
	v_cndmask_b32_e64 v3, v201, -v3, vcc
	v_cmp_gt_f32_e32 vcc, s23, v3
	v_mul_f32_e32 v4, 0x4f800000, v3
	s_nop 0
	v_cndmask_b32_e32 v3, v3, v4, vcc
	v_sqrt_f32_e32 v4, v3
	s_nop 0
	v_add_u32_e32 v5, -1, v4
	v_fma_f32 v6, -v5, v4, v3
	v_cmp_ge_f32_e64 s[0:1], 0, v6
	v_add_u32_e32 v6, 1, v4
	s_nop 0
	v_cndmask_b32_e64 v5, v4, v5, s[0:1]
	v_fma_f32 v4, -v6, v4, v3
	v_cmp_lt_f32_e64 s[0:1], 0, v4
	s_nop 1
	v_cndmask_b32_e64 v4, v5, v6, s[0:1]
	v_mul_f32_e32 v5, 0x37800000, v4
	v_cndmask_b32_e32 v4, v4, v5, vcc
	v_cmp_class_f32_e32 vcc, v3, v193
	s_nop 1
	v_cndmask_b32_e32 v3, v4, v3, vcc
	v_cmp_ngt_f32_e32 vcc, s24, v0
	s_nop 1
	v_cndmask_b32_e32 v0, 1.0, v3, vcc
	v_mul_f32_e32 v0, v1, v0
	v_mul_f32_e32 v0, v35, v0
	v_add_u32_e32 v1, 0x1800, v144
	ds_write2_b32 v1, v2, v34 offset0:160 offset1:192
	ds_write_b32 v144, v0 offset:43648
	v_add_f32_e32 v0, v31, v36
	v_mul_f32_e32 v0, 0xbfb8aa3b, v0
	v_exp_f32_e32 v0, v0
	v_add_f32_e32 v1, v15, v38
	v_mul_f32_e32 v1, 0xbfb8aa3b, v1
	v_exp_f32_e32 v1, v1
	v_add_f32_e32 v0, 1.0, v0
	v_rcp_f32_e32 v0, v0
	v_add_f32_e32 v1, 1.0, v1
	v_rcp_f32_e32 v1, v1
	v_mul_f32_e32 v0, v0, v32
	v_mul_f32_e32 v2, 0x3fb8aa3b, v0
	v_add_f32_e32 v0, v0, v0
	v_mul_f32_e32 v3, 0x3fb8aa3b, v0
	v_rndne_f32_e32 v3, v3
	v_fmamk_f32 v4, v3, 0xbf317218, v0
	v_fmac_f32_e32 v4, 0x3102e308, v3
	v_fmamk_f32 v5, v4, 0x395133b1, v192
	v_cmp_eq_f32_e32 vcc, s21, v3
	v_cvt_i32_f32_e32 v3, v3
	v_fmaak_f32 v5, v4, v5, 0x3c0887f9
	v_fmaak_f32 v5, v4, v5, 0x3d2aaa81
	v_fmaak_f32 v5, v4, v5, 0x3e2aaaab
	v_fma_f32 v5, v4, v5, 0.5
	v_ldexp_f32 v3, 1.0, v3
	v_mul_f32_e32 v5, v4, v5
	v_cndmask_b32_e32 v3, v3, v202, vcc
	v_fmac_f32_e32 v4, v4, v5
	v_add_f32_e32 v5, -1.0, v3
	v_fmac_f32_e32 v5, v3, v4
	v_add_f32_e32 v3, v5, v5
	v_cndmask_b32_e32 v3, v5, v3, vcc
	v_cmp_nlt_f32_e32 vcc, s22, v0
	v_exp_f32_e32 v2, v2
	s_mov_b32 s21, 0x84000
	v_cndmask_b32_e64 v3, v201, -v3, vcc
	v_cmp_gt_f32_e32 vcc, s23, v3
	v_mul_f32_e32 v4, 0x4f800000, v3
	s_mov_b32 s22, 0x2d000
	v_cndmask_b32_e32 v3, v3, v4, vcc
	v_sqrt_f32_e32 v4, v3
	s_mov_b32 s23, 0x59000
	v_add_u32_e32 v5, -1, v4
	v_fma_f32 v6, -v5, v4, v3
	v_cmp_ge_f32_e64 s[0:1], 0, v6
	v_add_u32_e32 v6, 1, v4
	s_nop 0
	v_cndmask_b32_e64 v5, v4, v5, s[0:1]
	v_fma_f32 v4, -v6, v4, v3
	v_cmp_lt_f32_e64 s[0:1], 0, v4
	s_nop 1
	v_cndmask_b32_e64 v4, v5, v6, s[0:1]
	v_mul_f32_e32 v5, 0x37800000, v4
	v_cndmask_b32_e32 v4, v4, v5, vcc
	v_cmp_class_f32_e32 vcc, v3, v193
	v_mov_b32_e32 v5, 0
	s_nop 0
	v_cndmask_b32_e32 v3, v4, v3, vcc
	v_cmp_ngt_f32_e32 vcc, s24, v0
	v_readlane_b32 s24, v248, 7
	s_nop 0
	v_cndmask_b32_e32 v0, 1.0, v3, vcc
	v_mul_f32_e32 v0, v1, v0
	v_mul_f32_e32 v0, v33, v0
	ds_write_b32 v144, v2 offset:7040
	ds_write_b32 v144, v0 offset:43904
	v_mov_b32_e32 v0, 0
	s_waitcnt lgkmcnt(0)
	s_barrier
	s_cbranch_scc1 .LBB0_915
	v_lshl_add_u64 v[2:3], v[64:65], 0, s[4:5]
	v_add_co_u32_e32 v4, vcc, 0x13000, v2
	s_sub_i32 s0, s2, s12
	s_nop 0
	v_addc_co_u32_e32 v5, vcc, 0, v3, vcc
	global_load_dwordx2 v[4:5], v[4:5], off
	s_cmp_eq_u32 s0, 1
	s_waitcnt vmcnt(0)
	v_fmac_f32_e32 v5, 0, v4
	s_cbranch_scc1 .LBB0_915
	v_add_co_u32_e32 v2, vcc, 0x12000, v2
	s_cmp_eq_u32 s0, 2
	s_nop 0
	v_addc_co_u32_e32 v3, vcc, 0, v3, vcc
	global_load_dwordx2 v[2:3], v[2:3], off
	s_waitcnt vmcnt(0)
	v_fmac_f32_e32 v3, v5, v2
	s_cbranch_scc1 .LBB0_914
	s_mul_i32 s1, s11, 36
	s_add_i32 s2, s1, 36
	s_ashr_i32 s3, s2, 31
	s_lshl_b64 s[2:3], s[2:3], 12
	v_readlane_b32 s1, v249, 47
	s_add_u32 s2, s1, s2
	v_readlane_b32 s1, v249, 48
	v_add_lshl_u32 v96, s13, v141, 3
	s_addc_u32 s3, s1, s3
	v_lshl_add_u64 v[4:5], s[2:3], 0, v[96:97]
	s_add_i32 s0, s0, -2
